# v35 plus transposer double-issue, x8 fast path, hand-written lora_weight and rw_prep
# speedup vs baseline: 1.0106x; 1.0030x over previous
; __device__ __forceinline__ unsigned pk4_i8(float a, float b, float c, float d, float s) {
;     const unsigned ua = __float_as_uint(__builtin_amdgcn_fmed3f(a * s, -127.f, 127.f) + 12582912.f), ub = __float_as_uint(__builtin_amdgcn_fmed3f(b * s, -127.f, 127.f) + 12582912.f);
;     const unsigned uc = __float_as_uint(__builtin_amdgcn_fmed3f(c * s, -127.f, 127.f) + 12582912.f), ud = __float_as_uint(__builtin_amdgcn_fmed3f(d * s, -127.f, 127.f) + 12582912.f);
;     return (ua & 0xffu) | ((ub & 0xffu) << 8) | ((uc & 0xffu) << 16) | (ud << 24);
; __device__ __forceinline__ void p0_prologue(Frame& F) {
;     { unsigned char* x8 = F.ws + WS_XB8; const float* xp = F.in[I_XP]; const float* xs = F.in[I_XS];
;       const size_t total8 = (size_t)MP * D / 8; const size_t gt = (size_t)blockIdx.x * 512 + F.tid, NT = (size_t)F.G * 512;
;       for (size_t e = gt; e < total8; e += NT) { const size_t el = e * 8; const int row = (int)(el / D);
;           u32x2 o = (u32x2){0u, 0u};
;           if (row < MR) { const float* src = row < MPR ? xp + el : xs + (el - (size_t)MPR * D); const f32x4 a = *(const f32x4*)src, b = *(const f32x4*)(src + 4);
;               o.x = pk4_i8(a[0], a[1], a[2], a[3], I8_ACT); o.y = pk4_i8(b[0], b[1], b[2], b[3], I8_ACT); }
;           *(u32x2*)(x8 + el) = o; } }
.LBB0_6:
	s_or_b64 exec, exec, s[0:1]
	s_lshl_b64 s[0:1], s[2:3], 9
	s_ashr_i32 s97, s96, 31
	v_or_b32_e32 v2, s0, v0
	v_mov_b32_e32 v3, s1
	s_lshl_b64 s[0:1], s[96:97], 9
	v_mov_b32_e32 v167, 0
	v_writelane_b32 v240, s0, 0
	v_lshlrev_b32_e32 v166, 3, v0
	s_nop 0
	v_writelane_b32 v240, s1, 1
	s_cmp_lg_u32 s96, 0x100
	s_cbranch_scc1 .Lx8_generic
	s_load_dwordx4 s[8:11], s[74:75], 0x0
	v_and_b32_e32 v7, 63, v0
	v_lshlrev_b32_e32 v4, 4, v7
	v_add_u32_e32 v6, 0x1000, v4
	v_lshlrev_b32_e32 v5, 2, v7
	v_mov_b32_e32 v1, 0x42fe0000
	s_mov_b32 s3, 0xc2fe0000
	s_mov_b32 s15, 0x040c0c00
	s_mov_b32 s16, 0x0c04000c
	s_lshr_b32 s20, s86, 6
	s_lshl_b32 s21, s2, 3
	s_add_u32 s20, s20, s21
	s_lshl_b32 s21, s20, 13
	s_lshl_b32 s22, s20, 11
	s_waitcnt lgkmcnt(0)
	s_add_u32 s24, s8, s21
	s_addc_u32 s25, s9, 0
	s_add_u32 s32, s90, s22
	s_addc_u32 s33, s91, 0
	s_add_u32 s32, s32, 0x49d00000
	s_addc_u32 s33, s33, 0
	global_load_dwordx4 v[8:11], v4, s[24:25]
	global_load_dwordx4 v[12:15], v4, s[24:25] offset:1024
	global_load_dwordx4 v[16:19], v4, s[24:25] offset:2048
	global_load_dwordx4 v[20:23], v4, s[24:25] offset:3072
	global_load_dwordx4 v[24:27], v6, s[24:25]
	global_load_dwordx4 v[28:31], v6, s[24:25] offset:1024
	global_load_dwordx4 v[32:35], v6, s[24:25] offset:2048
	global_load_dwordx4 v[36:39], v6, s[24:25] offset:3072
	s_add_u32 s24, s24, 0x1000000
	s_addc_u32 s25, s25, 0
	global_load_dwordx4 v[40:43], v4, s[24:25]
	global_load_dwordx4 v[44:47], v4, s[24:25] offset:1024
	global_load_dwordx4 v[48:51], v4, s[24:25] offset:2048
	global_load_dwordx4 v[52:55], v4, s[24:25] offset:3072
	global_load_dwordx4 v[56:59], v6, s[24:25]
	global_load_dwordx4 v[60:63], v6, s[24:25] offset:1024
	global_load_dwordx4 v[64:67], v6, s[24:25] offset:2048
	global_load_dwordx4 v[68:71], v6, s[24:25] offset:3072
	s_add_u32 s24, s24, 0x1000000
	s_addc_u32 s25, s25, 0
	s_waitcnt vmcnt(8)
	s_mov_b32 s23, 7
.Lx8_loop:
	s_waitcnt vmcnt(16)
	v_mul_f32_e32 v8, 0x41fe0000, v8
	v_mul_f32_e32 v9, 0x41fe0000, v9
	v_mul_f32_e32 v10, 0x41fe0000, v10
	v_mul_f32_e32 v11, 0x41fe0000, v11
	v_mul_f32_e32 v12, 0x41fe0000, v12
	v_mul_f32_e32 v13, 0x41fe0000, v13
	v_mul_f32_e32 v14, 0x41fe0000, v14
	v_mul_f32_e32 v15, 0x41fe0000, v15
	v_mul_f32_e32 v16, 0x41fe0000, v16
	v_mul_f32_e32 v17, 0x41fe0000, v17
	v_mul_f32_e32 v18, 0x41fe0000, v18
	v_mul_f32_e32 v19, 0x41fe0000, v19
	v_mul_f32_e32 v20, 0x41fe0000, v20
	v_mul_f32_e32 v21, 0x41fe0000, v21
	v_mul_f32_e32 v22, 0x41fe0000, v22
	v_mul_f32_e32 v23, 0x41fe0000, v23
	v_mul_f32_e32 v24, 0x41fe0000, v24
	v_mul_f32_e32 v25, 0x41fe0000, v25
	v_mul_f32_e32 v26, 0x41fe0000, v26
	v_mul_f32_e32 v27, 0x41fe0000, v27
	v_mul_f32_e32 v28, 0x41fe0000, v28
	v_mul_f32_e32 v29, 0x41fe0000, v29
	v_mul_f32_e32 v30, 0x41fe0000, v30
	v_mul_f32_e32 v31, 0x41fe0000, v31
	v_mul_f32_e32 v32, 0x41fe0000, v32
	v_mul_f32_e32 v33, 0x41fe0000, v33
	v_mul_f32_e32 v34, 0x41fe0000, v34
	v_mul_f32_e32 v35, 0x41fe0000, v35
	v_mul_f32_e32 v36, 0x41fe0000, v36
	v_mul_f32_e32 v37, 0x41fe0000, v37
	v_mul_f32_e32 v38, 0x41fe0000, v38
	v_mul_f32_e32 v39, 0x41fe0000, v39
	v_med3_f32 v8, v8, s3, v1
	v_med3_f32 v9, v9, s3, v1
	v_med3_f32 v10, v10, s3, v1
	v_med3_f32 v11, v11, s3, v1
	v_med3_f32 v12, v12, s3, v1
	v_med3_f32 v13, v13, s3, v1
	v_med3_f32 v14, v14, s3, v1
	v_med3_f32 v15, v15, s3, v1
	v_med3_f32 v16, v16, s3, v1
	v_med3_f32 v17, v17, s3, v1
	v_med3_f32 v18, v18, s3, v1
	v_med3_f32 v19, v19, s3, v1
	v_med3_f32 v20, v20, s3, v1
	v_med3_f32 v21, v21, s3, v1
	v_med3_f32 v22, v22, s3, v1
	v_med3_f32 v23, v23, s3, v1
	v_med3_f32 v24, v24, s3, v1
	v_med3_f32 v25, v25, s3, v1
	v_med3_f32 v26, v26, s3, v1
	v_med3_f32 v27, v27, s3, v1
	v_med3_f32 v28, v28, s3, v1
	v_med3_f32 v29, v29, s3, v1
	v_med3_f32 v30, v30, s3, v1
	v_med3_f32 v31, v31, s3, v1
	v_med3_f32 v32, v32, s3, v1
	v_med3_f32 v33, v33, s3, v1
	v_med3_f32 v34, v34, s3, v1
	v_med3_f32 v35, v35, s3, v1
	v_med3_f32 v36, v36, s3, v1
	v_med3_f32 v37, v37, s3, v1
	v_med3_f32 v38, v38, s3, v1
	v_med3_f32 v39, v39, s3, v1
	v_add_f32_e32 v8, 0x4b400000, v8
	v_add_f32_e32 v9, 0x4b400000, v9
	v_add_f32_e32 v10, 0x4b400000, v10
	v_add_f32_e32 v11, 0x4b400000, v11
	v_add_f32_e32 v12, 0x4b400000, v12
	v_add_f32_e32 v13, 0x4b400000, v13
	v_add_f32_e32 v14, 0x4b400000, v14
	v_add_f32_e32 v15, 0x4b400000, v15
	v_add_f32_e32 v16, 0x4b400000, v16
	v_add_f32_e32 v17, 0x4b400000, v17
	v_add_f32_e32 v18, 0x4b400000, v18
	v_add_f32_e32 v19, 0x4b400000, v19
	v_add_f32_e32 v20, 0x4b400000, v20
	v_add_f32_e32 v21, 0x4b400000, v21
	v_add_f32_e32 v22, 0x4b400000, v22
	v_add_f32_e32 v23, 0x4b400000, v23
	v_add_f32_e32 v24, 0x4b400000, v24
	v_add_f32_e32 v25, 0x4b400000, v25
	v_add_f32_e32 v26, 0x4b400000, v26
	v_add_f32_e32 v27, 0x4b400000, v27
	v_add_f32_e32 v28, 0x4b400000, v28
	v_add_f32_e32 v29, 0x4b400000, v29
	v_add_f32_e32 v30, 0x4b400000, v30
	v_add_f32_e32 v31, 0x4b400000, v31
	v_add_f32_e32 v32, 0x4b400000, v32
	v_add_f32_e32 v33, 0x4b400000, v33
	v_add_f32_e32 v34, 0x4b400000, v34
	v_add_f32_e32 v35, 0x4b400000, v35
	v_add_f32_e32 v36, 0x4b400000, v36
	v_add_f32_e32 v37, 0x4b400000, v37
	v_add_f32_e32 v38, 0x4b400000, v38
	v_add_f32_e32 v39, 0x4b400000, v39
	v_perm_b32 v8, v11, v8, s15
	v_perm_b32 v9, v10, v9, s16
	v_or_b32_e32 v72, v8, v9
	v_perm_b32 v12, v15, v12, s15
	v_perm_b32 v13, v14, v13, s16
	v_or_b32_e32 v73, v12, v13
	v_perm_b32 v16, v19, v16, s15
	v_perm_b32 v17, v18, v17, s16
	v_or_b32_e32 v74, v16, v17
	v_perm_b32 v20, v23, v20, s15
	v_perm_b32 v21, v22, v21, s16
	v_or_b32_e32 v75, v20, v21
	v_perm_b32 v24, v27, v24, s15
	v_perm_b32 v25, v26, v25, s16
	v_or_b32_e32 v76, v24, v25
	v_perm_b32 v28, v31, v28, s15
	v_perm_b32 v29, v30, v29, s16
	v_or_b32_e32 v77, v28, v29
	v_perm_b32 v32, v35, v32, s15
	v_perm_b32 v33, v34, v33, s16
	v_or_b32_e32 v78, v32, v33
	v_perm_b32 v36, v39, v36, s15
	v_perm_b32 v37, v38, v37, s16
	v_or_b32_e32 v79, v36, v37
	global_store_dword v5, v72, s[32:33]
	global_store_dword v5, v73, s[32:33] offset:256
	global_store_dword v5, v74, s[32:33] offset:512
	global_store_dword v5, v75, s[32:33] offset:768
	global_store_dword v5, v76, s[32:33] offset:1024
	global_store_dword v5, v77, s[32:33] offset:1280
	global_store_dword v5, v78, s[32:33] offset:1536
	global_store_dword v5, v79, s[32:33] offset:1792
	s_add_u32 s32, s32, 0x400000
	s_addc_u32 s33, s33, 0
	global_load_dwordx4 v[8:11], v4, s[24:25]
	global_load_dwordx4 v[12:15], v4, s[24:25] offset:1024
	global_load_dwordx4 v[16:19], v4, s[24:25] offset:2048
	global_load_dwordx4 v[20:23], v4, s[24:25] offset:3072
	global_load_dwordx4 v[24:27], v6, s[24:25]
	global_load_dwordx4 v[28:31], v6, s[24:25] offset:1024
	global_load_dwordx4 v[32:35], v6, s[24:25] offset:2048
	global_load_dwordx4 v[36:39], v6, s[24:25] offset:3072
	s_add_u32 s24, s24, 0x1000000
	s_addc_u32 s25, s25, 0
	s_waitcnt vmcnt(16)
; __device__ __forceinline__ unsigned pk4_i8(float a, float b, float c, float d, float s) {
;     const unsigned ua = __float_as_uint(__builtin_amdgcn_fmed3f(a * s, -127.f, 127.f) + 12582912.f), ub = __float_as_uint(__builtin_amdgcn_fmed3f(b * s, -127.f, 127.f) + 12582912.f);
;     const unsigned uc = __float_as_uint(__builtin_amdgcn_fmed3f(c * s, -127.f, 127.f) + 12582912.f), ud = __float_as_uint(__builtin_amdgcn_fmed3f(d * s, -127.f, 127.f) + 12582912.f);
;     return (ua & 0xffu) | ((ub & 0xffu) << 8) | ((uc & 0xffu) << 16) | (ud << 24);
; __device__ __forceinline__ void p0_prologue(Frame& F) {
;     { unsigned char* x8 = F.ws + WS_XB8; const float* xp = F.in[I_XP]; const float* xs = F.in[I_XS];
;       const size_t total8 = (size_t)MP * D / 8; const size_t gt = (size_t)blockIdx.x * 512 + F.tid, NT = (size_t)F.G * 512;
;       for (size_t e = gt; e < total8; e += NT) { const size_t el = e * 8; const int row = (int)(el / D);
;           u32x2 o = (u32x2){0u, 0u};
;           if (row < MR) { const float* src = row < MPR ? xp + el : xs + (el - (size_t)MPR * D); const f32x4 a = *(const f32x4*)src, b = *(const f32x4*)(src + 4);
;               o.x = pk4_i8(a[0], a[1], a[2], a[3], I8_ACT); o.y = pk4_i8(b[0], b[1], b[2], b[3], I8_ACT); }
;           *(u32x2*)(x8 + el) = o; } }
	v_mul_f32_e32 v40, 0x41fe0000, v40
	v_mul_f32_e32 v41, 0x41fe0000, v41
	v_mul_f32_e32 v42, 0x41fe0000, v42
	v_mul_f32_e32 v43, 0x41fe0000, v43
	v_mul_f32_e32 v44, 0x41fe0000, v44
	v_mul_f32_e32 v45, 0x41fe0000, v45
	v_mul_f32_e32 v46, 0x41fe0000, v46
	v_mul_f32_e32 v47, 0x41fe0000, v47
	v_mul_f32_e32 v48, 0x41fe0000, v48
	v_mul_f32_e32 v49, 0x41fe0000, v49
	v_mul_f32_e32 v50, 0x41fe0000, v50
	v_mul_f32_e32 v51, 0x41fe0000, v51
	v_mul_f32_e32 v52, 0x41fe0000, v52
	v_mul_f32_e32 v53, 0x41fe0000, v53
	v_mul_f32_e32 v54, 0x41fe0000, v54
	v_mul_f32_e32 v55, 0x41fe0000, v55
	v_mul_f32_e32 v56, 0x41fe0000, v56
	v_mul_f32_e32 v57, 0x41fe0000, v57
	v_mul_f32_e32 v58, 0x41fe0000, v58
	v_mul_f32_e32 v59, 0x41fe0000, v59
	v_mul_f32_e32 v60, 0x41fe0000, v60
	v_mul_f32_e32 v61, 0x41fe0000, v61
	v_mul_f32_e32 v62, 0x41fe0000, v62
	v_mul_f32_e32 v63, 0x41fe0000, v63
	v_mul_f32_e32 v64, 0x41fe0000, v64
	v_mul_f32_e32 v65, 0x41fe0000, v65
	v_mul_f32_e32 v66, 0x41fe0000, v66
	v_mul_f32_e32 v67, 0x41fe0000, v67
	v_mul_f32_e32 v68, 0x41fe0000, v68
	v_mul_f32_e32 v69, 0x41fe0000, v69
	v_mul_f32_e32 v70, 0x41fe0000, v70
	v_mul_f32_e32 v71, 0x41fe0000, v71
	v_med3_f32 v40, v40, s3, v1
	v_med3_f32 v41, v41, s3, v1
	v_med3_f32 v42, v42, s3, v1
	v_med3_f32 v43, v43, s3, v1
	v_med3_f32 v44, v44, s3, v1
	v_med3_f32 v45, v45, s3, v1
	v_med3_f32 v46, v46, s3, v1
	v_med3_f32 v47, v47, s3, v1
	v_med3_f32 v48, v48, s3, v1
	v_med3_f32 v49, v49, s3, v1
	v_med3_f32 v50, v50, s3, v1
	v_med3_f32 v51, v51, s3, v1
	v_med3_f32 v52, v52, s3, v1
	v_med3_f32 v53, v53, s3, v1
	v_med3_f32 v54, v54, s3, v1
	v_med3_f32 v55, v55, s3, v1
	v_med3_f32 v56, v56, s3, v1
	v_med3_f32 v57, v57, s3, v1
	v_med3_f32 v58, v58, s3, v1
	v_med3_f32 v59, v59, s3, v1
	v_med3_f32 v60, v60, s3, v1
	v_med3_f32 v61, v61, s3, v1
	v_med3_f32 v62, v62, s3, v1
	v_med3_f32 v63, v63, s3, v1
	v_med3_f32 v64, v64, s3, v1
	v_med3_f32 v65, v65, s3, v1
	v_med3_f32 v66, v66, s3, v1
	v_med3_f32 v67, v67, s3, v1
	v_med3_f32 v68, v68, s3, v1
	v_med3_f32 v69, v69, s3, v1
	v_med3_f32 v70, v70, s3, v1
	v_med3_f32 v71, v71, s3, v1
	v_add_f32_e32 v40, 0x4b400000, v40
	v_add_f32_e32 v41, 0x4b400000, v41
	v_add_f32_e32 v42, 0x4b400000, v42
	v_add_f32_e32 v43, 0x4b400000, v43
	v_add_f32_e32 v44, 0x4b400000, v44
	v_add_f32_e32 v45, 0x4b400000, v45
	v_add_f32_e32 v46, 0x4b400000, v46
	v_add_f32_e32 v47, 0x4b400000, v47
	v_add_f32_e32 v48, 0x4b400000, v48
	v_add_f32_e32 v49, 0x4b400000, v49
	v_add_f32_e32 v50, 0x4b400000, v50
	v_add_f32_e32 v51, 0x4b400000, v51
	v_add_f32_e32 v52, 0x4b400000, v52
	v_add_f32_e32 v53, 0x4b400000, v53
	v_add_f32_e32 v54, 0x4b400000, v54
	v_add_f32_e32 v55, 0x4b400000, v55
	v_add_f32_e32 v56, 0x4b400000, v56
	v_add_f32_e32 v57, 0x4b400000, v57
	v_add_f32_e32 v58, 0x4b400000, v58
	v_add_f32_e32 v59, 0x4b400000, v59
	v_add_f32_e32 v60, 0x4b400000, v60
	v_add_f32_e32 v61, 0x4b400000, v61
	v_add_f32_e32 v62, 0x4b400000, v62
	v_add_f32_e32 v63, 0x4b400000, v63
	v_add_f32_e32 v64, 0x4b400000, v64
	v_add_f32_e32 v65, 0x4b400000, v65
	v_add_f32_e32 v66, 0x4b400000, v66
	v_add_f32_e32 v67, 0x4b400000, v67
	v_add_f32_e32 v68, 0x4b400000, v68
	v_add_f32_e32 v69, 0x4b400000, v69
	v_add_f32_e32 v70, 0x4b400000, v70
	v_add_f32_e32 v71, 0x4b400000, v71
	v_perm_b32 v40, v43, v40, s15
	v_perm_b32 v41, v42, v41, s16
	v_or_b32_e32 v72, v40, v41
	v_perm_b32 v44, v47, v44, s15
	v_perm_b32 v45, v46, v45, s16
	v_or_b32_e32 v73, v44, v45
	v_perm_b32 v48, v51, v48, s15
	v_perm_b32 v49, v50, v49, s16
	v_or_b32_e32 v74, v48, v49
	v_perm_b32 v52, v55, v52, s15
	v_perm_b32 v53, v54, v53, s16
	v_or_b32_e32 v75, v52, v53
	v_perm_b32 v56, v59, v56, s15
	v_perm_b32 v57, v58, v57, s16
	v_or_b32_e32 v76, v56, v57
	v_perm_b32 v60, v63, v60, s15
	v_perm_b32 v61, v62, v61, s16
	v_or_b32_e32 v77, v60, v61
	v_perm_b32 v64, v67, v64, s15
	v_perm_b32 v65, v66, v65, s16
	v_or_b32_e32 v78, v64, v65
	v_perm_b32 v68, v71, v68, s15
	v_perm_b32 v69, v70, v69, s16
	v_or_b32_e32 v79, v68, v69
	global_store_dword v5, v72, s[32:33]
	global_store_dword v5, v73, s[32:33] offset:256
	global_store_dword v5, v74, s[32:33] offset:512
	global_store_dword v5, v75, s[32:33] offset:768
	global_store_dword v5, v76, s[32:33] offset:1024
	global_store_dword v5, v77, s[32:33] offset:1280
	global_store_dword v5, v78, s[32:33] offset:1536
	global_store_dword v5, v79, s[32:33] offset:1792
	s_add_u32 s32, s32, 0x400000
	s_addc_u32 s33, s33, 0
	global_load_dwordx4 v[40:43], v4, s[24:25]
	global_load_dwordx4 v[44:47], v4, s[24:25] offset:1024
	global_load_dwordx4 v[48:51], v4, s[24:25] offset:2048
	global_load_dwordx4 v[52:55], v4, s[24:25] offset:3072
	global_load_dwordx4 v[56:59], v6, s[24:25]
	global_load_dwordx4 v[60:63], v6, s[24:25] offset:1024
	global_load_dwordx4 v[64:67], v6, s[24:25] offset:2048
	global_load_dwordx4 v[68:71], v6, s[24:25] offset:3072
	s_add_u32 s24, s24, 0x1000000
	s_addc_u32 s25, s25, 0
	s_sub_u32 s23, s23, 1
	s_cmp_lg_u32 s23, 0
	s_cbranch_scc1 .Lx8_loop
; __device__ __forceinline__ void p0_prologue(Frame& F) {
;     { unsigned char* x8 = F.ws + WS_XB8; const float* xp = F.in[I_XP]; const float* xs = F.in[I_XS];
;       const size_t total8 = (size_t)MP * D / 8; const size_t gt = (size_t)blockIdx.x * 512 + F.tid, NT = (size_t)F.G * 512;
;       for (size_t e = gt; e < total8; e += NT) { const size_t el = e * 8; const int row = (int)(el / D);
;           u32x2 o = (u32x2){0u, 0u};
;           if (row < MR) { const float* src = row < MPR ? xp + el : xs + (el - (size_t)MPR * D); const f32x4 a = *(const f32x4*)src, b = *(const f32x4*)(src + 4);
;               o.x = pk4_i8(a[0], a[1], a[2], a[3], I8_ACT); o.y = pk4_i8(b[0], b[1], b[2], b[3], I8_ACT); }
;           *(u32x2*)(x8 + el) = o; } }
	s_waitcnt vmcnt(16)
	v_mul_f32_e32 v8, 0x41fe0000, v8
	v_mul_f32_e32 v9, 0x41fe0000, v9
	v_mul_f32_e32 v10, 0x41fe0000, v10
	v_mul_f32_e32 v11, 0x41fe0000, v11
	v_mul_f32_e32 v12, 0x41fe0000, v12
	v_mul_f32_e32 v13, 0x41fe0000, v13
	v_mul_f32_e32 v14, 0x41fe0000, v14
	v_mul_f32_e32 v15, 0x41fe0000, v15
	v_mul_f32_e32 v16, 0x41fe0000, v16
	v_mul_f32_e32 v17, 0x41fe0000, v17
	v_mul_f32_e32 v18, 0x41fe0000, v18
	v_mul_f32_e32 v19, 0x41fe0000, v19
	v_mul_f32_e32 v20, 0x41fe0000, v20
	v_mul_f32_e32 v21, 0x41fe0000, v21
	v_mul_f32_e32 v22, 0x41fe0000, v22
	v_mul_f32_e32 v23, 0x41fe0000, v23
	v_mul_f32_e32 v24, 0x41fe0000, v24
	v_mul_f32_e32 v25, 0x41fe0000, v25
	v_mul_f32_e32 v26, 0x41fe0000, v26
	v_mul_f32_e32 v27, 0x41fe0000, v27
	v_mul_f32_e32 v28, 0x41fe0000, v28
	v_mul_f32_e32 v29, 0x41fe0000, v29
	v_mul_f32_e32 v30, 0x41fe0000, v30
	v_mul_f32_e32 v31, 0x41fe0000, v31
	v_mul_f32_e32 v32, 0x41fe0000, v32
	v_mul_f32_e32 v33, 0x41fe0000, v33
	v_mul_f32_e32 v34, 0x41fe0000, v34
	v_mul_f32_e32 v35, 0x41fe0000, v35
	v_mul_f32_e32 v36, 0x41fe0000, v36
	v_mul_f32_e32 v37, 0x41fe0000, v37
	v_mul_f32_e32 v38, 0x41fe0000, v38
	v_mul_f32_e32 v39, 0x41fe0000, v39
	v_med3_f32 v8, v8, s3, v1
	v_med3_f32 v9, v9, s3, v1
	v_med3_f32 v10, v10, s3, v1
	v_med3_f32 v11, v11, s3, v1
	v_med3_f32 v12, v12, s3, v1
	v_med3_f32 v13, v13, s3, v1
	v_med3_f32 v14, v14, s3, v1
	v_med3_f32 v15, v15, s3, v1
	v_med3_f32 v16, v16, s3, v1
	v_med3_f32 v17, v17, s3, v1
	v_med3_f32 v18, v18, s3, v1
	v_med3_f32 v19, v19, s3, v1
	v_med3_f32 v20, v20, s3, v1
	v_med3_f32 v21, v21, s3, v1
	v_med3_f32 v22, v22, s3, v1
	v_med3_f32 v23, v23, s3, v1
	v_med3_f32 v24, v24, s3, v1
	v_med3_f32 v25, v25, s3, v1
	v_med3_f32 v26, v26, s3, v1
	v_med3_f32 v27, v27, s3, v1
	v_med3_f32 v28, v28, s3, v1
	v_med3_f32 v29, v29, s3, v1
	v_med3_f32 v30, v30, s3, v1
	v_med3_f32 v31, v31, s3, v1
	v_med3_f32 v32, v32, s3, v1
	v_med3_f32 v33, v33, s3, v1
	v_med3_f32 v34, v34, s3, v1
	v_med3_f32 v35, v35, s3, v1
	v_med3_f32 v36, v36, s3, v1
	v_med3_f32 v37, v37, s3, v1
	v_med3_f32 v38, v38, s3, v1
	v_med3_f32 v39, v39, s3, v1
	v_add_f32_e32 v8, 0x4b400000, v8
	v_add_f32_e32 v9, 0x4b400000, v9
	v_add_f32_e32 v10, 0x4b400000, v10
	v_add_f32_e32 v11, 0x4b400000, v11
	v_add_f32_e32 v12, 0x4b400000, v12
	v_add_f32_e32 v13, 0x4b400000, v13
	v_add_f32_e32 v14, 0x4b400000, v14
	v_add_f32_e32 v15, 0x4b400000, v15
	v_add_f32_e32 v16, 0x4b400000, v16
	v_add_f32_e32 v17, 0x4b400000, v17
	v_add_f32_e32 v18, 0x4b400000, v18
	v_add_f32_e32 v19, 0x4b400000, v19
	v_add_f32_e32 v20, 0x4b400000, v20
	v_add_f32_e32 v21, 0x4b400000, v21
	v_add_f32_e32 v22, 0x4b400000, v22
	v_add_f32_e32 v23, 0x4b400000, v23
	v_add_f32_e32 v24, 0x4b400000, v24
	v_add_f32_e32 v25, 0x4b400000, v25
	v_add_f32_e32 v26, 0x4b400000, v26
	v_add_f32_e32 v27, 0x4b400000, v27
	v_add_f32_e32 v28, 0x4b400000, v28
	v_add_f32_e32 v29, 0x4b400000, v29
	v_add_f32_e32 v30, 0x4b400000, v30
	v_add_f32_e32 v31, 0x4b400000, v31
	v_add_f32_e32 v32, 0x4b400000, v32
	v_add_f32_e32 v33, 0x4b400000, v33
	v_add_f32_e32 v34, 0x4b400000, v34
	v_add_f32_e32 v35, 0x4b400000, v35
	v_add_f32_e32 v36, 0x4b400000, v36
	v_add_f32_e32 v37, 0x4b400000, v37
	v_add_f32_e32 v38, 0x4b400000, v38
	v_add_f32_e32 v39, 0x4b400000, v39
	v_perm_b32 v8, v11, v8, s15
	v_perm_b32 v9, v10, v9, s16
	v_or_b32_e32 v72, v8, v9
	v_perm_b32 v12, v15, v12, s15
	v_perm_b32 v13, v14, v13, s16
	v_or_b32_e32 v73, v12, v13
	v_perm_b32 v16, v19, v16, s15
	v_perm_b32 v17, v18, v17, s16
	v_or_b32_e32 v74, v16, v17
	v_perm_b32 v20, v23, v20, s15
	v_perm_b32 v21, v22, v21, s16
	v_or_b32_e32 v75, v20, v21
	v_perm_b32 v24, v27, v24, s15
	v_perm_b32 v25, v26, v25, s16
	v_or_b32_e32 v76, v24, v25
	v_perm_b32 v28, v31, v28, s15
	v_perm_b32 v29, v30, v29, s16
	v_or_b32_e32 v77, v28, v29
	v_perm_b32 v32, v35, v32, s15
	v_perm_b32 v33, v34, v33, s16
	v_or_b32_e32 v78, v32, v33
	v_perm_b32 v36, v39, v36, s15
	v_perm_b32 v37, v38, v37, s16
	v_or_b32_e32 v79, v36, v37
	global_store_dword v5, v72, s[32:33]
	global_store_dword v5, v73, s[32:33] offset:256
	global_store_dword v5, v74, s[32:33] offset:512
	global_store_dword v5, v75, s[32:33] offset:768
	global_store_dword v5, v76, s[32:33] offset:1024
	global_store_dword v5, v77, s[32:33] offset:1280
	global_store_dword v5, v78, s[32:33] offset:1536
	global_store_dword v5, v79, s[32:33] offset:1792
	s_add_u32 s32, s32, 0x400000
	s_addc_u32 s33, s33, 0
	s_waitcnt vmcnt(8)
; __device__ __forceinline__ void p0_prologue(Frame& F) {
;     { unsigned char* x8 = F.ws + WS_XB8; const float* xp = F.in[I_XP]; const float* xs = F.in[I_XS];
;       const size_t total8 = (size_t)MP * D / 8; const size_t gt = (size_t)blockIdx.x * 512 + F.tid, NT = (size_t)F.G * 512;
;       for (size_t e = gt; e < total8; e += NT) { const size_t el = e * 8; const int row = (int)(el / D);
;           u32x2 o = (u32x2){0u, 0u};
;           if (row < MR) { const float* src = row < MPR ? xp + el : xs + (el - (size_t)MPR * D); const f32x4 a = *(const f32x4*)src, b = *(const f32x4*)(src + 4);
;               o.x = pk4_i8(a[0], a[1], a[2], a[3], I8_ACT); o.y = pk4_i8(b[0], b[1], b[2], b[3], I8_ACT); }
;           *(u32x2*)(x8 + el) = o; } }
	v_mul_f32_e32 v40, 0x41fe0000, v40
	v_mul_f32_e32 v41, 0x41fe0000, v41
	v_mul_f32_e32 v42, 0x41fe0000, v42
	v_mul_f32_e32 v43, 0x41fe0000, v43
	v_mul_f32_e32 v44, 0x41fe0000, v44
	v_mul_f32_e32 v45, 0x41fe0000, v45
	v_mul_f32_e32 v46, 0x41fe0000, v46
	v_mul_f32_e32 v47, 0x41fe0000, v47
	v_mul_f32_e32 v48, 0x41fe0000, v48
	v_mul_f32_e32 v49, 0x41fe0000, v49
	v_mul_f32_e32 v50, 0x41fe0000, v50
	v_mul_f32_e32 v51, 0x41fe0000, v51
	v_mul_f32_e32 v52, 0x41fe0000, v52
	v_mul_f32_e32 v53, 0x41fe0000, v53
	v_mul_f32_e32 v54, 0x41fe0000, v54
	v_mul_f32_e32 v55, 0x41fe0000, v55
	v_mul_f32_e32 v56, 0x41fe0000, v56
	v_mul_f32_e32 v57, 0x41fe0000, v57
	v_mul_f32_e32 v58, 0x41fe0000, v58
	v_mul_f32_e32 v59, 0x41fe0000, v59
	v_mul_f32_e32 v60, 0x41fe0000, v60
	v_mul_f32_e32 v61, 0x41fe0000, v61
	v_mul_f32_e32 v62, 0x41fe0000, v62
	v_mul_f32_e32 v63, 0x41fe0000, v63
	v_mul_f32_e32 v64, 0x41fe0000, v64
	v_mul_f32_e32 v65, 0x41fe0000, v65
	v_mul_f32_e32 v66, 0x41fe0000, v66
	v_mul_f32_e32 v67, 0x41fe0000, v67
	v_mul_f32_e32 v68, 0x41fe0000, v68
	v_mul_f32_e32 v69, 0x41fe0000, v69
	v_mul_f32_e32 v70, 0x41fe0000, v70
	v_mul_f32_e32 v71, 0x41fe0000, v71
	v_med3_f32 v40, v40, s3, v1
	v_med3_f32 v41, v41, s3, v1
	v_med3_f32 v42, v42, s3, v1
	v_med3_f32 v43, v43, s3, v1
	v_med3_f32 v44, v44, s3, v1
	v_med3_f32 v45, v45, s3, v1
	v_med3_f32 v46, v46, s3, v1
	v_med3_f32 v47, v47, s3, v1
	v_med3_f32 v48, v48, s3, v1
	v_med3_f32 v49, v49, s3, v1
	v_med3_f32 v50, v50, s3, v1
	v_med3_f32 v51, v51, s3, v1
	v_med3_f32 v52, v52, s3, v1
	v_med3_f32 v53, v53, s3, v1
	v_med3_f32 v54, v54, s3, v1
	v_med3_f32 v55, v55, s3, v1
	v_med3_f32 v56, v56, s3, v1
	v_med3_f32 v57, v57, s3, v1
	v_med3_f32 v58, v58, s3, v1
	v_med3_f32 v59, v59, s3, v1
	v_med3_f32 v60, v60, s3, v1
	v_med3_f32 v61, v61, s3, v1
	v_med3_f32 v62, v62, s3, v1
	v_med3_f32 v63, v63, s3, v1
	v_med3_f32 v64, v64, s3, v1
	v_med3_f32 v65, v65, s3, v1
	v_med3_f32 v66, v66, s3, v1
	v_med3_f32 v67, v67, s3, v1
	v_med3_f32 v68, v68, s3, v1
	v_med3_f32 v69, v69, s3, v1
	v_med3_f32 v70, v70, s3, v1
	v_med3_f32 v71, v71, s3, v1
	v_add_f32_e32 v40, 0x4b400000, v40
	v_add_f32_e32 v41, 0x4b400000, v41
	v_add_f32_e32 v42, 0x4b400000, v42
	v_add_f32_e32 v43, 0x4b400000, v43
	v_add_f32_e32 v44, 0x4b400000, v44
	v_add_f32_e32 v45, 0x4b400000, v45
	v_add_f32_e32 v46, 0x4b400000, v46
	v_add_f32_e32 v47, 0x4b400000, v47
	v_add_f32_e32 v48, 0x4b400000, v48
	v_add_f32_e32 v49, 0x4b400000, v49
	v_add_f32_e32 v50, 0x4b400000, v50
	v_add_f32_e32 v51, 0x4b400000, v51
	v_add_f32_e32 v52, 0x4b400000, v52
	v_add_f32_e32 v53, 0x4b400000, v53
	v_add_f32_e32 v54, 0x4b400000, v54
	v_add_f32_e32 v55, 0x4b400000, v55
	v_add_f32_e32 v56, 0x4b400000, v56
	v_add_f32_e32 v57, 0x4b400000, v57
	v_add_f32_e32 v58, 0x4b400000, v58
	v_add_f32_e32 v59, 0x4b400000, v59
	v_add_f32_e32 v60, 0x4b400000, v60
	v_add_f32_e32 v61, 0x4b400000, v61
	v_add_f32_e32 v62, 0x4b400000, v62
	v_add_f32_e32 v63, 0x4b400000, v63
	v_add_f32_e32 v64, 0x4b400000, v64
	v_add_f32_e32 v65, 0x4b400000, v65
	v_add_f32_e32 v66, 0x4b400000, v66
	v_add_f32_e32 v67, 0x4b400000, v67
	v_add_f32_e32 v68, 0x4b400000, v68
	v_add_f32_e32 v69, 0x4b400000, v69
	v_add_f32_e32 v70, 0x4b400000, v70
	v_add_f32_e32 v71, 0x4b400000, v71
	v_perm_b32 v40, v43, v40, s15
	v_perm_b32 v41, v42, v41, s16
	v_or_b32_e32 v72, v40, v41
	v_perm_b32 v44, v47, v44, s15
	v_perm_b32 v45, v46, v45, s16
	v_or_b32_e32 v73, v44, v45
	v_perm_b32 v48, v51, v48, s15
	v_perm_b32 v49, v50, v49, s16
	v_or_b32_e32 v74, v48, v49
	v_perm_b32 v52, v55, v52, s15
	v_perm_b32 v53, v54, v53, s16
	v_or_b32_e32 v75, v52, v53
	v_perm_b32 v56, v59, v56, s15
	v_perm_b32 v57, v58, v57, s16
	v_or_b32_e32 v76, v56, v57
	v_perm_b32 v60, v63, v60, s15
	v_perm_b32 v61, v62, v61, s16
	v_or_b32_e32 v77, v60, v61
	v_perm_b32 v64, v67, v64, s15
	v_perm_b32 v65, v66, v65, s16
	v_or_b32_e32 v78, v64, v65
	v_perm_b32 v68, v71, v68, s15
	v_perm_b32 v69, v70, v69, s16
	v_or_b32_e32 v79, v68, v69
	global_store_dword v5, v72, s[32:33]
	global_store_dword v5, v73, s[32:33] offset:256
	global_store_dword v5, v74, s[32:33] offset:512
	global_store_dword v5, v75, s[32:33] offset:768
	global_store_dword v5, v76, s[32:33] offset:1024
	global_store_dword v5, v77, s[32:33] offset:1280
	global_store_dword v5, v78, s[32:33] offset:1536
	global_store_dword v5, v79, s[32:33] offset:1792
	s_add_u32 s32, s32, 0x400000
	s_addc_u32 s33, s33, 0
	s_cmp_lt_u32 s20, 0x100
	s_cbranch_scc0 .Lx8_pad
; __device__ __forceinline__ void p0_prologue(Frame& F) {
;     { unsigned char* x8 = F.ws + WS_XB8; const float* xp = F.in[I_XP]; const float* xs = F.in[I_XS];
;       const size_t total8 = (size_t)MP * D / 8; const size_t gt = (size_t)blockIdx.x * 512 + F.tid, NT = (size_t)F.G * 512;
;       for (size_t e = gt; e < total8; e += NT) { const size_t el = e * 8; const int row = (int)(el / D);
;           u32x2 o = (u32x2){0u, 0u};
;           if (row < MR) { const float* src = row < MPR ? xp + el : xs + (el - (size_t)MPR * D); const f32x4 a = *(const f32x4*)src, b = *(const f32x4*)(src + 4);
;               o.x = pk4_i8(a[0], a[1], a[2], a[3], I8_ACT); o.y = pk4_i8(b[0], b[1], b[2], b[3], I8_ACT); }
;           *(u32x2*)(x8 + el) = o; } }
	s_add_u32 s24, s10, s21
	s_addc_u32 s25, s11, 0
	global_load_dwordx4 v[8:11], v4, s[24:25]
	global_load_dwordx4 v[12:15], v4, s[24:25] offset:1024
	global_load_dwordx4 v[16:19], v4, s[24:25] offset:2048
	global_load_dwordx4 v[20:23], v4, s[24:25] offset:3072
	global_load_dwordx4 v[24:27], v6, s[24:25]
	global_load_dwordx4 v[28:31], v6, s[24:25] offset:1024
	global_load_dwordx4 v[32:35], v6, s[24:25] offset:2048
	global_load_dwordx4 v[36:39], v6, s[24:25] offset:3072
	s_waitcnt vmcnt(0)
	v_mul_f32_e32 v8, 0x41fe0000, v8
	v_mul_f32_e32 v9, 0x41fe0000, v9
	v_mul_f32_e32 v10, 0x41fe0000, v10
	v_mul_f32_e32 v11, 0x41fe0000, v11
	v_mul_f32_e32 v12, 0x41fe0000, v12
	v_mul_f32_e32 v13, 0x41fe0000, v13
	v_mul_f32_e32 v14, 0x41fe0000, v14
	v_mul_f32_e32 v15, 0x41fe0000, v15
	v_mul_f32_e32 v16, 0x41fe0000, v16
	v_mul_f32_e32 v17, 0x41fe0000, v17
	v_mul_f32_e32 v18, 0x41fe0000, v18
	v_mul_f32_e32 v19, 0x41fe0000, v19
	v_mul_f32_e32 v20, 0x41fe0000, v20
	v_mul_f32_e32 v21, 0x41fe0000, v21
	v_mul_f32_e32 v22, 0x41fe0000, v22
	v_mul_f32_e32 v23, 0x41fe0000, v23
	v_mul_f32_e32 v24, 0x41fe0000, v24
	v_mul_f32_e32 v25, 0x41fe0000, v25
	v_mul_f32_e32 v26, 0x41fe0000, v26
	v_mul_f32_e32 v27, 0x41fe0000, v27
	v_mul_f32_e32 v28, 0x41fe0000, v28
	v_mul_f32_e32 v29, 0x41fe0000, v29
	v_mul_f32_e32 v30, 0x41fe0000, v30
	v_mul_f32_e32 v31, 0x41fe0000, v31
	v_mul_f32_e32 v32, 0x41fe0000, v32
	v_mul_f32_e32 v33, 0x41fe0000, v33
	v_mul_f32_e32 v34, 0x41fe0000, v34
	v_mul_f32_e32 v35, 0x41fe0000, v35
	v_mul_f32_e32 v36, 0x41fe0000, v36
	v_mul_f32_e32 v37, 0x41fe0000, v37
	v_mul_f32_e32 v38, 0x41fe0000, v38
	v_mul_f32_e32 v39, 0x41fe0000, v39
	v_med3_f32 v8, v8, s3, v1
	v_med3_f32 v9, v9, s3, v1
	v_med3_f32 v10, v10, s3, v1
	v_med3_f32 v11, v11, s3, v1
	v_med3_f32 v12, v12, s3, v1
	v_med3_f32 v13, v13, s3, v1
	v_med3_f32 v14, v14, s3, v1
	v_med3_f32 v15, v15, s3, v1
	v_med3_f32 v16, v16, s3, v1
	v_med3_f32 v17, v17, s3, v1
	v_med3_f32 v18, v18, s3, v1
	v_med3_f32 v19, v19, s3, v1
	v_med3_f32 v20, v20, s3, v1
	v_med3_f32 v21, v21, s3, v1
	v_med3_f32 v22, v22, s3, v1
	v_med3_f32 v23, v23, s3, v1
	v_med3_f32 v24, v24, s3, v1
	v_med3_f32 v25, v25, s3, v1
	v_med3_f32 v26, v26, s3, v1
	v_med3_f32 v27, v27, s3, v1
	v_med3_f32 v28, v28, s3, v1
	v_med3_f32 v29, v29, s3, v1
	v_med3_f32 v30, v30, s3, v1
	v_med3_f32 v31, v31, s3, v1
	v_med3_f32 v32, v32, s3, v1
	v_med3_f32 v33, v33, s3, v1
	v_med3_f32 v34, v34, s3, v1
	v_med3_f32 v35, v35, s3, v1
	v_med3_f32 v36, v36, s3, v1
	v_med3_f32 v37, v37, s3, v1
	v_med3_f32 v38, v38, s3, v1
	v_med3_f32 v39, v39, s3, v1
	v_add_f32_e32 v8, 0x4b400000, v8
	v_add_f32_e32 v9, 0x4b400000, v9
	v_add_f32_e32 v10, 0x4b400000, v10
	v_add_f32_e32 v11, 0x4b400000, v11
	v_add_f32_e32 v12, 0x4b400000, v12
	v_add_f32_e32 v13, 0x4b400000, v13
	v_add_f32_e32 v14, 0x4b400000, v14
	v_add_f32_e32 v15, 0x4b400000, v15
	v_add_f32_e32 v16, 0x4b400000, v16
	v_add_f32_e32 v17, 0x4b400000, v17
	v_add_f32_e32 v18, 0x4b400000, v18
	v_add_f32_e32 v19, 0x4b400000, v19
	v_add_f32_e32 v20, 0x4b400000, v20
	v_add_f32_e32 v21, 0x4b400000, v21
	v_add_f32_e32 v22, 0x4b400000, v22
	v_add_f32_e32 v23, 0x4b400000, v23
	v_add_f32_e32 v24, 0x4b400000, v24
	v_add_f32_e32 v25, 0x4b400000, v25
	v_add_f32_e32 v26, 0x4b400000, v26
	v_add_f32_e32 v27, 0x4b400000, v27
	v_add_f32_e32 v28, 0x4b400000, v28
	v_add_f32_e32 v29, 0x4b400000, v29
	v_add_f32_e32 v30, 0x4b400000, v30
	v_add_f32_e32 v31, 0x4b400000, v31
	v_add_f32_e32 v32, 0x4b400000, v32
	v_add_f32_e32 v33, 0x4b400000, v33
	v_add_f32_e32 v34, 0x4b400000, v34
	v_add_f32_e32 v35, 0x4b400000, v35
	v_add_f32_e32 v36, 0x4b400000, v36
	v_add_f32_e32 v37, 0x4b400000, v37
	v_add_f32_e32 v38, 0x4b400000, v38
	v_add_f32_e32 v39, 0x4b400000, v39
	v_perm_b32 v8, v11, v8, s15
	v_perm_b32 v9, v10, v9, s16
	v_or_b32_e32 v72, v8, v9
	v_perm_b32 v12, v15, v12, s15
	v_perm_b32 v13, v14, v13, s16
	v_or_b32_e32 v73, v12, v13
	v_perm_b32 v16, v19, v16, s15
	v_perm_b32 v17, v18, v17, s16
	v_or_b32_e32 v74, v16, v17
	v_perm_b32 v20, v23, v20, s15
	v_perm_b32 v21, v22, v21, s16
	v_or_b32_e32 v75, v20, v21
	v_perm_b32 v24, v27, v24, s15
	v_perm_b32 v25, v26, v25, s16
	v_or_b32_e32 v76, v24, v25
	v_perm_b32 v28, v31, v28, s15
	v_perm_b32 v29, v30, v29, s16
	v_or_b32_e32 v77, v28, v29
	v_perm_b32 v32, v35, v32, s15
	v_perm_b32 v33, v34, v33, s16
	v_or_b32_e32 v78, v32, v33
	v_perm_b32 v36, v39, v36, s15
	v_perm_b32 v37, v38, v37, s16
	v_or_b32_e32 v79, v36, v37
	global_store_dword v5, v72, s[32:33]
	global_store_dword v5, v73, s[32:33] offset:256
	global_store_dword v5, v74, s[32:33] offset:512
	global_store_dword v5, v75, s[32:33] offset:768
	global_store_dword v5, v76, s[32:33] offset:1024
	global_store_dword v5, v77, s[32:33] offset:1280
	global_store_dword v5, v78, s[32:33] offset:1536
	global_store_dword v5, v79, s[32:33] offset:1792
.Lx8_pad:
	s_lshl_b32 s22, s20, 8
	s_add_u32 s34, s90, s22
	s_addc_u32 s35, s91, 0
	s_add_u32 s34, s34, 0x4dd80000
	s_addc_u32 s35, s35, 0
	v_mov_b32_e32 v72, 0
	global_store_dword v5, v72, s[34:35]
	s_branch .Lx8_done
.Lx8_generic:
	s_mov_b64 s[0:1], 0x820000
	v_cmp_gt_u64_e32 vcc, s[0:1], v[2:3]
	s_and_saveexec_b64 s[0:1], vcc
	s_cbranch_execz .LBB0_11
	s_load_dwordx4 s[8:11], s[74:75], 0x0
	s_mov_b64 s[14:15], 0x810000
	s_mov_b64 s[16:17], 0x800000
	s_mov_b32 s18, 0x4b400000
	s_mov_b32 s19, 0x40c0c00
	s_waitcnt lgkmcnt(0)
	s_add_u32 s4, s10, 0xf0000000
	s_addc_u32 s5, s11, -1
	s_lshl_b64 s[10:11], s[2:3], 14
	s_lshl_b64 s[6:7], s[96:97], 14
	s_lshl_b64 s[12:13], s[2:3], 12
	v_lshl_or_b32 v4, v0, 5, s10
	s_add_u32 s10, s90, s12
	v_mov_b32_e32 v5, s11
	s_addc_u32 s11, s91, s13
	v_lshl_add_u64 v[6:7], s[10:11], 0, v[166:167]
	s_mov_b64 s[10:11], 0x49d00000
	v_lshl_add_u64 v[6:7], v[6:7], 0, s[10:11]
	s_lshl_b64 s[10:11], s[96:97], 12
	s_mov_b64 s[12:13], 0
	s_mov_b32 s3, 0xc2fe0000
	s_mov_b64 s[20:21], 0x81ffff
	v_mov_b32_e32 v1, 0x42fe0000
	s_branch .LBB0_9

; #define LAS __attribute__((address_space(3)))
;     if (ldw == 0) ldw = N;
;     LAS float* scr = (LAS float*)(F.lds + F.wave * 16384); const int lane = F.lane;
;     const int nblk = N / 32, nitems = (K / 64) * nblk;
;     for (int item = F.gw; item < nitems; item += F.NGW) { const int kb = item / nblk, nb = item % nblk, k0 = 64 * kb, n0 = 32 * nb;
;         int dr0 = n0; if (MAP == 1) { if (n0 < DFF) dr0 = (n0 >> 7) * 256 + (n0 & 127); else { const int uo = n0 - DFF; dr0 = (uo >> 7) * 256 + 128 + (uo & 127); } }
; #pragma unroll 8
;         for (int i = 0; i < 32; ++i) { const int kk = 2 * i + (lane >> 5); scr[kk * 33 + (lane & 31)] = W[(size_t)(k0 + kk) * ldw + n0 + (lane & 31)]; }
; __device__ __forceinline__ void p0_prologue(Frame& F) {
;     ...
;     transpose_f8_matrix<1, true>(F, F.in[I_F1IN], D, NFF, F.ws + WS_WFI, I8_W);
.Lx8_done:
	s_lshr_b32 s0, s86, 6
	s_lshl_b32 s79, s2, 3
	s_add_i32 s94, s0, s79
	s_lshl_b32 s92, s96, 3
	s_cmp_lt_i32 s94, 0xac00
	v_and_b32_e32 v178, 63, v0
	v_writelane_b32 v240, s0, 2
	s_cselect_b64 s[0:1], -1, 0
	v_writelane_b32 v240, s0, 3
	s_cmp_gt_i32 s94, 0xabff
	v_lshrrev_b32_e32 v162, 5, v178
	v_and_b32_e32 v164, 31, v0
	v_lshrrev_b32_e32 v163, 2, v178
	v_lshlrev_b32_e32 v167, 4, v0
	v_and_b32_e32 v165, 60, v178
	v_writelane_b32 v240, s1, 4
	s_cbranch_scc1 .LBB0_20
	s_load_dwordx2 s[0:1], s[74:75], 0x38
	v_readlane_b32 s3, v240, 2
	s_lshl_b32 s3, s3, 14
	v_lshlrev_b32_e32 v6, 2, v164
	v_mov_b32_e32 v7, 0
	s_add_i32 s3, s3, 0
	s_waitcnt lgkmcnt(0)
	v_lshl_add_u64 v[2:3], s[0:1], 0, v[6:7]
	v_add_u32_e32 v4, s3, v6
	v_and_b32_e32 v6, 48, v167
	v_mul_u32_u24_e32 v1, 0x84, v6
	v_lshl_add_u64 v[6:7], s[90:91], 0, v[6:7]
	s_mov_b64 s[4:5], 0x8300000
	v_add3_u32 v5, s3, v1, v165
	s_movk_i32 s1, 0x84
	v_lshl_add_u64 v[6:7], v[6:7], 0, s[4:5]
	v_or_b32_e32 v10, 16, v163
	v_mov_b32_e32 v1, v162
	s_mov_b32 s3, 0x15800
	s_mov_b32 s8, 0xc2fe0000
	v_mov_b32_e32 v11, 0x42fe0000
	s_mov_b32 s0, 0x4b400000
	v_add_u32_e32 v12, 0x400, v5
	s_mov_b32 s9, s94

;     ...
;         for (int i = 0; i < 32; ++i) { const int kk = 2 * i + (lane >> 5); scr[kk * 33 + (lane & 31)] = W[(size_t)(k0 + kk) * ldw + n0 + (lane & 31)]; }
.LBB0_18:
	s_lshl_b32 s12, s6, 1
	s_lshl_b32 s13, s7, 1
	v_or_b32_e32 v13, s12, v1
	v_or_b32_e32 v46, s13, v162
	s_add_i32 s14, s12, 4
	s_add_i32 s15, s13, 4
	s_add_i32 s16, s12, 8
	s_add_i32 s17, s13, 8
	s_add_i32 s18, s12, 12
	s_add_i32 s19, s13, 12
	s_add_i32 s20, s12, 16
	s_add_i32 s21, s13, 16
	s_add_i32 s22, s12, 20
	s_add_i32 s23, s13, 20
	s_add_i32 s24, s12, 24
	s_add_i32 s25, s13, 24
	s_add_i32 s12, s12, 28
	s_add_i32 s13, s13, 28
	v_add_u32_e32 v14, s4, v46
	v_or_b32_e32 v47, s14, v1
	v_or_b32_e32 v48, s15, v162
	v_or_b32_e32 v49, s16, v1
	v_or_b32_e32 v50, s17, v162
	v_or_b32_e32 v51, s18, v1
	v_or_b32_e32 v52, s19, v162
	v_or_b32_e32 v53, s20, v1
	v_or_b32_e32 v54, s21, v162
	v_or_b32_e32 v55, s22, v1
	v_or_b32_e32 v56, s23, v162
	v_or_b32_e32 v57, s24, v1
	v_or_b32_e32 v58, s25, v162
	v_or_b32_e32 v59, s12, v1
	v_or_b32_e32 v60, s13, v162
	v_add_u32_e32 v16, s5, v13
	v_mad_i64_i32 v[14:15], s[12:13], v14, s3, v[8:9]
	v_add_u32_e32 v20, s5, v47
	v_add_u32_e32 v18, s4, v48
	v_add_u32_e32 v24, s5, v49
	v_add_u32_e32 v22, s4, v50
	v_add_u32_e32 v28, s5, v51
	v_add_u32_e32 v26, s4, v52
	v_add_u32_e32 v32, s5, v53
	v_add_u32_e32 v30, s4, v54
	v_add_u32_e32 v36, s5, v55
	v_add_u32_e32 v34, s4, v56
	v_add_u32_e32 v40, s5, v57
	v_add_u32_e32 v38, s4, v58
	v_add_u32_e32 v44, s5, v59
	v_add_u32_e32 v42, s4, v60
	v_mad_i64_i32 v[16:17], s[12:13], v16, s3, v[8:9]
	v_mad_i64_i32 v[18:19], s[12:13], v18, s3, v[8:9]
	v_mad_i64_i32 v[20:21], s[12:13], v20, s3, v[8:9]
	v_mad_i64_i32 v[22:23], s[12:13], v22, s3, v[8:9]
	v_mad_i64_i32 v[24:25], s[12:13], v24, s3, v[8:9]
	v_mad_i64_i32 v[26:27], s[12:13], v26, s3, v[8:9]
	v_mad_i64_i32 v[28:29], s[12:13], v28, s3, v[8:9]
	v_mad_i64_i32 v[30:31], s[12:13], v30, s3, v[8:9]
	v_mad_i64_i32 v[32:33], s[12:13], v32, s3, v[8:9]
	v_mad_i64_i32 v[34:35], s[12:13], v34, s3, v[8:9]
	v_mad_i64_i32 v[36:37], s[12:13], v36, s3, v[8:9]
	v_mad_i64_i32 v[38:39], s[12:13], v38, s3, v[8:9]
	v_mad_i64_i32 v[40:41], s[12:13], v40, s3, v[8:9]
	v_mad_i64_i32 v[42:43], s[12:13], v42, s3, v[8:9]
	v_mad_i64_i32 v[44:45], s[12:13], v44, s3, v[8:9]
	global_load_dword v61, v[14:15], off
	global_load_dword v62, v[16:17], off
	global_load_dword v63, v[18:19], off
	global_load_dword v64, v[20:21], off
	global_load_dword v65, v[22:23], off
	global_load_dword v66, v[24:25], off
	global_load_dword v67, v[26:27], off
	global_load_dword v68, v[28:29], off
	global_load_dword v69, v[30:31], off
	global_load_dword v70, v[32:33], off
	global_load_dword v71, v[34:35], off
	global_load_dword v72, v[36:37], off
	global_load_dword v73, v[38:39], off
	global_load_dword v74, v[40:41], off
	global_load_dword v75, v[42:43], off
	global_load_dword v76, v[44:45], off
	s_add_i32 s7, s7, 16
	s_add_i32 s6, s6, 16
	s_add_i32 s11, s11, -16
	v_mad_u64_u32 v[14:15], s[12:13], v46, s1, v[4:5]
	s_cmp_lg_u32 s11, 0
	v_mad_u64_u32 v[16:17], s[12:13], v13, s1, v[4:5]
	v_mad_u64_u32 v[18:19], s[12:13], v48, s1, v[4:5]
	v_mad_u64_u32 v[20:21], s[12:13], v47, s1, v[4:5]
	v_mad_u64_u32 v[22:23], s[12:13], v50, s1, v[4:5]
	v_mad_u64_u32 v[24:25], s[12:13], v49, s1, v[4:5]
	v_mad_u64_u32 v[26:27], s[12:13], v52, s1, v[4:5]
	v_mad_u64_u32 v[28:29], s[12:13], v51, s1, v[4:5]
	v_mad_u64_u32 v[30:31], s[12:13], v54, s1, v[4:5]
	v_mad_u64_u32 v[32:33], s[12:13], v53, s1, v[4:5]
	v_mad_u64_u32 v[34:35], s[12:13], v56, s1, v[4:5]
	v_mad_u64_u32 v[36:37], s[12:13], v55, s1, v[4:5]
	v_mad_u64_u32 v[38:39], s[12:13], v58, s1, v[4:5]
	v_mad_u64_u32 v[40:41], s[12:13], v57, s1, v[4:5]
	v_mad_u64_u32 v[42:43], s[12:13], v60, s1, v[4:5]
	v_mad_u64_u32 v[44:45], s[12:13], v59, s1, v[4:5]
	s_lshl_b32 s12, s6, 1
	s_lshl_b32 s13, s7, 1
	v_or_b32_e32 v85, s12, v1
	v_or_b32_e32 v118, s13, v162
	s_add_i32 s14, s12, 4
	s_add_i32 s15, s13, 4
	s_add_i32 s16, s12, 8
	s_add_i32 s17, s13, 8
	s_add_i32 s18, s12, 12
	s_add_i32 s19, s13, 12
	s_add_i32 s20, s12, 16
	s_add_i32 s21, s13, 16
	s_add_i32 s22, s12, 20
	s_add_i32 s23, s13, 20
	s_add_i32 s24, s12, 24
	s_add_i32 s25, s13, 24
	s_add_i32 s12, s12, 28
	s_add_i32 s13, s13, 28
	v_add_u32_e32 v86, s4, v118
	v_or_b32_e32 v119, s14, v1
	v_or_b32_e32 v120, s15, v162
	v_or_b32_e32 v121, s16, v1
	v_or_b32_e32 v122, s17, v162
	v_or_b32_e32 v123, s18, v1
	v_or_b32_e32 v124, s19, v162
	v_or_b32_e32 v125, s20, v1
	v_or_b32_e32 v126, s21, v162
	v_or_b32_e32 v127, s22, v1
	v_or_b32_e32 v128, s23, v162
	v_or_b32_e32 v129, s24, v1
	v_or_b32_e32 v130, s25, v162
	v_or_b32_e32 v131, s12, v1
	v_or_b32_e32 v132, s13, v162
	v_add_u32_e32 v88, s5, v85
	v_mad_i64_i32 v[86:87], s[12:13], v86, s3, v[8:9]
	v_add_u32_e32 v92, s5, v119
	v_add_u32_e32 v90, s4, v120
	v_add_u32_e32 v96, s5, v121
	v_add_u32_e32 v94, s4, v122
	v_add_u32_e32 v100, s5, v123
	v_add_u32_e32 v98, s4, v124
	v_add_u32_e32 v104, s5, v125
	v_add_u32_e32 v102, s4, v126
	v_add_u32_e32 v108, s5, v127
	v_add_u32_e32 v106, s4, v128
	v_add_u32_e32 v112, s5, v129
	v_add_u32_e32 v110, s4, v130
	v_add_u32_e32 v116, s5, v131
	v_add_u32_e32 v114, s4, v132
	v_mad_i64_i32 v[88:89], s[12:13], v88, s3, v[8:9]
	v_mad_i64_i32 v[90:91], s[12:13], v90, s3, v[8:9]
	v_mad_i64_i32 v[92:93], s[12:13], v92, s3, v[8:9]
	v_mad_i64_i32 v[94:95], s[12:13], v94, s3, v[8:9]
	v_mad_i64_i32 v[96:97], s[12:13], v96, s3, v[8:9]
	v_mad_i64_i32 v[98:99], s[12:13], v98, s3, v[8:9]
	v_mad_i64_i32 v[100:101], s[12:13], v100, s3, v[8:9]
	v_mad_i64_i32 v[102:103], s[12:13], v102, s3, v[8:9]
	v_mad_i64_i32 v[104:105], s[12:13], v104, s3, v[8:9]
	v_mad_i64_i32 v[106:107], s[12:13], v106, s3, v[8:9]
	v_mad_i64_i32 v[108:109], s[12:13], v108, s3, v[8:9]
	v_mad_i64_i32 v[110:111], s[12:13], v110, s3, v[8:9]
	v_mad_i64_i32 v[112:113], s[12:13], v112, s3, v[8:9]
; #define LAS __attribute__((address_space(3)))
; #define LDS_WAIT() asm volatile("s_waitcnt lgkmcnt(0)" ::: "memory")
;     ...
;         for (int i = 0; i < 32; ++i) { const int kk = 2 * i + (lane >> 5); scr[kk * 33 + (lane & 31)] = W[(size_t)(k0 + kk) * ldw + n0 + (lane & 31)]; }
;         LDS_WAIT(); asm volatile("" ::: "memory");
;         const int c = lane & 3;
; #pragma unroll
;         for (int j = 0; j < 2; ++j) { const int n = (lane >> 2) + 16 * j; const LAS float* sp = scr + (16 * c) * 33 + n;
;             u32x4 o;
;             if (QI8) { o.x = pk4_i8(sp[0 * 33], sp[1 * 33], sp[2 * 33], sp[3 * 33], scl); o.y = pk4_i8(sp[4 * 33], sp[5 * 33], sp[6 * 33], sp[7 * 33], scl);
;                 o.z = pk4_i8(sp[8 * 33], sp[9 * 33], sp[10 * 33], sp[11 * 33], scl); o.w = pk4_i8(sp[12 * 33], sp[13 * 33], sp[14 * 33], sp[15 * 33], scl); }
	v_mad_i64_i32 v[114:115], s[12:13], v114, s3, v[8:9]
	v_mad_i64_i32 v[116:117], s[12:13], v116, s3, v[8:9]
	global_load_dword v133, v[86:87], off
	global_load_dword v134, v[88:89], off
	global_load_dword v135, v[90:91], off
	global_load_dword v136, v[92:93], off
	global_load_dword v137, v[94:95], off
	global_load_dword v138, v[96:97], off
	global_load_dword v139, v[98:99], off
	global_load_dword v140, v[100:101], off
	global_load_dword v141, v[102:103], off
	global_load_dword v142, v[104:105], off
	global_load_dword v143, v[106:107], off
	global_load_dword v144, v[108:109], off
	global_load_dword v145, v[110:111], off
	global_load_dword v146, v[112:113], off
	global_load_dword v147, v[114:115], off
	global_load_dword v148, v[116:117], off
	s_add_i32 s7, s7, 16
	s_add_i32 s6, s6, 16
	s_add_i32 s11, s11, -16
	v_mad_u64_u32 v[86:87], s[12:13], v118, s1, v[4:5]
	s_cmp_lg_u32 s11, 0
	v_mad_u64_u32 v[88:89], s[12:13], v85, s1, v[4:5]
	v_mad_u64_u32 v[90:91], s[12:13], v120, s1, v[4:5]
	v_mad_u64_u32 v[92:93], s[12:13], v119, s1, v[4:5]
	v_mad_u64_u32 v[94:95], s[12:13], v122, s1, v[4:5]
	v_mad_u64_u32 v[96:97], s[12:13], v121, s1, v[4:5]
	v_mad_u64_u32 v[98:99], s[12:13], v124, s1, v[4:5]
	v_mad_u64_u32 v[100:101], s[12:13], v123, s1, v[4:5]
	v_mad_u64_u32 v[102:103], s[12:13], v126, s1, v[4:5]
	v_mad_u64_u32 v[104:105], s[12:13], v125, s1, v[4:5]
	v_mad_u64_u32 v[106:107], s[12:13], v128, s1, v[4:5]
	v_mad_u64_u32 v[108:109], s[12:13], v127, s1, v[4:5]
	v_mad_u64_u32 v[110:111], s[12:13], v130, s1, v[4:5]
	v_mad_u64_u32 v[112:113], s[12:13], v129, s1, v[4:5]
	v_mad_u64_u32 v[114:115], s[12:13], v132, s1, v[4:5]
	v_mad_u64_u32 v[116:117], s[12:13], v131, s1, v[4:5]
	s_waitcnt vmcnt(31)
	ds_write_b32 v14, v61
	s_waitcnt vmcnt(30)
	ds_write_b32 v16, v62
	s_waitcnt vmcnt(29)
	ds_write_b32 v18, v63
	s_waitcnt vmcnt(28)
	ds_write_b32 v20, v64
	s_waitcnt vmcnt(27)
	ds_write_b32 v22, v65
	s_waitcnt vmcnt(26)
	ds_write_b32 v24, v66
	s_waitcnt vmcnt(25)
	ds_write_b32 v26, v67
	s_waitcnt vmcnt(24)
	ds_write_b32 v28, v68
	s_waitcnt vmcnt(23)
	ds_write_b32 v30, v69
	s_waitcnt vmcnt(22)
	ds_write_b32 v32, v70
	s_waitcnt vmcnt(21)
	ds_write_b32 v34, v71
	s_waitcnt vmcnt(20)
	ds_write_b32 v36, v72
	s_waitcnt vmcnt(19)
	ds_write_b32 v38, v73
	s_waitcnt vmcnt(18)
	ds_write_b32 v40, v74
	s_waitcnt vmcnt(17)
	ds_write_b32 v42, v75
	s_waitcnt vmcnt(16)
	ds_write_b32 v44, v76
	s_waitcnt vmcnt(15)
	ds_write_b32 v86, v133
	s_waitcnt vmcnt(14)
	ds_write_b32 v88, v134
	s_waitcnt vmcnt(13)
	ds_write_b32 v90, v135
	s_waitcnt vmcnt(12)
	ds_write_b32 v92, v136
	s_waitcnt vmcnt(11)
	ds_write_b32 v94, v137
	s_waitcnt vmcnt(10)
	ds_write_b32 v96, v138
	s_waitcnt vmcnt(9)
	ds_write_b32 v98, v139
	s_waitcnt vmcnt(8)
	ds_write_b32 v100, v140
	s_waitcnt vmcnt(7)
	ds_write_b32 v102, v141
	s_waitcnt vmcnt(6)
	ds_write_b32 v104, v142
	s_waitcnt vmcnt(5)
	ds_write_b32 v106, v143
	s_waitcnt vmcnt(4)
	ds_write_b32 v108, v144
	s_waitcnt vmcnt(3)
	ds_write_b32 v110, v145
	s_waitcnt vmcnt(2)
	ds_write_b32 v112, v146
	s_waitcnt vmcnt(1)
	ds_write_b32 v114, v147
	s_waitcnt vmcnt(0)
	ds_write_b32 v116, v148
	s_waitcnt lgkmcnt(0)
	ds_read2_b32 v[8:9], v5 offset1:16
	ds_read2_b32 v[20:21], v5 offset0:33 offset1:49
	ds_read2_b32 v[22:23], v5 offset0:66 offset1:82
	ds_read2_b32 v[24:25], v5 offset0:99 offset1:115
	ds_read2_b32 v[28:29], v5 offset0:132 offset1:148
	ds_read2_b32 v[32:33], v5 offset0:165 offset1:181
	ds_read2_b32 v[34:35], v5 offset0:198 offset1:214
	ds_read2_b32 v[36:37], v5 offset0:231 offset1:247
	s_ashr_i32 s5, s4, 31
	s_waitcnt lgkmcnt(7)
	v_mul_f32_e32 v8, 0x44fe0000, v8
	v_med3_f32 v14, v8, s8, v11
	s_waitcnt lgkmcnt(6)
	v_mul_f32_e32 v8, 0x44fe0000, v20
	v_med3_f32 v16, v8, s8, v11
	s_waitcnt lgkmcnt(5)
	v_mul_f32_e32 v8, 0x44fe0000, v22
	v_med3_f32 v26, v8, s8, v11
	s_waitcnt lgkmcnt(4)
	v_mul_f32_e32 v8, 0x44fe0000, v24
	v_med3_f32 v30, v8, s8, v11
	s_waitcnt lgkmcnt(3)
	v_mul_f32_e32 v8, 0x44fe0000, v28
	v_med3_f32 v15, v8, s8, v11
	s_waitcnt lgkmcnt(2)
	v_mul_f32_e32 v8, 0x44fe0000, v32
	v_med3_f32 v17, v8, s8, v11
	s_waitcnt lgkmcnt(1)
	v_mul_f32_e32 v8, 0x44fe0000, v34
	v_med3_f32 v27, v8, s8, v11
	s_waitcnt lgkmcnt(0)
	v_mul_f32_e32 v8, 0x44fe0000, v36
	v_pk_add_f32 v[16:17], v[16:17], s[0:1] op_sel_hi:[1,0]
	v_pk_add_f32 v[26:27], v[26:27], s[0:1] op_sel_hi:[1,0]
	v_med3_f32 v31, v8, s8, v11
	v_lshlrev_b32_e32 v8, 8, v17
	v_lshlrev_b32_e32 v13, 8, v16
	v_lshlrev_b32_e32 v16, 16, v27
	v_lshlrev_b32_e32 v17, 16, v26
	ds_read2_b32 v[26:27], v12 offset0:8 offset1:24
	v_pk_add_f32 v[30:31], v[30:31], s[0:1] op_sel_hi:[1,0]
	v_pk_add_f32 v[14:15], v[14:15], s[0:1] op_sel_hi:[1,0]
	v_lshlrev_b32_e32 v20, 24, v31
	v_and_b32_e32 v8, 0xff00, v8
	v_lshlrev_b32_e32 v22, 24, v30
	v_or_b32_sdwa v15, v20, v15 dst_sel:DWORD dst_unused:UNUSED_PAD src0_sel:DWORD src1_sel:BYTE_0
	ds_read2_b32 v[30:31], v12 offset0:41 offset1:57
	ds_read2_b32 v[38:39], v12 offset0:74 offset1:90
	ds_read2_b32 v[40:41], v12 offset0:107 offset1:123
	v_and_b32_e32 v16, 0xff0000, v16
	v_or_b32_e32 v8, v15, v8
	ds_read2_b32 v[46:47], v12 offset0:140 offset1:156
	v_or_b32_e32 v15, v8, v16
	s_waitcnt lgkmcnt(4)
; #define LAS __attribute__((address_space(3)))
; __device__ __forceinline__ unsigned pk4_f8(float a, float b, float c, float d) { int w = __builtin_amdgcn_cvt_pk_fp8_f32(a, b, 0, false); w = __builtin_amdgcn_cvt_pk_fp8_f32(c, d, w, true); return (unsigned)w; }
; #define LDS_WAIT() asm volatile("s_waitcnt lgkmcnt(0)" ::: "memory")
;     ...
;         for (int j = 0; j < 2; ++j) { const int n = (lane >> 2) + 16 * j; const LAS float* sp = scr + (16 * c) * 33 + n;
;             u32x4 o;
;             if (QI8) { o.x = pk4_i8(sp[0 * 33], sp[1 * 33], sp[2 * 33], sp[3 * 33], scl); o.y = pk4_i8(sp[4 * 33], sp[5 * 33], sp[6 * 33], sp[7 * 33], scl);
;                 o.z = pk4_i8(sp[8 * 33], sp[9 * 33], sp[10 * 33], sp[11 * 33], scl); o.w = pk4_i8(sp[12 * 33], sp[13 * 33], sp[14 * 33], sp[15 * 33], scl); }
;             else {
;             o.x = pk4_f8(sp[0 * 33] * scl, sp[1 * 33] * scl, sp[2 * 33] * scl, sp[3 * 33] * scl); o.y = pk4_f8(sp[4 * 33] * scl, sp[5 * 33] * scl, sp[6 * 33] * scl, sp[7 * 33] * scl);
;             o.z = pk4_f8(sp[8 * 33] * scl, sp[9 * 33] * scl, sp[10 * 33] * scl, sp[11 * 33] * scl); o.w = pk4_f8(sp[12 * 33] * scl, sp[13 * 33] * scl, sp[14 * 33] * scl, sp[15 * 33] * scl); }
;             *(u32x4*)(WT + (size_t)(dr0 + n) * K + k0 + 16 * c) = o; }
;         LDS_WAIT(); asm volatile("" ::: "memory"); }
	v_mul_f32_e32 v8, 0x44fe0000, v26
	v_med3_f32 v16, v8, s8, v11
	s_waitcnt lgkmcnt(3)
	v_mul_f32_e32 v8, 0x44fe0000, v30
	v_med3_f32 v42, v8, s8, v11
	s_waitcnt lgkmcnt(2)
	v_mul_f32_e32 v8, 0x44fe0000, v38
	ds_read2_b32 v[50:51], v12 offset0:173 offset1:189
	ds_read2_b32 v[52:53], v12 offset0:206 offset1:222
	ds_read2_b32 v[54:55], v12 offset0:239 offset1:255
	v_and_b32_e32 v13, 0xff00, v13
	v_or_b32_sdwa v14, v22, v14 dst_sel:DWORD dst_unused:UNUSED_PAD src0_sel:DWORD src1_sel:BYTE_0
	v_med3_f32 v44, v8, s8, v11
	s_waitcnt lgkmcnt(4)
	v_mul_f32_e32 v8, 0x44fe0000, v40
	v_and_b32_e32 v17, 0xff0000, v17
	v_or_b32_e32 v13, v14, v13
	v_med3_f32 v48, v8, s8, v11
	s_waitcnt lgkmcnt(3)
	v_mul_f32_e32 v8, 0x44fe0000, v46
	v_or_b32_e32 v14, v13, v17
	v_med3_f32 v17, v8, s8, v11
	s_waitcnt lgkmcnt(2)
	v_mul_f32_e32 v8, 0x44fe0000, v50
	v_med3_f32 v43, v8, s8, v11
	s_waitcnt lgkmcnt(1)
	v_mul_f32_e32 v8, 0x44fe0000, v52
	v_med3_f32 v45, v8, s8, v11
	s_waitcnt lgkmcnt(0)
	v_mul_f32_e32 v8, 0x44fe0000, v54
	v_med3_f32 v49, v8, s8, v11
	v_pk_add_f32 v[42:43], v[42:43], s[0:1] op_sel_hi:[1,0]
	v_pk_add_f32 v[48:49], v[48:49], s[0:1] op_sel_hi:[1,0]
	v_pk_add_f32 v[16:17], v[16:17], s[0:1] op_sel_hi:[1,0]
	v_pk_add_f32 v[44:45], v[44:45], s[0:1] op_sel_hi:[1,0]
	v_lshlrev_b32_e32 v8, 8, v43
	v_lshlrev_b32_e32 v13, 8, v42
	v_lshlrev_b32_e32 v24, 24, v49
	v_lshlrev_b32_e32 v26, 24, v48
	v_add_u32_e32 v42, s10, v163
	v_and_b32_e32 v8, 0xff00, v8
	v_and_b32_e32 v13, 0xff00, v13
	v_lshlrev_b32_e32 v20, 16, v45
	v_lshlrev_b32_e32 v22, 16, v44
	v_or_b32_sdwa v17, v24, v17 dst_sel:DWORD dst_unused:UNUSED_PAD src0_sel:DWORD src1_sel:BYTE_0
	v_or_b32_sdwa v16, v26, v16 dst_sel:DWORD dst_unused:UNUSED_PAD src0_sel:DWORD src1_sel:BYTE_0
	v_ashrrev_i32_e32 v43, 31, v42
	v_lshl_add_u64 v[18:19], v[6:7], 0, s[4:5]
	v_and_b32_e32 v20, 0xff0000, v20
	v_and_b32_e32 v22, 0xff0000, v22
	v_or_b32_e32 v8, v17, v8
	v_or_b32_e32 v13, v16, v13
	v_lshlrev_b64 v[42:43], 12, v[42:43]
	v_or_b32_e32 v17, v8, v20
	v_or_b32_e32 v16, v13, v22
	v_lshl_add_u64 v[42:43], v[18:19], 0, v[42:43]
	v_mul_f32_e32 v8, 0x44fe0000, v9
	v_mul_f32_e32 v9, 0x44fe0000, v21
	v_mul_f32_e32 v13, 0x44fe0000, v33
	global_store_dwordx4 v[42:43], v[14:17], off
	v_med3_f32 v8, v8, s8, v11
	s_add_i32 s9, s9, s92
	v_med3_f32 v14, v9, s8, v11
	v_mul_f32_e32 v9, 0x44fe0000, v23
	v_med3_f32 v15, v13, s8, v11
	v_mul_f32_e32 v13, 0x44fe0000, v35
	v_med3_f32 v16, v9, s8, v11
	v_mul_f32_e32 v9, 0x44fe0000, v25
	v_med3_f32 v17, v13, s8, v11
	v_mul_f32_e32 v13, 0x44fe0000, v37
	v_med3_f32 v20, v9, s8, v11
	v_mul_f32_e32 v9, 0x44fe0000, v29
	v_med3_f32 v21, v13, s8, v11
	v_med3_f32 v9, v9, s8, v11
	v_pk_add_f32 v[14:15], v[14:15], s[0:1] op_sel_hi:[1,0]
	v_pk_add_f32 v[16:17], v[16:17], s[0:1] op_sel_hi:[1,0]
	v_pk_add_f32 v[20:21], v[20:21], s[0:1] op_sel_hi:[1,0]
	v_pk_add_f32 v[8:9], v[8:9], s[0:1] op_sel_hi:[1,0]
	v_lshlrev_b32_e32 v13, 8, v15
	v_lshlrev_b32_e32 v15, 16, v17
	v_lshlrev_b32_e32 v17, 24, v21
	v_lshlrev_b32_e32 v14, 8, v14
	v_and_b32_e32 v13, 0xff00, v13
	v_lshlrev_b32_e32 v20, 24, v20
	v_or_b32_sdwa v9, v17, v9 dst_sel:DWORD dst_unused:UNUSED_PAD src0_sel:DWORD src1_sel:BYTE_0
	v_and_b32_e32 v14, 0xff00, v14
	v_lshlrev_b32_e32 v16, 16, v16
	v_and_b32_e32 v15, 0xff0000, v15
	v_or_b32_sdwa v8, v20, v8 dst_sel:DWORD dst_unused:UNUSED_PAD src0_sel:DWORD src1_sel:BYTE_0
	v_or_b32_e32 v9, v9, v13
	v_and_b32_e32 v16, 0xff0000, v16
	v_or_b32_e32 v8, v8, v14
	v_or_b32_e32 v15, v9, v15
	v_mul_f32_e32 v9, 0x44fe0000, v31
	v_mul_f32_e32 v13, 0x44fe0000, v51
	v_or_b32_e32 v14, v8, v16
	v_med3_f32 v16, v9, s8, v11
	v_mul_f32_e32 v9, 0x44fe0000, v39
	v_med3_f32 v17, v13, s8, v11
	v_mul_f32_e32 v13, 0x44fe0000, v53
	v_med3_f32 v20, v9, s8, v11
	v_mul_f32_e32 v9, 0x44fe0000, v41
	v_med3_f32 v21, v13, s8, v11
	v_mul_f32_e32 v13, 0x44fe0000, v55
	v_mul_f32_e32 v8, 0x44fe0000, v27
	v_med3_f32 v22, v9, s8, v11
	v_mul_f32_e32 v9, 0x44fe0000, v47
	v_med3_f32 v23, v13, s8, v11
	v_med3_f32 v8, v8, s8, v11
	v_med3_f32 v9, v9, s8, v11
	v_pk_add_f32 v[16:17], v[16:17], s[0:1] op_sel_hi:[1,0]
	v_pk_add_f32 v[22:23], v[22:23], s[0:1] op_sel_hi:[1,0]
	v_pk_add_f32 v[8:9], v[8:9], s[0:1] op_sel_hi:[1,0]
	v_pk_add_f32 v[20:21], v[20:21], s[0:1] op_sel_hi:[1,0]
	v_lshlrev_b32_e32 v16, 8, v16
	v_lshlrev_b32_e32 v22, 24, v22
	v_lshlrev_b32_e32 v13, 8, v17
	v_and_b32_e32 v16, 0xff00, v16
	v_lshlrev_b32_e32 v17, 16, v21
	v_lshlrev_b32_e32 v20, 16, v20
	v_lshlrev_b32_e32 v21, 24, v23
	v_or_b32_sdwa v8, v22, v8 dst_sel:DWORD dst_unused:UNUSED_PAD src0_sel:DWORD src1_sel:BYTE_0
	v_and_b32_e32 v13, 0xff00, v13
	v_and_b32_e32 v20, 0xff0000, v20
	v_or_b32_sdwa v9, v21, v9 dst_sel:DWORD dst_unused:UNUSED_PAD src0_sel:DWORD src1_sel:BYTE_0
	v_or_b32_e32 v8, v8, v16
	v_and_b32_e32 v17, 0xff0000, v17
	v_or_b32_e32 v9, v9, v13
	v_or_b32_e32 v16, v8, v20
	v_add_u32_e32 v8, s10, v10
	v_or_b32_e32 v17, v9, v17
	v_ashrrev_i32_e32 v9, 31, v8
	v_lshlrev_b64 v[8:9], 12, v[8:9]
	v_lshl_add_u64 v[8:9], v[18:19], 0, v[8:9]
	global_store_dwordx4 v[8:9], v[14:17], off
	s_waitcnt lgkmcnt(0)
	s_cmp_lt_i32 s9, 0xac00
	s_cbranch_scc1 .LBB0_13

;     ...
;         int dr0 = n0; if (MAP == 1) { if (n0 < DFF) dr0 = (n0 >> 7) * 256 + (n0 & 127); else { const int uo = n0 - DFF; dr0 = (uo >> 7) * 256 + 128 + (uo & 127); } }
; #pragma unroll 8
;         for (int i = 0; i < 32; ++i) { const int kk = 2 * i + (lane >> 5); scr[kk * 33 + (lane & 31)] = W[(size_t)(k0 + kk) * ldw + n0 + (lane & 31)]; }
.LBB0_25:
	s_lshl_b32 s11, s5, 1
	s_lshl_b32 s12, s10, 1
	v_or_b32_e32 v11, s11, v1
	v_or_b32_e32 v44, s12, v162
	s_add_i32 s13, s11, 4
	s_add_i32 s14, s12, 4
	s_add_i32 s15, s11, 8
	s_add_i32 s16, s12, 8
	s_add_i32 s17, s11, 12
	s_add_i32 s18, s12, 12
	s_add_i32 s19, s11, 16
	s_add_i32 s20, s12, 16
	s_add_i32 s21, s11, 20
	s_add_i32 s22, s12, 20
	s_add_i32 s23, s11, 24
	s_add_i32 s24, s12, 24
	s_add_i32 s11, s11, 28
	s_add_i32 s12, s12, 28
	v_add_u32_e32 v14, s4, v44
	v_or_b32_e32 v45, s13, v1
	v_or_b32_e32 v46, s14, v162
	v_or_b32_e32 v47, s15, v1
	v_or_b32_e32 v48, s16, v162
	v_or_b32_e32 v49, s17, v1
	v_or_b32_e32 v50, s18, v162
	v_or_b32_e32 v51, s19, v1
	v_or_b32_e32 v52, s20, v162
	v_or_b32_e32 v53, s21, v1
	v_or_b32_e32 v54, s22, v162
	v_or_b32_e32 v55, s23, v1
	v_or_b32_e32 v56, s24, v162
	v_or_b32_e32 v57, s11, v1
	v_or_b32_e32 v58, s12, v162
	v_add_u32_e32 v12, s1, v11
	v_ashrrev_i32_e32 v15, 31, v14
	v_add_u32_e32 v16, s1, v45
	v_add_u32_e32 v18, s4, v46
	v_add_u32_e32 v20, s1, v47
	v_add_u32_e32 v22, s4, v48
	v_add_u32_e32 v24, s1, v49
	v_add_u32_e32 v26, s4, v50
	v_add_u32_e32 v28, s1, v51
	v_add_u32_e32 v30, s4, v52
	v_add_u32_e32 v32, s1, v53
	v_add_u32_e32 v34, s4, v54
	v_add_u32_e32 v36, s1, v55
	v_add_u32_e32 v38, s4, v56
	v_add_u32_e32 v40, s1, v57
	v_add_u32_e32 v42, s4, v58
	v_ashrrev_i32_e32 v13, 31, v12
	v_lshlrev_b64 v[14:15], 14, v[14:15]
	v_ashrrev_i32_e32 v19, 31, v18
	v_ashrrev_i32_e32 v17, 31, v16
	v_ashrrev_i32_e32 v23, 31, v22
	v_ashrrev_i32_e32 v21, 31, v20
	v_ashrrev_i32_e32 v27, 31, v26
	v_ashrrev_i32_e32 v25, 31, v24
	v_ashrrev_i32_e32 v31, 31, v30
	v_ashrrev_i32_e32 v29, 31, v28
	v_ashrrev_i32_e32 v35, 31, v34
	v_ashrrev_i32_e32 v33, 31, v32
	v_ashrrev_i32_e32 v39, 31, v38
	v_ashrrev_i32_e32 v37, 31, v36
	v_ashrrev_i32_e32 v43, 31, v42
	v_ashrrev_i32_e32 v41, 31, v40
	v_lshlrev_b64 v[12:13], 14, v[12:13]
	v_lshl_add_u64 v[14:15], v[8:9], 0, v[14:15]
	v_lshlrev_b64 v[16:17], 14, v[16:17]
	v_lshlrev_b64 v[18:19], 14, v[18:19]
	v_lshlrev_b64 v[20:21], 14, v[20:21]
	v_lshlrev_b64 v[22:23], 14, v[22:23]
	v_lshlrev_b64 v[24:25], 14, v[24:25]
	v_lshlrev_b64 v[26:27], 14, v[26:27]
	v_lshlrev_b64 v[28:29], 14, v[28:29]
	v_lshlrev_b64 v[30:31], 14, v[30:31]
	v_lshlrev_b64 v[32:33], 14, v[32:33]
	v_lshlrev_b64 v[34:35], 14, v[34:35]
	v_lshlrev_b64 v[36:37], 14, v[36:37]
	v_lshlrev_b64 v[38:39], 14, v[38:39]
	v_lshlrev_b64 v[40:41], 14, v[40:41]
	v_lshlrev_b64 v[42:43], 14, v[42:43]
	v_lshl_add_u64 v[12:13], v[8:9], 0, v[12:13]
	v_lshl_add_u64 v[18:19], v[8:9], 0, v[18:19]
	v_lshl_add_u64 v[16:17], v[8:9], 0, v[16:17]
	v_lshl_add_u64 v[22:23], v[8:9], 0, v[22:23]
	v_lshl_add_u64 v[20:21], v[8:9], 0, v[20:21]
	v_lshl_add_u64 v[26:27], v[8:9], 0, v[26:27]
	v_lshl_add_u64 v[24:25], v[8:9], 0, v[24:25]
	v_lshl_add_u64 v[30:31], v[8:9], 0, v[30:31]
	v_lshl_add_u64 v[28:29], v[8:9], 0, v[28:29]
	v_lshl_add_u64 v[34:35], v[8:9], 0, v[34:35]
	v_lshl_add_u64 v[32:33], v[8:9], 0, v[32:33]
	v_lshl_add_u64 v[38:39], v[8:9], 0, v[38:39]
	v_lshl_add_u64 v[36:37], v[8:9], 0, v[36:37]
	v_lshl_add_u64 v[42:43], v[8:9], 0, v[42:43]
	v_lshl_add_u64 v[40:41], v[8:9], 0, v[40:41]
	global_load_dword v59, v[14:15], off
	global_load_dword v60, v[12:13], off
	global_load_dword v61, v[18:19], off
	global_load_dword v62, v[16:17], off
	global_load_dword v63, v[22:23], off
	global_load_dword v64, v[20:21], off
	global_load_dword v65, v[26:27], off
	global_load_dword v66, v[24:25], off
	global_load_dword v67, v[30:31], off
	global_load_dword v68, v[28:29], off
	global_load_dword v69, v[34:35], off
	global_load_dword v70, v[32:33], off
	global_load_dword v71, v[38:39], off
	global_load_dword v72, v[36:37], off
	global_load_dword v73, v[42:43], off
	global_load_dword v74, v[40:41], off
	s_add_i32 s10, s10, 16
	s_add_i32 s5, s5, 16
	s_add_i32 s9, s9, -16
	v_mad_u64_u32 v[12:13], s[12:13], v44, s6, v[4:5]
	s_cmp_lg_u32 s9, 0
	v_mad_u64_u32 v[14:15], s[12:13], v11, s6, v[4:5]
	v_mad_u64_u32 v[16:17], s[12:13], v46, s6, v[4:5]
	v_mad_u64_u32 v[18:19], s[12:13], v45, s6, v[4:5]
	v_mad_u64_u32 v[20:21], s[12:13], v48, s6, v[4:5]
	v_mad_u64_u32 v[22:23], s[12:13], v47, s6, v[4:5]
	v_mad_u64_u32 v[24:25], s[12:13], v50, s6, v[4:5]
	v_mad_u64_u32 v[26:27], s[12:13], v49, s6, v[4:5]
	v_mad_u64_u32 v[28:29], s[12:13], v52, s6, v[4:5]
	v_mad_u64_u32 v[30:31], s[12:13], v51, s6, v[4:5]
	v_mad_u64_u32 v[32:33], s[12:13], v54, s6, v[4:5]
	v_mad_u64_u32 v[34:35], s[12:13], v53, s6, v[4:5]
	v_mad_u64_u32 v[36:37], s[12:13], v56, s6, v[4:5]
	v_mad_u64_u32 v[38:39], s[12:13], v55, s6, v[4:5]
	v_mad_u64_u32 v[40:41], s[12:13], v58, s6, v[4:5]
	v_mad_u64_u32 v[42:43], s[12:13], v57, s6, v[4:5]
	s_lshl_b32 s11, s5, 1
	s_lshl_b32 s12, s10, 1
	v_or_b32_e32 v85, s11, v1
	v_or_b32_e32 v118, s12, v162
	s_add_i32 s13, s11, 4
	s_add_i32 s14, s12, 4
	s_add_i32 s15, s11, 8
	s_add_i32 s16, s12, 8
	s_add_i32 s17, s11, 12
	s_add_i32 s18, s12, 12
	s_add_i32 s19, s11, 16
	s_add_i32 s20, s12, 16
	s_add_i32 s21, s11, 20
	s_add_i32 s22, s12, 20
	s_add_i32 s23, s11, 24
	s_add_i32 s24, s12, 24
	s_add_i32 s11, s11, 28
	s_add_i32 s12, s12, 28
	v_add_u32_e32 v88, s4, v118
	v_or_b32_e32 v119, s13, v1
	v_or_b32_e32 v120, s14, v162
	v_or_b32_e32 v121, s15, v1
	v_or_b32_e32 v122, s16, v162
	v_or_b32_e32 v123, s17, v1
	v_or_b32_e32 v124, s18, v162
	v_or_b32_e32 v125, s19, v1
	v_or_b32_e32 v126, s20, v162
	v_or_b32_e32 v127, s21, v1
	v_or_b32_e32 v128, s22, v162
	v_or_b32_e32 v129, s23, v1
	v_or_b32_e32 v130, s24, v162
	v_or_b32_e32 v131, s11, v1
	v_or_b32_e32 v132, s12, v162
	v_add_u32_e32 v86, s1, v85
	v_ashrrev_i32_e32 v89, 31, v88
	v_add_u32_e32 v90, s1, v119
	v_add_u32_e32 v92, s4, v120
;     ...
;         for (int i = 0; i < 32; ++i) { const int kk = 2 * i + (lane >> 5); scr[kk * 33 + (lane & 31)] = W[(size_t)(k0 + kk) * ldw + n0 + (lane & 31)]; }
	v_add_u32_e32 v94, s1, v121
	v_add_u32_e32 v96, s4, v122
	v_add_u32_e32 v98, s1, v123
	v_add_u32_e32 v100, s4, v124
	v_add_u32_e32 v102, s1, v125
	v_add_u32_e32 v104, s4, v126
	v_add_u32_e32 v106, s1, v127
	v_add_u32_e32 v108, s4, v128
	v_add_u32_e32 v110, s1, v129
	v_add_u32_e32 v112, s4, v130
	v_add_u32_e32 v114, s1, v131
	v_add_u32_e32 v116, s4, v132
	v_ashrrev_i32_e32 v87, 31, v86
	v_lshlrev_b64 v[88:89], 14, v[88:89]
	v_ashrrev_i32_e32 v93, 31, v92
	v_ashrrev_i32_e32 v91, 31, v90
	v_ashrrev_i32_e32 v97, 31, v96
	v_ashrrev_i32_e32 v95, 31, v94
	v_ashrrev_i32_e32 v101, 31, v100
	v_ashrrev_i32_e32 v99, 31, v98
	v_ashrrev_i32_e32 v105, 31, v104
	v_ashrrev_i32_e32 v103, 31, v102
	v_ashrrev_i32_e32 v109, 31, v108
	v_ashrrev_i32_e32 v107, 31, v106
	v_ashrrev_i32_e32 v113, 31, v112
	v_ashrrev_i32_e32 v111, 31, v110
	v_ashrrev_i32_e32 v117, 31, v116
	v_ashrrev_i32_e32 v115, 31, v114
	v_lshlrev_b64 v[86:87], 14, v[86:87]
	v_lshl_add_u64 v[88:89], v[8:9], 0, v[88:89]
	v_lshlrev_b64 v[90:91], 14, v[90:91]
	v_lshlrev_b64 v[92:93], 14, v[92:93]
	v_lshlrev_b64 v[94:95], 14, v[94:95]
	v_lshlrev_b64 v[96:97], 14, v[96:97]
	v_lshlrev_b64 v[98:99], 14, v[98:99]
	v_lshlrev_b64 v[100:101], 14, v[100:101]
	v_lshlrev_b64 v[102:103], 14, v[102:103]
	v_lshlrev_b64 v[104:105], 14, v[104:105]
	v_lshlrev_b64 v[106:107], 14, v[106:107]
	v_lshlrev_b64 v[108:109], 14, v[108:109]
	v_lshlrev_b64 v[110:111], 14, v[110:111]
	v_lshlrev_b64 v[112:113], 14, v[112:113]
	v_lshlrev_b64 v[114:115], 14, v[114:115]
	v_lshlrev_b64 v[116:117], 14, v[116:117]
	v_lshl_add_u64 v[86:87], v[8:9], 0, v[86:87]
	v_lshl_add_u64 v[92:93], v[8:9], 0, v[92:93]
	v_lshl_add_u64 v[90:91], v[8:9], 0, v[90:91]
	v_lshl_add_u64 v[96:97], v[8:9], 0, v[96:97]
	v_lshl_add_u64 v[94:95], v[8:9], 0, v[94:95]
	v_lshl_add_u64 v[100:101], v[8:9], 0, v[100:101]
	v_lshl_add_u64 v[98:99], v[8:9], 0, v[98:99]
	v_lshl_add_u64 v[104:105], v[8:9], 0, v[104:105]
	v_lshl_add_u64 v[102:103], v[8:9], 0, v[102:103]
	v_lshl_add_u64 v[108:109], v[8:9], 0, v[108:109]
	v_lshl_add_u64 v[106:107], v[8:9], 0, v[106:107]
	v_lshl_add_u64 v[112:113], v[8:9], 0, v[112:113]
	v_lshl_add_u64 v[110:111], v[8:9], 0, v[110:111]
	v_lshl_add_u64 v[116:117], v[8:9], 0, v[116:117]
	v_lshl_add_u64 v[114:115], v[8:9], 0, v[114:115]
	global_load_dword v133, v[88:89], off
	global_load_dword v134, v[86:87], off
	global_load_dword v135, v[92:93], off
	global_load_dword v136, v[90:91], off
	global_load_dword v137, v[96:97], off
	global_load_dword v138, v[94:95], off
	global_load_dword v139, v[100:101], off
	global_load_dword v140, v[98:99], off
	global_load_dword v141, v[104:105], off
	global_load_dword v142, v[102:103], off
	global_load_dword v143, v[108:109], off
	global_load_dword v144, v[106:107], off
	global_load_dword v145, v[112:113], off
	global_load_dword v146, v[110:111], off
	global_load_dword v147, v[116:117], off
	global_load_dword v148, v[114:115], off
	s_add_i32 s10, s10, 16
	s_add_i32 s5, s5, 16
	s_add_i32 s9, s9, -16
	v_mad_u64_u32 v[86:87], s[12:13], v118, s6, v[4:5]
	s_cmp_lg_u32 s9, 0
	v_mad_u64_u32 v[88:89], s[12:13], v85, s6, v[4:5]
	v_mad_u64_u32 v[90:91], s[12:13], v120, s6, v[4:5]
	v_mad_u64_u32 v[92:93], s[12:13], v119, s6, v[4:5]
	v_mad_u64_u32 v[94:95], s[12:13], v122, s6, v[4:5]
	v_mad_u64_u32 v[96:97], s[12:13], v121, s6, v[4:5]
	v_mad_u64_u32 v[98:99], s[12:13], v124, s6, v[4:5]
	v_mad_u64_u32 v[100:101], s[12:13], v123, s6, v[4:5]
	v_mad_u64_u32 v[102:103], s[12:13], v126, s6, v[4:5]
	v_mad_u64_u32 v[104:105], s[12:13], v125, s6, v[4:5]
	v_mad_u64_u32 v[106:107], s[12:13], v128, s6, v[4:5]
	v_mad_u64_u32 v[108:109], s[12:13], v127, s6, v[4:5]
	v_mad_u64_u32 v[110:111], s[12:13], v130, s6, v[4:5]
	v_mad_u64_u32 v[112:113], s[12:13], v129, s6, v[4:5]
	v_mad_u64_u32 v[114:115], s[12:13], v132, s6, v[4:5]
	v_mad_u64_u32 v[116:117], s[12:13], v131, s6, v[4:5]
	s_waitcnt vmcnt(31)
	ds_write_b32 v12, v59
	s_waitcnt vmcnt(30)
	ds_write_b32 v14, v60
	s_waitcnt vmcnt(29)
	ds_write_b32 v16, v61
	s_waitcnt vmcnt(28)
	ds_write_b32 v18, v62
	s_waitcnt vmcnt(27)
	ds_write_b32 v20, v63
	s_waitcnt vmcnt(26)
	ds_write_b32 v22, v64
	s_waitcnt vmcnt(25)
	ds_write_b32 v24, v65
	s_waitcnt vmcnt(24)
	ds_write_b32 v26, v66
	s_waitcnt vmcnt(23)
	ds_write_b32 v28, v67
	s_waitcnt vmcnt(22)
	ds_write_b32 v30, v68
	s_waitcnt vmcnt(21)
	ds_write_b32 v32, v69
	s_waitcnt vmcnt(20)
	ds_write_b32 v34, v70
	s_waitcnt vmcnt(19)
	ds_write_b32 v36, v71
	s_waitcnt vmcnt(18)
; #define LAS __attribute__((address_space(3)))
; __device__ __forceinline__ unsigned pk4_f8(float a, float b, float c, float d) { int w = __builtin_amdgcn_cvt_pk_fp8_f32(a, b, 0, false); w = __builtin_amdgcn_cvt_pk_fp8_f32(c, d, w, true); return (unsigned)w; }
; #define LDS_WAIT() asm volatile("s_waitcnt lgkmcnt(0)" ::: "memory")
;     ...
;         for (int i = 0; i < 32; ++i) { const int kk = 2 * i + (lane >> 5); scr[kk * 33 + (lane & 31)] = W[(size_t)(k0 + kk) * ldw + n0 + (lane & 31)]; }
;         LDS_WAIT(); asm volatile("" ::: "memory");
;         const int c = lane & 3;
; #pragma unroll
;         for (int j = 0; j < 2; ++j) { const int n = (lane >> 2) + 16 * j; const LAS float* sp = scr + (16 * c) * 33 + n;
;             u32x4 o;
;             if (QI8) { o.x = pk4_i8(sp[0 * 33], sp[1 * 33], sp[2 * 33], sp[3 * 33], scl); o.y = pk4_i8(sp[4 * 33], sp[5 * 33], sp[6 * 33], sp[7 * 33], scl);
;                 o.z = pk4_i8(sp[8 * 33], sp[9 * 33], sp[10 * 33], sp[11 * 33], scl); o.w = pk4_i8(sp[12 * 33], sp[13 * 33], sp[14 * 33], sp[15 * 33], scl); }
;             else {
;             o.x = pk4_f8(sp[0 * 33] * scl, sp[1 * 33] * scl, sp[2 * 33] * scl, sp[3 * 33] * scl); o.y = pk4_f8(sp[4 * 33] * scl, sp[5 * 33] * scl, sp[6 * 33] * scl, sp[7 * 33] * scl);
;             o.z = pk4_f8(sp[8 * 33] * scl, sp[9 * 33] * scl, sp[10 * 33] * scl, sp[11 * 33] * scl); o.w = pk4_f8(sp[12 * 33] * scl, sp[13 * 33] * scl, sp[14 * 33] * scl, sp[15 * 33] * scl); }
;             *(u32x4*)(WT + (size_t)(dr0 + n) * K + k0 + 16 * c) = o; }
;         LDS_WAIT(); asm volatile("" ::: "memory"); }
	ds_write_b32 v38, v72
	s_waitcnt vmcnt(17)
	ds_write_b32 v40, v73
	s_waitcnt vmcnt(16)
	ds_write_b32 v42, v74
	s_waitcnt vmcnt(15)
	ds_write_b32 v86, v133
	s_waitcnt vmcnt(14)
	ds_write_b32 v88, v134
	s_waitcnt vmcnt(13)
	ds_write_b32 v90, v135
	s_waitcnt vmcnt(12)
	ds_write_b32 v92, v136
	s_waitcnt vmcnt(11)
	ds_write_b32 v94, v137
	s_waitcnt vmcnt(10)
	ds_write_b32 v96, v138
	s_waitcnt vmcnt(9)
	ds_write_b32 v98, v139
	s_waitcnt vmcnt(8)
	ds_write_b32 v100, v140
	s_waitcnt vmcnt(7)
	ds_write_b32 v102, v141
	s_waitcnt vmcnt(6)
	ds_write_b32 v104, v142
	s_waitcnt vmcnt(5)
	ds_write_b32 v106, v143
	s_waitcnt vmcnt(4)
	ds_write_b32 v108, v144
	s_waitcnt vmcnt(3)
	ds_write_b32 v110, v145
	s_waitcnt vmcnt(2)
	ds_write_b32 v112, v146
	s_waitcnt vmcnt(1)
	ds_write_b32 v114, v147
	s_waitcnt vmcnt(0)
	ds_write_b32 v116, v148
	s_waitcnt lgkmcnt(0)
	ds_read2_b32 v[8:9], v5 offset1:16
	ds_read2_b32 v[16:17], v5 offset0:33 offset1:49
	ds_read2_b32 v[18:19], v5 offset0:66 offset1:82
	ds_read2_b32 v[22:23], v5 offset0:99 offset1:115
	v_mov_b32_e32 v12, 0
	s_waitcnt lgkmcnt(3)
	v_mul_f32_e32 v8, 0x43000000, v8
	s_waitcnt lgkmcnt(2)
	v_mul_f32_e32 v11, 0x43000000, v16
	v_cvt_pk_fp8_f32 v12, v8, v11
	ds_read2_b32 v[24:25], v5 offset0:132 offset1:148
	ds_read2_b32 v[26:27], v5 offset0:165 offset1:181
	ds_read2_b32 v[28:29], v5 offset0:198 offset1:214
	s_waitcnt lgkmcnt(4)
	v_mul_f32_e32 v13, 0x43000000, v18
	s_waitcnt lgkmcnt(3)
	v_mul_f32_e32 v8, 0x43000000, v22
	v_cvt_pk_fp8_f32 v12, v13, v8 op_sel:[0,0,1]
	s_waitcnt lgkmcnt(2)
	v_mul_f32_e32 v8, 0x43000000, v24
	s_waitcnt lgkmcnt(1)
	v_mul_f32_e32 v11, 0x43000000, v26
	v_mov_b32_e32 v13, 0
	ds_read2_b32 v[30:31], v5 offset0:231 offset1:247
	v_cvt_pk_fp8_f32 v13, v8, v11
	v_add_u32_e32 v8, 0x400, v5
	ds_read2_b32 v[32:33], v8 offset0:8 offset1:24
	ds_read2_b32 v[34:35], v8 offset0:41 offset1:57
	ds_read2_b32 v[36:37], v8 offset0:74 offset1:90
	ds_read2_b32 v[38:39], v8 offset0:107 offset1:123
	ds_read2_b32 v[40:41], v8 offset0:140 offset1:156
	ds_read2_b32 v[42:43], v8 offset0:173 offset1:189
	s_waitcnt lgkmcnt(7)
	v_mul_f32_e32 v14, 0x43000000, v28
	s_waitcnt lgkmcnt(6)
	v_mul_f32_e32 v11, 0x43000000, v30
	v_cvt_pk_fp8_f32 v13, v14, v11 op_sel:[0,0,1]
	s_waitcnt lgkmcnt(5)
	v_mul_f32_e32 v11, 0x43000000, v32
	s_waitcnt lgkmcnt(4)
	v_mul_f32_e32 v15, 0x43000000, v34
	v_mov_b32_e32 v14, 0
	ds_read2_b32 v[44:45], v8 offset0:206 offset1:222
	ds_read2_b32 v[46:47], v8 offset0:239 offset1:255
	v_cvt_pk_fp8_f32 v14, v11, v15
	s_waitcnt lgkmcnt(3)
	v_mul_f32_e32 v11, 0x43000000, v40
	s_waitcnt lgkmcnt(2)
	v_mul_f32_e32 v22, 0x43000000, v42
	v_mov_b32_e32 v15, 0
	v_cvt_pk_fp8_f32 v15, v11, v22
	v_mul_f32_e32 v16, 0x43000000, v36
	v_mul_f32_e32 v18, 0x43000000, v38
	s_waitcnt lgkmcnt(1)
	v_mul_f32_e32 v8, 0x43000000, v44
	s_waitcnt lgkmcnt(0)
	v_mul_f32_e32 v11, 0x43000000, v46
	v_cvt_pk_fp8_f32 v14, v16, v18 op_sel:[0,0,1]
	v_cvt_pk_fp8_f32 v15, v8, v11 op_sel:[0,0,1]
	v_or_b32_e32 v8, s0, v163
	s_ashr_i32 s5, s4, 31
	v_mul_lo_u32 v48, v8, s7
	v_lshl_add_u64 v[20:21], v[6:7], 0, s[4:5]
	v_ashrrev_i32_e32 v49, 31, v48
	v_lshl_add_u64 v[48:49], v[20:21], 0, v[48:49]
	global_store_dwordx4 v[48:49], v[12:15], off
	v_mul_f32_e32 v8, 0x43000000, v9
	v_mul_f32_e32 v9, 0x43000000, v17
	v_mov_b32_e32 v12, 0
	v_cvt_pk_fp8_f32 v12, v8, v9
	v_mul_f32_e32 v8, 0x43000000, v25
	v_mul_f32_e32 v9, 0x43000000, v27
	v_mov_b32_e32 v13, 0
	v_cvt_pk_fp8_f32 v13, v8, v9
	v_mul_f32_e32 v11, 0x43000000, v19
	v_mul_f32_e32 v14, 0x43000000, v23
	v_mul_f32_e32 v8, 0x43000000, v29
	v_mul_f32_e32 v9, 0x43000000, v31
	v_cvt_pk_fp8_f32 v12, v11, v14 op_sel:[0,0,1]
	v_cvt_pk_fp8_f32 v13, v8, v9 op_sel:[0,0,1]
	v_mul_f32_e32 v8, 0x43000000, v33
	v_mul_f32_e32 v9, 0x43000000, v35
	v_mov_b32_e32 v14, 0
	v_cvt_pk_fp8_f32 v14, v8, v9
	v_mul_f32_e32 v8, 0x43000000, v41
	v_mul_f32_e32 v9, 0x43000000, v43
	v_mov_b32_e32 v15, 0
	v_cvt_pk_fp8_f32 v15, v8, v9
	v_mul_f32_e32 v11, 0x43000000, v37
	v_mul_f32_e32 v16, 0x43000000, v39
	v_mul_f32_e32 v8, 0x43000000, v45
	v_mul_f32_e32 v9, 0x43000000, v47
	v_cvt_pk_fp8_f32 v14, v11, v16 op_sel:[0,0,1]
	v_cvt_pk_fp8_f32 v15, v8, v9 op_sel:[0,0,1]
	v_or_b32_e32 v8, s0, v10
	v_mul_lo_u32 v8, v8, s7
	v_ashrrev_i32_e32 v9, 31, v8
	v_lshl_add_u64 v[8:9], v[20:21], 0, v[8:9]
	global_store_dwordx4 v[8:9], v[12:15], off
	s_waitcnt lgkmcnt(0)
	s_add_i32 s8, s8, s92
	s_cmpk_lt_i32 s8, 0x5600
	s_cbranch_scc1 .LBB0_24

; template <int MAP>
; __device__ __forceinline__ void transpose_item(const float* W, int K, int N, int ldw, bf16* WT, LAS float* scr, int item, int lane) {
;     ...
;     for (int i = 0; i < 32; ++i) { const int kk = 2 * i + (lane >> 5); scr[kk * 33 + (lane & 31)] = W[(size_t)(k0 + kk) * ldw + n0 + (lane & 31)]; }
.LBB0_30:
	s_lshl_b32 s14, s13, 1
	s_lshl_b32 s15, s9, 1
	v_or_b32_e32 v13, s14, v1
	v_or_b32_e32 v15, s15, v162
	s_add_i32 s16, s14, 4
	s_add_i32 s17, s15, 4
	s_add_i32 s18, s14, 8
	s_add_i32 s19, s15, 8
	s_add_i32 s20, s14, 12
	s_add_i32 s21, s15, 12
	s_add_i32 s22, s14, 16
	s_add_i32 s23, s15, 16
	s_add_i32 s24, s14, 20
	s_add_i32 s25, s15, 20
	s_add_i32 s26, s14, 24
	s_add_i32 s27, s15, 24
	s_add_i32 s14, s14, 28
	s_add_i32 s15, s15, 28
	v_add_u32_e32 v16, s8, v15
	v_or_b32_e32 v48, s16, v1
	v_or_b32_e32 v49, s17, v162
	v_or_b32_e32 v50, s18, v1
	v_or_b32_e32 v51, s19, v162
	v_or_b32_e32 v52, s20, v1
	v_or_b32_e32 v53, s21, v162
	v_or_b32_e32 v54, s22, v1
	v_or_b32_e32 v55, s23, v162
	v_or_b32_e32 v56, s24, v1
	v_or_b32_e32 v57, s25, v162
	v_or_b32_e32 v58, s26, v1
	v_or_b32_e32 v59, s27, v162
	v_or_b32_e32 v60, s14, v1
	v_or_b32_e32 v61, s15, v162
	v_add_u32_e32 v18, s5, v13
	v_mad_i64_i32 v[16:17], s[14:15], v16, s10, v[8:9]
	v_add_u32_e32 v22, s5, v48
	v_add_u32_e32 v20, s8, v49
	v_add_u32_e32 v26, s5, v50
	v_add_u32_e32 v24, s8, v51
	v_add_u32_e32 v30, s5, v52
	v_add_u32_e32 v28, s8, v53
	v_add_u32_e32 v34, s5, v54
	v_add_u32_e32 v32, s8, v55
	v_add_u32_e32 v38, s5, v56
	v_add_u32_e32 v36, s8, v57
	v_add_u32_e32 v42, s5, v58
	v_add_u32_e32 v40, s8, v59
	v_add_u32_e32 v46, s5, v60
	v_add_u32_e32 v44, s8, v61
	v_mad_i64_i32 v[18:19], s[14:15], v18, s10, v[8:9]
	v_mad_i64_i32 v[20:21], s[14:15], v20, s10, v[8:9]
	v_mad_i64_i32 v[22:23], s[14:15], v22, s10, v[8:9]
	v_mad_i64_i32 v[24:25], s[14:15], v24, s10, v[8:9]
	v_mad_i64_i32 v[26:27], s[14:15], v26, s10, v[8:9]
	v_mad_i64_i32 v[28:29], s[14:15], v28, s10, v[8:9]
	v_mad_i64_i32 v[30:31], s[14:15], v30, s10, v[8:9]
	v_mad_i64_i32 v[32:33], s[14:15], v32, s10, v[8:9]
	v_mad_i64_i32 v[34:35], s[14:15], v34, s10, v[8:9]
	v_mad_i64_i32 v[36:37], s[14:15], v36, s10, v[8:9]
	v_mad_i64_i32 v[38:39], s[14:15], v38, s10, v[8:9]
	v_mad_i64_i32 v[40:41], s[14:15], v40, s10, v[8:9]
	v_mad_i64_i32 v[42:43], s[14:15], v42, s10, v[8:9]
	v_mad_i64_i32 v[44:45], s[14:15], v44, s10, v[8:9]
	v_mad_i64_i32 v[46:47], s[14:15], v46, s10, v[8:9]
	global_load_dword v62, v[16:17], off
	global_load_dword v63, v[18:19], off
	global_load_dword v64, v[20:21], off
	global_load_dword v65, v[22:23], off
	global_load_dword v66, v[24:25], off
	global_load_dword v67, v[26:27], off
	global_load_dword v68, v[28:29], off
	global_load_dword v69, v[30:31], off
	global_load_dword v70, v[32:33], off
	global_load_dword v71, v[34:35], off
	global_load_dword v72, v[36:37], off
	global_load_dword v73, v[38:39], off
	global_load_dword v74, v[40:41], off
	global_load_dword v75, v[42:43], off
	global_load_dword v76, v[44:45], off
	global_load_dword v77, v[46:47], off
	s_add_i32 s9, s9, 16
	s_add_i32 s13, s13, 16
	s_add_i32 s12, s12, -16
	v_mad_u64_u32 v[16:17], s[14:15], v15, s3, v[4:5]
	s_cmp_lg_u32 s12, 0
	v_mad_u64_u32 v[18:19], s[14:15], v13, s3, v[4:5]
	v_mad_u64_u32 v[20:21], s[14:15], v49, s3, v[4:5]
	v_mad_u64_u32 v[22:23], s[14:15], v48, s3, v[4:5]
	v_mad_u64_u32 v[24:25], s[14:15], v51, s3, v[4:5]
	v_mad_u64_u32 v[26:27], s[14:15], v50, s3, v[4:5]
	v_mad_u64_u32 v[28:29], s[14:15], v53, s3, v[4:5]
	v_mad_u64_u32 v[30:31], s[14:15], v52, s3, v[4:5]
	v_mad_u64_u32 v[32:33], s[14:15], v55, s3, v[4:5]
	v_mad_u64_u32 v[34:35], s[14:15], v54, s3, v[4:5]
	v_mad_u64_u32 v[36:37], s[14:15], v57, s3, v[4:5]
	v_mad_u64_u32 v[38:39], s[14:15], v56, s3, v[4:5]
	v_mad_u64_u32 v[40:41], s[14:15], v59, s3, v[4:5]
	v_mad_u64_u32 v[42:43], s[14:15], v58, s3, v[4:5]
	v_mad_u64_u32 v[44:45], s[14:15], v61, s3, v[4:5]
	v_mad_u64_u32 v[46:47], s[14:15], v60, s3, v[4:5]
	s_lshl_b32 s14, s13, 1
	s_lshl_b32 s15, s9, 1
	v_or_b32_e32 v85, s14, v1
	v_or_b32_e32 v87, s15, v162
	s_add_i32 s16, s14, 4
	s_add_i32 s17, s15, 4
	s_add_i32 s18, s14, 8
	s_add_i32 s19, s15, 8
	s_add_i32 s20, s14, 12
	s_add_i32 s21, s15, 12
	s_add_i32 s22, s14, 16
	s_add_i32 s23, s15, 16
	s_add_i32 s24, s14, 20
	s_add_i32 s25, s15, 20
	s_add_i32 s26, s14, 24
	s_add_i32 s27, s15, 24
	s_add_i32 s14, s14, 28
	s_add_i32 s15, s15, 28
	v_add_u32_e32 v88, s8, v87
	v_or_b32_e32 v120, s16, v1
	v_or_b32_e32 v121, s17, v162
	v_or_b32_e32 v122, s18, v1
	v_or_b32_e32 v123, s19, v162
	v_or_b32_e32 v124, s20, v1
	v_or_b32_e32 v125, s21, v162
	v_or_b32_e32 v126, s22, v1
	v_or_b32_e32 v127, s23, v162
	v_or_b32_e32 v128, s24, v1
	v_or_b32_e32 v129, s25, v162
	v_or_b32_e32 v130, s26, v1
	v_or_b32_e32 v131, s27, v162
	v_or_b32_e32 v132, s14, v1
	v_or_b32_e32 v133, s15, v162
	v_add_u32_e32 v90, s5, v85
	v_mad_i64_i32 v[88:89], s[14:15], v88, s10, v[8:9]
	v_add_u32_e32 v94, s5, v120
	v_add_u32_e32 v92, s8, v121
	v_add_u32_e32 v98, s5, v122
	v_add_u32_e32 v96, s8, v123
	v_add_u32_e32 v102, s5, v124
	v_add_u32_e32 v100, s8, v125
	v_add_u32_e32 v106, s5, v126
	v_add_u32_e32 v104, s8, v127
	v_add_u32_e32 v110, s5, v128
	v_add_u32_e32 v108, s8, v129
	v_add_u32_e32 v114, s5, v130
	v_add_u32_e32 v112, s8, v131
	v_add_u32_e32 v118, s5, v132
	v_add_u32_e32 v116, s8, v133
	v_mad_i64_i32 v[90:91], s[14:15], v90, s10, v[8:9]
	v_mad_i64_i32 v[92:93], s[14:15], v92, s10, v[8:9]
	v_mad_i64_i32 v[94:95], s[14:15], v94, s10, v[8:9]
	v_mad_i64_i32 v[96:97], s[14:15], v96, s10, v[8:9]
	v_mad_i64_i32 v[98:99], s[14:15], v98, s10, v[8:9]
	v_mad_i64_i32 v[100:101], s[14:15], v100, s10, v[8:9]
	v_mad_i64_i32 v[102:103], s[14:15], v102, s10, v[8:9]
	v_mad_i64_i32 v[104:105], s[14:15], v104, s10, v[8:9]
	v_mad_i64_i32 v[106:107], s[14:15], v106, s10, v[8:9]
	v_mad_i64_i32 v[108:109], s[14:15], v108, s10, v[8:9]
	v_mad_i64_i32 v[110:111], s[14:15], v110, s10, v[8:9]
; #define LAS __attribute__((address_space(3)))
; __device__ __forceinline__ unsigned pk2(float lo, float hi) { return cvt_pk_bf16(lo, hi); }
; #define LDS_WAIT() asm volatile("s_waitcnt lgkmcnt(0)" ::: "memory")
; template <int MAP>
; __device__ __forceinline__ void transpose_item(const float* W, int K, int N, int ldw, bf16* WT, LAS float* scr, int item, int lane) {
;     ...
;     for (int i = 0; i < 32; ++i) { const int kk = 2 * i + (lane >> 5); scr[kk * 33 + (lane & 31)] = W[(size_t)(k0 + kk) * ldw + n0 + (lane & 31)]; }
;     LDS_WAIT(); asm volatile("" ::: "memory");
;     const int c = lane & 7;
; #pragma unroll
;     for (int j = 0; j < 4; ++j) { const int n = (lane >> 3) + 8 * j; const LAS float* s = scr + (8 * c) * 33 + n;
;         u32x4 o; o.x = pk2(s[0 * 33], s[1 * 33]); o.y = pk2(s[2 * 33], s[3 * 33]); o.z = pk2(s[4 * 33], s[5 * 33]); o.w = pk2(s[6 * 33], s[7 * 33]);
;         *(u32x4*)(WT + (size_t)(dr0 + n) * K + k0 + 8 * c) = o; }
;     LDS_WAIT(); asm volatile("" ::: "memory");
	v_mad_i64_i32 v[112:113], s[14:15], v112, s10, v[8:9]
	v_mad_i64_i32 v[114:115], s[14:15], v114, s10, v[8:9]
	v_mad_i64_i32 v[116:117], s[14:15], v116, s10, v[8:9]
	v_mad_i64_i32 v[118:119], s[14:15], v118, s10, v[8:9]
	global_load_dword v134, v[88:89], off
	global_load_dword v135, v[90:91], off
	global_load_dword v136, v[92:93], off
	global_load_dword v137, v[94:95], off
	global_load_dword v138, v[96:97], off
	global_load_dword v139, v[98:99], off
	global_load_dword v140, v[100:101], off
	global_load_dword v141, v[102:103], off
	global_load_dword v142, v[104:105], off
	global_load_dword v143, v[106:107], off
	global_load_dword v144, v[108:109], off
	global_load_dword v145, v[110:111], off
	global_load_dword v146, v[112:113], off
	global_load_dword v147, v[114:115], off
	global_load_dword v148, v[116:117], off
	global_load_dword v149, v[118:119], off
	s_add_i32 s9, s9, 16
	s_add_i32 s13, s13, 16
	s_add_i32 s12, s12, -16
	v_mad_u64_u32 v[88:89], s[14:15], v87, s3, v[4:5]
	s_cmp_lg_u32 s12, 0
	v_mad_u64_u32 v[90:91], s[14:15], v85, s3, v[4:5]
	v_mad_u64_u32 v[92:93], s[14:15], v121, s3, v[4:5]
	v_mad_u64_u32 v[94:95], s[14:15], v120, s3, v[4:5]
	v_mad_u64_u32 v[96:97], s[14:15], v123, s3, v[4:5]
	v_mad_u64_u32 v[98:99], s[14:15], v122, s3, v[4:5]
	v_mad_u64_u32 v[100:101], s[14:15], v125, s3, v[4:5]
	v_mad_u64_u32 v[102:103], s[14:15], v124, s3, v[4:5]
	v_mad_u64_u32 v[104:105], s[14:15], v127, s3, v[4:5]
	v_mad_u64_u32 v[106:107], s[14:15], v126, s3, v[4:5]
	v_mad_u64_u32 v[108:109], s[14:15], v129, s3, v[4:5]
	v_mad_u64_u32 v[110:111], s[14:15], v128, s3, v[4:5]
	v_mad_u64_u32 v[112:113], s[14:15], v131, s3, v[4:5]
	v_mad_u64_u32 v[114:115], s[14:15], v130, s3, v[4:5]
	v_mad_u64_u32 v[116:117], s[14:15], v133, s3, v[4:5]
	v_mad_u64_u32 v[118:119], s[14:15], v132, s3, v[4:5]
	s_waitcnt vmcnt(31)
	ds_write_b32 v16, v62
	s_waitcnt vmcnt(30)
	ds_write_b32 v18, v63
	s_waitcnt vmcnt(29)
	ds_write_b32 v20, v64
	s_waitcnt vmcnt(28)
	ds_write_b32 v22, v65
	s_waitcnt vmcnt(27)
	ds_write_b32 v24, v66
	s_waitcnt vmcnt(26)
	ds_write_b32 v26, v67
	s_waitcnt vmcnt(25)
	ds_write_b32 v28, v68
	s_waitcnt vmcnt(24)
	ds_write_b32 v30, v69
	s_waitcnt vmcnt(23)
	ds_write_b32 v32, v70
	s_waitcnt vmcnt(22)
	ds_write_b32 v34, v71
	s_waitcnt vmcnt(21)
	ds_write_b32 v36, v72
	s_waitcnt vmcnt(20)
	ds_write_b32 v38, v73
	s_waitcnt vmcnt(19)
	ds_write_b32 v40, v74
	s_waitcnt vmcnt(18)
	ds_write_b32 v42, v75
	s_waitcnt vmcnt(17)
	ds_write_b32 v44, v76
	s_waitcnt vmcnt(16)
	ds_write_b32 v46, v77
	s_waitcnt vmcnt(15)
	ds_write_b32 v88, v134
	s_waitcnt vmcnt(14)
	ds_write_b32 v90, v135
	s_waitcnt vmcnt(13)
	ds_write_b32 v92, v136
	s_waitcnt vmcnt(12)
	ds_write_b32 v94, v137
	s_waitcnt vmcnt(11)
	ds_write_b32 v96, v138
	s_waitcnt vmcnt(10)
	ds_write_b32 v98, v139
	s_waitcnt vmcnt(9)
	ds_write_b32 v100, v140
	s_waitcnt vmcnt(8)
	ds_write_b32 v102, v141
	s_waitcnt vmcnt(7)
	ds_write_b32 v104, v142
	s_waitcnt vmcnt(6)
	ds_write_b32 v106, v143
	s_waitcnt vmcnt(5)
	ds_write_b32 v108, v144
	s_waitcnt vmcnt(4)
	ds_write_b32 v110, v145
	s_waitcnt vmcnt(3)
	ds_write_b32 v112, v146
	s_waitcnt vmcnt(2)
	ds_write_b32 v114, v147
	s_waitcnt vmcnt(1)
	ds_write_b32 v116, v148
	s_waitcnt vmcnt(0)
	ds_write_b32 v118, v149
	s_waitcnt lgkmcnt(0)
	ds_read2_b32 v[8:9], v5 offset0:33 offset1:41
	ds_read2_b32 v[20:21], v5 offset1:8
	ds_read2_b32 v[22:23], v5 offset0:66 offset1:74
	ds_read2_b32 v[24:25], v5 offset0:99 offset1:107
	ds_read2_b32 v[26:27], v5 offset0:132 offset1:140
	ds_read2_b32 v[28:29], v5 offset0:165 offset1:173
	ds_read2_b32 v[30:31], v5 offset0:198 offset1:206
	ds_read2_b32 v[32:33], v5 offset0:231 offset1:239
	v_or_b32_e32 v36, s4, v14
	s_ashr_i32 s9, s8, 31
	v_ashrrev_i32_e32 v37, 31, v36
	v_lshl_add_u64 v[34:35], s[8:9], 1, v[6:7]
	v_lshlrev_b64 v[36:37], 13, v[36:37]
	s_waitcnt lgkmcnt(6)
	v_cvt_pk_bf16_f32 v16, v20, v8
	s_waitcnt lgkmcnt(4)
	v_cvt_pk_bf16_f32 v17, v22, v24
	s_waitcnt lgkmcnt(2)
	v_cvt_pk_bf16_f32 v18, v26, v28
	s_waitcnt lgkmcnt(0)
	v_cvt_pk_bf16_f32 v19, v30, v32
	v_lshl_add_u64 v[36:37], v[34:35], 0, v[36:37]
	v_or_b32_e32 v8, s4, v10
	global_store_dwordx4 v[36:37], v[16:19], off
	s_add_i32 s11, s11, s92
	s_cmpk_lt_i32 s11, 0x2000
	v_cvt_pk_bf16_f32 v16, v21, v9
	v_ashrrev_i32_e32 v9, 31, v8
	v_cvt_pk_bf16_f32 v17, v23, v25
	v_cvt_pk_bf16_f32 v18, v27, v29
	v_cvt_pk_bf16_f32 v19, v31, v33
	v_lshlrev_b64 v[8:9], 13, v[8:9]
	ds_read2_b32 v[20:21], v5 offset0:49 offset1:57
	ds_read2_b32 v[22:23], v5 offset0:16 offset1:24
	ds_read2_b32 v[24:25], v5 offset0:82 offset1:90
	ds_read2_b32 v[26:27], v5 offset0:115 offset1:123
	ds_read2_b32 v[28:29], v5 offset0:148 offset1:156
	ds_read2_b32 v[30:31], v5 offset0:181 offset1:189
	ds_read2_b32 v[32:33], v5 offset0:214 offset1:222
	ds_read2_b32 v[36:37], v5 offset0:247 offset1:255
	v_lshl_add_u64 v[8:9], v[34:35], 0, v[8:9]
	global_store_dwordx4 v[8:9], v[16:19], off
	v_or_b32_e32 v8, s4, v11
	v_ashrrev_i32_e32 v9, 31, v8
	v_lshlrev_b64 v[8:9], 13, v[8:9]
	s_waitcnt lgkmcnt(6)
	v_cvt_pk_bf16_f32 v16, v22, v20
	s_waitcnt lgkmcnt(4)
	v_cvt_pk_bf16_f32 v17, v24, v26
	s_waitcnt lgkmcnt(2)
	v_cvt_pk_bf16_f32 v18, v28, v30
	s_waitcnt lgkmcnt(0)
	v_cvt_pk_bf16_f32 v19, v32, v36
	v_lshl_add_u64 v[8:9], v[34:35], 0, v[8:9]
	global_store_dwordx4 v[8:9], v[16:19], off
	v_or_b32_e32 v8, s4, v12
	v_ashrrev_i32_e32 v9, 31, v8
	v_lshlrev_b64 v[8:9], 13, v[8:9]
	v_cvt_pk_bf16_f32 v16, v23, v21
	v_cvt_pk_bf16_f32 v17, v25, v27
	v_cvt_pk_bf16_f32 v18, v29, v31
	v_cvt_pk_bf16_f32 v19, v33, v37
	v_lshl_add_u64 v[8:9], v[34:35], 0, v[8:9]
	global_store_dwordx4 v[8:9], v[16:19], off
	s_waitcnt lgkmcnt(0)
	s_cbranch_scc1 .LBB0_29

; template <int MAP>
; __device__ __forceinline__ void transpose_item(const float* W, int K, int N, int ldw, bf16* WT, LAS float* scr, int item, int lane) {
;     ...
;     for (int i = 0; i < 32; ++i) { const int kk = 2 * i + (lane >> 5); scr[kk * 33 + (lane & 31)] = W[(size_t)(k0 + kk) * ldw + n0 + (lane & 31)]; }
.LBB0_35:
	s_lshl_b32 s14, s13, 1
	s_lshl_b32 s15, s12, 1
	v_or_b32_e32 v13, s14, v1
	v_or_b32_e32 v15, s15, v162
	s_add_i32 s16, s14, 4
	s_add_i32 s17, s15, 4
	s_add_i32 s18, s14, 8
	s_add_i32 s19, s15, 8
	s_add_i32 s20, s14, 12
	s_add_i32 s21, s15, 12
	s_add_i32 s22, s14, 16
	s_add_i32 s23, s15, 16
	s_add_i32 s24, s14, 20
	s_add_i32 s25, s15, 20
	s_add_i32 s26, s14, 24
	s_add_i32 s27, s15, 24
	s_add_i32 s14, s14, 28
	s_add_i32 s15, s15, 28
	v_add_u32_e32 v16, s8, v15
	v_or_b32_e32 v48, s16, v1
	v_or_b32_e32 v49, s17, v162
	v_or_b32_e32 v50, s18, v1
	v_or_b32_e32 v51, s19, v162
	v_or_b32_e32 v52, s20, v1
	v_or_b32_e32 v53, s21, v162
	v_or_b32_e32 v54, s22, v1
	v_or_b32_e32 v55, s23, v162
	v_or_b32_e32 v56, s24, v1
	v_or_b32_e32 v57, s25, v162
	v_or_b32_e32 v58, s26, v1
	v_or_b32_e32 v59, s27, v162
	v_or_b32_e32 v60, s14, v1
	v_or_b32_e32 v61, s15, v162
	v_add_u32_e32 v18, s5, v13
	v_mad_i64_i32 v[16:17], s[14:15], v16, s10, v[8:9]
	v_add_u32_e32 v22, s5, v48
	v_add_u32_e32 v20, s8, v49
	v_add_u32_e32 v26, s5, v50
	v_add_u32_e32 v24, s8, v51
	v_add_u32_e32 v30, s5, v52
	v_add_u32_e32 v28, s8, v53
	v_add_u32_e32 v34, s5, v54
	v_add_u32_e32 v32, s8, v55
	v_add_u32_e32 v38, s5, v56
	v_add_u32_e32 v36, s8, v57
	v_add_u32_e32 v42, s5, v58
	v_add_u32_e32 v40, s8, v59
	v_add_u32_e32 v46, s5, v60
	v_add_u32_e32 v44, s8, v61
	v_mad_i64_i32 v[18:19], s[14:15], v18, s10, v[8:9]
	v_mad_i64_i32 v[20:21], s[14:15], v20, s10, v[8:9]
	v_mad_i64_i32 v[22:23], s[14:15], v22, s10, v[8:9]
	v_mad_i64_i32 v[24:25], s[14:15], v24, s10, v[8:9]
	v_mad_i64_i32 v[26:27], s[14:15], v26, s10, v[8:9]
	v_mad_i64_i32 v[28:29], s[14:15], v28, s10, v[8:9]
	v_mad_i64_i32 v[30:31], s[14:15], v30, s10, v[8:9]
	v_mad_i64_i32 v[32:33], s[14:15], v32, s10, v[8:9]
	v_mad_i64_i32 v[34:35], s[14:15], v34, s10, v[8:9]
	v_mad_i64_i32 v[36:37], s[14:15], v36, s10, v[8:9]
	v_mad_i64_i32 v[38:39], s[14:15], v38, s10, v[8:9]
	v_mad_i64_i32 v[40:41], s[14:15], v40, s10, v[8:9]
	v_mad_i64_i32 v[42:43], s[14:15], v42, s10, v[8:9]
	v_mad_i64_i32 v[44:45], s[14:15], v44, s10, v[8:9]
	v_mad_i64_i32 v[46:47], s[14:15], v46, s10, v[8:9]
	global_load_dword v62, v[16:17], off
	global_load_dword v63, v[18:19], off
	global_load_dword v64, v[20:21], off
	global_load_dword v65, v[22:23], off
	global_load_dword v66, v[24:25], off
	global_load_dword v67, v[26:27], off
	global_load_dword v68, v[28:29], off
	global_load_dword v69, v[30:31], off
	global_load_dword v70, v[32:33], off
	global_load_dword v71, v[34:35], off
	global_load_dword v72, v[36:37], off
	global_load_dword v73, v[38:39], off
	global_load_dword v74, v[40:41], off
	global_load_dword v75, v[42:43], off
	global_load_dword v76, v[44:45], off
	global_load_dword v77, v[46:47], off
	s_add_i32 s12, s12, 16
	s_add_i32 s13, s13, 16
	s_add_i32 s9, s9, -16
	v_mad_u64_u32 v[16:17], s[14:15], v15, s3, v[4:5]
	s_cmp_lg_u32 s9, 0
	v_mad_u64_u32 v[18:19], s[14:15], v13, s3, v[4:5]
	v_mad_u64_u32 v[20:21], s[14:15], v49, s3, v[4:5]
	v_mad_u64_u32 v[22:23], s[14:15], v48, s3, v[4:5]
	v_mad_u64_u32 v[24:25], s[14:15], v51, s3, v[4:5]
	v_mad_u64_u32 v[26:27], s[14:15], v50, s3, v[4:5]
	v_mad_u64_u32 v[28:29], s[14:15], v53, s3, v[4:5]
	v_mad_u64_u32 v[30:31], s[14:15], v52, s3, v[4:5]
	v_mad_u64_u32 v[32:33], s[14:15], v55, s3, v[4:5]
	v_mad_u64_u32 v[34:35], s[14:15], v54, s3, v[4:5]
	v_mad_u64_u32 v[36:37], s[14:15], v57, s3, v[4:5]
	v_mad_u64_u32 v[38:39], s[14:15], v56, s3, v[4:5]
	v_mad_u64_u32 v[40:41], s[14:15], v59, s3, v[4:5]
	v_mad_u64_u32 v[42:43], s[14:15], v58, s3, v[4:5]
	v_mad_u64_u32 v[44:45], s[14:15], v61, s3, v[4:5]
	v_mad_u64_u32 v[46:47], s[14:15], v60, s3, v[4:5]
	s_lshl_b32 s14, s13, 1
	s_lshl_b32 s15, s12, 1
	v_or_b32_e32 v85, s14, v1
	v_or_b32_e32 v87, s15, v162
	s_add_i32 s16, s14, 4
	s_add_i32 s17, s15, 4
	s_add_i32 s18, s14, 8
	s_add_i32 s19, s15, 8
	s_add_i32 s20, s14, 12
	s_add_i32 s21, s15, 12
	s_add_i32 s22, s14, 16
	s_add_i32 s23, s15, 16
	s_add_i32 s24, s14, 20
	s_add_i32 s25, s15, 20
	s_add_i32 s26, s14, 24
	s_add_i32 s27, s15, 24
	s_add_i32 s14, s14, 28
	s_add_i32 s15, s15, 28
	v_add_u32_e32 v88, s8, v87
	v_or_b32_e32 v120, s16, v1
	v_or_b32_e32 v121, s17, v162
	v_or_b32_e32 v122, s18, v1
	v_or_b32_e32 v123, s19, v162
	v_or_b32_e32 v124, s20, v1
	v_or_b32_e32 v125, s21, v162
	v_or_b32_e32 v126, s22, v1
	v_or_b32_e32 v127, s23, v162
	v_or_b32_e32 v128, s24, v1
	v_or_b32_e32 v129, s25, v162
	v_or_b32_e32 v130, s26, v1
	v_or_b32_e32 v131, s27, v162
	v_or_b32_e32 v132, s14, v1
	v_or_b32_e32 v133, s15, v162
	v_add_u32_e32 v90, s5, v85
	v_mad_i64_i32 v[88:89], s[14:15], v88, s10, v[8:9]
	v_add_u32_e32 v94, s5, v120
	v_add_u32_e32 v92, s8, v121
	v_add_u32_e32 v98, s5, v122
	v_add_u32_e32 v96, s8, v123
	v_add_u32_e32 v102, s5, v124
	v_add_u32_e32 v100, s8, v125
	v_add_u32_e32 v106, s5, v126
	v_add_u32_e32 v104, s8, v127
	v_add_u32_e32 v110, s5, v128
	v_add_u32_e32 v108, s8, v129
	v_add_u32_e32 v114, s5, v130
	v_add_u32_e32 v112, s8, v131
	v_add_u32_e32 v118, s5, v132
	v_add_u32_e32 v116, s8, v133
	v_mad_i64_i32 v[90:91], s[14:15], v90, s10, v[8:9]
	v_mad_i64_i32 v[92:93], s[14:15], v92, s10, v[8:9]
	v_mad_i64_i32 v[94:95], s[14:15], v94, s10, v[8:9]
	v_mad_i64_i32 v[96:97], s[14:15], v96, s10, v[8:9]
	v_mad_i64_i32 v[98:99], s[14:15], v98, s10, v[8:9]
	v_mad_i64_i32 v[100:101], s[14:15], v100, s10, v[8:9]
	v_mad_i64_i32 v[102:103], s[14:15], v102, s10, v[8:9]
	v_mad_i64_i32 v[104:105], s[14:15], v104, s10, v[8:9]
	v_mad_i64_i32 v[106:107], s[14:15], v106, s10, v[8:9]
	v_mad_i64_i32 v[108:109], s[14:15], v108, s10, v[8:9]
	v_mad_i64_i32 v[110:111], s[14:15], v110, s10, v[8:9]
; #define LAS __attribute__((address_space(3)))
; __device__ __forceinline__ unsigned pk2(float lo, float hi) { return cvt_pk_bf16(lo, hi); }
; #define LDS_WAIT() asm volatile("s_waitcnt lgkmcnt(0)" ::: "memory")
; template <int MAP>
; __device__ __forceinline__ void transpose_item(const float* W, int K, int N, int ldw, bf16* WT, LAS float* scr, int item, int lane) {
;     ...
;     for (int i = 0; i < 32; ++i) { const int kk = 2 * i + (lane >> 5); scr[kk * 33 + (lane & 31)] = W[(size_t)(k0 + kk) * ldw + n0 + (lane & 31)]; }
;     LDS_WAIT(); asm volatile("" ::: "memory");
;     const int c = lane & 7;
; #pragma unroll
;     for (int j = 0; j < 4; ++j) { const int n = (lane >> 3) + 8 * j; const LAS float* s = scr + (8 * c) * 33 + n;
;         u32x4 o; o.x = pk2(s[0 * 33], s[1 * 33]); o.y = pk2(s[2 * 33], s[3 * 33]); o.z = pk2(s[4 * 33], s[5 * 33]); o.w = pk2(s[6 * 33], s[7 * 33]);
;         *(u32x4*)(WT + (size_t)(dr0 + n) * K + k0 + 8 * c) = o; }
;     LDS_WAIT(); asm volatile("" ::: "memory");
	v_mad_i64_i32 v[112:113], s[14:15], v112, s10, v[8:9]
	v_mad_i64_i32 v[114:115], s[14:15], v114, s10, v[8:9]
	v_mad_i64_i32 v[116:117], s[14:15], v116, s10, v[8:9]
	v_mad_i64_i32 v[118:119], s[14:15], v118, s10, v[8:9]
	global_load_dword v134, v[88:89], off
	global_load_dword v135, v[90:91], off
	global_load_dword v136, v[92:93], off
	global_load_dword v137, v[94:95], off
	global_load_dword v138, v[96:97], off
	global_load_dword v139, v[98:99], off
	global_load_dword v140, v[100:101], off
	global_load_dword v141, v[102:103], off
	global_load_dword v142, v[104:105], off
	global_load_dword v143, v[106:107], off
	global_load_dword v144, v[108:109], off
	global_load_dword v145, v[110:111], off
	global_load_dword v146, v[112:113], off
	global_load_dword v147, v[114:115], off
	global_load_dword v148, v[116:117], off
	global_load_dword v149, v[118:119], off
	s_add_i32 s12, s12, 16
	s_add_i32 s13, s13, 16
	s_add_i32 s9, s9, -16
	v_mad_u64_u32 v[88:89], s[14:15], v87, s3, v[4:5]
	s_cmp_lg_u32 s9, 0
	v_mad_u64_u32 v[90:91], s[14:15], v85, s3, v[4:5]
	v_mad_u64_u32 v[92:93], s[14:15], v121, s3, v[4:5]
	v_mad_u64_u32 v[94:95], s[14:15], v120, s3, v[4:5]
	v_mad_u64_u32 v[96:97], s[14:15], v123, s3, v[4:5]
	v_mad_u64_u32 v[98:99], s[14:15], v122, s3, v[4:5]
	v_mad_u64_u32 v[100:101], s[14:15], v125, s3, v[4:5]
	v_mad_u64_u32 v[102:103], s[14:15], v124, s3, v[4:5]
	v_mad_u64_u32 v[104:105], s[14:15], v127, s3, v[4:5]
	v_mad_u64_u32 v[106:107], s[14:15], v126, s3, v[4:5]
	v_mad_u64_u32 v[108:109], s[14:15], v129, s3, v[4:5]
	v_mad_u64_u32 v[110:111], s[14:15], v128, s3, v[4:5]
	v_mad_u64_u32 v[112:113], s[14:15], v131, s3, v[4:5]
	v_mad_u64_u32 v[114:115], s[14:15], v130, s3, v[4:5]
	v_mad_u64_u32 v[116:117], s[14:15], v133, s3, v[4:5]
	v_mad_u64_u32 v[118:119], s[14:15], v132, s3, v[4:5]
	s_waitcnt vmcnt(31)
	ds_write_b32 v16, v62
	s_waitcnt vmcnt(30)
	ds_write_b32 v18, v63
	s_waitcnt vmcnt(29)
	ds_write_b32 v20, v64
	s_waitcnt vmcnt(28)
	ds_write_b32 v22, v65
	s_waitcnt vmcnt(27)
	ds_write_b32 v24, v66
	s_waitcnt vmcnt(26)
	ds_write_b32 v26, v67
	s_waitcnt vmcnt(25)
	ds_write_b32 v28, v68
	s_waitcnt vmcnt(24)
	ds_write_b32 v30, v69
	s_waitcnt vmcnt(23)
	ds_write_b32 v32, v70
	s_waitcnt vmcnt(22)
	ds_write_b32 v34, v71
	s_waitcnt vmcnt(21)
	ds_write_b32 v36, v72
	s_waitcnt vmcnt(20)
	ds_write_b32 v38, v73
	s_waitcnt vmcnt(19)
	ds_write_b32 v40, v74
	s_waitcnt vmcnt(18)
	ds_write_b32 v42, v75
	s_waitcnt vmcnt(17)
	ds_write_b32 v44, v76
	s_waitcnt vmcnt(16)
	ds_write_b32 v46, v77
	s_waitcnt vmcnt(15)
	ds_write_b32 v88, v134
	s_waitcnt vmcnt(14)
	ds_write_b32 v90, v135
	s_waitcnt vmcnt(13)
	ds_write_b32 v92, v136
	s_waitcnt vmcnt(12)
	ds_write_b32 v94, v137
	s_waitcnt vmcnt(11)
	ds_write_b32 v96, v138
	s_waitcnt vmcnt(10)
	ds_write_b32 v98, v139
	s_waitcnt vmcnt(9)
	ds_write_b32 v100, v140
	s_waitcnt vmcnt(8)
	ds_write_b32 v102, v141
	s_waitcnt vmcnt(7)
	ds_write_b32 v104, v142
	s_waitcnt vmcnt(6)
	ds_write_b32 v106, v143
	s_waitcnt vmcnt(5)
	ds_write_b32 v108, v144
	s_waitcnt vmcnt(4)
	ds_write_b32 v110, v145
	s_waitcnt vmcnt(3)
	ds_write_b32 v112, v146
	s_waitcnt vmcnt(2)
	ds_write_b32 v114, v147
	s_waitcnt vmcnt(1)
	ds_write_b32 v116, v148
	s_waitcnt vmcnt(0)
	ds_write_b32 v118, v149
	s_waitcnt lgkmcnt(0)
	ds_read2_b32 v[8:9], v5 offset0:33 offset1:41
	ds_read2_b32 v[20:21], v5 offset1:8
	ds_read2_b32 v[22:23], v5 offset0:66 offset1:74
	ds_read2_b32 v[24:25], v5 offset0:99 offset1:107
	ds_read2_b32 v[26:27], v5 offset0:132 offset1:140
	ds_read2_b32 v[28:29], v5 offset0:165 offset1:173
	ds_read2_b32 v[30:31], v5 offset0:198 offset1:206
	ds_read2_b32 v[32:33], v5 offset0:231 offset1:239
	v_or_b32_e32 v36, s4, v14
	s_ashr_i32 s9, s8, 31
	v_ashrrev_i32_e32 v37, 31, v36
	v_lshl_add_u64 v[34:35], s[8:9], 1, v[6:7]
	v_lshlrev_b64 v[36:37], 13, v[36:37]
	s_waitcnt lgkmcnt(6)
	v_cvt_pk_bf16_f32 v16, v20, v8
	s_waitcnt lgkmcnt(4)
	v_cvt_pk_bf16_f32 v17, v22, v24
	s_waitcnt lgkmcnt(2)
	v_cvt_pk_bf16_f32 v18, v26, v28
	s_waitcnt lgkmcnt(0)
	v_cvt_pk_bf16_f32 v19, v30, v32
	v_lshl_add_u64 v[36:37], v[34:35], 0, v[36:37]
	v_or_b32_e32 v8, s4, v10
	global_store_dwordx4 v[36:37], v[16:19], off
	s_add_i32 s11, s11, s92
	s_cmpk_lt_i32 s11, 0x25c0
	v_cvt_pk_bf16_f32 v16, v21, v9
	v_ashrrev_i32_e32 v9, 31, v8
	v_cvt_pk_bf16_f32 v17, v23, v25
	v_cvt_pk_bf16_f32 v18, v27, v29
	v_cvt_pk_bf16_f32 v19, v31, v33
	v_lshlrev_b64 v[8:9], 13, v[8:9]
	ds_read2_b32 v[20:21], v5 offset0:49 offset1:57
	ds_read2_b32 v[22:23], v5 offset0:16 offset1:24
	ds_read2_b32 v[24:25], v5 offset0:82 offset1:90
	ds_read2_b32 v[26:27], v5 offset0:115 offset1:123
	ds_read2_b32 v[28:29], v5 offset0:148 offset1:156
	ds_read2_b32 v[30:31], v5 offset0:181 offset1:189
	ds_read2_b32 v[32:33], v5 offset0:214 offset1:222
	ds_read2_b32 v[36:37], v5 offset0:247 offset1:255
	v_lshl_add_u64 v[8:9], v[34:35], 0, v[8:9]
	global_store_dwordx4 v[8:9], v[16:19], off
	v_or_b32_e32 v8, s4, v11
	v_ashrrev_i32_e32 v9, 31, v8
	v_lshlrev_b64 v[8:9], 13, v[8:9]
	s_waitcnt lgkmcnt(6)
	v_cvt_pk_bf16_f32 v16, v22, v20
	s_waitcnt lgkmcnt(4)
	v_cvt_pk_bf16_f32 v17, v24, v26
	s_waitcnt lgkmcnt(2)
	v_cvt_pk_bf16_f32 v18, v28, v30
	s_waitcnt lgkmcnt(0)
	v_cvt_pk_bf16_f32 v19, v32, v36
	v_lshl_add_u64 v[8:9], v[34:35], 0, v[8:9]
	global_store_dwordx4 v[8:9], v[16:19], off
	v_or_b32_e32 v8, s4, v12
	v_ashrrev_i32_e32 v9, 31, v8
	v_lshlrev_b64 v[8:9], 13, v[8:9]
	v_cvt_pk_bf16_f32 v16, v23, v21
	v_cvt_pk_bf16_f32 v17, v25, v27
	v_cvt_pk_bf16_f32 v18, v29, v31
	v_cvt_pk_bf16_f32 v19, v33, v37
	v_lshl_add_u64 v[8:9], v[34:35], 0, v[8:9]
	global_store_dwordx4 v[8:9], v[16:19], off
	s_waitcnt lgkmcnt(0)
	s_cbranch_scc1 .LBB0_34

;     ...
;         int dr0 = n0; if (MAP == 1) { if (n0 < DFF) dr0 = (n0 >> 7) * 256 + (n0 & 127); else { const int uo = n0 - DFF; dr0 = (uo >> 7) * 256 + 128 + (uo & 127); } }
; #pragma unroll 8
;         for (int i = 0; i < 32; ++i) { const int kk = 2 * i + (lane >> 5); scr[kk * 33 + (lane & 31)] = W[(size_t)(k0 + kk) * ldw + n0 + (lane & 31)]; }
.LBB0_40:
	s_lshl_b32 s16, s15, 1
	s_lshl_b32 s17, s14, 1
	v_or_b32_e32 v13, s16, v1
	v_or_b32_e32 v15, s17, v162
	s_add_i32 s18, s16, 4
	s_add_i32 s19, s17, 4
	s_add_i32 s20, s16, 8
	s_add_i32 s21, s17, 8
	s_add_i32 s22, s16, 12
	s_add_i32 s23, s17, 12
	s_add_i32 s24, s16, 16
	s_add_i32 s25, s17, 16
	s_add_i32 s26, s16, 20
	s_add_i32 s27, s17, 20
	s_add_i32 s28, s16, 24
	s_add_i32 s29, s17, 24
	s_add_i32 s16, s16, 28
	s_add_i32 s17, s17, 28
	v_add_u32_e32 v16, s10, v15
	v_or_b32_e32 v48, s18, v1
	v_or_b32_e32 v49, s19, v162
	v_or_b32_e32 v50, s20, v1
	v_or_b32_e32 v51, s21, v162
	v_or_b32_e32 v52, s22, v1
	v_or_b32_e32 v53, s23, v162
	v_or_b32_e32 v54, s24, v1
	v_or_b32_e32 v55, s25, v162
	v_or_b32_e32 v56, s26, v1
	v_or_b32_e32 v57, s27, v162
	v_or_b32_e32 v58, s28, v1
	v_or_b32_e32 v59, s29, v162
	v_or_b32_e32 v60, s16, v1
	v_or_b32_e32 v61, s17, v162
	v_add_u32_e32 v18, s9, v13
	v_mad_i64_i32 v[16:17], s[16:17], v16, s5, v[8:9]
	v_add_u32_e32 v22, s9, v48
	v_add_u32_e32 v20, s10, v49
	v_add_u32_e32 v26, s9, v50
	v_add_u32_e32 v24, s10, v51
	v_add_u32_e32 v30, s9, v52
	v_add_u32_e32 v28, s10, v53
	v_add_u32_e32 v34, s9, v54
	v_add_u32_e32 v32, s10, v55
	v_add_u32_e32 v38, s9, v56
	v_add_u32_e32 v36, s10, v57
	v_add_u32_e32 v42, s9, v58
	v_add_u32_e32 v40, s10, v59
	v_add_u32_e32 v46, s9, v60
	v_add_u32_e32 v44, s10, v61
	v_mad_i64_i32 v[18:19], s[16:17], v18, s5, v[8:9]
	v_mad_i64_i32 v[20:21], s[16:17], v20, s5, v[8:9]
	v_mad_i64_i32 v[22:23], s[16:17], v22, s5, v[8:9]
	v_mad_i64_i32 v[24:25], s[16:17], v24, s5, v[8:9]
	v_mad_i64_i32 v[26:27], s[16:17], v26, s5, v[8:9]
	v_mad_i64_i32 v[28:29], s[16:17], v28, s5, v[8:9]
	v_mad_i64_i32 v[30:31], s[16:17], v30, s5, v[8:9]
	v_mad_i64_i32 v[32:33], s[16:17], v32, s5, v[8:9]
	v_mad_i64_i32 v[34:35], s[16:17], v34, s5, v[8:9]
	v_mad_i64_i32 v[36:37], s[16:17], v36, s5, v[8:9]
	v_mad_i64_i32 v[38:39], s[16:17], v38, s5, v[8:9]
	v_mad_i64_i32 v[40:41], s[16:17], v40, s5, v[8:9]
	v_mad_i64_i32 v[42:43], s[16:17], v42, s5, v[8:9]
	v_mad_i64_i32 v[44:45], s[16:17], v44, s5, v[8:9]
	v_mad_i64_i32 v[46:47], s[16:17], v46, s5, v[8:9]
	global_load_dword v62, v[16:17], off
	global_load_dword v63, v[18:19], off
	global_load_dword v64, v[20:21], off
	global_load_dword v65, v[22:23], off
	global_load_dword v66, v[24:25], off
	global_load_dword v67, v[26:27], off
	global_load_dword v68, v[28:29], off
	global_load_dword v69, v[30:31], off
	global_load_dword v70, v[32:33], off
	global_load_dword v71, v[34:35], off
	global_load_dword v72, v[36:37], off
	global_load_dword v73, v[38:39], off
	global_load_dword v74, v[40:41], off
	global_load_dword v75, v[42:43], off
	global_load_dword v76, v[44:45], off
	global_load_dword v77, v[46:47], off
	s_add_i32 s14, s14, 16
	s_add_i32 s15, s15, 16
	s_add_i32 s11, s11, -16
	v_mad_u64_u32 v[16:17], s[16:17], v15, s3, v[4:5]
	s_cmp_lg_u32 s11, 0
	v_mad_u64_u32 v[18:19], s[16:17], v13, s3, v[4:5]
	v_mad_u64_u32 v[20:21], s[16:17], v49, s3, v[4:5]
	v_mad_u64_u32 v[22:23], s[16:17], v48, s3, v[4:5]
	v_mad_u64_u32 v[24:25], s[16:17], v51, s3, v[4:5]
	v_mad_u64_u32 v[26:27], s[16:17], v50, s3, v[4:5]
	v_mad_u64_u32 v[28:29], s[16:17], v53, s3, v[4:5]
	v_mad_u64_u32 v[30:31], s[16:17], v52, s3, v[4:5]
	v_mad_u64_u32 v[32:33], s[16:17], v55, s3, v[4:5]
	v_mad_u64_u32 v[34:35], s[16:17], v54, s3, v[4:5]
	v_mad_u64_u32 v[36:37], s[16:17], v57, s3, v[4:5]
	v_mad_u64_u32 v[38:39], s[16:17], v56, s3, v[4:5]
	v_mad_u64_u32 v[40:41], s[16:17], v59, s3, v[4:5]
	v_mad_u64_u32 v[42:43], s[16:17], v58, s3, v[4:5]
	v_mad_u64_u32 v[44:45], s[16:17], v61, s3, v[4:5]
	v_mad_u64_u32 v[46:47], s[16:17], v60, s3, v[4:5]
	s_lshl_b32 s16, s15, 1
	s_lshl_b32 s17, s14, 1
	v_or_b32_e32 v85, s16, v1
	v_or_b32_e32 v87, s17, v162
	s_add_i32 s18, s16, 4
	s_add_i32 s19, s17, 4
	s_add_i32 s20, s16, 8
	s_add_i32 s21, s17, 8
	s_add_i32 s22, s16, 12
	s_add_i32 s23, s17, 12
	s_add_i32 s24, s16, 16
	s_add_i32 s25, s17, 16
	s_add_i32 s26, s16, 20
	s_add_i32 s27, s17, 20
	s_add_i32 s28, s16, 24
	s_add_i32 s29, s17, 24
	s_add_i32 s16, s16, 28
	s_add_i32 s17, s17, 28
	v_add_u32_e32 v88, s10, v87
	v_or_b32_e32 v120, s18, v1
	v_or_b32_e32 v121, s19, v162
	v_or_b32_e32 v122, s20, v1
	v_or_b32_e32 v123, s21, v162
	v_or_b32_e32 v124, s22, v1
	v_or_b32_e32 v125, s23, v162
	v_or_b32_e32 v126, s24, v1
	v_or_b32_e32 v127, s25, v162
	v_or_b32_e32 v128, s26, v1
	v_or_b32_e32 v129, s27, v162
	v_or_b32_e32 v130, s28, v1
	v_or_b32_e32 v131, s29, v162
	v_or_b32_e32 v132, s16, v1
	v_or_b32_e32 v133, s17, v162
	v_add_u32_e32 v90, s9, v85
	v_mad_i64_i32 v[88:89], s[16:17], v88, s5, v[8:9]
	v_add_u32_e32 v94, s9, v120
	v_add_u32_e32 v92, s10, v121
	v_add_u32_e32 v98, s9, v122
	v_add_u32_e32 v96, s10, v123
	v_add_u32_e32 v102, s9, v124
	v_add_u32_e32 v100, s10, v125
	v_add_u32_e32 v106, s9, v126
	v_add_u32_e32 v104, s10, v127
	v_add_u32_e32 v110, s9, v128
	v_add_u32_e32 v108, s10, v129
	v_add_u32_e32 v114, s9, v130
	v_add_u32_e32 v112, s10, v131
	v_add_u32_e32 v118, s9, v132
	v_add_u32_e32 v116, s10, v133
	v_mad_i64_i32 v[90:91], s[16:17], v90, s5, v[8:9]
	v_mad_i64_i32 v[92:93], s[16:17], v92, s5, v[8:9]
	v_mad_i64_i32 v[94:95], s[16:17], v94, s5, v[8:9]
	v_mad_i64_i32 v[96:97], s[16:17], v96, s5, v[8:9]
	v_mad_i64_i32 v[98:99], s[16:17], v98, s5, v[8:9]
	v_mad_i64_i32 v[100:101], s[16:17], v100, s5, v[8:9]
	v_mad_i64_i32 v[102:103], s[16:17], v102, s5, v[8:9]
	v_mad_i64_i32 v[104:105], s[16:17], v104, s5, v[8:9]
	v_mad_i64_i32 v[106:107], s[16:17], v106, s5, v[8:9]
	v_mad_i64_i32 v[108:109], s[16:17], v108, s5, v[8:9]
	v_mad_i64_i32 v[110:111], s[16:17], v110, s5, v[8:9]
	v_mad_i64_i32 v[112:113], s[16:17], v112, s5, v[8:9]
; #define LAS __attribute__((address_space(3)))
; #define LDS_WAIT() asm volatile("s_waitcnt lgkmcnt(0)" ::: "memory")
;     ...
;         for (int i = 0; i < 32; ++i) { const int kk = 2 * i + (lane >> 5); scr[kk * 33 + (lane & 31)] = W[(size_t)(k0 + kk) * ldw + n0 + (lane & 31)]; }
;         LDS_WAIT(); asm volatile("" ::: "memory");
;         const int c = lane & 3;
; #pragma unroll
;         for (int j = 0; j < 2; ++j) { const int n = (lane >> 2) + 16 * j; const LAS float* sp = scr + (16 * c) * 33 + n;
;             u32x4 o;
;             if (QI8) { o.x = pk4_i8(sp[0 * 33], sp[1 * 33], sp[2 * 33], sp[3 * 33], scl); o.y = pk4_i8(sp[4 * 33], sp[5 * 33], sp[6 * 33], sp[7 * 33], scl);
;                 o.z = pk4_i8(sp[8 * 33], sp[9 * 33], sp[10 * 33], sp[11 * 33], scl); o.w = pk4_i8(sp[12 * 33], sp[13 * 33], sp[14 * 33], sp[15 * 33], scl); }
	v_mad_i64_i32 v[114:115], s[16:17], v114, s5, v[8:9]
	v_mad_i64_i32 v[116:117], s[16:17], v116, s5, v[8:9]
	v_mad_i64_i32 v[118:119], s[16:17], v118, s5, v[8:9]
	global_load_dword v134, v[88:89], off
	global_load_dword v135, v[90:91], off
	global_load_dword v136, v[92:93], off
	global_load_dword v137, v[94:95], off
	global_load_dword v138, v[96:97], off
	global_load_dword v139, v[98:99], off
	global_load_dword v140, v[100:101], off
	global_load_dword v141, v[102:103], off
	global_load_dword v142, v[104:105], off
	global_load_dword v143, v[106:107], off
	global_load_dword v144, v[108:109], off
	global_load_dword v145, v[110:111], off
	global_load_dword v146, v[112:113], off
	global_load_dword v147, v[114:115], off
	global_load_dword v148, v[116:117], off
	global_load_dword v149, v[118:119], off
	s_add_i32 s14, s14, 16
	s_add_i32 s15, s15, 16
	s_add_i32 s11, s11, -16
	v_mad_u64_u32 v[88:89], s[16:17], v87, s3, v[4:5]
	s_cmp_lg_u32 s11, 0
	v_mad_u64_u32 v[90:91], s[16:17], v85, s3, v[4:5]
	v_mad_u64_u32 v[92:93], s[16:17], v121, s3, v[4:5]
	v_mad_u64_u32 v[94:95], s[16:17], v120, s3, v[4:5]
	v_mad_u64_u32 v[96:97], s[16:17], v123, s3, v[4:5]
	v_mad_u64_u32 v[98:99], s[16:17], v122, s3, v[4:5]
	v_mad_u64_u32 v[100:101], s[16:17], v125, s3, v[4:5]
	v_mad_u64_u32 v[102:103], s[16:17], v124, s3, v[4:5]
	v_mad_u64_u32 v[104:105], s[16:17], v127, s3, v[4:5]
	v_mad_u64_u32 v[106:107], s[16:17], v126, s3, v[4:5]
	v_mad_u64_u32 v[108:109], s[16:17], v129, s3, v[4:5]
	v_mad_u64_u32 v[110:111], s[16:17], v128, s3, v[4:5]
	v_mad_u64_u32 v[112:113], s[16:17], v131, s3, v[4:5]
	v_mad_u64_u32 v[114:115], s[16:17], v130, s3, v[4:5]
	v_mad_u64_u32 v[116:117], s[16:17], v133, s3, v[4:5]
	v_mad_u64_u32 v[118:119], s[16:17], v132, s3, v[4:5]
	s_waitcnt vmcnt(31)
	ds_write_b32 v16, v62
	s_waitcnt vmcnt(30)
	ds_write_b32 v18, v63
	s_waitcnt vmcnt(29)
	ds_write_b32 v20, v64
	s_waitcnt vmcnt(28)
	ds_write_b32 v22, v65
	s_waitcnt vmcnt(27)
	ds_write_b32 v24, v66
	s_waitcnt vmcnt(26)
	ds_write_b32 v26, v67
	s_waitcnt vmcnt(25)
	ds_write_b32 v28, v68
	s_waitcnt vmcnt(24)
	ds_write_b32 v30, v69
	s_waitcnt vmcnt(23)
	ds_write_b32 v32, v70
	s_waitcnt vmcnt(22)
	ds_write_b32 v34, v71
	s_waitcnt vmcnt(21)
	ds_write_b32 v36, v72
	s_waitcnt vmcnt(20)
	ds_write_b32 v38, v73
	s_waitcnt vmcnt(19)
	ds_write_b32 v40, v74
	s_waitcnt vmcnt(18)
	ds_write_b32 v42, v75
	s_waitcnt vmcnt(17)
	ds_write_b32 v44, v76
	s_waitcnt vmcnt(16)
	ds_write_b32 v46, v77
	s_waitcnt vmcnt(15)
	ds_write_b32 v88, v134
	s_waitcnt vmcnt(14)
	ds_write_b32 v90, v135
	s_waitcnt vmcnt(13)
	ds_write_b32 v92, v136
	s_waitcnt vmcnt(12)
	ds_write_b32 v94, v137
	s_waitcnt vmcnt(11)
	ds_write_b32 v96, v138
	s_waitcnt vmcnt(10)
	ds_write_b32 v98, v139
	s_waitcnt vmcnt(9)
	ds_write_b32 v100, v140
	s_waitcnt vmcnt(8)
	ds_write_b32 v102, v141
	s_waitcnt vmcnt(7)
	ds_write_b32 v104, v142
	s_waitcnt vmcnt(6)
	ds_write_b32 v106, v143
	s_waitcnt vmcnt(5)
	ds_write_b32 v108, v144
	s_waitcnt vmcnt(4)
	ds_write_b32 v110, v145
	s_waitcnt vmcnt(3)
	ds_write_b32 v112, v146
	s_waitcnt vmcnt(2)
	ds_write_b32 v114, v147
	s_waitcnt vmcnt(1)
	ds_write_b32 v116, v148
	s_waitcnt vmcnt(0)
	ds_write_b32 v118, v149
	s_waitcnt lgkmcnt(0)
	ds_read2_b32 v[8:9], v5 offset1:16
	ds_read2_b32 v[22:23], v5 offset0:33 offset1:49
	ds_read2_b32 v[24:25], v5 offset0:66 offset1:82
	ds_read2_b32 v[26:27], v5 offset0:99 offset1:115
	ds_read2_b32 v[30:31], v5 offset0:132 offset1:148
	ds_read2_b32 v[34:35], v5 offset0:165 offset1:181
	ds_read2_b32 v[36:37], v5 offset0:198 offset1:214
	ds_read2_b32 v[38:39], v5 offset0:231 offset1:247
	s_ashr_i32 s11, s10, 31
	s_waitcnt lgkmcnt(7)
	v_mul_f32_e32 v8, 0x44fe0000, v8
	v_med3_f32 v16, v8, s12, v11
	s_waitcnt lgkmcnt(6)
	v_mul_f32_e32 v8, 0x44fe0000, v22
	v_med3_f32 v18, v8, s12, v11
	s_waitcnt lgkmcnt(5)
	v_mul_f32_e32 v8, 0x44fe0000, v24
	v_med3_f32 v28, v8, s12, v11
	s_waitcnt lgkmcnt(4)
	v_mul_f32_e32 v8, 0x44fe0000, v26
	v_med3_f32 v32, v8, s12, v11
	s_waitcnt lgkmcnt(3)
	v_mul_f32_e32 v8, 0x44fe0000, v30
	v_med3_f32 v17, v8, s12, v11
	s_waitcnt lgkmcnt(2)
	v_mul_f32_e32 v8, 0x44fe0000, v34
	v_med3_f32 v19, v8, s12, v11
	s_waitcnt lgkmcnt(1)
	v_mul_f32_e32 v8, 0x44fe0000, v36
	v_med3_f32 v29, v8, s12, v11
	s_waitcnt lgkmcnt(0)
	v_mul_f32_e32 v8, 0x44fe0000, v38
	v_pk_add_f32 v[18:19], v[18:19], s[4:5] op_sel_hi:[1,0]
	v_pk_add_f32 v[28:29], v[28:29], s[4:5] op_sel_hi:[1,0]
	v_med3_f32 v33, v8, s12, v11
	v_lshlrev_b32_e32 v13, 8, v18
	v_lshlrev_b32_e32 v15, 16, v29
	v_lshlrev_b32_e32 v18, 16, v28
	ds_read2_b32 v[28:29], v12 offset0:8 offset1:24
	v_pk_add_f32 v[32:33], v[32:33], s[4:5] op_sel_hi:[1,0]
	v_pk_add_f32 v[16:17], v[16:17], s[4:5] op_sel_hi:[1,0]
	v_lshlrev_b32_e32 v8, 8, v19
	v_lshlrev_b32_e32 v19, 24, v33
	v_and_b32_e32 v8, 0xff00, v8
	v_lshlrev_b32_e32 v22, 24, v32
	v_or_b32_sdwa v17, v19, v17 dst_sel:DWORD dst_unused:UNUSED_PAD src0_sel:DWORD src1_sel:BYTE_0
	ds_read2_b32 v[32:33], v12 offset0:41 offset1:57
	ds_read2_b32 v[40:41], v12 offset0:74 offset1:90
	ds_read2_b32 v[42:43], v12 offset0:107 offset1:123
	v_and_b32_e32 v13, 0xff00, v13
	v_and_b32_e32 v15, 0xff0000, v15
	v_or_b32_sdwa v16, v22, v16 dst_sel:DWORD dst_unused:UNUSED_PAD src0_sel:DWORD src1_sel:BYTE_0
	v_or_b32_e32 v8, v17, v8
	ds_read2_b32 v[48:49], v12 offset0:140 offset1:156
	v_and_b32_e32 v18, 0xff0000, v18
	v_or_b32_e32 v13, v16, v13
	v_or_b32_e32 v17, v8, v15
	s_waitcnt lgkmcnt(4)
; #define LAS __attribute__((address_space(3)))
; __device__ __forceinline__ unsigned pk4_f8(float a, float b, float c, float d) { int w = __builtin_amdgcn_cvt_pk_fp8_f32(a, b, 0, false); w = __builtin_amdgcn_cvt_pk_fp8_f32(c, d, w, true); return (unsigned)w; }
; #define LDS_WAIT() asm volatile("s_waitcnt lgkmcnt(0)" ::: "memory")
;     ...
;         for (int j = 0; j < 2; ++j) { const int n = (lane >> 2) + 16 * j; const LAS float* sp = scr + (16 * c) * 33 + n;
;             u32x4 o;
;             if (QI8) { o.x = pk4_i8(sp[0 * 33], sp[1 * 33], sp[2 * 33], sp[3 * 33], scl); o.y = pk4_i8(sp[4 * 33], sp[5 * 33], sp[6 * 33], sp[7 * 33], scl);
;                 o.z = pk4_i8(sp[8 * 33], sp[9 * 33], sp[10 * 33], sp[11 * 33], scl); o.w = pk4_i8(sp[12 * 33], sp[13 * 33], sp[14 * 33], sp[15 * 33], scl); }
;             else {
;             o.x = pk4_f8(sp[0 * 33] * scl, sp[1 * 33] * scl, sp[2 * 33] * scl, sp[3 * 33] * scl); o.y = pk4_f8(sp[4 * 33] * scl, sp[5 * 33] * scl, sp[6 * 33] * scl, sp[7 * 33] * scl);
;             o.z = pk4_f8(sp[8 * 33] * scl, sp[9 * 33] * scl, sp[10 * 33] * scl, sp[11 * 33] * scl); o.w = pk4_f8(sp[12 * 33] * scl, sp[13 * 33] * scl, sp[14 * 33] * scl, sp[15 * 33] * scl); }
;             *(u32x4*)(WT + (size_t)(dr0 + n) * K + k0 + 16 * c) = o; }
;         LDS_WAIT(); asm volatile("" ::: "memory"); }
	v_mul_f32_e32 v8, 0x44fe0000, v28
	v_or_b32_e32 v16, v13, v18
	v_med3_f32 v18, v8, s12, v11
	s_waitcnt lgkmcnt(3)
	v_mul_f32_e32 v8, 0x44fe0000, v32
	v_med3_f32 v44, v8, s12, v11
	s_waitcnt lgkmcnt(2)
	v_mul_f32_e32 v8, 0x44fe0000, v40
	ds_read2_b32 v[52:53], v12 offset0:173 offset1:189
	ds_read2_b32 v[54:55], v12 offset0:206 offset1:222
	ds_read2_b32 v[56:57], v12 offset0:239 offset1:255
	v_med3_f32 v46, v8, s12, v11
	s_waitcnt lgkmcnt(4)
	v_mul_f32_e32 v8, 0x44fe0000, v42
	v_med3_f32 v50, v8, s12, v11
	s_waitcnt lgkmcnt(3)
	v_mul_f32_e32 v8, 0x44fe0000, v48
	v_med3_f32 v19, v8, s12, v11
	s_waitcnt lgkmcnt(2)
	v_mul_f32_e32 v8, 0x44fe0000, v52
	v_med3_f32 v45, v8, s12, v11
	s_waitcnt lgkmcnt(1)
	v_mul_f32_e32 v8, 0x44fe0000, v54
	v_med3_f32 v47, v8, s12, v11
	s_waitcnt lgkmcnt(0)
	v_mul_f32_e32 v8, 0x44fe0000, v56
	v_med3_f32 v51, v8, s12, v11
	v_pk_add_f32 v[44:45], v[44:45], s[4:5] op_sel_hi:[1,0]
	v_pk_add_f32 v[50:51], v[50:51], s[4:5] op_sel_hi:[1,0]
	v_pk_add_f32 v[18:19], v[18:19], s[4:5] op_sel_hi:[1,0]
	v_pk_add_f32 v[46:47], v[46:47], s[4:5] op_sel_hi:[1,0]
	v_lshlrev_b32_e32 v8, 8, v45
	v_lshlrev_b32_e32 v13, 8, v44
	v_lshlrev_b32_e32 v24, 24, v51
	v_lshlrev_b32_e32 v26, 24, v50
	v_or_b32_e32 v44, s8, v163
	v_and_b32_e32 v8, 0xff00, v8
	v_and_b32_e32 v13, 0xff00, v13
	v_lshlrev_b32_e32 v15, 16, v47
	v_lshlrev_b32_e32 v22, 16, v46
	v_or_b32_sdwa v19, v24, v19 dst_sel:DWORD dst_unused:UNUSED_PAD src0_sel:DWORD src1_sel:BYTE_0
	v_or_b32_sdwa v18, v26, v18 dst_sel:DWORD dst_unused:UNUSED_PAD src0_sel:DWORD src1_sel:BYTE_0
	v_ashrrev_i32_e32 v45, 31, v44
	v_lshl_add_u64 v[20:21], v[6:7], 0, s[10:11]
	v_and_b32_e32 v15, 0xff0000, v15
	v_and_b32_e32 v22, 0xff0000, v22
	v_or_b32_e32 v8, v19, v8
	v_or_b32_e32 v13, v18, v13
	v_lshlrev_b64 v[44:45], 12, v[44:45]
	v_or_b32_e32 v19, v8, v15
	v_or_b32_e32 v18, v13, v22
	v_lshl_add_u64 v[44:45], v[20:21], 0, v[44:45]
	v_mul_f32_e32 v8, 0x44fe0000, v9
	v_mul_f32_e32 v9, 0x44fe0000, v23
	v_mul_f32_e32 v13, 0x44fe0000, v35
	global_store_dwordx4 v[44:45], v[16:19], off
	v_med3_f32 v8, v8, s12, v11
	s_add_i32 s13, s13, s92
	v_med3_f32 v16, v9, s12, v11
	v_mul_f32_e32 v9, 0x44fe0000, v25
	v_med3_f32 v17, v13, s12, v11
	v_mul_f32_e32 v13, 0x44fe0000, v37
	v_med3_f32 v18, v9, s12, v11
	v_mul_f32_e32 v9, 0x44fe0000, v27
	v_med3_f32 v19, v13, s12, v11
	v_mul_f32_e32 v13, 0x44fe0000, v39
	v_med3_f32 v22, v9, s12, v11
	v_mul_f32_e32 v9, 0x44fe0000, v31
	v_med3_f32 v23, v13, s12, v11
	v_pk_add_f32 v[16:17], v[16:17], s[4:5] op_sel_hi:[1,0]
	v_pk_add_f32 v[18:19], v[18:19], s[4:5] op_sel_hi:[1,0]
	v_med3_f32 v9, v9, s12, v11
	v_pk_add_f32 v[22:23], v[22:23], s[4:5] op_sel_hi:[1,0]
	v_lshlrev_b32_e32 v13, 8, v17
	v_lshlrev_b32_e32 v17, 16, v18
	v_pk_add_f32 v[8:9], v[8:9], s[4:5] op_sel_hi:[1,0]
	v_and_b32_e32 v18, 0xff0000, v17
	v_lshlrev_b32_e32 v17, 24, v23
	v_lshlrev_b32_e32 v15, 8, v16
	v_and_b32_e32 v13, 0xff00, v13
	v_lshlrev_b32_e32 v16, 16, v19
	v_lshlrev_b32_e32 v19, 24, v22
	v_or_b32_sdwa v9, v17, v9 dst_sel:DWORD dst_unused:UNUSED_PAD src0_sel:DWORD src1_sel:BYTE_0
	v_and_b32_e32 v15, 0xff00, v15
	v_and_b32_e32 v16, 0xff0000, v16
	v_or_b32_sdwa v8, v19, v8 dst_sel:DWORD dst_unused:UNUSED_PAD src0_sel:DWORD src1_sel:BYTE_0
	v_or_b32_e32 v9, v9, v13
	v_or_b32_e32 v8, v8, v15
	v_or_b32_e32 v17, v9, v16
	v_mul_f32_e32 v9, 0x44fe0000, v33
	v_mul_f32_e32 v13, 0x44fe0000, v53
	v_or_b32_e32 v16, v8, v18
	v_med3_f32 v18, v9, s12, v11
	v_mul_f32_e32 v9, 0x44fe0000, v41
	v_med3_f32 v19, v13, s12, v11
	v_mul_f32_e32 v13, 0x44fe0000, v55
	v_med3_f32 v22, v9, s12, v11
	v_mul_f32_e32 v9, 0x44fe0000, v43
	v_med3_f32 v23, v13, s12, v11
	v_mul_f32_e32 v13, 0x44fe0000, v57
	v_mul_f32_e32 v8, 0x44fe0000, v29
	v_med3_f32 v24, v9, s12, v11
	v_mul_f32_e32 v9, 0x44fe0000, v49
	v_med3_f32 v25, v13, s12, v11
	v_pk_add_f32 v[18:19], v[18:19], s[4:5] op_sel_hi:[1,0]
	v_pk_add_f32 v[22:23], v[22:23], s[4:5] op_sel_hi:[1,0]
	v_med3_f32 v8, v8, s12, v11
	v_med3_f32 v9, v9, s12, v11
	v_pk_add_f32 v[24:25], v[24:25], s[4:5] op_sel_hi:[1,0]
	v_lshlrev_b32_e32 v13, 8, v19
	v_lshlrev_b32_e32 v19, 16, v22
	v_pk_add_f32 v[8:9], v[8:9], s[4:5] op_sel_hi:[1,0]
	v_lshlrev_b32_e32 v15, 8, v18
	v_lshlrev_b32_e32 v18, 16, v23
	v_and_b32_e32 v22, 0xff0000, v19
	v_lshlrev_b32_e32 v19, 24, v25
	v_lshlrev_b32_e32 v23, 24, v24
	v_and_b32_e32 v13, 0xff00, v13
	v_and_b32_e32 v15, 0xff00, v15
	v_or_b32_sdwa v9, v19, v9 dst_sel:DWORD dst_unused:UNUSED_PAD src0_sel:DWORD src1_sel:BYTE_0
	v_or_b32_sdwa v8, v23, v8 dst_sel:DWORD dst_unused:UNUSED_PAD src0_sel:DWORD src1_sel:BYTE_0
	v_and_b32_e32 v18, 0xff0000, v18
	v_or_b32_e32 v9, v9, v13
	v_or_b32_e32 v8, v8, v15
	v_or_b32_e32 v19, v9, v18
	v_or_b32_e32 v18, v8, v22
	v_or_b32_e32 v8, s8, v10
	v_ashrrev_i32_e32 v9, 31, v8
	v_lshlrev_b64 v[8:9], 12, v[8:9]
	v_lshl_add_u64 v[8:9], v[20:21], 0, v[8:9]
	global_store_dwordx4 v[8:9], v[16:19], off
	s_waitcnt lgkmcnt(0)
	s_cmpk_lt_i32 s13, 0x4000
	s_cbranch_scc1 .LBB0_39

;     ...
;         int dr0 = n0; if (MAP == 1) { if (n0 < DFF) dr0 = (n0 >> 7) * 256 + (n0 & 127); else { const int uo = n0 - DFF; dr0 = (uo >> 7) * 256 + 128 + (uo & 127); } }
; #pragma unroll 8
;         for (int i = 0; i < 32; ++i) { const int kk = 2 * i + (lane >> 5); scr[kk * 33 + (lane & 31)] = W[(size_t)(k0 + kk) * ldw + n0 + (lane & 31)]; }
.LBB0_45:
	s_lshl_b32 s18, s17, 1
	s_lshl_b32 s19, s16, 1
	v_or_b32_e32 v48, s18, v1
	v_or_b32_e32 v49, s19, v162
	s_add_i32 s20, s18, 4
	s_add_i32 s21, s19, 4
	s_add_i32 s22, s18, 8
	s_add_i32 s23, s19, 8
	s_add_i32 s24, s18, 12
	s_add_i32 s25, s19, 12
	s_add_i32 s26, s18, 16
	s_add_i32 s27, s19, 16
	s_add_i32 s28, s18, 20
	s_add_i32 s29, s19, 20
	s_add_i32 s30, s18, 24
	s_add_i32 s31, s19, 24
	s_add_i32 s18, s18, 28
	s_add_i32 s19, s19, 28
	v_add_u32_e32 v16, s12, v49
	v_or_b32_e32 v50, s20, v1
	v_or_b32_e32 v51, s21, v162
	v_or_b32_e32 v52, s22, v1
	v_or_b32_e32 v53, s23, v162
	v_or_b32_e32 v54, s24, v1
	v_or_b32_e32 v55, s25, v162
	v_or_b32_e32 v56, s26, v1
	v_or_b32_e32 v57, s27, v162
	v_or_b32_e32 v58, s28, v1
	v_or_b32_e32 v59, s29, v162
	v_or_b32_e32 v60, s30, v1
	v_or_b32_e32 v61, s31, v162
	v_or_b32_e32 v62, s18, v1
	v_or_b32_e32 v63, s19, v162
	v_add_u32_e32 v18, s11, v48
	v_mad_i64_i32 v[16:17], s[18:19], v16, s9, v[10:11]
	v_add_u32_e32 v22, s11, v50
	v_add_u32_e32 v20, s12, v51
	v_add_u32_e32 v26, s11, v52
	v_add_u32_e32 v24, s12, v53
	v_add_u32_e32 v30, s11, v54
	v_add_u32_e32 v28, s12, v55
	v_add_u32_e32 v34, s11, v56
	v_add_u32_e32 v32, s12, v57
	v_add_u32_e32 v38, s11, v58
	v_add_u32_e32 v36, s12, v59
	v_add_u32_e32 v42, s11, v60
	v_add_u32_e32 v40, s12, v61
	v_add_u32_e32 v46, s11, v62
	v_add_u32_e32 v44, s12, v63
	v_mad_i64_i32 v[18:19], s[18:19], v18, s9, v[10:11]
	v_mad_i64_i32 v[20:21], s[18:19], v20, s9, v[10:11]
	v_mad_i64_i32 v[22:23], s[18:19], v22, s9, v[10:11]
	v_mad_i64_i32 v[24:25], s[18:19], v24, s9, v[10:11]
	v_mad_i64_i32 v[26:27], s[18:19], v26, s9, v[10:11]
	v_mad_i64_i32 v[28:29], s[18:19], v28, s9, v[10:11]
	v_mad_i64_i32 v[30:31], s[18:19], v30, s9, v[10:11]
	v_mad_i64_i32 v[32:33], s[18:19], v32, s9, v[10:11]
	v_mad_i64_i32 v[34:35], s[18:19], v34, s9, v[10:11]
	v_mad_i64_i32 v[36:37], s[18:19], v36, s9, v[10:11]
	v_mad_i64_i32 v[38:39], s[18:19], v38, s9, v[10:11]
	v_mad_i64_i32 v[40:41], s[18:19], v40, s9, v[10:11]
	v_mad_i64_i32 v[42:43], s[18:19], v42, s9, v[10:11]
	v_mad_i64_i32 v[44:45], s[18:19], v44, s9, v[10:11]
	v_mad_i64_i32 v[46:47], s[18:19], v46, s9, v[10:11]
	global_load_dword v64, v[16:17], off
	global_load_dword v65, v[18:19], off
	global_load_dword v66, v[20:21], off
	global_load_dword v67, v[22:23], off
	global_load_dword v68, v[24:25], off
	global_load_dword v69, v[26:27], off
	global_load_dword v70, v[28:29], off
	global_load_dword v71, v[30:31], off
	global_load_dword v72, v[32:33], off
	global_load_dword v73, v[34:35], off
	global_load_dword v74, v[36:37], off
	global_load_dword v75, v[38:39], off
	global_load_dword v76, v[40:41], off
	global_load_dword v77, v[42:43], off
	global_load_dword v78, v[44:45], off
	global_load_dword v79, v[46:47], off
	s_add_i32 s16, s16, 16
	s_add_i32 s17, s17, 16
	s_add_i32 s13, s13, -16
	v_mad_u64_u32 v[16:17], s[18:19], v49, s3, v[2:3]
	s_cmp_lg_u32 s13, 0
	v_mad_u64_u32 v[18:19], s[18:19], v48, s3, v[2:3]
	v_mad_u64_u32 v[20:21], s[18:19], v51, s3, v[2:3]
	v_mad_u64_u32 v[22:23], s[18:19], v50, s3, v[2:3]
	v_mad_u64_u32 v[24:25], s[18:19], v53, s3, v[2:3]
	v_mad_u64_u32 v[26:27], s[18:19], v52, s3, v[2:3]
	v_mad_u64_u32 v[28:29], s[18:19], v55, s3, v[2:3]
	v_mad_u64_u32 v[30:31], s[18:19], v54, s3, v[2:3]
	v_mad_u64_u32 v[32:33], s[18:19], v57, s3, v[2:3]
	v_mad_u64_u32 v[34:35], s[18:19], v56, s3, v[2:3]
	v_mad_u64_u32 v[36:37], s[18:19], v59, s3, v[2:3]
	v_mad_u64_u32 v[38:39], s[18:19], v58, s3, v[2:3]
	v_mad_u64_u32 v[40:41], s[18:19], v61, s3, v[2:3]
	v_mad_u64_u32 v[42:43], s[18:19], v60, s3, v[2:3]
	v_mad_u64_u32 v[44:45], s[18:19], v63, s3, v[2:3]
	v_mad_u64_u32 v[46:47], s[18:19], v62, s3, v[2:3]
	s_lshl_b32 s18, s17, 1
	s_lshl_b32 s19, s16, 1
	v_or_b32_e32 v116, s18, v1
	v_or_b32_e32 v117, s19, v162
	s_add_i32 s20, s18, 4
	s_add_i32 s21, s19, 4
	s_add_i32 s22, s18, 8
	s_add_i32 s23, s19, 8
	s_add_i32 s24, s18, 12
	s_add_i32 s25, s19, 12
	s_add_i32 s26, s18, 16
	s_add_i32 s27, s19, 16
	s_add_i32 s28, s18, 20
	s_add_i32 s29, s19, 20
	s_add_i32 s30, s18, 24
	s_add_i32 s31, s19, 24
	s_add_i32 s18, s18, 28
	s_add_i32 s19, s19, 28
	v_add_u32_e32 v84, s12, v117
	v_or_b32_e32 v118, s20, v1
	v_or_b32_e32 v119, s21, v162
	v_or_b32_e32 v120, s22, v1
	v_or_b32_e32 v121, s23, v162
	v_or_b32_e32 v122, s24, v1
	v_or_b32_e32 v123, s25, v162
	v_or_b32_e32 v124, s26, v1
	v_or_b32_e32 v125, s27, v162
	v_or_b32_e32 v126, s28, v1
	v_or_b32_e32 v127, s29, v162
	v_or_b32_e32 v128, s30, v1
	v_or_b32_e32 v129, s31, v162
	v_or_b32_e32 v130, s18, v1
	v_or_b32_e32 v131, s19, v162
	v_add_u32_e32 v86, s11, v116
	v_mad_i64_i32 v[84:85], s[18:19], v84, s9, v[10:11]
	v_add_u32_e32 v90, s11, v118
	v_add_u32_e32 v88, s12, v119
	v_add_u32_e32 v94, s11, v120
	v_add_u32_e32 v92, s12, v121
	v_add_u32_e32 v98, s11, v122
	v_add_u32_e32 v96, s12, v123
	v_add_u32_e32 v102, s11, v124
	v_add_u32_e32 v100, s12, v125
	v_add_u32_e32 v106, s11, v126
	v_add_u32_e32 v104, s12, v127
	v_add_u32_e32 v110, s11, v128
	v_add_u32_e32 v108, s12, v129
	v_add_u32_e32 v114, s11, v130
	v_add_u32_e32 v112, s12, v131
	v_mad_i64_i32 v[86:87], s[18:19], v86, s9, v[10:11]
	v_mad_i64_i32 v[88:89], s[18:19], v88, s9, v[10:11]
	v_mad_i64_i32 v[90:91], s[18:19], v90, s9, v[10:11]
	v_mad_i64_i32 v[92:93], s[18:19], v92, s9, v[10:11]
	v_mad_i64_i32 v[94:95], s[18:19], v94, s9, v[10:11]
	v_mad_i64_i32 v[96:97], s[18:19], v96, s9, v[10:11]
	v_mad_i64_i32 v[98:99], s[18:19], v98, s9, v[10:11]
	v_mad_i64_i32 v[100:101], s[18:19], v100, s9, v[10:11]
	v_mad_i64_i32 v[102:103], s[18:19], v102, s9, v[10:11]
	v_mad_i64_i32 v[104:105], s[18:19], v104, s9, v[10:11]
	v_mad_i64_i32 v[106:107], s[18:19], v106, s9, v[10:11]
; #define LAS __attribute__((address_space(3)))
; #define LDS_WAIT() asm volatile("s_waitcnt lgkmcnt(0)" ::: "memory")
;     ...
;         for (int i = 0; i < 32; ++i) { const int kk = 2 * i + (lane >> 5); scr[kk * 33 + (lane & 31)] = W[(size_t)(k0 + kk) * ldw + n0 + (lane & 31)]; }
;         LDS_WAIT(); asm volatile("" ::: "memory");
;         const int c = lane & 3;
; #pragma unroll
;         for (int j = 0; j < 2; ++j) { const int n = (lane >> 2) + 16 * j; const LAS float* sp = scr + (16 * c) * 33 + n;
;             u32x4 o;
;             if (QI8) { o.x = pk4_i8(sp[0 * 33], sp[1 * 33], sp[2 * 33], sp[3 * 33], scl); o.y = pk4_i8(sp[4 * 33], sp[5 * 33], sp[6 * 33], sp[7 * 33], scl);
;                 o.z = pk4_i8(sp[8 * 33], sp[9 * 33], sp[10 * 33], sp[11 * 33], scl); o.w = pk4_i8(sp[12 * 33], sp[13 * 33], sp[14 * 33], sp[15 * 33], scl); }
	v_mad_i64_i32 v[108:109], s[18:19], v108, s9, v[10:11]
	v_mad_i64_i32 v[110:111], s[18:19], v110, s9, v[10:11]
	v_mad_i64_i32 v[112:113], s[18:19], v112, s9, v[10:11]
	v_mad_i64_i32 v[114:115], s[18:19], v114, s9, v[10:11]
	global_load_dword v132, v[84:85], off
	global_load_dword v133, v[86:87], off
	global_load_dword v134, v[88:89], off
	global_load_dword v135, v[90:91], off
	global_load_dword v136, v[92:93], off
	global_load_dword v137, v[94:95], off
	global_load_dword v138, v[96:97], off
	global_load_dword v139, v[98:99], off
	global_load_dword v140, v[100:101], off
	global_load_dword v141, v[102:103], off
	global_load_dword v142, v[104:105], off
	global_load_dword v143, v[106:107], off
	global_load_dword v144, v[108:109], off
	global_load_dword v145, v[110:111], off
	global_load_dword v146, v[112:113], off
	global_load_dword v147, v[114:115], off
	s_add_i32 s16, s16, 16
	s_add_i32 s17, s17, 16
	s_add_i32 s13, s13, -16
	v_mad_u64_u32 v[84:85], s[18:19], v117, s3, v[2:3]
	s_cmp_lg_u32 s13, 0
	v_mad_u64_u32 v[86:87], s[18:19], v116, s3, v[2:3]
	v_mad_u64_u32 v[88:89], s[18:19], v119, s3, v[2:3]
	v_mad_u64_u32 v[90:91], s[18:19], v118, s3, v[2:3]
	v_mad_u64_u32 v[92:93], s[18:19], v121, s3, v[2:3]
	v_mad_u64_u32 v[94:95], s[18:19], v120, s3, v[2:3]
	v_mad_u64_u32 v[96:97], s[18:19], v123, s3, v[2:3]
	v_mad_u64_u32 v[98:99], s[18:19], v122, s3, v[2:3]
	v_mad_u64_u32 v[100:101], s[18:19], v125, s3, v[2:3]
	v_mad_u64_u32 v[102:103], s[18:19], v124, s3, v[2:3]
	v_mad_u64_u32 v[104:105], s[18:19], v127, s3, v[2:3]
	v_mad_u64_u32 v[106:107], s[18:19], v126, s3, v[2:3]
	v_mad_u64_u32 v[108:109], s[18:19], v129, s3, v[2:3]
	v_mad_u64_u32 v[110:111], s[18:19], v128, s3, v[2:3]
	v_mad_u64_u32 v[112:113], s[18:19], v131, s3, v[2:3]
	v_mad_u64_u32 v[114:115], s[18:19], v130, s3, v[2:3]
	s_waitcnt vmcnt(31)
	ds_write_b32 v16, v64
	s_waitcnt vmcnt(30)
	ds_write_b32 v18, v65
	s_waitcnt vmcnt(29)
	ds_write_b32 v20, v66
	s_waitcnt vmcnt(28)
	ds_write_b32 v22, v67
	s_waitcnt vmcnt(27)
	ds_write_b32 v24, v68
	s_waitcnt vmcnt(26)
	ds_write_b32 v26, v69
	s_waitcnt vmcnt(25)
	ds_write_b32 v28, v70
	s_waitcnt vmcnt(24)
	ds_write_b32 v30, v71
	s_waitcnt vmcnt(23)
	ds_write_b32 v32, v72
	s_waitcnt vmcnt(22)
	ds_write_b32 v34, v73
	s_waitcnt vmcnt(21)
	ds_write_b32 v36, v74
	s_waitcnt vmcnt(20)
	ds_write_b32 v38, v75
	s_waitcnt vmcnt(19)
	ds_write_b32 v40, v76
	s_waitcnt vmcnt(18)
	ds_write_b32 v42, v77
	s_waitcnt vmcnt(17)
	ds_write_b32 v44, v78
	s_waitcnt vmcnt(16)
	ds_write_b32 v46, v79
	s_waitcnt vmcnt(15)
	ds_write_b32 v84, v132
	s_waitcnt vmcnt(14)
	ds_write_b32 v86, v133
	s_waitcnt vmcnt(13)
	ds_write_b32 v88, v134
	s_waitcnt vmcnt(12)
	ds_write_b32 v90, v135
	s_waitcnt vmcnt(11)
	ds_write_b32 v92, v136
	s_waitcnt vmcnt(10)
	ds_write_b32 v94, v137
	s_waitcnt vmcnt(9)
	ds_write_b32 v96, v138
	s_waitcnt vmcnt(8)
	ds_write_b32 v98, v139
	s_waitcnt vmcnt(7)
	ds_write_b32 v100, v140
	s_waitcnt vmcnt(6)
	ds_write_b32 v102, v141
	s_waitcnt vmcnt(5)
	ds_write_b32 v104, v142
	s_waitcnt vmcnt(4)
	ds_write_b32 v106, v143
	s_waitcnt vmcnt(3)
	ds_write_b32 v108, v144
	s_waitcnt vmcnt(2)
	ds_write_b32 v110, v145
	s_waitcnt vmcnt(1)
	ds_write_b32 v112, v146
	s_waitcnt vmcnt(0)
	ds_write_b32 v114, v147
	s_waitcnt lgkmcnt(0)
	ds_read2_b32 v[10:11], v3 offset1:16
	ds_read2_b32 v[22:23], v3 offset0:33 offset1:49
	ds_read2_b32 v[24:25], v3 offset0:66 offset1:82
	ds_read2_b32 v[26:27], v3 offset0:99 offset1:115
	ds_read2_b32 v[30:31], v3 offset0:132 offset1:148
	ds_read2_b32 v[34:35], v3 offset0:165 offset1:181
	ds_read2_b32 v[36:37], v3 offset0:198 offset1:214
	ds_read2_b32 v[38:39], v3 offset0:231 offset1:247
	s_ashr_i32 s13, s12, 31
	s_waitcnt lgkmcnt(7)
	v_mul_f32_e32 v10, 0x44fe0000, v10
	v_med3_f32 v16, v10, s14, v12
	s_waitcnt lgkmcnt(6)
	v_mul_f32_e32 v10, 0x44fe0000, v22
	v_med3_f32 v18, v10, s14, v12
	s_waitcnt lgkmcnt(5)
	v_mul_f32_e32 v10, 0x44fe0000, v24
	v_med3_f32 v28, v10, s14, v12
	s_waitcnt lgkmcnt(4)
	v_mul_f32_e32 v10, 0x44fe0000, v26
	v_med3_f32 v32, v10, s14, v12
	s_waitcnt lgkmcnt(3)
	v_mul_f32_e32 v10, 0x44fe0000, v30
	v_med3_f32 v17, v10, s14, v12
	s_waitcnt lgkmcnt(2)
	v_mul_f32_e32 v10, 0x44fe0000, v34
	v_med3_f32 v19, v10, s14, v12
	s_waitcnt lgkmcnt(1)
	v_mul_f32_e32 v10, 0x44fe0000, v36
	v_med3_f32 v29, v10, s14, v12
	s_waitcnt lgkmcnt(0)
	v_mul_f32_e32 v10, 0x44fe0000, v38
	v_pk_add_f32 v[18:19], v[18:19], s[8:9] op_sel_hi:[1,0]
	v_pk_add_f32 v[28:29], v[28:29], s[8:9] op_sel_hi:[1,0]
	v_med3_f32 v33, v10, s14, v12
	v_lshlrev_b32_e32 v10, 8, v19
	v_lshlrev_b32_e32 v19, 16, v29
	v_lshlrev_b32_e32 v22, 16, v28
	ds_read2_b32 v[28:29], v13 offset0:8 offset1:24
	v_pk_add_f32 v[32:33], v[32:33], s[8:9] op_sel_hi:[1,0]
	v_pk_add_f32 v[16:17], v[16:17], s[8:9] op_sel_hi:[1,0]
	v_lshlrev_b32_e32 v24, 24, v33
	v_and_b32_e32 v10, 0xff00, v10
	v_lshlrev_b32_e32 v26, 24, v32
	v_or_b32_sdwa v17, v24, v17 dst_sel:DWORD dst_unused:UNUSED_PAD src0_sel:DWORD src1_sel:BYTE_0
	ds_read2_b32 v[32:33], v13 offset0:41 offset1:57
	ds_read2_b32 v[40:41], v13 offset0:74 offset1:90
	ds_read2_b32 v[42:43], v13 offset0:107 offset1:123
	v_lshlrev_b32_e32 v18, 8, v18
	v_and_b32_e32 v19, 0xff0000, v19
	v_or_b32_e32 v10, v17, v10
	ds_read2_b32 v[48:49], v13 offset0:140 offset1:156
	v_and_b32_e32 v18, 0xff00, v18
	v_or_b32_sdwa v16, v26, v16 dst_sel:DWORD dst_unused:UNUSED_PAD src0_sel:DWORD src1_sel:BYTE_0
	v_or_b32_e32 v17, v10, v19
	s_waitcnt lgkmcnt(4)
; #define LAS __attribute__((address_space(3)))
; __device__ __forceinline__ unsigned pk4_f8(float a, float b, float c, float d) { int w = __builtin_amdgcn_cvt_pk_fp8_f32(a, b, 0, false); w = __builtin_amdgcn_cvt_pk_fp8_f32(c, d, w, true); return (unsigned)w; }
; #define LDS_WAIT() asm volatile("s_waitcnt lgkmcnt(0)" ::: "memory")
;     ...
;         for (int j = 0; j < 2; ++j) { const int n = (lane >> 2) + 16 * j; const LAS float* sp = scr + (16 * c) * 33 + n;
;             u32x4 o;
;             if (QI8) { o.x = pk4_i8(sp[0 * 33], sp[1 * 33], sp[2 * 33], sp[3 * 33], scl); o.y = pk4_i8(sp[4 * 33], sp[5 * 33], sp[6 * 33], sp[7 * 33], scl);
;                 o.z = pk4_i8(sp[8 * 33], sp[9 * 33], sp[10 * 33], sp[11 * 33], scl); o.w = pk4_i8(sp[12 * 33], sp[13 * 33], sp[14 * 33], sp[15 * 33], scl); }
;             else {
;             o.x = pk4_f8(sp[0 * 33] * scl, sp[1 * 33] * scl, sp[2 * 33] * scl, sp[3 * 33] * scl); o.y = pk4_f8(sp[4 * 33] * scl, sp[5 * 33] * scl, sp[6 * 33] * scl, sp[7 * 33] * scl);
;             o.z = pk4_f8(sp[8 * 33] * scl, sp[9 * 33] * scl, sp[10 * 33] * scl, sp[11 * 33] * scl); o.w = pk4_f8(sp[12 * 33] * scl, sp[13 * 33] * scl, sp[14 * 33] * scl, sp[15 * 33] * scl); }
;             *(u32x4*)(WT + (size_t)(dr0 + n) * K + k0 + 16 * c) = o; }
;         LDS_WAIT(); asm volatile("" ::: "memory"); }
; __device__ __forceinline__ void p0_prologue(Frame& F) {
;     ...
;       transpose_f8_matrix<0, true>(F, W + 6144, D, 2048, w8 + (size_t)10240 * D, I8_W, ldw);
	v_mul_f32_e32 v10, 0x44fe0000, v28
	v_or_b32_e32 v16, v16, v18
	v_med3_f32 v18, v10, s14, v12
	s_waitcnt lgkmcnt(3)
	v_mul_f32_e32 v10, 0x44fe0000, v32
	v_med3_f32 v44, v10, s14, v12
	s_waitcnt lgkmcnt(2)
	v_mul_f32_e32 v10, 0x44fe0000, v40
	ds_read2_b32 v[52:53], v13 offset0:173 offset1:189
	ds_read2_b32 v[54:55], v13 offset0:206 offset1:222
	ds_read2_b32 v[56:57], v13 offset0:239 offset1:255
	v_med3_f32 v46, v10, s14, v12
	s_waitcnt lgkmcnt(4)
	v_mul_f32_e32 v10, 0x44fe0000, v42
	v_med3_f32 v50, v10, s14, v12
	s_waitcnt lgkmcnt(3)
	v_mul_f32_e32 v10, 0x44fe0000, v48
	v_med3_f32 v19, v10, s14, v12
	s_waitcnt lgkmcnt(2)
	v_mul_f32_e32 v10, 0x44fe0000, v52
	v_med3_f32 v45, v10, s14, v12
	s_waitcnt lgkmcnt(1)
	v_mul_f32_e32 v10, 0x44fe0000, v54
	v_med3_f32 v47, v10, s14, v12
	s_waitcnt lgkmcnt(0)
	v_mul_f32_e32 v10, 0x44fe0000, v56
	v_med3_f32 v51, v10, s14, v12
	v_and_b32_e32 v22, 0xff0000, v22
	v_pk_add_f32 v[44:45], v[44:45], s[8:9] op_sel_hi:[1,0]
	v_pk_add_f32 v[50:51], v[50:51], s[8:9] op_sel_hi:[1,0]
	v_or_b32_e32 v16, v16, v22
	v_pk_add_f32 v[18:19], v[18:19], s[8:9] op_sel_hi:[1,0]
	v_pk_add_f32 v[46:47], v[46:47], s[8:9] op_sel_hi:[1,0]
	v_lshlrev_b32_e32 v10, 8, v45
	v_lshlrev_b32_e32 v22, 8, v44
	v_lshlrev_b32_e32 v28, 24, v51
	v_lshlrev_b32_e32 v30, 24, v50
	v_or_b32_e32 v44, s10, v163
	v_and_b32_e32 v10, 0xff00, v10
	v_and_b32_e32 v22, 0xff00, v22
	v_lshlrev_b32_e32 v24, 16, v47
	v_lshlrev_b32_e32 v26, 16, v46
	v_or_b32_sdwa v19, v28, v19 dst_sel:DWORD dst_unused:UNUSED_PAD src0_sel:DWORD src1_sel:BYTE_0
	v_or_b32_sdwa v18, v30, v18 dst_sel:DWORD dst_unused:UNUSED_PAD src0_sel:DWORD src1_sel:BYTE_0
	v_ashrrev_i32_e32 v45, 31, v44
	v_lshl_add_u64 v[20:21], v[8:9], 0, s[12:13]
	v_and_b32_e32 v24, 0xff0000, v24
	v_and_b32_e32 v26, 0xff0000, v26
	v_or_b32_e32 v10, v19, v10
	v_or_b32_e32 v18, v18, v22
	v_lshlrev_b64 v[44:45], 12, v[44:45]
	v_or_b32_e32 v19, v10, v24
	v_or_b32_e32 v18, v18, v26
	v_lshl_add_u64 v[44:45], v[20:21], 0, v[44:45]
	v_mul_f32_e32 v10, 0x44fe0000, v11
	v_mul_f32_e32 v11, 0x44fe0000, v23
	global_store_dwordx4 v[44:45], v[16:19], off
	v_mul_f32_e32 v23, 0x44fe0000, v39
	v_med3_f32 v23, v23, s14, v12
	v_med3_f32 v16, v11, s14, v12
	v_mul_f32_e32 v11, 0x44fe0000, v25
	v_med3_f32 v18, v11, s14, v12
	v_mul_f32_e32 v11, 0x44fe0000, v27
	v_mul_f32_e32 v17, 0x44fe0000, v35
	v_med3_f32 v22, v11, s14, v12
	v_mul_f32_e32 v11, 0x44fe0000, v31
	v_med3_f32 v17, v17, s14, v12
	v_mul_f32_e32 v19, 0x44fe0000, v37
	v_med3_f32 v10, v10, s14, v12
	v_med3_f32 v11, v11, s14, v12
	v_med3_f32 v19, v19, s14, v12
	v_pk_add_f32 v[16:17], v[16:17], s[8:9] op_sel_hi:[1,0]
	v_pk_add_f32 v[22:23], v[22:23], s[8:9] op_sel_hi:[1,0]
	v_pk_add_f32 v[10:11], v[10:11], s[8:9] op_sel_hi:[1,0]
	v_pk_add_f32 v[18:19], v[18:19], s[8:9] op_sel_hi:[1,0]
	v_lshlrev_b32_e32 v17, 8, v17
	v_lshlrev_b32_e32 v23, 24, v23
	v_lshlrev_b32_e32 v16, 8, v16
	v_and_b32_e32 v17, 0xff00, v17
	v_lshlrev_b32_e32 v19, 16, v19
	v_lshlrev_b32_e32 v22, 24, v22
	v_or_b32_sdwa v11, v23, v11 dst_sel:DWORD dst_unused:UNUSED_PAD src0_sel:DWORD src1_sel:BYTE_0
	v_and_b32_e32 v16, 0xff00, v16
	v_lshlrev_b32_e32 v18, 16, v18
	v_and_b32_e32 v19, 0xff0000, v19
	v_or_b32_sdwa v10, v22, v10 dst_sel:DWORD dst_unused:UNUSED_PAD src0_sel:DWORD src1_sel:BYTE_0
	v_or_b32_e32 v11, v11, v17
	v_and_b32_e32 v18, 0xff0000, v18
	v_or_b32_e32 v10, v10, v16
	v_or_b32_e32 v17, v11, v19
	v_mul_f32_e32 v11, 0x44fe0000, v33
	v_or_b32_e32 v16, v10, v18
	v_med3_f32 v18, v11, s14, v12
	v_mul_f32_e32 v11, 0x44fe0000, v41
	v_med3_f32 v22, v11, s14, v12
	v_mul_f32_e32 v11, 0x44fe0000, v43
	v_mul_f32_e32 v19, 0x44fe0000, v53
	v_mul_f32_e32 v25, 0x44fe0000, v57
	v_mul_f32_e32 v10, 0x44fe0000, v29
	v_med3_f32 v24, v11, s14, v12
	v_mul_f32_e32 v11, 0x44fe0000, v49
	v_med3_f32 v19, v19, s14, v12
	v_mul_f32_e32 v23, 0x44fe0000, v55
	v_med3_f32 v25, v25, s14, v12
	v_med3_f32 v10, v10, s14, v12
	v_med3_f32 v11, v11, s14, v12
	v_med3_f32 v23, v23, s14, v12
	v_pk_add_f32 v[18:19], v[18:19], s[8:9] op_sel_hi:[1,0]
	v_pk_add_f32 v[24:25], v[24:25], s[8:9] op_sel_hi:[1,0]
	v_pk_add_f32 v[10:11], v[10:11], s[8:9] op_sel_hi:[1,0]
	v_pk_add_f32 v[22:23], v[22:23], s[8:9] op_sel_hi:[1,0]
	v_lshlrev_b32_e32 v18, 8, v18
	v_lshlrev_b32_e32 v24, 24, v24
	v_lshlrev_b32_e32 v19, 8, v19
	v_and_b32_e32 v18, 0xff00, v18
	v_lshlrev_b32_e32 v22, 16, v22
	v_lshlrev_b32_e32 v25, 24, v25
	v_or_b32_sdwa v10, v24, v10 dst_sel:DWORD dst_unused:UNUSED_PAD src0_sel:DWORD src1_sel:BYTE_0
	v_and_b32_e32 v19, 0xff00, v19
	v_lshlrev_b32_e32 v23, 16, v23
	v_and_b32_e32 v22, 0xff0000, v22
	v_or_b32_sdwa v11, v25, v11 dst_sel:DWORD dst_unused:UNUSED_PAD src0_sel:DWORD src1_sel:BYTE_0
	v_or_b32_e32 v10, v10, v18
	v_and_b32_e32 v23, 0xff0000, v23
	v_or_b32_e32 v11, v11, v19
	v_or_b32_e32 v18, v10, v22
	v_or_b32_e32 v10, s10, v15
	v_or_b32_e32 v19, v11, v23
	v_ashrrev_i32_e32 v11, 31, v10
	v_lshlrev_b64 v[10:11], 12, v[10:11]
	v_lshl_add_u64 v[10:11], v[20:21], 0, v[10:11]
	global_store_dwordx4 v[10:11], v[16:19], off
	s_waitcnt lgkmcnt(0)
	s_add_i32 s15, s15, s92
	s_cmpk_lt_i32 s15, 0x1000
	s_cbranch_scc1 .LBB0_44
	v_lshlrev_b32_e32 v6, 2, v164
	v_mov_b32_e32 v7, 0
	v_lshl_add_u64 v[8:9], s[0:1], 0, v[6:7]
	s_mov_b64 s[8:9], 0x6000
	v_lshl_add_u64 v[8:9], v[8:9], 0, s[8:9]
	s_mov_b64 s[8:9], 0x38300000
	v_lshl_add_u64 v[10:11], v[4:5], 0, s[8:9]
	s_mov_b32 s3, 0x16b80
	s_movk_i32 s9, 0x84
	s_mov_b32 s14, 0xc2fe0000
	s_mov_b32 s8, 0x4b400000
	v_mov_b32_e32 v7, 0x42fe0000
	s_mov_b32 s15, s94

;     ...
;         int dr0 = n0; if (MAP == 1) { if (n0 < DFF) dr0 = (n0 >> 7) * 256 + (n0 & 127); else { const int uo = n0 - DFF; dr0 = (uo >> 7) * 256 + 128 + (uo & 127); } }
; #pragma unroll 8
;         for (int i = 0; i < 32; ++i) { const int kk = 2 * i + (lane >> 5); scr[kk * 33 + (lane & 31)] = W[(size_t)(k0 + kk) * ldw + n0 + (lane & 31)]; }
.LBB0_49:
	s_lshl_b32 s18, s17, 1
	s_lshl_b32 s19, s16, 1
	v_or_b32_e32 v48, s18, v1
	v_or_b32_e32 v49, s19, v162
	s_add_i32 s20, s18, 4
	s_add_i32 s21, s19, 4
	s_add_i32 s22, s18, 8
	s_add_i32 s23, s19, 8
	s_add_i32 s24, s18, 12
	s_add_i32 s25, s19, 12
	s_add_i32 s26, s18, 16
	s_add_i32 s27, s19, 16
	s_add_i32 s28, s18, 20
	s_add_i32 s29, s19, 20
	s_add_i32 s30, s18, 24
	s_add_i32 s31, s19, 24
	s_add_i32 s18, s18, 28
	s_add_i32 s19, s19, 28
	v_add_u32_e32 v16, s12, v49
	v_or_b32_e32 v50, s20, v1
	v_or_b32_e32 v51, s21, v162
	v_or_b32_e32 v52, s22, v1
	v_or_b32_e32 v53, s23, v162
	v_or_b32_e32 v54, s24, v1
	v_or_b32_e32 v55, s25, v162
	v_or_b32_e32 v56, s26, v1
	v_or_b32_e32 v57, s27, v162
	v_or_b32_e32 v58, s28, v1
	v_or_b32_e32 v59, s29, v162
	v_or_b32_e32 v60, s30, v1
	v_or_b32_e32 v61, s31, v162
	v_or_b32_e32 v62, s18, v1
	v_or_b32_e32 v63, s19, v162
	v_add_u32_e32 v18, s11, v48
	v_mad_i64_i32 v[16:17], s[18:19], v16, s3, v[12:13]
	v_add_u32_e32 v22, s11, v50
	v_add_u32_e32 v20, s12, v51
	v_add_u32_e32 v26, s11, v52
	v_add_u32_e32 v24, s12, v53
	v_add_u32_e32 v30, s11, v54
	v_add_u32_e32 v28, s12, v55
	v_add_u32_e32 v34, s11, v56
	v_add_u32_e32 v32, s12, v57
	v_add_u32_e32 v38, s11, v58
	v_add_u32_e32 v36, s12, v59
	v_add_u32_e32 v42, s11, v60
	v_add_u32_e32 v40, s12, v61
	v_add_u32_e32 v46, s11, v62
	v_add_u32_e32 v44, s12, v63
	v_mad_i64_i32 v[18:19], s[18:19], v18, s3, v[12:13]
	v_mad_i64_i32 v[20:21], s[18:19], v20, s3, v[12:13]
	v_mad_i64_i32 v[22:23], s[18:19], v22, s3, v[12:13]
	v_mad_i64_i32 v[24:25], s[18:19], v24, s3, v[12:13]
	v_mad_i64_i32 v[26:27], s[18:19], v26, s3, v[12:13]
	v_mad_i64_i32 v[28:29], s[18:19], v28, s3, v[12:13]
	v_mad_i64_i32 v[30:31], s[18:19], v30, s3, v[12:13]
	v_mad_i64_i32 v[32:33], s[18:19], v32, s3, v[12:13]
	v_mad_i64_i32 v[34:35], s[18:19], v34, s3, v[12:13]
	v_mad_i64_i32 v[36:37], s[18:19], v36, s3, v[12:13]
	v_mad_i64_i32 v[38:39], s[18:19], v38, s3, v[12:13]
	v_mad_i64_i32 v[40:41], s[18:19], v40, s3, v[12:13]
	v_mad_i64_i32 v[42:43], s[18:19], v42, s3, v[12:13]
	v_mad_i64_i32 v[44:45], s[18:19], v44, s3, v[12:13]
	v_mad_i64_i32 v[46:47], s[18:19], v46, s3, v[12:13]
	global_load_dword v64, v[16:17], off
	global_load_dword v65, v[18:19], off
	global_load_dword v66, v[20:21], off
	global_load_dword v67, v[22:23], off
	global_load_dword v68, v[24:25], off
	global_load_dword v69, v[26:27], off
	global_load_dword v70, v[28:29], off
	global_load_dword v71, v[30:31], off
	global_load_dword v72, v[32:33], off
	global_load_dword v73, v[34:35], off
	global_load_dword v74, v[36:37], off
	global_load_dword v75, v[38:39], off
	global_load_dword v76, v[40:41], off
	global_load_dword v77, v[42:43], off
	global_load_dword v78, v[44:45], off
	global_load_dword v79, v[46:47], off
	s_add_i32 s16, s16, 16
	s_add_i32 s17, s17, 16
	s_add_i32 s13, s13, -16
	v_mad_u64_u32 v[16:17], s[18:19], v49, s9, v[2:3]
	s_cmp_lg_u32 s13, 0
	v_mad_u64_u32 v[18:19], s[18:19], v48, s9, v[2:3]
	v_mad_u64_u32 v[20:21], s[18:19], v51, s9, v[2:3]
	v_mad_u64_u32 v[22:23], s[18:19], v50, s9, v[2:3]
	v_mad_u64_u32 v[24:25], s[18:19], v53, s9, v[2:3]
	v_mad_u64_u32 v[26:27], s[18:19], v52, s9, v[2:3]
	v_mad_u64_u32 v[28:29], s[18:19], v55, s9, v[2:3]
	v_mad_u64_u32 v[30:31], s[18:19], v54, s9, v[2:3]
	v_mad_u64_u32 v[32:33], s[18:19], v57, s9, v[2:3]
	v_mad_u64_u32 v[34:35], s[18:19], v56, s9, v[2:3]
	v_mad_u64_u32 v[36:37], s[18:19], v59, s9, v[2:3]
	v_mad_u64_u32 v[38:39], s[18:19], v58, s9, v[2:3]
	v_mad_u64_u32 v[40:41], s[18:19], v61, s9, v[2:3]
	v_mad_u64_u32 v[42:43], s[18:19], v60, s9, v[2:3]
	v_mad_u64_u32 v[44:45], s[18:19], v63, s9, v[2:3]
	v_mad_u64_u32 v[46:47], s[18:19], v62, s9, v[2:3]
	s_lshl_b32 s18, s17, 1
	s_lshl_b32 s19, s16, 1
	v_or_b32_e32 v116, s18, v1
	v_or_b32_e32 v117, s19, v162
	s_add_i32 s20, s18, 4
	s_add_i32 s21, s19, 4
	s_add_i32 s22, s18, 8
	s_add_i32 s23, s19, 8
	s_add_i32 s24, s18, 12
	s_add_i32 s25, s19, 12
	s_add_i32 s26, s18, 16
	s_add_i32 s27, s19, 16
	s_add_i32 s28, s18, 20
	s_add_i32 s29, s19, 20
	s_add_i32 s30, s18, 24
	s_add_i32 s31, s19, 24
	s_add_i32 s18, s18, 28
	s_add_i32 s19, s19, 28
	v_add_u32_e32 v84, s12, v117
	v_or_b32_e32 v118, s20, v1
	v_or_b32_e32 v119, s21, v162
	v_or_b32_e32 v120, s22, v1
	v_or_b32_e32 v121, s23, v162
	v_or_b32_e32 v122, s24, v1
	v_or_b32_e32 v123, s25, v162
	v_or_b32_e32 v124, s26, v1
	v_or_b32_e32 v125, s27, v162
	v_or_b32_e32 v126, s28, v1
	v_or_b32_e32 v127, s29, v162
	v_or_b32_e32 v128, s30, v1
	v_or_b32_e32 v129, s31, v162
	v_or_b32_e32 v130, s18, v1
	v_or_b32_e32 v131, s19, v162
	v_add_u32_e32 v86, s11, v116
	v_mad_i64_i32 v[84:85], s[18:19], v84, s3, v[12:13]
	v_add_u32_e32 v90, s11, v118
	v_add_u32_e32 v88, s12, v119
	v_add_u32_e32 v94, s11, v120
	v_add_u32_e32 v92, s12, v121
	v_add_u32_e32 v98, s11, v122
	v_add_u32_e32 v96, s12, v123
	v_add_u32_e32 v102, s11, v124
	v_add_u32_e32 v100, s12, v125
	v_add_u32_e32 v106, s11, v126
	v_add_u32_e32 v104, s12, v127
	v_add_u32_e32 v110, s11, v128
	v_add_u32_e32 v108, s12, v129
	v_add_u32_e32 v114, s11, v130
	v_add_u32_e32 v112, s12, v131
	v_mad_i64_i32 v[86:87], s[18:19], v86, s3, v[12:13]
	v_mad_i64_i32 v[88:89], s[18:19], v88, s3, v[12:13]
	v_mad_i64_i32 v[90:91], s[18:19], v90, s3, v[12:13]
	v_mad_i64_i32 v[92:93], s[18:19], v92, s3, v[12:13]
	v_mad_i64_i32 v[94:95], s[18:19], v94, s3, v[12:13]
	v_mad_i64_i32 v[96:97], s[18:19], v96, s3, v[12:13]
	v_mad_i64_i32 v[98:99], s[18:19], v98, s3, v[12:13]
	v_mad_i64_i32 v[100:101], s[18:19], v100, s3, v[12:13]
	v_mad_i64_i32 v[102:103], s[18:19], v102, s3, v[12:13]
	v_mad_i64_i32 v[104:105], s[18:19], v104, s3, v[12:13]
	v_mad_i64_i32 v[106:107], s[18:19], v106, s3, v[12:13]
; #define LAS __attribute__((address_space(3)))
; #define LDS_WAIT() asm volatile("s_waitcnt lgkmcnt(0)" ::: "memory")
;     ...
;         for (int i = 0; i < 32; ++i) { const int kk = 2 * i + (lane >> 5); scr[kk * 33 + (lane & 31)] = W[(size_t)(k0 + kk) * ldw + n0 + (lane & 31)]; }
;         LDS_WAIT(); asm volatile("" ::: "memory");
;         const int c = lane & 3;
; #pragma unroll
;         for (int j = 0; j < 2; ++j) { const int n = (lane >> 2) + 16 * j; const LAS float* sp = scr + (16 * c) * 33 + n;
;             u32x4 o;
;             if (QI8) { o.x = pk4_i8(sp[0 * 33], sp[1 * 33], sp[2 * 33], sp[3 * 33], scl); o.y = pk4_i8(sp[4 * 33], sp[5 * 33], sp[6 * 33], sp[7 * 33], scl);
;                 o.z = pk4_i8(sp[8 * 33], sp[9 * 33], sp[10 * 33], sp[11 * 33], scl); o.w = pk4_i8(sp[12 * 33], sp[13 * 33], sp[14 * 33], sp[15 * 33], scl); }
	v_mad_i64_i32 v[108:109], s[18:19], v108, s3, v[12:13]
	v_mad_i64_i32 v[110:111], s[18:19], v110, s3, v[12:13]
	v_mad_i64_i32 v[112:113], s[18:19], v112, s3, v[12:13]
	v_mad_i64_i32 v[114:115], s[18:19], v114, s3, v[12:13]
	global_load_dword v132, v[84:85], off
	global_load_dword v133, v[86:87], off
	global_load_dword v134, v[88:89], off
	global_load_dword v135, v[90:91], off
	global_load_dword v136, v[92:93], off
	global_load_dword v137, v[94:95], off
	global_load_dword v138, v[96:97], off
	global_load_dword v139, v[98:99], off
	global_load_dword v140, v[100:101], off
	global_load_dword v141, v[102:103], off
	global_load_dword v142, v[104:105], off
	global_load_dword v143, v[106:107], off
	global_load_dword v144, v[108:109], off
	global_load_dword v145, v[110:111], off
	global_load_dword v146, v[112:113], off
	global_load_dword v147, v[114:115], off
	s_add_i32 s16, s16, 16
	s_add_i32 s17, s17, 16
	s_add_i32 s13, s13, -16
	v_mad_u64_u32 v[84:85], s[18:19], v117, s9, v[2:3]
	s_cmp_lg_u32 s13, 0
	v_mad_u64_u32 v[86:87], s[18:19], v116, s9, v[2:3]
	v_mad_u64_u32 v[88:89], s[18:19], v119, s9, v[2:3]
	v_mad_u64_u32 v[90:91], s[18:19], v118, s9, v[2:3]
	v_mad_u64_u32 v[92:93], s[18:19], v121, s9, v[2:3]
	v_mad_u64_u32 v[94:95], s[18:19], v120, s9, v[2:3]
	v_mad_u64_u32 v[96:97], s[18:19], v123, s9, v[2:3]
	v_mad_u64_u32 v[98:99], s[18:19], v122, s9, v[2:3]
	v_mad_u64_u32 v[100:101], s[18:19], v125, s9, v[2:3]
	v_mad_u64_u32 v[102:103], s[18:19], v124, s9, v[2:3]
	v_mad_u64_u32 v[104:105], s[18:19], v127, s9, v[2:3]
	v_mad_u64_u32 v[106:107], s[18:19], v126, s9, v[2:3]
	v_mad_u64_u32 v[108:109], s[18:19], v129, s9, v[2:3]
	v_mad_u64_u32 v[110:111], s[18:19], v128, s9, v[2:3]
	v_mad_u64_u32 v[112:113], s[18:19], v131, s9, v[2:3]
	v_mad_u64_u32 v[114:115], s[18:19], v130, s9, v[2:3]
	s_waitcnt vmcnt(31)
	ds_write_b32 v16, v64
	s_waitcnt vmcnt(30)
	ds_write_b32 v18, v65
	s_waitcnt vmcnt(29)
	ds_write_b32 v20, v66
	s_waitcnt vmcnt(28)
	ds_write_b32 v22, v67
	s_waitcnt vmcnt(27)
	ds_write_b32 v24, v68
	s_waitcnt vmcnt(26)
	ds_write_b32 v26, v69
	s_waitcnt vmcnt(25)
	ds_write_b32 v28, v70
	s_waitcnt vmcnt(24)
	ds_write_b32 v30, v71
	s_waitcnt vmcnt(23)
	ds_write_b32 v32, v72
	s_waitcnt vmcnt(22)
	ds_write_b32 v34, v73
	s_waitcnt vmcnt(21)
	ds_write_b32 v36, v74
	s_waitcnt vmcnt(20)
	ds_write_b32 v38, v75
	s_waitcnt vmcnt(19)
	ds_write_b32 v40, v76
	s_waitcnt vmcnt(18)
	ds_write_b32 v42, v77
	s_waitcnt vmcnt(17)
	ds_write_b32 v44, v78
	s_waitcnt vmcnt(16)
	ds_write_b32 v46, v79
	s_waitcnt vmcnt(15)
	ds_write_b32 v84, v132
	s_waitcnt vmcnt(14)
	ds_write_b32 v86, v133
	s_waitcnt vmcnt(13)
	ds_write_b32 v88, v134
	s_waitcnt vmcnt(12)
	ds_write_b32 v90, v135
	s_waitcnt vmcnt(11)
	ds_write_b32 v92, v136
	s_waitcnt vmcnt(10)
	ds_write_b32 v94, v137
	s_waitcnt vmcnt(9)
	ds_write_b32 v96, v138
	s_waitcnt vmcnt(8)
	ds_write_b32 v98, v139
	s_waitcnt vmcnt(7)
	ds_write_b32 v100, v140
	s_waitcnt vmcnt(6)
	ds_write_b32 v102, v141
	s_waitcnt vmcnt(5)
	ds_write_b32 v104, v142
	s_waitcnt vmcnt(4)
	ds_write_b32 v106, v143
	s_waitcnt vmcnt(3)
	ds_write_b32 v108, v144
	s_waitcnt vmcnt(2)
	ds_write_b32 v110, v145
	s_waitcnt vmcnt(1)
	ds_write_b32 v112, v146
	s_waitcnt vmcnt(0)
	ds_write_b32 v114, v147
	s_waitcnt lgkmcnt(0)
	ds_read2_b32 v[12:13], v3 offset1:16
	ds_read2_b32 v[22:23], v3 offset0:33 offset1:49
	ds_read2_b32 v[24:25], v3 offset0:66 offset1:82
	ds_read2_b32 v[26:27], v3 offset0:99 offset1:115
	ds_read2_b32 v[30:31], v3 offset0:132 offset1:148
	ds_read2_b32 v[34:35], v3 offset0:165 offset1:181
	ds_read2_b32 v[36:37], v3 offset0:198 offset1:214
	ds_read2_b32 v[38:39], v3 offset0:231 offset1:247
	s_ashr_i32 s13, s12, 31
	s_waitcnt lgkmcnt(7)
	v_mul_f32_e32 v12, 0x44fe0000, v12
	v_med3_f32 v16, v12, s14, v7
	s_waitcnt lgkmcnt(6)
	v_mul_f32_e32 v12, 0x44fe0000, v22
	v_med3_f32 v18, v12, s14, v7
	s_waitcnt lgkmcnt(5)
	v_mul_f32_e32 v12, 0x44fe0000, v24
	v_med3_f32 v28, v12, s14, v7
	s_waitcnt lgkmcnt(4)
	v_mul_f32_e32 v12, 0x44fe0000, v26
	v_med3_f32 v32, v12, s14, v7
	s_waitcnt lgkmcnt(3)
	v_mul_f32_e32 v12, 0x44fe0000, v30
	v_med3_f32 v17, v12, s14, v7
	s_waitcnt lgkmcnt(2)
	v_mul_f32_e32 v12, 0x44fe0000, v34
	v_med3_f32 v19, v12, s14, v7
	s_waitcnt lgkmcnt(1)
	v_mul_f32_e32 v12, 0x44fe0000, v36
	v_med3_f32 v29, v12, s14, v7
	s_waitcnt lgkmcnt(0)
	v_mul_f32_e32 v12, 0x44fe0000, v38
	v_med3_f32 v33, v12, s14, v7
	v_pk_add_f32 v[18:19], v[18:19], s[8:9] op_sel_hi:[1,0]
	v_pk_add_f32 v[32:33], v[32:33], s[8:9] op_sel_hi:[1,0]
	v_pk_add_f32 v[16:17], v[16:17], s[8:9] op_sel_hi:[1,0]
	v_pk_add_f32 v[28:29], v[28:29], s[8:9] op_sel_hi:[1,0]
	v_lshlrev_b32_e32 v12, 8, v19
	v_lshlrev_b32_e32 v24, 24, v33
	v_and_b32_e32 v12, 0xff00, v12
	v_lshlrev_b32_e32 v19, 16, v29
	v_or_b32_sdwa v17, v24, v17 dst_sel:DWORD dst_unused:UNUSED_PAD src0_sel:DWORD src1_sel:BYTE_0
	v_and_b32_e32 v19, 0xff0000, v19
	v_or_b32_e32 v12, v17, v12
	v_or_b32_e32 v17, v12, v19
	v_add_u32_e32 v12, 0x400, v3
	v_lshlrev_b32_e32 v22, 16, v28
	v_lshlrev_b32_e32 v26, 24, v32
	ds_read2_b32 v[28:29], v12 offset0:8 offset1:24
	ds_read2_b32 v[32:33], v12 offset0:41 offset1:57
	ds_read2_b32 v[40:41], v12 offset0:74 offset1:90
	ds_read2_b32 v[42:43], v12 offset0:107 offset1:123
	ds_read2_b32 v[48:49], v12 offset0:140 offset1:156
	ds_read2_b32 v[52:53], v12 offset0:173 offset1:189
	ds_read2_b32 v[54:55], v12 offset0:206 offset1:222
	ds_read2_b32 v[56:57], v12 offset0:239 offset1:255
	s_waitcnt lgkmcnt(6)
; #define LAS __attribute__((address_space(3)))
; __device__ __forceinline__ unsigned pk4_f8(float a, float b, float c, float d) { int w = __builtin_amdgcn_cvt_pk_fp8_f32(a, b, 0, false); w = __builtin_amdgcn_cvt_pk_fp8_f32(c, d, w, true); return (unsigned)w; }
; #define LDS_WAIT() asm volatile("s_waitcnt lgkmcnt(0)" ::: "memory")
;     ...
;         for (int j = 0; j < 2; ++j) { const int n = (lane >> 2) + 16 * j; const LAS float* sp = scr + (16 * c) * 33 + n;
;             u32x4 o;
;             if (QI8) { o.x = pk4_i8(sp[0 * 33], sp[1 * 33], sp[2 * 33], sp[3 * 33], scl); o.y = pk4_i8(sp[4 * 33], sp[5 * 33], sp[6 * 33], sp[7 * 33], scl);
;                 o.z = pk4_i8(sp[8 * 33], sp[9 * 33], sp[10 * 33], sp[11 * 33], scl); o.w = pk4_i8(sp[12 * 33], sp[13 * 33], sp[14 * 33], sp[15 * 33], scl); }
;             else {
;             o.x = pk4_f8(sp[0 * 33] * scl, sp[1 * 33] * scl, sp[2 * 33] * scl, sp[3 * 33] * scl); o.y = pk4_f8(sp[4 * 33] * scl, sp[5 * 33] * scl, sp[6 * 33] * scl, sp[7 * 33] * scl);
;             o.z = pk4_f8(sp[8 * 33] * scl, sp[9 * 33] * scl, sp[10 * 33] * scl, sp[11 * 33] * scl); o.w = pk4_f8(sp[12 * 33] * scl, sp[13 * 33] * scl, sp[14 * 33] * scl, sp[15 * 33] * scl); }
;             *(u32x4*)(WT + (size_t)(dr0 + n) * K + k0 + 16 * c) = o; }
;         LDS_WAIT(); asm volatile("" ::: "memory"); }
; __device__ __forceinline__ void p0_prologue(Frame& F) {
;     ...
;       transpose_f8_matrix<0, true>(F, W + 8192, D, 2048, w8 + (size_t)12288 * D, I8_W, ldw); }
	v_mul_f32_e32 v19, 0x44fe0000, v32
	v_med3_f32 v44, v19, s14, v7
	s_waitcnt lgkmcnt(5)
	v_mul_f32_e32 v19, 0x44fe0000, v40
	v_med3_f32 v46, v19, s14, v7
	s_waitcnt lgkmcnt(4)
	v_mul_f32_e32 v19, 0x44fe0000, v42
	s_waitcnt lgkmcnt(3)
	v_mul_f32_e32 v12, 0x44fe0000, v48
	v_med3_f32 v50, v19, s14, v7
	v_med3_f32 v19, v12, s14, v7
	s_waitcnt lgkmcnt(2)
	v_mul_f32_e32 v12, 0x44fe0000, v52
	v_lshlrev_b32_e32 v18, 8, v18
	v_med3_f32 v45, v12, s14, v7
	s_waitcnt lgkmcnt(1)
	v_mul_f32_e32 v12, 0x44fe0000, v54
	v_and_b32_e32 v18, 0xff00, v18
	v_or_b32_sdwa v16, v26, v16 dst_sel:DWORD dst_unused:UNUSED_PAD src0_sel:DWORD src1_sel:BYTE_0
	v_med3_f32 v47, v12, s14, v7
	s_waitcnt lgkmcnt(0)
	v_mul_f32_e32 v12, 0x44fe0000, v56
	v_or_b32_e32 v16, v16, v18
	v_mul_f32_e32 v18, 0x44fe0000, v28
	v_med3_f32 v51, v12, s14, v7
	v_and_b32_e32 v22, 0xff0000, v22
	v_med3_f32 v18, v18, s14, v7
	v_pk_add_f32 v[44:45], v[44:45], s[8:9] op_sel_hi:[1,0]
	v_pk_add_f32 v[50:51], v[50:51], s[8:9] op_sel_hi:[1,0]
	v_or_b32_e32 v16, v16, v22
	v_pk_add_f32 v[18:19], v[18:19], s[8:9] op_sel_hi:[1,0]
	v_pk_add_f32 v[46:47], v[46:47], s[8:9] op_sel_hi:[1,0]
	v_lshlrev_b32_e32 v12, 8, v45
	v_lshlrev_b32_e32 v22, 8, v44
	v_lshlrev_b32_e32 v28, 24, v51
	v_lshlrev_b32_e32 v30, 24, v50
	v_or_b32_e32 v44, s10, v163
	v_and_b32_e32 v12, 0xff00, v12
	v_and_b32_e32 v22, 0xff00, v22
	v_lshlrev_b32_e32 v24, 16, v47
	v_lshlrev_b32_e32 v26, 16, v46
	v_or_b32_sdwa v19, v28, v19 dst_sel:DWORD dst_unused:UNUSED_PAD src0_sel:DWORD src1_sel:BYTE_0
	v_or_b32_sdwa v18, v30, v18 dst_sel:DWORD dst_unused:UNUSED_PAD src0_sel:DWORD src1_sel:BYTE_0
	v_ashrrev_i32_e32 v45, 31, v44
	v_lshl_add_u64 v[20:21], v[10:11], 0, s[12:13]
	v_and_b32_e32 v24, 0xff0000, v24
	v_and_b32_e32 v26, 0xff0000, v26
	v_or_b32_e32 v12, v19, v12
	v_or_b32_e32 v18, v18, v22
	v_lshlrev_b64 v[44:45], 12, v[44:45]
	v_or_b32_e32 v19, v12, v24
	v_or_b32_e32 v18, v18, v26
	v_lshl_add_u64 v[44:45], v[20:21], 0, v[44:45]
	v_mul_f32_e32 v12, 0x44fe0000, v13
	v_mul_f32_e32 v13, 0x44fe0000, v23
	global_store_dwordx4 v[44:45], v[16:19], off
	v_mul_f32_e32 v23, 0x44fe0000, v39
	v_med3_f32 v23, v23, s14, v7
	v_med3_f32 v16, v13, s14, v7
	v_mul_f32_e32 v13, 0x44fe0000, v25
	v_med3_f32 v18, v13, s14, v7
	v_mul_f32_e32 v13, 0x44fe0000, v27
	v_mul_f32_e32 v17, 0x44fe0000, v35
	v_med3_f32 v22, v13, s14, v7
	v_mul_f32_e32 v13, 0x44fe0000, v31
	v_med3_f32 v17, v17, s14, v7
	v_mul_f32_e32 v19, 0x44fe0000, v37
	v_med3_f32 v12, v12, s14, v7
	v_med3_f32 v13, v13, s14, v7
	v_med3_f32 v19, v19, s14, v7
	v_pk_add_f32 v[16:17], v[16:17], s[8:9] op_sel_hi:[1,0]
	v_pk_add_f32 v[22:23], v[22:23], s[8:9] op_sel_hi:[1,0]
	v_pk_add_f32 v[12:13], v[12:13], s[8:9] op_sel_hi:[1,0]
	v_pk_add_f32 v[18:19], v[18:19], s[8:9] op_sel_hi:[1,0]
	v_lshlrev_b32_e32 v17, 8, v17
	v_lshlrev_b32_e32 v23, 24, v23
	v_lshlrev_b32_e32 v16, 8, v16
	v_and_b32_e32 v17, 0xff00, v17
	v_lshlrev_b32_e32 v19, 16, v19
	v_lshlrev_b32_e32 v22, 24, v22
	v_or_b32_sdwa v13, v23, v13 dst_sel:DWORD dst_unused:UNUSED_PAD src0_sel:DWORD src1_sel:BYTE_0
	v_and_b32_e32 v16, 0xff00, v16
	v_lshlrev_b32_e32 v18, 16, v18
	v_and_b32_e32 v19, 0xff0000, v19
	v_or_b32_sdwa v12, v22, v12 dst_sel:DWORD dst_unused:UNUSED_PAD src0_sel:DWORD src1_sel:BYTE_0
	v_or_b32_e32 v13, v13, v17
	v_and_b32_e32 v18, 0xff0000, v18
	v_or_b32_e32 v12, v12, v16
	v_or_b32_e32 v17, v13, v19
	v_mul_f32_e32 v13, 0x44fe0000, v33
	v_or_b32_e32 v16, v12, v18
	v_med3_f32 v18, v13, s14, v7
	v_mul_f32_e32 v13, 0x44fe0000, v41
	v_med3_f32 v22, v13, s14, v7
	v_mul_f32_e32 v13, 0x44fe0000, v43
	v_mul_f32_e32 v19, 0x44fe0000, v53
	v_mul_f32_e32 v25, 0x44fe0000, v57
	v_mul_f32_e32 v12, 0x44fe0000, v29
	v_med3_f32 v24, v13, s14, v7
	v_mul_f32_e32 v13, 0x44fe0000, v49
	v_med3_f32 v19, v19, s14, v7
	v_mul_f32_e32 v23, 0x44fe0000, v55
	v_med3_f32 v25, v25, s14, v7
	v_med3_f32 v12, v12, s14, v7
	v_med3_f32 v13, v13, s14, v7
	v_med3_f32 v23, v23, s14, v7
	v_pk_add_f32 v[18:19], v[18:19], s[8:9] op_sel_hi:[1,0]
	v_pk_add_f32 v[24:25], v[24:25], s[8:9] op_sel_hi:[1,0]
	v_pk_add_f32 v[12:13], v[12:13], s[8:9] op_sel_hi:[1,0]
	v_pk_add_f32 v[22:23], v[22:23], s[8:9] op_sel_hi:[1,0]
	v_lshlrev_b32_e32 v18, 8, v18
	v_lshlrev_b32_e32 v24, 24, v24
	v_lshlrev_b32_e32 v19, 8, v19
	v_and_b32_e32 v18, 0xff00, v18
	v_lshlrev_b32_e32 v22, 16, v22
	v_lshlrev_b32_e32 v25, 24, v25
	v_or_b32_sdwa v12, v24, v12 dst_sel:DWORD dst_unused:UNUSED_PAD src0_sel:DWORD src1_sel:BYTE_0
	v_and_b32_e32 v19, 0xff00, v19
	v_lshlrev_b32_e32 v23, 16, v23
	v_and_b32_e32 v22, 0xff0000, v22
	v_or_b32_sdwa v13, v25, v13 dst_sel:DWORD dst_unused:UNUSED_PAD src0_sel:DWORD src1_sel:BYTE_0
	v_or_b32_e32 v12, v12, v18
	v_and_b32_e32 v23, 0xff0000, v23
	v_or_b32_e32 v13, v13, v19
	v_or_b32_e32 v18, v12, v22
	v_or_b32_e32 v12, s10, v15
	v_or_b32_e32 v19, v13, v23
	v_ashrrev_i32_e32 v13, 31, v12
	v_lshlrev_b64 v[12:13], 12, v[12:13]
	v_lshl_add_u64 v[12:13], v[20:21], 0, v[12:13]
	global_store_dwordx4 v[12:13], v[16:19], off
	s_waitcnt lgkmcnt(0)
	s_add_i32 s15, s15, s92
	s_cmpk_lt_i32 s15, 0x1000
	s_cbranch_scc1 .LBB0_48
	v_mov_b32_e32 v7, 0
	v_lshl_add_u64 v[6:7], s[0:1], 0, v[6:7]
	s_mov_b64 s[0:1], 0x8000
	v_lshl_add_u64 v[6:7], v[6:7], 0, s[0:1]
	s_mov_b64 s[0:1], 0x38b00000
	v_lshl_add_u64 v[4:5], v[4:5], 0, s[0:1]
	s_mov_b32 s1, 0x16b80
	s_movk_i32 s3, 0x84
	s_mov_b32 s12, 0xc2fe0000
	s_mov_b32 s0, 0x4b400000
	v_mov_b32_e32 v10, 0x42fe0000
	s_mov_b32 s13, s94

;     ...
; #pragma unroll 8
;         for (int i = 0; i < 32; ++i) { const int kk = 2 * i + (lane >> 5); scr[kk * 33 + (lane & 31)] = W[(size_t)(k0 + kk) * ldw + n0 + (lane & 31)]; }
.LBB0_53:
	s_lshl_b32 s16, s15, 1
	s_lshl_b32 s17, s14, 1
	v_or_b32_e32 v11, s16, v1
	v_or_b32_e32 v46, s17, v162
	s_add_i32 s18, s16, 4
	s_add_i32 s19, s17, 4
	s_add_i32 s20, s16, 8
	s_add_i32 s21, s17, 8
	s_add_i32 s22, s16, 12
	s_add_i32 s23, s17, 12
	s_add_i32 s24, s16, 16
	s_add_i32 s25, s17, 16
	s_add_i32 s26, s16, 20
	s_add_i32 s27, s17, 20
	s_add_i32 s28, s16, 24
	s_add_i32 s29, s17, 24
	s_add_i32 s16, s16, 28
	s_add_i32 s17, s17, 28
	v_add_u32_e32 v12, s10, v46
	v_or_b32_e32 v47, s18, v1
	v_or_b32_e32 v48, s19, v162
	v_or_b32_e32 v49, s20, v1
	v_or_b32_e32 v50, s21, v162
	v_or_b32_e32 v51, s22, v1
	v_or_b32_e32 v52, s23, v162
	v_or_b32_e32 v53, s24, v1
	v_or_b32_e32 v54, s25, v162
	v_or_b32_e32 v55, s26, v1
	v_or_b32_e32 v56, s27, v162
	v_or_b32_e32 v57, s28, v1
	v_or_b32_e32 v58, s29, v162
	v_or_b32_e32 v59, s16, v1
	v_or_b32_e32 v60, s17, v162
	v_add_u32_e32 v16, s9, v11
	v_mad_i64_i32 v[12:13], s[16:17], v12, s1, v[8:9]
	v_add_u32_e32 v20, s9, v47
	v_add_u32_e32 v18, s10, v48
	v_add_u32_e32 v24, s9, v49
	v_add_u32_e32 v22, s10, v50
	v_add_u32_e32 v28, s9, v51
	v_add_u32_e32 v26, s10, v52
	v_add_u32_e32 v32, s9, v53
	v_add_u32_e32 v30, s10, v54
	v_add_u32_e32 v36, s9, v55
	v_add_u32_e32 v34, s10, v56
	v_add_u32_e32 v40, s9, v57
	v_add_u32_e32 v38, s10, v58
	v_add_u32_e32 v44, s9, v59
	v_add_u32_e32 v42, s10, v60
	v_mad_i64_i32 v[16:17], s[16:17], v16, s1, v[8:9]
	v_mad_i64_i32 v[18:19], s[16:17], v18, s1, v[8:9]
	v_mad_i64_i32 v[20:21], s[16:17], v20, s1, v[8:9]
	v_mad_i64_i32 v[22:23], s[16:17], v22, s1, v[8:9]
	v_mad_i64_i32 v[24:25], s[16:17], v24, s1, v[8:9]
	v_mad_i64_i32 v[26:27], s[16:17], v26, s1, v[8:9]
	v_mad_i64_i32 v[28:29], s[16:17], v28, s1, v[8:9]
	v_mad_i64_i32 v[30:31], s[16:17], v30, s1, v[8:9]
	v_mad_i64_i32 v[32:33], s[16:17], v32, s1, v[8:9]
	v_mad_i64_i32 v[34:35], s[16:17], v34, s1, v[8:9]
	v_mad_i64_i32 v[36:37], s[16:17], v36, s1, v[8:9]
	v_mad_i64_i32 v[38:39], s[16:17], v38, s1, v[8:9]
	v_mad_i64_i32 v[40:41], s[16:17], v40, s1, v[8:9]
	v_mad_i64_i32 v[42:43], s[16:17], v42, s1, v[8:9]
	v_mad_i64_i32 v[44:45], s[16:17], v44, s1, v[8:9]
	global_load_dword v61, v[12:13], off
	global_load_dword v62, v[16:17], off
	global_load_dword v63, v[18:19], off
	global_load_dword v64, v[20:21], off
	global_load_dword v65, v[22:23], off
	global_load_dword v66, v[24:25], off
	global_load_dword v67, v[26:27], off
	global_load_dword v68, v[28:29], off
	global_load_dword v69, v[30:31], off
	global_load_dword v70, v[32:33], off
	global_load_dword v71, v[34:35], off
	global_load_dword v72, v[36:37], off
	global_load_dword v73, v[38:39], off
	global_load_dword v74, v[40:41], off
	global_load_dword v75, v[42:43], off
	global_load_dword v76, v[44:45], off
	s_add_i32 s14, s14, 16
	s_add_i32 s15, s15, 16
	s_add_i32 s11, s11, -16
	v_mad_u64_u32 v[12:13], s[16:17], v46, s3, v[2:3]
	s_cmp_lg_u32 s11, 0
	v_mad_u64_u32 v[16:17], s[16:17], v11, s3, v[2:3]
	v_mad_u64_u32 v[18:19], s[16:17], v48, s3, v[2:3]
	v_mad_u64_u32 v[20:21], s[16:17], v47, s3, v[2:3]
	v_mad_u64_u32 v[22:23], s[16:17], v50, s3, v[2:3]
	v_mad_u64_u32 v[24:25], s[16:17], v49, s3, v[2:3]
	v_mad_u64_u32 v[26:27], s[16:17], v52, s3, v[2:3]
	v_mad_u64_u32 v[28:29], s[16:17], v51, s3, v[2:3]
	v_mad_u64_u32 v[30:31], s[16:17], v54, s3, v[2:3]
	v_mad_u64_u32 v[32:33], s[16:17], v53, s3, v[2:3]
	v_mad_u64_u32 v[34:35], s[16:17], v56, s3, v[2:3]
	v_mad_u64_u32 v[36:37], s[16:17], v55, s3, v[2:3]
	v_mad_u64_u32 v[38:39], s[16:17], v58, s3, v[2:3]
	v_mad_u64_u32 v[40:41], s[16:17], v57, s3, v[2:3]
	v_mad_u64_u32 v[42:43], s[16:17], v60, s3, v[2:3]
	v_mad_u64_u32 v[44:45], s[16:17], v59, s3, v[2:3]
	s_lshl_b32 s16, s15, 1
	s_lshl_b32 s17, s14, 1
	v_or_b32_e32 v85, s16, v1
	v_or_b32_e32 v120, s17, v162
	s_add_i32 s18, s16, 4
	s_add_i32 s19, s17, 4
	s_add_i32 s20, s16, 8
	s_add_i32 s21, s17, 8
	s_add_i32 s22, s16, 12
	s_add_i32 s23, s17, 12
	s_add_i32 s24, s16, 16
	s_add_i32 s25, s17, 16
	s_add_i32 s26, s16, 20
	s_add_i32 s27, s17, 20
	s_add_i32 s28, s16, 24
	s_add_i32 s29, s17, 24
	s_add_i32 s16, s16, 28
	s_add_i32 s17, s17, 28
	v_add_u32_e32 v86, s10, v120
	v_or_b32_e32 v121, s18, v1
	v_or_b32_e32 v122, s19, v162
	v_or_b32_e32 v123, s20, v1
	v_or_b32_e32 v124, s21, v162
	v_or_b32_e32 v125, s22, v1
	v_or_b32_e32 v126, s23, v162
	v_or_b32_e32 v127, s24, v1
	v_or_b32_e32 v128, s25, v162
	v_or_b32_e32 v129, s26, v1
	v_or_b32_e32 v130, s27, v162
	v_or_b32_e32 v131, s28, v1
	v_or_b32_e32 v132, s29, v162
	v_or_b32_e32 v133, s16, v1
	v_or_b32_e32 v134, s17, v162
	v_add_u32_e32 v90, s9, v85
	v_mad_i64_i32 v[86:87], s[16:17], v86, s1, v[8:9]
	v_add_u32_e32 v94, s9, v121
	v_add_u32_e32 v92, s10, v122
	v_add_u32_e32 v98, s9, v123
	v_add_u32_e32 v96, s10, v124
	v_add_u32_e32 v102, s9, v125
	v_add_u32_e32 v100, s10, v126
	v_add_u32_e32 v106, s9, v127
	v_add_u32_e32 v104, s10, v128
	v_add_u32_e32 v110, s9, v129
	v_add_u32_e32 v108, s10, v130
	v_add_u32_e32 v114, s9, v131
	v_add_u32_e32 v112, s10, v132
	v_add_u32_e32 v118, s9, v133
	v_add_u32_e32 v116, s10, v134
	v_mad_i64_i32 v[90:91], s[16:17], v90, s1, v[8:9]
	v_mad_i64_i32 v[92:93], s[16:17], v92, s1, v[8:9]
	v_mad_i64_i32 v[94:95], s[16:17], v94, s1, v[8:9]
	v_mad_i64_i32 v[96:97], s[16:17], v96, s1, v[8:9]
	v_mad_i64_i32 v[98:99], s[16:17], v98, s1, v[8:9]
	v_mad_i64_i32 v[100:101], s[16:17], v100, s1, v[8:9]
	v_mad_i64_i32 v[102:103], s[16:17], v102, s1, v[8:9]
	v_mad_i64_i32 v[104:105], s[16:17], v104, s1, v[8:9]
	v_mad_i64_i32 v[106:107], s[16:17], v106, s1, v[8:9]
	v_mad_i64_i32 v[108:109], s[16:17], v108, s1, v[8:9]
	v_mad_i64_i32 v[110:111], s[16:17], v110, s1, v[8:9]
	v_mad_i64_i32 v[112:113], s[16:17], v112, s1, v[8:9]
; #define LAS __attribute__((address_space(3)))
; #define LDS_WAIT() asm volatile("s_waitcnt lgkmcnt(0)" ::: "memory")
;     ...
;         for (int i = 0; i < 32; ++i) { const int kk = 2 * i + (lane >> 5); scr[kk * 33 + (lane & 31)] = W[(size_t)(k0 + kk) * ldw + n0 + (lane & 31)]; }
;         LDS_WAIT(); asm volatile("" ::: "memory");
;         const int c = lane & 3;
; #pragma unroll
;         for (int j = 0; j < 2; ++j) { const int n = (lane >> 2) + 16 * j; const LAS float* sp = scr + (16 * c) * 33 + n;
;             u32x4 o;
;             if (QI8) { o.x = pk4_i8(sp[0 * 33], sp[1 * 33], sp[2 * 33], sp[3 * 33], scl); o.y = pk4_i8(sp[4 * 33], sp[5 * 33], sp[6 * 33], sp[7 * 33], scl);
;                 o.z = pk4_i8(sp[8 * 33], sp[9 * 33], sp[10 * 33], sp[11 * 33], scl); o.w = pk4_i8(sp[12 * 33], sp[13 * 33], sp[14 * 33], sp[15 * 33], scl); }
	v_mad_i64_i32 v[114:115], s[16:17], v114, s1, v[8:9]
	v_mad_i64_i32 v[116:117], s[16:17], v116, s1, v[8:9]
	v_mad_i64_i32 v[118:119], s[16:17], v118, s1, v[8:9]
	global_load_dword v135, v[86:87], off
	global_load_dword v136, v[90:91], off
	global_load_dword v137, v[92:93], off
	global_load_dword v138, v[94:95], off
	global_load_dword v139, v[96:97], off
	global_load_dword v140, v[98:99], off
	global_load_dword v141, v[100:101], off
	global_load_dword v142, v[102:103], off
	global_load_dword v143, v[104:105], off
	global_load_dword v144, v[106:107], off
	global_load_dword v145, v[108:109], off
	global_load_dword v146, v[110:111], off
	global_load_dword v147, v[112:113], off
	global_load_dword v148, v[114:115], off
	global_load_dword v149, v[116:117], off
	global_load_dword v150, v[118:119], off
	s_add_i32 s14, s14, 16
	s_add_i32 s15, s15, 16
	s_add_i32 s11, s11, -16
	v_mad_u64_u32 v[86:87], s[16:17], v120, s3, v[2:3]
	s_cmp_lg_u32 s11, 0
	v_mad_u64_u32 v[90:91], s[16:17], v85, s3, v[2:3]
	v_mad_u64_u32 v[92:93], s[16:17], v122, s3, v[2:3]
	v_mad_u64_u32 v[94:95], s[16:17], v121, s3, v[2:3]
	v_mad_u64_u32 v[96:97], s[16:17], v124, s3, v[2:3]
	v_mad_u64_u32 v[98:99], s[16:17], v123, s3, v[2:3]
	v_mad_u64_u32 v[100:101], s[16:17], v126, s3, v[2:3]
	v_mad_u64_u32 v[102:103], s[16:17], v125, s3, v[2:3]
	v_mad_u64_u32 v[104:105], s[16:17], v128, s3, v[2:3]
	v_mad_u64_u32 v[106:107], s[16:17], v127, s3, v[2:3]
	v_mad_u64_u32 v[108:109], s[16:17], v130, s3, v[2:3]
	v_mad_u64_u32 v[110:111], s[16:17], v129, s3, v[2:3]
	v_mad_u64_u32 v[112:113], s[16:17], v132, s3, v[2:3]
	v_mad_u64_u32 v[114:115], s[16:17], v131, s3, v[2:3]
	v_mad_u64_u32 v[116:117], s[16:17], v134, s3, v[2:3]
	v_mad_u64_u32 v[118:119], s[16:17], v133, s3, v[2:3]
	s_waitcnt vmcnt(31)
	ds_write_b32 v12, v61
	s_waitcnt vmcnt(30)
	ds_write_b32 v16, v62
	s_waitcnt vmcnt(29)
	ds_write_b32 v18, v63
	s_waitcnt vmcnt(28)
	ds_write_b32 v20, v64
	s_waitcnt vmcnt(27)
	ds_write_b32 v22, v65
	s_waitcnt vmcnt(26)
	ds_write_b32 v24, v66
	s_waitcnt vmcnt(25)
	ds_write_b32 v26, v67
	s_waitcnt vmcnt(24)
	ds_write_b32 v28, v68
	s_waitcnt vmcnt(23)
	ds_write_b32 v30, v69
	s_waitcnt vmcnt(22)
	ds_write_b32 v32, v70
	s_waitcnt vmcnt(21)
	ds_write_b32 v34, v71
	s_waitcnt vmcnt(20)
	ds_write_b32 v36, v72
	s_waitcnt vmcnt(19)
	ds_write_b32 v38, v73
	s_waitcnt vmcnt(18)
	ds_write_b32 v40, v74
	s_waitcnt vmcnt(17)
	ds_write_b32 v42, v75
	s_waitcnt vmcnt(16)
	ds_write_b32 v44, v76
	s_waitcnt vmcnt(15)
	ds_write_b32 v86, v135
	s_waitcnt vmcnt(14)
	ds_write_b32 v90, v136
	s_waitcnt vmcnt(13)
	ds_write_b32 v92, v137
	s_waitcnt vmcnt(12)
	ds_write_b32 v94, v138
	s_waitcnt vmcnt(11)
	ds_write_b32 v96, v139
	s_waitcnt vmcnt(10)
	ds_write_b32 v98, v140
	s_waitcnt vmcnt(9)
	ds_write_b32 v100, v141
	s_waitcnt vmcnt(8)
	ds_write_b32 v102, v142
	s_waitcnt vmcnt(7)
	ds_write_b32 v104, v143
	s_waitcnt vmcnt(6)
	ds_write_b32 v106, v144
	s_waitcnt vmcnt(5)
	ds_write_b32 v108, v145
	s_waitcnt vmcnt(4)
	ds_write_b32 v110, v146
	s_waitcnt vmcnt(3)
	ds_write_b32 v112, v147
	s_waitcnt vmcnt(2)
	ds_write_b32 v114, v148
	s_waitcnt vmcnt(1)
	ds_write_b32 v116, v149
	s_waitcnt vmcnt(0)
	ds_write_b32 v118, v150
	s_waitcnt lgkmcnt(0)
	ds_read2_b32 v[8:9], v3 offset1:16
	ds_read2_b32 v[20:21], v3 offset0:33 offset1:49
	ds_read2_b32 v[22:23], v3 offset0:66 offset1:82
	ds_read2_b32 v[24:25], v3 offset0:99 offset1:115
	ds_read2_b32 v[28:29], v3 offset0:132 offset1:148
	ds_read2_b32 v[32:33], v3 offset0:165 offset1:181
	ds_read2_b32 v[34:35], v3 offset0:198 offset1:214
	ds_read2_b32 v[36:37], v3 offset0:231 offset1:247
	s_ashr_i32 s11, s10, 31
	s_waitcnt lgkmcnt(7)
	v_mul_f32_e32 v8, 0x44fe0000, v8
	v_med3_f32 v16, v8, s12, v10
	s_waitcnt lgkmcnt(6)
	v_mul_f32_e32 v8, 0x44fe0000, v20
	v_med3_f32 v18, v8, s12, v10
	s_waitcnt lgkmcnt(5)
	v_mul_f32_e32 v8, 0x44fe0000, v22
	v_med3_f32 v26, v8, s12, v10
	s_waitcnt lgkmcnt(4)
	v_mul_f32_e32 v8, 0x44fe0000, v24
	v_med3_f32 v30, v8, s12, v10
	s_waitcnt lgkmcnt(3)
	v_mul_f32_e32 v8, 0x44fe0000, v28
	v_med3_f32 v17, v8, s12, v10
	s_waitcnt lgkmcnt(2)
	v_mul_f32_e32 v8, 0x44fe0000, v32
	v_med3_f32 v19, v8, s12, v10
	s_waitcnt lgkmcnt(1)
	v_mul_f32_e32 v8, 0x44fe0000, v34
	v_med3_f32 v27, v8, s12, v10
	s_waitcnt lgkmcnt(0)
	v_mul_f32_e32 v8, 0x44fe0000, v36
	v_med3_f32 v31, v8, s12, v10
	v_pk_add_f32 v[18:19], v[18:19], s[0:1] op_sel_hi:[1,0]
	v_pk_add_f32 v[30:31], v[30:31], s[0:1] op_sel_hi:[1,0]
	v_pk_add_f32 v[16:17], v[16:17], s[0:1] op_sel_hi:[1,0]
	v_pk_add_f32 v[26:27], v[26:27], s[0:1] op_sel_hi:[1,0]
	v_lshlrev_b32_e32 v8, 8, v19
	v_lshlrev_b32_e32 v20, 24, v31
	v_lshlrev_b32_e32 v11, 8, v18
	v_and_b32_e32 v8, 0xff00, v8
	v_lshlrev_b32_e32 v18, 16, v27
	v_or_b32_sdwa v17, v20, v17 dst_sel:DWORD dst_unused:UNUSED_PAD src0_sel:DWORD src1_sel:BYTE_0
	v_and_b32_e32 v18, 0xff0000, v18
	v_or_b32_e32 v8, v17, v8
	v_or_b32_e32 v17, v8, v18
	v_add_u32_e32 v8, 0x400, v3
	v_lshlrev_b32_e32 v19, 16, v26
	v_lshlrev_b32_e32 v22, 24, v30
	ds_read2_b32 v[26:27], v8 offset0:8 offset1:24
	ds_read2_b32 v[30:31], v8 offset0:41 offset1:57
	ds_read2_b32 v[38:39], v8 offset0:74 offset1:90
	ds_read2_b32 v[40:41], v8 offset0:107 offset1:123
	ds_read2_b32 v[46:47], v8 offset0:140 offset1:156
	v_and_b32_e32 v11, 0xff00, v11
	v_or_b32_sdwa v16, v22, v16 dst_sel:DWORD dst_unused:UNUSED_PAD src0_sel:DWORD src1_sel:BYTE_0
	ds_read2_b32 v[50:51], v8 offset0:173 offset1:189
	ds_read2_b32 v[52:53], v8 offset0:206 offset1:222
	ds_read2_b32 v[54:55], v8 offset0:239 offset1:255
	v_and_b32_e32 v19, 0xff0000, v19
	v_or_b32_e32 v11, v16, v11
	v_or_b32_e32 v16, v11, v19
	s_waitcnt lgkmcnt(7)
; #define LAS __attribute__((address_space(3)))
; __device__ __forceinline__ unsigned pk4_f8(float a, float b, float c, float d) { int w = __builtin_amdgcn_cvt_pk_fp8_f32(a, b, 0, false); w = __builtin_amdgcn_cvt_pk_fp8_f32(c, d, w, true); return (unsigned)w; }
; #define LDS_WAIT() asm volatile("s_waitcnt lgkmcnt(0)" ::: "memory")
;     ...
;         for (int j = 0; j < 2; ++j) { const int n = (lane >> 2) + 16 * j; const LAS float* sp = scr + (16 * c) * 33 + n;
;             u32x4 o;
;             if (QI8) { o.x = pk4_i8(sp[0 * 33], sp[1 * 33], sp[2 * 33], sp[3 * 33], scl); o.y = pk4_i8(sp[4 * 33], sp[5 * 33], sp[6 * 33], sp[7 * 33], scl);
;                 o.z = pk4_i8(sp[8 * 33], sp[9 * 33], sp[10 * 33], sp[11 * 33], scl); o.w = pk4_i8(sp[12 * 33], sp[13 * 33], sp[14 * 33], sp[15 * 33], scl); }
;             else {
;             o.x = pk4_f8(sp[0 * 33] * scl, sp[1 * 33] * scl, sp[2 * 33] * scl, sp[3 * 33] * scl); o.y = pk4_f8(sp[4 * 33] * scl, sp[5 * 33] * scl, sp[6 * 33] * scl, sp[7 * 33] * scl);
;             o.z = pk4_f8(sp[8 * 33] * scl, sp[9 * 33] * scl, sp[10 * 33] * scl, sp[11 * 33] * scl); o.w = pk4_f8(sp[12 * 33] * scl, sp[13 * 33] * scl, sp[14 * 33] * scl, sp[15 * 33] * scl); }
;             *(u32x4*)(WT + (size_t)(dr0 + n) * K + k0 + 16 * c) = o; }
;         LDS_WAIT(); asm volatile("" ::: "memory"); }
	v_mul_f32_e32 v11, 0x44fe0000, v26
	s_waitcnt lgkmcnt(3)
	v_mul_f32_e32 v8, 0x44fe0000, v46
	v_med3_f32 v18, v11, s12, v10
	v_mul_f32_e32 v11, 0x44fe0000, v30
	v_med3_f32 v19, v8, s12, v10
	s_waitcnt lgkmcnt(2)
	v_mul_f32_e32 v8, 0x44fe0000, v50
	v_med3_f32 v42, v11, s12, v10
	v_mul_f32_e32 v11, 0x44fe0000, v38
	v_med3_f32 v43, v8, s12, v10
	s_waitcnt lgkmcnt(1)
	v_mul_f32_e32 v8, 0x44fe0000, v52
	v_med3_f32 v44, v11, s12, v10
	v_mul_f32_e32 v11, 0x44fe0000, v40
	v_med3_f32 v45, v8, s12, v10
	s_waitcnt lgkmcnt(0)
	v_mul_f32_e32 v8, 0x44fe0000, v54
	v_med3_f32 v48, v11, s12, v10
	v_med3_f32 v49, v8, s12, v10
	v_pk_add_f32 v[42:43], v[42:43], s[0:1] op_sel_hi:[1,0]
	v_pk_add_f32 v[48:49], v[48:49], s[0:1] op_sel_hi:[1,0]
	v_pk_add_f32 v[18:19], v[18:19], s[0:1] op_sel_hi:[1,0]
	v_pk_add_f32 v[44:45], v[44:45], s[0:1] op_sel_hi:[1,0]
	v_lshlrev_b32_e32 v8, 8, v43
	v_lshlrev_b32_e32 v11, 8, v42
	v_lshlrev_b32_e32 v24, 24, v49
	v_lshlrev_b32_e32 v26, 24, v48
	v_or_b32_e32 v42, s8, v163
	v_and_b32_e32 v8, 0xff00, v8
	v_and_b32_e32 v11, 0xff00, v11
	v_lshlrev_b32_e32 v20, 16, v45
	v_lshlrev_b32_e32 v22, 16, v44
	v_or_b32_sdwa v19, v24, v19 dst_sel:DWORD dst_unused:UNUSED_PAD src0_sel:DWORD src1_sel:BYTE_0
	v_or_b32_sdwa v18, v26, v18 dst_sel:DWORD dst_unused:UNUSED_PAD src0_sel:DWORD src1_sel:BYTE_0
	v_ashrrev_i32_e32 v43, 31, v42
	v_lshl_add_u64 v[12:13], v[4:5], 0, s[10:11]
	v_and_b32_e32 v20, 0xff0000, v20
	v_and_b32_e32 v22, 0xff0000, v22
	v_or_b32_e32 v8, v19, v8
	v_or_b32_e32 v11, v18, v11
	v_lshlrev_b64 v[42:43], 12, v[42:43]
	v_or_b32_e32 v19, v8, v20
	v_or_b32_e32 v18, v11, v22
	v_lshl_add_u64 v[42:43], v[12:13], 0, v[42:43]
	v_mul_f32_e32 v8, 0x44fe0000, v9
	v_mul_f32_e32 v9, 0x44fe0000, v21
	v_mul_f32_e32 v11, 0x44fe0000, v33
	global_store_dwordx4 v[42:43], v[16:19], off
	v_med3_f32 v8, v8, s12, v10
	s_add_i32 s13, s13, s92
	v_med3_f32 v16, v9, s12, v10
	v_mul_f32_e32 v9, 0x44fe0000, v23
	v_med3_f32 v17, v11, s12, v10
	v_mul_f32_e32 v11, 0x44fe0000, v35
	v_med3_f32 v18, v9, s12, v10
	v_mul_f32_e32 v9, 0x44fe0000, v25
	v_med3_f32 v19, v11, s12, v10
	v_mul_f32_e32 v11, 0x44fe0000, v37
	v_med3_f32 v20, v9, s12, v10
	v_mul_f32_e32 v9, 0x44fe0000, v29
	v_med3_f32 v21, v11, s12, v10
	v_med3_f32 v9, v9, s12, v10
	v_pk_add_f32 v[16:17], v[16:17], s[0:1] op_sel_hi:[1,0]
	v_pk_add_f32 v[18:19], v[18:19], s[0:1] op_sel_hi:[1,0]
	v_pk_add_f32 v[20:21], v[20:21], s[0:1] op_sel_hi:[1,0]
	v_pk_add_f32 v[8:9], v[8:9], s[0:1] op_sel_hi:[1,0]
	v_lshlrev_b32_e32 v11, 8, v17
	v_lshlrev_b32_e32 v17, 16, v19
	v_lshlrev_b32_e32 v19, 24, v21
	v_lshlrev_b32_e32 v16, 8, v16
	v_and_b32_e32 v11, 0xff00, v11
	v_lshlrev_b32_e32 v20, 24, v20
	v_or_b32_sdwa v9, v19, v9 dst_sel:DWORD dst_unused:UNUSED_PAD src0_sel:DWORD src1_sel:BYTE_0
	v_and_b32_e32 v16, 0xff00, v16
	v_lshlrev_b32_e32 v18, 16, v18
	v_and_b32_e32 v17, 0xff0000, v17
	v_or_b32_sdwa v8, v20, v8 dst_sel:DWORD dst_unused:UNUSED_PAD src0_sel:DWORD src1_sel:BYTE_0
	v_or_b32_e32 v9, v9, v11
	v_and_b32_e32 v18, 0xff0000, v18
	v_or_b32_e32 v8, v8, v16
	v_or_b32_e32 v17, v9, v17
	v_mul_f32_e32 v9, 0x44fe0000, v31
	v_mul_f32_e32 v11, 0x44fe0000, v51
	v_or_b32_e32 v16, v8, v18
	v_med3_f32 v18, v9, s12, v10
	v_mul_f32_e32 v9, 0x44fe0000, v39
	v_med3_f32 v19, v11, s12, v10
	v_mul_f32_e32 v11, 0x44fe0000, v53
	v_med3_f32 v20, v9, s12, v10
	v_mul_f32_e32 v9, 0x44fe0000, v41
	v_med3_f32 v21, v11, s12, v10
	v_mul_f32_e32 v11, 0x44fe0000, v55
	v_mul_f32_e32 v8, 0x44fe0000, v27
	v_med3_f32 v22, v9, s12, v10
	v_mul_f32_e32 v9, 0x44fe0000, v47
	v_med3_f32 v23, v11, s12, v10
	v_med3_f32 v8, v8, s12, v10
	v_med3_f32 v9, v9, s12, v10
	v_pk_add_f32 v[18:19], v[18:19], s[0:1] op_sel_hi:[1,0]
	v_pk_add_f32 v[22:23], v[22:23], s[0:1] op_sel_hi:[1,0]
	v_pk_add_f32 v[8:9], v[8:9], s[0:1] op_sel_hi:[1,0]
	v_pk_add_f32 v[20:21], v[20:21], s[0:1] op_sel_hi:[1,0]
	v_lshlrev_b32_e32 v18, 8, v18
	v_lshlrev_b32_e32 v22, 24, v22
	v_lshlrev_b32_e32 v11, 8, v19
	v_and_b32_e32 v18, 0xff00, v18
	v_lshlrev_b32_e32 v19, 16, v21
	v_lshlrev_b32_e32 v20, 16, v20
	v_lshlrev_b32_e32 v21, 24, v23
	v_or_b32_sdwa v8, v22, v8 dst_sel:DWORD dst_unused:UNUSED_PAD src0_sel:DWORD src1_sel:BYTE_0
	v_and_b32_e32 v11, 0xff00, v11
	v_and_b32_e32 v20, 0xff0000, v20
	v_or_b32_sdwa v9, v21, v9 dst_sel:DWORD dst_unused:UNUSED_PAD src0_sel:DWORD src1_sel:BYTE_0
	v_or_b32_e32 v8, v8, v18
	v_and_b32_e32 v19, 0xff0000, v19
	v_or_b32_e32 v9, v9, v11
	v_or_b32_e32 v18, v8, v20
	v_or_b32_e32 v8, s8, v15
	v_or_b32_e32 v19, v9, v19
	v_ashrrev_i32_e32 v9, 31, v8
	v_lshlrev_b64 v[8:9], 12, v[8:9]
	v_lshl_add_u64 v[8:9], v[12:13], 0, v[8:9]
	global_store_dwordx4 v[8:9], v[16:19], off
	s_waitcnt lgkmcnt(0)
	s_cmpk_lt_i32 s13, 0x1000
	s_cbranch_scc1 .LBB0_52

; template <int MAP>
; __device__ __forceinline__ void transpose_item(const float* W, int K, int N, int ldw, bf16* WT, LAS float* scr, int item, int lane) {
;     ...
;     for (int i = 0; i < 32; ++i) { const int kk = 2 * i + (lane >> 5); scr[kk * 33 + (lane & 31)] = W[(size_t)(k0 + kk) * ldw + n0 + (lane & 31)]; }
.LBB0_61:
	s_lshl_b32 s11, s5, 1
	s_lshl_b32 s12, s10, 1
	v_or_b32_e32 v5, s11, v1
	v_or_b32_e32 v48, s12, v162
	s_add_i32 s13, s11, 4
	s_add_i32 s14, s12, 4
	s_add_i32 s15, s11, 8
	s_add_i32 s16, s12, 8
	s_add_i32 s17, s11, 12
	s_add_i32 s18, s12, 12
	s_add_i32 s19, s11, 16
	s_add_i32 s20, s12, 16
	s_add_i32 s21, s11, 20
	s_add_i32 s22, s12, 20
	s_add_i32 s23, s11, 24
	s_add_i32 s24, s12, 24
	s_add_i32 s11, s11, 28
	s_add_i32 s12, s12, 28
	v_add_u32_e32 v18, s4, v48
	v_or_b32_e32 v49, s13, v1
	v_or_b32_e32 v50, s14, v162
	v_or_b32_e32 v51, s15, v1
	v_or_b32_e32 v52, s16, v162
	v_or_b32_e32 v53, s17, v1
	v_or_b32_e32 v54, s18, v162
	v_or_b32_e32 v55, s19, v1
	v_or_b32_e32 v56, s20, v162
	v_or_b32_e32 v57, s21, v1
	v_or_b32_e32 v58, s22, v162
	v_or_b32_e32 v59, s23, v1
	v_or_b32_e32 v60, s24, v162
	v_or_b32_e32 v61, s11, v1
	v_or_b32_e32 v62, s12, v162
	v_add_u32_e32 v16, s1, v5
	v_ashrrev_i32_e32 v19, 31, v18
	v_add_u32_e32 v20, s1, v49
	v_add_u32_e32 v22, s4, v50
	v_add_u32_e32 v24, s1, v51
	v_add_u32_e32 v26, s4, v52
	v_add_u32_e32 v28, s1, v53
	v_add_u32_e32 v30, s4, v54
	v_add_u32_e32 v32, s1, v55
	v_add_u32_e32 v34, s4, v56
	v_add_u32_e32 v36, s1, v57
	v_add_u32_e32 v38, s4, v58
	v_add_u32_e32 v40, s1, v59
	v_add_u32_e32 v42, s4, v60
	v_add_u32_e32 v44, s1, v61
	v_add_u32_e32 v46, s4, v62
	v_ashrrev_i32_e32 v17, 31, v16
	v_lshlrev_b64 v[18:19], 14, v[18:19]
	v_ashrrev_i32_e32 v23, 31, v22
	v_ashrrev_i32_e32 v21, 31, v20
	v_ashrrev_i32_e32 v27, 31, v26
	v_ashrrev_i32_e32 v25, 31, v24
	v_ashrrev_i32_e32 v31, 31, v30
	v_ashrrev_i32_e32 v29, 31, v28
	v_ashrrev_i32_e32 v35, 31, v34
	v_ashrrev_i32_e32 v33, 31, v32
	v_ashrrev_i32_e32 v39, 31, v38
	v_ashrrev_i32_e32 v37, 31, v36
	v_ashrrev_i32_e32 v43, 31, v42
	v_ashrrev_i32_e32 v41, 31, v40
	v_ashrrev_i32_e32 v47, 31, v46
	v_ashrrev_i32_e32 v45, 31, v44
	v_lshlrev_b64 v[16:17], 14, v[16:17]
	v_lshl_add_u64 v[18:19], v[10:11], 0, v[18:19]
	v_lshlrev_b64 v[20:21], 14, v[20:21]
	v_lshlrev_b64 v[22:23], 14, v[22:23]
	v_lshlrev_b64 v[24:25], 14, v[24:25]
	v_lshlrev_b64 v[26:27], 14, v[26:27]
	v_lshlrev_b64 v[28:29], 14, v[28:29]
	v_lshlrev_b64 v[30:31], 14, v[30:31]
	v_lshlrev_b64 v[32:33], 14, v[32:33]
	v_lshlrev_b64 v[34:35], 14, v[34:35]
	v_lshlrev_b64 v[36:37], 14, v[36:37]
	v_lshlrev_b64 v[38:39], 14, v[38:39]
	v_lshlrev_b64 v[40:41], 14, v[40:41]
	v_lshlrev_b64 v[42:43], 14, v[42:43]
	v_lshlrev_b64 v[44:45], 14, v[44:45]
	v_lshlrev_b64 v[46:47], 14, v[46:47]
	v_lshl_add_u64 v[16:17], v[10:11], 0, v[16:17]
	v_lshl_add_u64 v[22:23], v[10:11], 0, v[22:23]
	v_lshl_add_u64 v[20:21], v[10:11], 0, v[20:21]
	v_lshl_add_u64 v[26:27], v[10:11], 0, v[26:27]
	v_lshl_add_u64 v[24:25], v[10:11], 0, v[24:25]
	v_lshl_add_u64 v[30:31], v[10:11], 0, v[30:31]
	v_lshl_add_u64 v[28:29], v[10:11], 0, v[28:29]
	v_lshl_add_u64 v[34:35], v[10:11], 0, v[34:35]
	v_lshl_add_u64 v[32:33], v[10:11], 0, v[32:33]
	v_lshl_add_u64 v[38:39], v[10:11], 0, v[38:39]
	v_lshl_add_u64 v[36:37], v[10:11], 0, v[36:37]
	v_lshl_add_u64 v[42:43], v[10:11], 0, v[42:43]
	v_lshl_add_u64 v[40:41], v[10:11], 0, v[40:41]
	v_lshl_add_u64 v[46:47], v[10:11], 0, v[46:47]
	v_lshl_add_u64 v[44:45], v[10:11], 0, v[44:45]
	global_load_dword v63, v[18:19], off
	global_load_dword v64, v[16:17], off
	global_load_dword v65, v[22:23], off
	global_load_dword v66, v[20:21], off
	global_load_dword v67, v[26:27], off
	global_load_dword v68, v[24:25], off
	global_load_dword v69, v[30:31], off
	global_load_dword v70, v[28:29], off
	global_load_dword v71, v[34:35], off
	global_load_dword v72, v[32:33], off
	global_load_dword v73, v[38:39], off
	global_load_dword v74, v[36:37], off
	global_load_dword v75, v[42:43], off
	global_load_dword v76, v[40:41], off
	global_load_dword v77, v[46:47], off
	global_load_dword v78, v[44:45], off
	s_add_i32 s10, s10, 16
	s_add_i32 s5, s5, 16
	s_add_i32 s9, s9, -16
	v_mad_u64_u32 v[16:17], s[12:13], v48, s3, v[2:3]
	s_cmp_lg_u32 s9, 0
	v_mad_u64_u32 v[18:19], s[12:13], v5, s3, v[2:3]
	v_mad_u64_u32 v[20:21], s[12:13], v50, s3, v[2:3]
	v_mad_u64_u32 v[22:23], s[12:13], v49, s3, v[2:3]
	v_mad_u64_u32 v[24:25], s[12:13], v52, s3, v[2:3]
	v_mad_u64_u32 v[26:27], s[12:13], v51, s3, v[2:3]
	v_mad_u64_u32 v[28:29], s[12:13], v54, s3, v[2:3]
	v_mad_u64_u32 v[30:31], s[12:13], v53, s3, v[2:3]
	v_mad_u64_u32 v[32:33], s[12:13], v56, s3, v[2:3]
	v_mad_u64_u32 v[34:35], s[12:13], v55, s3, v[2:3]
	v_mad_u64_u32 v[36:37], s[12:13], v58, s3, v[2:3]
	v_mad_u64_u32 v[38:39], s[12:13], v57, s3, v[2:3]
	v_mad_u64_u32 v[40:41], s[12:13], v60, s3, v[2:3]
	v_mad_u64_u32 v[42:43], s[12:13], v59, s3, v[2:3]
	v_mad_u64_u32 v[44:45], s[12:13], v62, s3, v[2:3]
	v_mad_u64_u32 v[46:47], s[12:13], v61, s3, v[2:3]
	s_lshl_b32 s11, s5, 1
	s_lshl_b32 s12, s10, 1
	v_or_b32_e32 v85, s11, v1
	v_or_b32_e32 v128, s12, v162
	s_add_i32 s13, s11, 4
	s_add_i32 s14, s12, 4
	s_add_i32 s15, s11, 8
	s_add_i32 s16, s12, 8
	s_add_i32 s17, s11, 12
	s_add_i32 s18, s12, 12
	s_add_i32 s19, s11, 16
	s_add_i32 s20, s12, 16
	s_add_i32 s21, s11, 20
	s_add_i32 s22, s12, 20
	s_add_i32 s23, s11, 24
	s_add_i32 s24, s12, 24
	s_add_i32 s11, s11, 28
	s_add_i32 s12, s12, 28
	v_add_u32_e32 v98, s4, v128
	v_or_b32_e32 v129, s13, v1
	v_or_b32_e32 v130, s14, v162
	v_or_b32_e32 v131, s15, v1
	v_or_b32_e32 v132, s16, v162
	v_or_b32_e32 v133, s17, v1
	v_or_b32_e32 v134, s18, v162
	v_or_b32_e32 v135, s19, v1
	v_or_b32_e32 v136, s20, v162
	v_or_b32_e32 v137, s21, v1
	v_or_b32_e32 v138, s22, v162
	v_or_b32_e32 v139, s23, v1
	v_or_b32_e32 v140, s24, v162
	v_or_b32_e32 v141, s11, v1
	v_or_b32_e32 v142, s12, v162
	v_add_u32_e32 v96, s1, v85
	v_ashrrev_i32_e32 v99, 31, v98
	v_add_u32_e32 v100, s1, v129
; template <int MAP>
; __device__ __forceinline__ void transpose_item(const float* W, int K, int N, int ldw, bf16* WT, LAS float* scr, int item, int lane) {
;     ...
;     for (int i = 0; i < 32; ++i) { const int kk = 2 * i + (lane >> 5); scr[kk * 33 + (lane & 31)] = W[(size_t)(k0 + kk) * ldw + n0 + (lane & 31)]; }
	v_add_u32_e32 v102, s4, v130
	v_add_u32_e32 v104, s1, v131
	v_add_u32_e32 v106, s4, v132
	v_add_u32_e32 v108, s1, v133
	v_add_u32_e32 v110, s4, v134
	v_add_u32_e32 v112, s1, v135
	v_add_u32_e32 v114, s4, v136
	v_add_u32_e32 v116, s1, v137
	v_add_u32_e32 v118, s4, v138
	v_add_u32_e32 v120, s1, v139
	v_add_u32_e32 v122, s4, v140
	v_add_u32_e32 v124, s1, v141
	v_add_u32_e32 v126, s4, v142
	v_ashrrev_i32_e32 v97, 31, v96
	v_lshlrev_b64 v[98:99], 14, v[98:99]
	v_ashrrev_i32_e32 v103, 31, v102
	v_ashrrev_i32_e32 v101, 31, v100
	v_ashrrev_i32_e32 v107, 31, v106
	v_ashrrev_i32_e32 v105, 31, v104
	v_ashrrev_i32_e32 v111, 31, v110
	v_ashrrev_i32_e32 v109, 31, v108
	v_ashrrev_i32_e32 v115, 31, v114
	v_ashrrev_i32_e32 v113, 31, v112
	v_ashrrev_i32_e32 v119, 31, v118
	v_ashrrev_i32_e32 v117, 31, v116
	v_ashrrev_i32_e32 v123, 31, v122
	v_ashrrev_i32_e32 v121, 31, v120
	v_ashrrev_i32_e32 v127, 31, v126
	v_ashrrev_i32_e32 v125, 31, v124
	v_lshlrev_b64 v[96:97], 14, v[96:97]
	v_lshl_add_u64 v[98:99], v[10:11], 0, v[98:99]
	v_lshlrev_b64 v[100:101], 14, v[100:101]
	v_lshlrev_b64 v[102:103], 14, v[102:103]
	v_lshlrev_b64 v[104:105], 14, v[104:105]
	v_lshlrev_b64 v[106:107], 14, v[106:107]
	v_lshlrev_b64 v[108:109], 14, v[108:109]
	v_lshlrev_b64 v[110:111], 14, v[110:111]
	v_lshlrev_b64 v[112:113], 14, v[112:113]
	v_lshlrev_b64 v[114:115], 14, v[114:115]
	v_lshlrev_b64 v[116:117], 14, v[116:117]
	v_lshlrev_b64 v[118:119], 14, v[118:119]
	v_lshlrev_b64 v[120:121], 14, v[120:121]
	v_lshlrev_b64 v[122:123], 14, v[122:123]
	v_lshlrev_b64 v[124:125], 14, v[124:125]
	v_lshlrev_b64 v[126:127], 14, v[126:127]
	v_lshl_add_u64 v[96:97], v[10:11], 0, v[96:97]
	v_lshl_add_u64 v[102:103], v[10:11], 0, v[102:103]
	v_lshl_add_u64 v[100:101], v[10:11], 0, v[100:101]
	v_lshl_add_u64 v[106:107], v[10:11], 0, v[106:107]
	v_lshl_add_u64 v[104:105], v[10:11], 0, v[104:105]
	v_lshl_add_u64 v[110:111], v[10:11], 0, v[110:111]
	v_lshl_add_u64 v[108:109], v[10:11], 0, v[108:109]
	v_lshl_add_u64 v[114:115], v[10:11], 0, v[114:115]
	v_lshl_add_u64 v[112:113], v[10:11], 0, v[112:113]
	v_lshl_add_u64 v[118:119], v[10:11], 0, v[118:119]
	v_lshl_add_u64 v[116:117], v[10:11], 0, v[116:117]
	v_lshl_add_u64 v[122:123], v[10:11], 0, v[122:123]
	v_lshl_add_u64 v[120:121], v[10:11], 0, v[120:121]
	v_lshl_add_u64 v[126:127], v[10:11], 0, v[126:127]
	v_lshl_add_u64 v[124:125], v[10:11], 0, v[124:125]
	global_load_dword v143, v[98:99], off
	global_load_dword v144, v[96:97], off
	global_load_dword v145, v[102:103], off
	global_load_dword v146, v[100:101], off
	global_load_dword v147, v[106:107], off
	global_load_dword v148, v[104:105], off
	global_load_dword v149, v[110:111], off
	global_load_dword v150, v[108:109], off
	global_load_dword v151, v[114:115], off
	global_load_dword v152, v[112:113], off
	global_load_dword v153, v[118:119], off
	global_load_dword v154, v[116:117], off
	global_load_dword v155, v[122:123], off
	global_load_dword v156, v[120:121], off
	global_load_dword v157, v[126:127], off
	global_load_dword v158, v[124:125], off
	s_add_i32 s10, s10, 16
	s_add_i32 s5, s5, 16
	s_add_i32 s9, s9, -16
	v_mad_u64_u32 v[96:97], s[12:13], v128, s3, v[2:3]
	s_cmp_lg_u32 s9, 0
	v_mad_u64_u32 v[98:99], s[12:13], v85, s3, v[2:3]
	v_mad_u64_u32 v[100:101], s[12:13], v130, s3, v[2:3]
	v_mad_u64_u32 v[102:103], s[12:13], v129, s3, v[2:3]
	v_mad_u64_u32 v[104:105], s[12:13], v132, s3, v[2:3]
	v_mad_u64_u32 v[106:107], s[12:13], v131, s3, v[2:3]
	v_mad_u64_u32 v[108:109], s[12:13], v134, s3, v[2:3]
	v_mad_u64_u32 v[110:111], s[12:13], v133, s3, v[2:3]
	v_mad_u64_u32 v[112:113], s[12:13], v136, s3, v[2:3]
	v_mad_u64_u32 v[114:115], s[12:13], v135, s3, v[2:3]
	v_mad_u64_u32 v[116:117], s[12:13], v138, s3, v[2:3]
	v_mad_u64_u32 v[118:119], s[12:13], v137, s3, v[2:3]
	v_mad_u64_u32 v[120:121], s[12:13], v140, s3, v[2:3]
	v_mad_u64_u32 v[122:123], s[12:13], v139, s3, v[2:3]
	v_mad_u64_u32 v[124:125], s[12:13], v142, s3, v[2:3]
	v_mad_u64_u32 v[126:127], s[12:13], v141, s3, v[2:3]
	s_waitcnt vmcnt(31)
	ds_write_b32 v16, v63
	s_waitcnt vmcnt(30)
	ds_write_b32 v18, v64
	s_waitcnt vmcnt(29)
; #define LAS __attribute__((address_space(3)))
; __device__ __forceinline__ unsigned pk2(float lo, float hi) { return cvt_pk_bf16(lo, hi); }
; #define LDS_WAIT() asm volatile("s_waitcnt lgkmcnt(0)" ::: "memory")
; template <int MAP>
; __device__ __forceinline__ void transpose_item(const float* W, int K, int N, int ldw, bf16* WT, LAS float* scr, int item, int lane) {
;     ...
;     for (int i = 0; i < 32; ++i) { const int kk = 2 * i + (lane >> 5); scr[kk * 33 + (lane & 31)] = W[(size_t)(k0 + kk) * ldw + n0 + (lane & 31)]; }
;     LDS_WAIT(); asm volatile("" ::: "memory");
;     const int c = lane & 7;
; #pragma unroll
;     for (int j = 0; j < 4; ++j) { const int n = (lane >> 3) + 8 * j; const LAS float* s = scr + (8 * c) * 33 + n;
;         u32x4 o; o.x = pk2(s[0 * 33], s[1 * 33]); o.y = pk2(s[2 * 33], s[3 * 33]); o.z = pk2(s[4 * 33], s[5 * 33]); o.w = pk2(s[6 * 33], s[7 * 33]);
;         *(u32x4*)(WT + (size_t)(dr0 + n) * K + k0 + 8 * c) = o; }
	ds_write_b32 v20, v65
	s_waitcnt vmcnt(28)
	ds_write_b32 v22, v66
	s_waitcnt vmcnt(27)
	ds_write_b32 v24, v67
	s_waitcnt vmcnt(26)
	ds_write_b32 v26, v68
	s_waitcnt vmcnt(25)
	ds_write_b32 v28, v69
	s_waitcnt vmcnt(24)
	ds_write_b32 v30, v70
	s_waitcnt vmcnt(23)
	ds_write_b32 v32, v71
	s_waitcnt vmcnt(22)
	ds_write_b32 v34, v72
	s_waitcnt vmcnt(21)
	ds_write_b32 v36, v73
	s_waitcnt vmcnt(20)
	ds_write_b32 v38, v74
	s_waitcnt vmcnt(19)
	ds_write_b32 v40, v75
	s_waitcnt vmcnt(18)
	ds_write_b32 v42, v76
	s_waitcnt vmcnt(17)
	ds_write_b32 v44, v77
	s_waitcnt vmcnt(16)
	ds_write_b32 v46, v78
	s_waitcnt vmcnt(15)
	ds_write_b32 v96, v143
	s_waitcnt vmcnt(14)
	ds_write_b32 v98, v144
	s_waitcnt vmcnt(13)
	ds_write_b32 v100, v145
	s_waitcnt vmcnt(12)
	ds_write_b32 v102, v146
	s_waitcnt vmcnt(11)
	ds_write_b32 v104, v147
	s_waitcnt vmcnt(10)
	ds_write_b32 v106, v148
	s_waitcnt vmcnt(9)
	ds_write_b32 v108, v149
	s_waitcnt vmcnt(8)
	ds_write_b32 v110, v150
	s_waitcnt vmcnt(7)
	ds_write_b32 v112, v151
	s_waitcnt vmcnt(6)
	ds_write_b32 v114, v152
	s_waitcnt vmcnt(5)
	ds_write_b32 v116, v153
	s_waitcnt vmcnt(4)
	ds_write_b32 v118, v154
	s_waitcnt vmcnt(3)
	ds_write_b32 v120, v155
	s_waitcnt vmcnt(2)
	ds_write_b32 v122, v156
	s_waitcnt vmcnt(1)
	ds_write_b32 v124, v157
	s_waitcnt vmcnt(0)
	ds_write_b32 v126, v158
	s_waitcnt lgkmcnt(0)
	ds_read2_b32 v[10:11], v3 offset0:33 offset1:41
	ds_read2_b32 v[20:21], v3 offset1:8
	ds_read2_b32 v[22:23], v3 offset0:66 offset1:74
	ds_read2_b32 v[24:25], v3 offset0:99 offset1:107
	ds_read2_b32 v[26:27], v3 offset0:132 offset1:140
	ds_read2_b32 v[28:29], v3 offset0:165 offset1:173
	ds_read2_b32 v[30:31], v3 offset0:198 offset1:206
	ds_read2_b32 v[32:33], v3 offset0:231 offset1:239
	v_or_b32_e32 v36, s0, v14
	s_ashr_i32 s5, s4, 31
	v_ashrrev_i32_e32 v37, 31, v36
	v_lshl_add_u64 v[34:35], s[4:5], 1, v[8:9]
	v_lshlrev_b64 v[36:37], 12, v[36:37]
	s_waitcnt lgkmcnt(6)
	v_cvt_pk_bf16_f32 v16, v20, v10
	s_waitcnt lgkmcnt(4)
	v_cvt_pk_bf16_f32 v17, v22, v24
	s_waitcnt lgkmcnt(2)
	v_cvt_pk_bf16_f32 v18, v26, v28
	s_waitcnt lgkmcnt(0)
	v_cvt_pk_bf16_f32 v19, v30, v32
	v_lshl_add_u64 v[36:37], v[34:35], 0, v[36:37]
	v_or_b32_e32 v10, s0, v12
	global_store_dwordx4 v[36:37], v[16:19], off
	s_add_i32 s8, s8, s92
	s_cmpk_lt_i32 s8, 0x1000
	v_cvt_pk_bf16_f32 v16, v21, v11
	v_ashrrev_i32_e32 v11, 31, v10
	v_cvt_pk_bf16_f32 v17, v23, v25
	v_cvt_pk_bf16_f32 v18, v27, v29
	v_cvt_pk_bf16_f32 v19, v31, v33
	v_lshlrev_b64 v[10:11], 12, v[10:11]
	ds_read2_b32 v[20:21], v3 offset0:49 offset1:57
	ds_read2_b32 v[22:23], v3 offset0:16 offset1:24
	ds_read2_b32 v[24:25], v3 offset0:82 offset1:90
	ds_read2_b32 v[26:27], v3 offset0:115 offset1:123
	ds_read2_b32 v[28:29], v3 offset0:148 offset1:156
	ds_read2_b32 v[30:31], v3 offset0:181 offset1:189
	ds_read2_b32 v[32:33], v3 offset0:214 offset1:222
	ds_read2_b32 v[36:37], v3 offset0:247 offset1:255
	v_lshl_add_u64 v[10:11], v[34:35], 0, v[10:11]
	global_store_dwordx4 v[10:11], v[16:19], off
	v_or_b32_e32 v10, s0, v13
	v_ashrrev_i32_e32 v11, 31, v10
	v_lshlrev_b64 v[10:11], 12, v[10:11]
	s_waitcnt lgkmcnt(6)
	v_cvt_pk_bf16_f32 v16, v22, v20
	s_waitcnt lgkmcnt(4)
	v_cvt_pk_bf16_f32 v17, v24, v26
	s_waitcnt lgkmcnt(2)
	v_cvt_pk_bf16_f32 v18, v28, v30
	s_waitcnt lgkmcnt(0)
	v_cvt_pk_bf16_f32 v19, v32, v36
	v_lshl_add_u64 v[10:11], v[34:35], 0, v[10:11]
	global_store_dwordx4 v[10:11], v[16:19], off
	v_or_b32_e32 v10, s0, v15
	v_ashrrev_i32_e32 v11, 31, v10
	v_lshlrev_b64 v[10:11], 12, v[10:11]
	v_cvt_pk_bf16_f32 v16, v23, v21
	v_cvt_pk_bf16_f32 v17, v25, v27
	v_cvt_pk_bf16_f32 v18, v29, v31
	v_cvt_pk_bf16_f32 v19, v33, v37
	v_lshl_add_u64 v[10:11], v[34:35], 0, v[10:11]
	global_store_dwordx4 v[10:11], v[16:19], off
	s_waitcnt lgkmcnt(0)
	s_cbranch_scc1 .LBB0_60
	s_load_dwordx2 s[0:1], s[74:75], 0xd0
	v_lshlrev_b32_e32 v8, 2, v164
	v_mov_b32_e32 v9, 0
	s_movk_i32 s3, 0x84
	s_mov_b32 s8, s94
	s_waitcnt lgkmcnt(0)
	v_lshl_add_u64 v[6:7], s[0:1], 0, v[8:9]
	v_lshlrev_b32_e32 v8, 1, v4
	v_lshl_add_u64 v[4:5], s[90:91], 0, v[8:9]
	s_mov_b64 s[0:1], 0x68d00000
	v_lshl_add_u64 v[4:5], v[4:5], 0, s[0:1]

; template <int MAP>
; __device__ __forceinline__ void transpose_item(const float* W, int K, int N, int ldw, bf16* WT, LAS float* scr, int item, int lane) {
;     ...
;     for (int i = 0; i < 32; ++i) { const int kk = 2 * i + (lane >> 5); scr[kk * 33 + (lane & 31)] = W[(size_t)(k0 + kk) * ldw + n0 + (lane & 31)]; }
.LBB0_65:
	s_lshl_b32 s11, s10, 1
	s_lshl_b32 s12, s9, 1
	v_or_b32_e32 v46, s11, v1
	v_or_b32_e32 v47, s12, v162
	s_add_i32 s13, s11, 4
	s_add_i32 s14, s12, 4
	s_add_i32 s15, s11, 8
	s_add_i32 s16, s12, 8
	s_add_i32 s17, s11, 12
	s_add_i32 s18, s12, 12
	s_add_i32 s19, s11, 16
	s_add_i32 s20, s12, 16
	s_add_i32 s21, s11, 20
	s_add_i32 s22, s12, 20
	s_add_i32 s23, s11, 24
	s_add_i32 s24, s12, 24
	s_add_i32 s11, s11, 28
	s_add_i32 s12, s12, 28
	v_add_u32_e32 v16, s4, v47
	v_or_b32_e32 v48, s13, v1
	v_or_b32_e32 v49, s14, v162
	v_or_b32_e32 v50, s15, v1
	v_or_b32_e32 v51, s16, v162
	v_or_b32_e32 v52, s17, v1
	v_or_b32_e32 v53, s18, v162
	v_or_b32_e32 v54, s19, v1
	v_or_b32_e32 v55, s20, v162
	v_or_b32_e32 v56, s21, v1
	v_or_b32_e32 v57, s22, v162
	v_or_b32_e32 v58, s23, v1
	v_or_b32_e32 v59, s24, v162
	v_or_b32_e32 v60, s11, v1
	v_or_b32_e32 v61, s12, v162
	v_add_u32_e32 v10, s1, v46
	v_ashrrev_i32_e32 v17, 31, v16
	v_add_u32_e32 v18, s1, v48
	v_add_u32_e32 v20, s4, v49
	v_add_u32_e32 v22, s1, v50
	v_add_u32_e32 v24, s4, v51
	v_add_u32_e32 v26, s1, v52
	v_add_u32_e32 v28, s4, v53
	v_add_u32_e32 v30, s1, v54
	v_add_u32_e32 v32, s4, v55
	v_add_u32_e32 v34, s1, v56
	v_add_u32_e32 v36, s4, v57
	v_add_u32_e32 v38, s1, v58
	v_add_u32_e32 v40, s4, v59
	v_add_u32_e32 v42, s1, v60
	v_add_u32_e32 v44, s4, v61
	v_ashrrev_i32_e32 v11, 31, v10
	v_lshlrev_b64 v[16:17], 14, v[16:17]
	v_ashrrev_i32_e32 v21, 31, v20
	v_ashrrev_i32_e32 v19, 31, v18
	v_ashrrev_i32_e32 v25, 31, v24
	v_ashrrev_i32_e32 v23, 31, v22
	v_ashrrev_i32_e32 v29, 31, v28
	v_ashrrev_i32_e32 v27, 31, v26
	v_ashrrev_i32_e32 v33, 31, v32
	v_ashrrev_i32_e32 v31, 31, v30
	v_ashrrev_i32_e32 v37, 31, v36
	v_ashrrev_i32_e32 v35, 31, v34
	v_ashrrev_i32_e32 v41, 31, v40
	v_ashrrev_i32_e32 v39, 31, v38
	v_ashrrev_i32_e32 v45, 31, v44
	v_ashrrev_i32_e32 v43, 31, v42
	v_lshlrev_b64 v[10:11], 14, v[10:11]
	v_lshl_add_u64 v[16:17], v[8:9], 0, v[16:17]
	v_lshlrev_b64 v[18:19], 14, v[18:19]
	v_lshlrev_b64 v[20:21], 14, v[20:21]
	v_lshlrev_b64 v[22:23], 14, v[22:23]
	v_lshlrev_b64 v[24:25], 14, v[24:25]
	v_lshlrev_b64 v[26:27], 14, v[26:27]
	v_lshlrev_b64 v[28:29], 14, v[28:29]
	v_lshlrev_b64 v[30:31], 14, v[30:31]
	v_lshlrev_b64 v[32:33], 14, v[32:33]
	v_lshlrev_b64 v[34:35], 14, v[34:35]
	v_lshlrev_b64 v[36:37], 14, v[36:37]
	v_lshlrev_b64 v[38:39], 14, v[38:39]
	v_lshlrev_b64 v[40:41], 14, v[40:41]
	v_lshlrev_b64 v[42:43], 14, v[42:43]
	v_lshlrev_b64 v[44:45], 14, v[44:45]
	v_lshl_add_u64 v[10:11], v[8:9], 0, v[10:11]
	v_lshl_add_u64 v[20:21], v[8:9], 0, v[20:21]
	v_lshl_add_u64 v[18:19], v[8:9], 0, v[18:19]
	v_lshl_add_u64 v[24:25], v[8:9], 0, v[24:25]
	v_lshl_add_u64 v[22:23], v[8:9], 0, v[22:23]
	v_lshl_add_u64 v[28:29], v[8:9], 0, v[28:29]
	v_lshl_add_u64 v[26:27], v[8:9], 0, v[26:27]
	v_lshl_add_u64 v[32:33], v[8:9], 0, v[32:33]
	v_lshl_add_u64 v[30:31], v[8:9], 0, v[30:31]
	v_lshl_add_u64 v[36:37], v[8:9], 0, v[36:37]
	v_lshl_add_u64 v[34:35], v[8:9], 0, v[34:35]
	v_lshl_add_u64 v[40:41], v[8:9], 0, v[40:41]
	v_lshl_add_u64 v[38:39], v[8:9], 0, v[38:39]
	v_lshl_add_u64 v[44:45], v[8:9], 0, v[44:45]
	v_lshl_add_u64 v[42:43], v[8:9], 0, v[42:43]
	global_load_dword v62, v[16:17], off
	global_load_dword v63, v[10:11], off
	global_load_dword v64, v[20:21], off
	global_load_dword v65, v[18:19], off
	global_load_dword v66, v[24:25], off
	global_load_dword v67, v[22:23], off
	global_load_dword v68, v[28:29], off
	global_load_dword v69, v[26:27], off
	global_load_dword v70, v[32:33], off
	global_load_dword v71, v[30:31], off
	global_load_dword v72, v[36:37], off
	global_load_dword v73, v[34:35], off
	global_load_dword v74, v[40:41], off
	global_load_dword v75, v[38:39], off
	global_load_dword v76, v[44:45], off
	global_load_dword v77, v[42:43], off
	s_add_i32 s9, s9, 16
	s_add_i32 s10, s10, 16
	s_add_i32 s5, s5, -16
	v_mad_u64_u32 v[10:11], s[12:13], v47, s3, v[2:3]
	s_cmp_lg_u32 s5, 0
	v_mad_u64_u32 v[16:17], s[12:13], v46, s3, v[2:3]
	v_mad_u64_u32 v[18:19], s[12:13], v49, s3, v[2:3]
	v_mad_u64_u32 v[20:21], s[12:13], v48, s3, v[2:3]
	v_mad_u64_u32 v[22:23], s[12:13], v51, s3, v[2:3]
	v_mad_u64_u32 v[24:25], s[12:13], v50, s3, v[2:3]
	v_mad_u64_u32 v[26:27], s[12:13], v53, s3, v[2:3]
	v_mad_u64_u32 v[28:29], s[12:13], v52, s3, v[2:3]
	v_mad_u64_u32 v[30:31], s[12:13], v55, s3, v[2:3]
	v_mad_u64_u32 v[32:33], s[12:13], v54, s3, v[2:3]
	v_mad_u64_u32 v[34:35], s[12:13], v57, s3, v[2:3]
	v_mad_u64_u32 v[36:37], s[12:13], v56, s3, v[2:3]
	v_mad_u64_u32 v[38:39], s[12:13], v59, s3, v[2:3]
	v_mad_u64_u32 v[40:41], s[12:13], v58, s3, v[2:3]
	v_mad_u64_u32 v[42:43], s[12:13], v61, s3, v[2:3]
	v_mad_u64_u32 v[44:45], s[12:13], v60, s3, v[2:3]
	s_lshl_b32 s11, s10, 1
	s_lshl_b32 s12, s9, 1
	v_or_b32_e32 v120, s11, v1
	v_or_b32_e32 v121, s12, v162
	s_add_i32 s13, s11, 4
	s_add_i32 s14, s12, 4
	s_add_i32 s15, s11, 8
	s_add_i32 s16, s12, 8
	s_add_i32 s17, s11, 12
	s_add_i32 s18, s12, 12
	s_add_i32 s19, s11, 16
	s_add_i32 s20, s12, 16
	s_add_i32 s21, s11, 20
	s_add_i32 s22, s12, 20
	s_add_i32 s23, s11, 24
	s_add_i32 s24, s12, 24
	s_add_i32 s11, s11, 28
	s_add_i32 s12, s12, 28
	v_add_u32_e32 v90, s4, v121
	v_or_b32_e32 v122, s13, v1
	v_or_b32_e32 v123, s14, v162
	v_or_b32_e32 v124, s15, v1
	v_or_b32_e32 v125, s16, v162
	v_or_b32_e32 v126, s17, v1
	v_or_b32_e32 v127, s18, v162
	v_or_b32_e32 v128, s19, v1
	v_or_b32_e32 v129, s20, v162
	v_or_b32_e32 v130, s21, v1
	v_or_b32_e32 v131, s22, v162
	v_or_b32_e32 v132, s23, v1
	v_or_b32_e32 v133, s24, v162
	v_or_b32_e32 v134, s11, v1
	v_or_b32_e32 v135, s12, v162
	v_add_u32_e32 v84, s1, v120
	v_ashrrev_i32_e32 v91, 31, v90
	v_add_u32_e32 v92, s1, v122
	v_add_u32_e32 v94, s4, v123
; template <int MAP>
; __device__ __forceinline__ void transpose_item(const float* W, int K, int N, int ldw, bf16* WT, LAS float* scr, int item, int lane) {
;     ...
;     for (int i = 0; i < 32; ++i) { const int kk = 2 * i + (lane >> 5); scr[kk * 33 + (lane & 31)] = W[(size_t)(k0 + kk) * ldw + n0 + (lane & 31)]; }
	v_add_u32_e32 v96, s1, v124
	v_add_u32_e32 v98, s4, v125
	v_add_u32_e32 v100, s1, v126
	v_add_u32_e32 v102, s4, v127
	v_add_u32_e32 v104, s1, v128
	v_add_u32_e32 v106, s4, v129
	v_add_u32_e32 v108, s1, v130
	v_add_u32_e32 v110, s4, v131
	v_add_u32_e32 v112, s1, v132
	v_add_u32_e32 v114, s4, v133
	v_add_u32_e32 v116, s1, v134
	v_add_u32_e32 v118, s4, v135
	v_ashrrev_i32_e32 v85, 31, v84
	v_lshlrev_b64 v[90:91], 14, v[90:91]
	v_ashrrev_i32_e32 v95, 31, v94
	v_ashrrev_i32_e32 v93, 31, v92
	v_ashrrev_i32_e32 v99, 31, v98
	v_ashrrev_i32_e32 v97, 31, v96
	v_ashrrev_i32_e32 v103, 31, v102
	v_ashrrev_i32_e32 v101, 31, v100
	v_ashrrev_i32_e32 v107, 31, v106
	v_ashrrev_i32_e32 v105, 31, v104
	v_ashrrev_i32_e32 v111, 31, v110
	v_ashrrev_i32_e32 v109, 31, v108
	v_ashrrev_i32_e32 v115, 31, v114
	v_ashrrev_i32_e32 v113, 31, v112
	v_ashrrev_i32_e32 v119, 31, v118
	v_ashrrev_i32_e32 v117, 31, v116
	v_lshlrev_b64 v[84:85], 14, v[84:85]
	v_lshl_add_u64 v[90:91], v[8:9], 0, v[90:91]
	v_lshlrev_b64 v[92:93], 14, v[92:93]
	v_lshlrev_b64 v[94:95], 14, v[94:95]
	v_lshlrev_b64 v[96:97], 14, v[96:97]
	v_lshlrev_b64 v[98:99], 14, v[98:99]
	v_lshlrev_b64 v[100:101], 14, v[100:101]
	v_lshlrev_b64 v[102:103], 14, v[102:103]
	v_lshlrev_b64 v[104:105], 14, v[104:105]
	v_lshlrev_b64 v[106:107], 14, v[106:107]
	v_lshlrev_b64 v[108:109], 14, v[108:109]
	v_lshlrev_b64 v[110:111], 14, v[110:111]
	v_lshlrev_b64 v[112:113], 14, v[112:113]
	v_lshlrev_b64 v[114:115], 14, v[114:115]
	v_lshlrev_b64 v[116:117], 14, v[116:117]
	v_lshlrev_b64 v[118:119], 14, v[118:119]
	v_lshl_add_u64 v[84:85], v[8:9], 0, v[84:85]
	v_lshl_add_u64 v[94:95], v[8:9], 0, v[94:95]
	v_lshl_add_u64 v[92:93], v[8:9], 0, v[92:93]
	v_lshl_add_u64 v[98:99], v[8:9], 0, v[98:99]
	v_lshl_add_u64 v[96:97], v[8:9], 0, v[96:97]
	v_lshl_add_u64 v[102:103], v[8:9], 0, v[102:103]
	v_lshl_add_u64 v[100:101], v[8:9], 0, v[100:101]
	v_lshl_add_u64 v[106:107], v[8:9], 0, v[106:107]
	v_lshl_add_u64 v[104:105], v[8:9], 0, v[104:105]
	v_lshl_add_u64 v[110:111], v[8:9], 0, v[110:111]
	v_lshl_add_u64 v[108:109], v[8:9], 0, v[108:109]
	v_lshl_add_u64 v[114:115], v[8:9], 0, v[114:115]
	v_lshl_add_u64 v[112:113], v[8:9], 0, v[112:113]
	v_lshl_add_u64 v[118:119], v[8:9], 0, v[118:119]
	v_lshl_add_u64 v[116:117], v[8:9], 0, v[116:117]
	global_load_dword v136, v[90:91], off
	global_load_dword v137, v[84:85], off
	global_load_dword v138, v[94:95], off
	global_load_dword v139, v[92:93], off
	global_load_dword v140, v[98:99], off
	global_load_dword v141, v[96:97], off
	global_load_dword v142, v[102:103], off
	global_load_dword v143, v[100:101], off
	global_load_dword v144, v[106:107], off
	global_load_dword v145, v[104:105], off
	global_load_dword v146, v[110:111], off
	global_load_dword v147, v[108:109], off
	global_load_dword v148, v[114:115], off
	global_load_dword v149, v[112:113], off
	global_load_dword v150, v[118:119], off
	global_load_dword v151, v[116:117], off
	s_add_i32 s9, s9, 16
	s_add_i32 s10, s10, 16
	s_add_i32 s5, s5, -16
	v_mad_u64_u32 v[84:85], s[12:13], v121, s3, v[2:3]
	s_cmp_lg_u32 s5, 0
	v_mad_u64_u32 v[90:91], s[12:13], v120, s3, v[2:3]
	v_mad_u64_u32 v[92:93], s[12:13], v123, s3, v[2:3]
	v_mad_u64_u32 v[94:95], s[12:13], v122, s3, v[2:3]
	v_mad_u64_u32 v[96:97], s[12:13], v125, s3, v[2:3]
	v_mad_u64_u32 v[98:99], s[12:13], v124, s3, v[2:3]
	v_mad_u64_u32 v[100:101], s[12:13], v127, s3, v[2:3]
	v_mad_u64_u32 v[102:103], s[12:13], v126, s3, v[2:3]
	v_mad_u64_u32 v[104:105], s[12:13], v129, s3, v[2:3]
	v_mad_u64_u32 v[106:107], s[12:13], v128, s3, v[2:3]
	v_mad_u64_u32 v[108:109], s[12:13], v131, s3, v[2:3]
	v_mad_u64_u32 v[110:111], s[12:13], v130, s3, v[2:3]
	v_mad_u64_u32 v[112:113], s[12:13], v133, s3, v[2:3]
	v_mad_u64_u32 v[114:115], s[12:13], v132, s3, v[2:3]
	v_mad_u64_u32 v[116:117], s[12:13], v135, s3, v[2:3]
	v_mad_u64_u32 v[118:119], s[12:13], v134, s3, v[2:3]
	s_waitcnt vmcnt(31)
; #define LAS __attribute__((address_space(3)))
; __device__ __forceinline__ unsigned pk2(float lo, float hi) { return cvt_pk_bf16(lo, hi); }
; #define LDS_WAIT() asm volatile("s_waitcnt lgkmcnt(0)" ::: "memory")
; template <int MAP>
; __device__ __forceinline__ void transpose_item(const float* W, int K, int N, int ldw, bf16* WT, LAS float* scr, int item, int lane) {
;     ...
;     for (int i = 0; i < 32; ++i) { const int kk = 2 * i + (lane >> 5); scr[kk * 33 + (lane & 31)] = W[(size_t)(k0 + kk) * ldw + n0 + (lane & 31)]; }
;     LDS_WAIT(); asm volatile("" ::: "memory");
;     const int c = lane & 7;
; #pragma unroll
;     for (int j = 0; j < 4; ++j) { const int n = (lane >> 3) + 8 * j; const LAS float* s = scr + (8 * c) * 33 + n;
;         u32x4 o; o.x = pk2(s[0 * 33], s[1 * 33]); o.y = pk2(s[2 * 33], s[3 * 33]); o.z = pk2(s[4 * 33], s[5 * 33]); o.w = pk2(s[6 * 33], s[7 * 33]);
;         *(u32x4*)(WT + (size_t)(dr0 + n) * K + k0 + 8 * c) = o; }
	ds_write_b32 v10, v62
	s_waitcnt vmcnt(30)
	ds_write_b32 v16, v63
	s_waitcnt vmcnt(29)
	ds_write_b32 v18, v64
	s_waitcnt vmcnt(28)
	ds_write_b32 v20, v65
	s_waitcnt vmcnt(27)
	ds_write_b32 v22, v66
	s_waitcnt vmcnt(26)
	ds_write_b32 v24, v67
	s_waitcnt vmcnt(25)
	ds_write_b32 v26, v68
	s_waitcnt vmcnt(24)
	ds_write_b32 v28, v69
	s_waitcnt vmcnt(23)
	ds_write_b32 v30, v70
	s_waitcnt vmcnt(22)
	ds_write_b32 v32, v71
	s_waitcnt vmcnt(21)
	ds_write_b32 v34, v72
	s_waitcnt vmcnt(20)
	ds_write_b32 v36, v73
	s_waitcnt vmcnt(19)
	ds_write_b32 v38, v74
	s_waitcnt vmcnt(18)
	ds_write_b32 v40, v75
	s_waitcnt vmcnt(17)
	ds_write_b32 v42, v76
	s_waitcnt vmcnt(16)
	ds_write_b32 v44, v77
	s_waitcnt vmcnt(15)
	ds_write_b32 v84, v136
	s_waitcnt vmcnt(14)
	ds_write_b32 v90, v137
	s_waitcnt vmcnt(13)
	ds_write_b32 v92, v138
	s_waitcnt vmcnt(12)
	ds_write_b32 v94, v139
	s_waitcnt vmcnt(11)
	ds_write_b32 v96, v140
	s_waitcnt vmcnt(10)
	ds_write_b32 v98, v141
	s_waitcnt vmcnt(9)
	ds_write_b32 v100, v142
	s_waitcnt vmcnt(8)
	ds_write_b32 v102, v143
	s_waitcnt vmcnt(7)
	ds_write_b32 v104, v144
	s_waitcnt vmcnt(6)
	ds_write_b32 v106, v145
	s_waitcnt vmcnt(5)
	ds_write_b32 v108, v146
	s_waitcnt vmcnt(4)
	ds_write_b32 v110, v147
	s_waitcnt vmcnt(3)
	ds_write_b32 v112, v148
	s_waitcnt vmcnt(2)
	ds_write_b32 v114, v149
	s_waitcnt vmcnt(1)
	ds_write_b32 v116, v150
	s_waitcnt vmcnt(0)
	ds_write_b32 v118, v151
	s_waitcnt lgkmcnt(0)
	ds_read2_b32 v[16:17], v3 offset0:33 offset1:41
	ds_read2_b32 v[18:19], v3 offset1:8
	ds_read2_b32 v[20:21], v3 offset0:66 offset1:74
	ds_read2_b32 v[22:23], v3 offset0:99 offset1:107
	ds_read2_b32 v[24:25], v3 offset0:132 offset1:140
	ds_read2_b32 v[26:27], v3 offset0:165 offset1:173
	ds_read2_b32 v[28:29], v3 offset0:198 offset1:206
	ds_read2_b32 v[30:31], v3 offset0:231 offset1:239
	v_or_b32_e32 v34, s0, v14
	s_ashr_i32 s5, s4, 31
	v_ashrrev_i32_e32 v35, 31, v34
	v_lshl_add_u64 v[32:33], s[4:5], 1, v[4:5]
	v_lshlrev_b64 v[34:35], 12, v[34:35]
	s_waitcnt lgkmcnt(6)
	v_cvt_pk_bf16_f32 v8, v18, v16
	s_waitcnt lgkmcnt(4)
	v_cvt_pk_bf16_f32 v9, v20, v22
	s_waitcnt lgkmcnt(2)
	v_cvt_pk_bf16_f32 v10, v24, v26
	s_waitcnt lgkmcnt(0)
	v_cvt_pk_bf16_f32 v11, v28, v30
	v_lshl_add_u64 v[34:35], v[32:33], 0, v[34:35]
	v_or_b32_e32 v16, s0, v12
	global_store_dwordx4 v[34:35], v[8:11], off
	s_add_i32 s8, s8, s92
	s_cmpk_lt_i32 s8, 0x1000
	v_cvt_pk_bf16_f32 v8, v19, v17
	v_ashrrev_i32_e32 v17, 31, v16
	v_cvt_pk_bf16_f32 v9, v21, v23
	v_cvt_pk_bf16_f32 v10, v25, v27
	v_cvt_pk_bf16_f32 v11, v29, v31
	v_lshlrev_b64 v[16:17], 12, v[16:17]
	ds_read2_b32 v[18:19], v3 offset0:49 offset1:57
	ds_read2_b32 v[20:21], v3 offset0:16 offset1:24
	ds_read2_b32 v[22:23], v3 offset0:82 offset1:90
	ds_read2_b32 v[24:25], v3 offset0:115 offset1:123
	ds_read2_b32 v[26:27], v3 offset0:148 offset1:156
	ds_read2_b32 v[28:29], v3 offset0:181 offset1:189
	ds_read2_b32 v[30:31], v3 offset0:214 offset1:222
	ds_read2_b32 v[34:35], v3 offset0:247 offset1:255
	v_lshl_add_u64 v[16:17], v[32:33], 0, v[16:17]
	global_store_dwordx4 v[16:17], v[8:11], off
	v_or_b32_e32 v16, s0, v13
	v_ashrrev_i32_e32 v17, 31, v16
	v_lshlrev_b64 v[16:17], 12, v[16:17]
	s_waitcnt lgkmcnt(6)
	v_cvt_pk_bf16_f32 v8, v20, v18
	s_waitcnt lgkmcnt(4)
	v_cvt_pk_bf16_f32 v9, v22, v24
	s_waitcnt lgkmcnt(2)
	v_cvt_pk_bf16_f32 v10, v26, v28
	s_waitcnt lgkmcnt(0)
	v_cvt_pk_bf16_f32 v11, v30, v34
	v_lshl_add_u64 v[16:17], v[32:33], 0, v[16:17]
	global_store_dwordx4 v[16:17], v[8:11], off
	v_or_b32_e32 v16, s0, v15
	v_ashrrev_i32_e32 v17, 31, v16
	v_lshlrev_b64 v[16:17], 12, v[16:17]
	v_cvt_pk_bf16_f32 v8, v21, v19
	v_cvt_pk_bf16_f32 v9, v23, v25
	v_cvt_pk_bf16_f32 v10, v27, v29
	v_cvt_pk_bf16_f32 v11, v31, v35
	v_lshl_add_u64 v[16:17], v[32:33], 0, v[16:17]
	global_store_dwordx4 v[16:17], v[8:11], off
	s_waitcnt lgkmcnt(0)
	s_cbranch_scc1 .LBB0_64

;     ...
; #pragma unroll 8
;         for (int i = 0; i < 32; ++i) { const int kk = 2 * i + (lane >> 5); scr[kk * 33 + (lane & 31)] = W[(size_t)(k0 + kk) * ldw + n0 + (lane & 31)]; }
.LBB0_70:
	s_lshl_b32 s11, s10, 1
	s_lshl_b32 s12, s9, 1
	v_or_b32_e32 v44, s11, v1
	v_or_b32_e32 v45, s12, v162
	s_add_i32 s13, s11, 4
	s_add_i32 s14, s12, 4
	s_add_i32 s15, s11, 8
	s_add_i32 s16, s12, 8
	s_add_i32 s17, s11, 12
	s_add_i32 s18, s12, 12
	s_add_i32 s19, s11, 16
	s_add_i32 s20, s12, 16
	s_add_i32 s21, s11, 20
	s_add_i32 s22, s12, 20
	s_add_i32 s23, s11, 24
	s_add_i32 s24, s12, 24
	s_add_i32 s11, s11, 28
	s_add_i32 s12, s12, 28
	v_add_u32_e32 v14, s6, v45
	v_or_b32_e32 v46, s13, v1
	v_or_b32_e32 v47, s14, v162
	v_or_b32_e32 v48, s15, v1
	v_or_b32_e32 v49, s16, v162
	v_or_b32_e32 v50, s17, v1
	v_or_b32_e32 v51, s18, v162
	v_or_b32_e32 v52, s19, v1
	v_or_b32_e32 v53, s20, v162
	v_or_b32_e32 v54, s21, v1
	v_or_b32_e32 v55, s22, v162
	v_or_b32_e32 v56, s23, v1
	v_or_b32_e32 v57, s24, v162
	v_or_b32_e32 v58, s11, v1
	v_or_b32_e32 v59, s12, v162
	v_add_u32_e32 v12, s5, v44
	v_ashrrev_i32_e32 v15, 31, v14
	v_add_u32_e32 v16, s5, v46
	v_add_u32_e32 v18, s6, v47
	v_add_u32_e32 v20, s5, v48
	v_add_u32_e32 v22, s6, v49
	v_add_u32_e32 v24, s5, v50
	v_add_u32_e32 v26, s6, v51
	v_add_u32_e32 v28, s5, v52
	v_add_u32_e32 v30, s6, v53
	v_add_u32_e32 v32, s5, v54
	v_add_u32_e32 v34, s6, v55
	v_add_u32_e32 v36, s5, v56
	v_add_u32_e32 v38, s6, v57
	v_add_u32_e32 v40, s5, v58
	v_add_u32_e32 v42, s6, v59
	v_ashrrev_i32_e32 v13, 31, v12
	v_lshlrev_b64 v[14:15], 14, v[14:15]
	v_ashrrev_i32_e32 v19, 31, v18
	v_ashrrev_i32_e32 v17, 31, v16
	v_ashrrev_i32_e32 v23, 31, v22
	v_ashrrev_i32_e32 v21, 31, v20
	v_ashrrev_i32_e32 v27, 31, v26
	v_ashrrev_i32_e32 v25, 31, v24
	v_ashrrev_i32_e32 v31, 31, v30
	v_ashrrev_i32_e32 v29, 31, v28
	v_ashrrev_i32_e32 v35, 31, v34
	v_ashrrev_i32_e32 v33, 31, v32
	v_ashrrev_i32_e32 v39, 31, v38
	v_ashrrev_i32_e32 v37, 31, v36
	v_ashrrev_i32_e32 v43, 31, v42
	v_ashrrev_i32_e32 v41, 31, v40
	v_lshlrev_b64 v[12:13], 14, v[12:13]
	v_lshl_add_u64 v[14:15], v[8:9], 0, v[14:15]
	v_lshlrev_b64 v[16:17], 14, v[16:17]
	v_lshlrev_b64 v[18:19], 14, v[18:19]
	v_lshlrev_b64 v[20:21], 14, v[20:21]
	v_lshlrev_b64 v[22:23], 14, v[22:23]
	v_lshlrev_b64 v[24:25], 14, v[24:25]
	v_lshlrev_b64 v[26:27], 14, v[26:27]
	v_lshlrev_b64 v[28:29], 14, v[28:29]
	v_lshlrev_b64 v[30:31], 14, v[30:31]
	v_lshlrev_b64 v[32:33], 14, v[32:33]
	v_lshlrev_b64 v[34:35], 14, v[34:35]
	v_lshlrev_b64 v[36:37], 14, v[36:37]
	v_lshlrev_b64 v[38:39], 14, v[38:39]
	v_lshlrev_b64 v[40:41], 14, v[40:41]
	v_lshlrev_b64 v[42:43], 14, v[42:43]
	v_lshl_add_u64 v[12:13], v[8:9], 0, v[12:13]
	v_lshl_add_u64 v[18:19], v[8:9], 0, v[18:19]
	v_lshl_add_u64 v[16:17], v[8:9], 0, v[16:17]
	v_lshl_add_u64 v[22:23], v[8:9], 0, v[22:23]
	v_lshl_add_u64 v[20:21], v[8:9], 0, v[20:21]
	v_lshl_add_u64 v[26:27], v[8:9], 0, v[26:27]
	v_lshl_add_u64 v[24:25], v[8:9], 0, v[24:25]
	v_lshl_add_u64 v[30:31], v[8:9], 0, v[30:31]
	v_lshl_add_u64 v[28:29], v[8:9], 0, v[28:29]
	v_lshl_add_u64 v[34:35], v[8:9], 0, v[34:35]
	v_lshl_add_u64 v[32:33], v[8:9], 0, v[32:33]
	v_lshl_add_u64 v[38:39], v[8:9], 0, v[38:39]
	v_lshl_add_u64 v[36:37], v[8:9], 0, v[36:37]
	v_lshl_add_u64 v[42:43], v[8:9], 0, v[42:43]
	v_lshl_add_u64 v[40:41], v[8:9], 0, v[40:41]
	global_load_dword v60, v[14:15], off
	global_load_dword v61, v[12:13], off
	global_load_dword v62, v[18:19], off
	global_load_dword v63, v[16:17], off
	global_load_dword v64, v[22:23], off
	global_load_dword v65, v[20:21], off
	global_load_dword v66, v[26:27], off
	global_load_dword v67, v[24:25], off
	global_load_dword v68, v[30:31], off
	global_load_dword v69, v[28:29], off
	global_load_dword v70, v[34:35], off
	global_load_dword v71, v[32:33], off
	global_load_dword v72, v[38:39], off
	global_load_dword v73, v[36:37], off
	global_load_dword v74, v[42:43], off
	global_load_dword v75, v[40:41], off
	s_add_i32 s9, s9, 16
	s_add_i32 s10, s10, 16
	s_add_i32 s7, s7, -16
	v_mad_u64_u32 v[12:13], s[12:13], v45, s1, v[2:3]
	s_cmp_lg_u32 s7, 0
	v_mad_u64_u32 v[14:15], s[12:13], v44, s1, v[2:3]
	v_mad_u64_u32 v[16:17], s[12:13], v47, s1, v[2:3]
	v_mad_u64_u32 v[18:19], s[12:13], v46, s1, v[2:3]
	v_mad_u64_u32 v[20:21], s[12:13], v49, s1, v[2:3]
	v_mad_u64_u32 v[22:23], s[12:13], v48, s1, v[2:3]
	v_mad_u64_u32 v[24:25], s[12:13], v51, s1, v[2:3]
	v_mad_u64_u32 v[26:27], s[12:13], v50, s1, v[2:3]
	v_mad_u64_u32 v[28:29], s[12:13], v53, s1, v[2:3]
	v_mad_u64_u32 v[30:31], s[12:13], v52, s1, v[2:3]
	v_mad_u64_u32 v[32:33], s[12:13], v55, s1, v[2:3]
	v_mad_u64_u32 v[34:35], s[12:13], v54, s1, v[2:3]
	v_mad_u64_u32 v[36:37], s[12:13], v57, s1, v[2:3]
	v_mad_u64_u32 v[38:39], s[12:13], v56, s1, v[2:3]
	v_mad_u64_u32 v[40:41], s[12:13], v59, s1, v[2:3]
	v_mad_u64_u32 v[42:43], s[12:13], v58, s1, v[2:3]
	s_lshl_b32 s11, s10, 1
	s_lshl_b32 s12, s9, 1
	v_or_b32_e32 v116, s11, v1
	v_or_b32_e32 v117, s12, v162
	s_add_i32 s13, s11, 4
	s_add_i32 s14, s12, 4
	s_add_i32 s15, s11, 8
	s_add_i32 s16, s12, 8
	s_add_i32 s17, s11, 12
	s_add_i32 s18, s12, 12
	s_add_i32 s19, s11, 16
	s_add_i32 s20, s12, 16
	s_add_i32 s21, s11, 20
	s_add_i32 s22, s12, 20
	s_add_i32 s23, s11, 24
	s_add_i32 s24, s12, 24
	s_add_i32 s11, s11, 28
	s_add_i32 s12, s12, 28
	v_add_u32_e32 v86, s6, v117
	v_or_b32_e32 v118, s13, v1
	v_or_b32_e32 v119, s14, v162
	v_or_b32_e32 v120, s15, v1
	v_or_b32_e32 v121, s16, v162
	v_or_b32_e32 v122, s17, v1
	v_or_b32_e32 v123, s18, v162
	v_or_b32_e32 v124, s19, v1
	v_or_b32_e32 v125, s20, v162
	v_or_b32_e32 v126, s21, v1
	v_or_b32_e32 v127, s22, v162
	v_or_b32_e32 v128, s23, v1
	v_or_b32_e32 v129, s24, v162
	v_or_b32_e32 v130, s11, v1
	v_or_b32_e32 v131, s12, v162
	v_add_u32_e32 v84, s5, v116
	v_ashrrev_i32_e32 v87, 31, v86
	v_add_u32_e32 v88, s5, v118
	v_add_u32_e32 v90, s6, v119
;     ...
; #pragma unroll 8
;         for (int i = 0; i < 32; ++i) { const int kk = 2 * i + (lane >> 5); scr[kk * 33 + (lane & 31)] = W[(size_t)(k0 + kk) * ldw + n0 + (lane & 31)]; }
	v_add_u32_e32 v92, s5, v120
	v_add_u32_e32 v94, s6, v121
	v_add_u32_e32 v96, s5, v122
	v_add_u32_e32 v98, s6, v123
	v_add_u32_e32 v100, s5, v124
	v_add_u32_e32 v102, s6, v125
	v_add_u32_e32 v104, s5, v126
	v_add_u32_e32 v106, s6, v127
	v_add_u32_e32 v108, s5, v128
	v_add_u32_e32 v110, s6, v129
	v_add_u32_e32 v112, s5, v130
	v_add_u32_e32 v114, s6, v131
	v_ashrrev_i32_e32 v85, 31, v84
	v_lshlrev_b64 v[86:87], 14, v[86:87]
	v_ashrrev_i32_e32 v91, 31, v90
	v_ashrrev_i32_e32 v89, 31, v88
	v_ashrrev_i32_e32 v95, 31, v94
	v_ashrrev_i32_e32 v93, 31, v92
	v_ashrrev_i32_e32 v99, 31, v98
	v_ashrrev_i32_e32 v97, 31, v96
	v_ashrrev_i32_e32 v103, 31, v102
	v_ashrrev_i32_e32 v101, 31, v100
	v_ashrrev_i32_e32 v107, 31, v106
	v_ashrrev_i32_e32 v105, 31, v104
	v_ashrrev_i32_e32 v111, 31, v110
	v_ashrrev_i32_e32 v109, 31, v108
	v_ashrrev_i32_e32 v115, 31, v114
	v_ashrrev_i32_e32 v113, 31, v112
	v_lshlrev_b64 v[84:85], 14, v[84:85]
	v_lshl_add_u64 v[86:87], v[8:9], 0, v[86:87]
	v_lshlrev_b64 v[88:89], 14, v[88:89]
	v_lshlrev_b64 v[90:91], 14, v[90:91]
	v_lshlrev_b64 v[92:93], 14, v[92:93]
	v_lshlrev_b64 v[94:95], 14, v[94:95]
	v_lshlrev_b64 v[96:97], 14, v[96:97]
	v_lshlrev_b64 v[98:99], 14, v[98:99]
	v_lshlrev_b64 v[100:101], 14, v[100:101]
	v_lshlrev_b64 v[102:103], 14, v[102:103]
	v_lshlrev_b64 v[104:105], 14, v[104:105]
	v_lshlrev_b64 v[106:107], 14, v[106:107]
	v_lshlrev_b64 v[108:109], 14, v[108:109]
	v_lshlrev_b64 v[110:111], 14, v[110:111]
	v_lshlrev_b64 v[112:113], 14, v[112:113]
	v_lshlrev_b64 v[114:115], 14, v[114:115]
	v_lshl_add_u64 v[84:85], v[8:9], 0, v[84:85]
	v_lshl_add_u64 v[90:91], v[8:9], 0, v[90:91]
	v_lshl_add_u64 v[88:89], v[8:9], 0, v[88:89]
	v_lshl_add_u64 v[94:95], v[8:9], 0, v[94:95]
	v_lshl_add_u64 v[92:93], v[8:9], 0, v[92:93]
	v_lshl_add_u64 v[98:99], v[8:9], 0, v[98:99]
	v_lshl_add_u64 v[96:97], v[8:9], 0, v[96:97]
	v_lshl_add_u64 v[102:103], v[8:9], 0, v[102:103]
	v_lshl_add_u64 v[100:101], v[8:9], 0, v[100:101]
	v_lshl_add_u64 v[106:107], v[8:9], 0, v[106:107]
	v_lshl_add_u64 v[104:105], v[8:9], 0, v[104:105]
	v_lshl_add_u64 v[110:111], v[8:9], 0, v[110:111]
	v_lshl_add_u64 v[108:109], v[8:9], 0, v[108:109]
	v_lshl_add_u64 v[114:115], v[8:9], 0, v[114:115]
	v_lshl_add_u64 v[112:113], v[8:9], 0, v[112:113]
	global_load_dword v132, v[86:87], off
	global_load_dword v133, v[84:85], off
	global_load_dword v134, v[90:91], off
	global_load_dword v135, v[88:89], off
	global_load_dword v136, v[94:95], off
	global_load_dword v137, v[92:93], off
	global_load_dword v138, v[98:99], off
	global_load_dword v139, v[96:97], off
	global_load_dword v140, v[102:103], off
	global_load_dword v141, v[100:101], off
	global_load_dword v142, v[106:107], off
	global_load_dword v143, v[104:105], off
	global_load_dword v144, v[110:111], off
	global_load_dword v145, v[108:109], off
	global_load_dword v146, v[114:115], off
	global_load_dword v147, v[112:113], off
	s_add_i32 s9, s9, 16
	s_add_i32 s10, s10, 16
	s_add_i32 s7, s7, -16
	v_mad_u64_u32 v[84:85], s[12:13], v117, s1, v[2:3]
	s_cmp_lg_u32 s7, 0
	v_mad_u64_u32 v[86:87], s[12:13], v116, s1, v[2:3]
	v_mad_u64_u32 v[88:89], s[12:13], v119, s1, v[2:3]
	v_mad_u64_u32 v[90:91], s[12:13], v118, s1, v[2:3]
	v_mad_u64_u32 v[92:93], s[12:13], v121, s1, v[2:3]
	v_mad_u64_u32 v[94:95], s[12:13], v120, s1, v[2:3]
	v_mad_u64_u32 v[96:97], s[12:13], v123, s1, v[2:3]
	v_mad_u64_u32 v[98:99], s[12:13], v122, s1, v[2:3]
	v_mad_u64_u32 v[100:101], s[12:13], v125, s1, v[2:3]
	v_mad_u64_u32 v[102:103], s[12:13], v124, s1, v[2:3]
	v_mad_u64_u32 v[104:105], s[12:13], v127, s1, v[2:3]
	v_mad_u64_u32 v[106:107], s[12:13], v126, s1, v[2:3]
	v_mad_u64_u32 v[108:109], s[12:13], v129, s1, v[2:3]
	v_mad_u64_u32 v[110:111], s[12:13], v128, s1, v[2:3]
	v_mad_u64_u32 v[112:113], s[12:13], v131, s1, v[2:3]
	v_mad_u64_u32 v[114:115], s[12:13], v130, s1, v[2:3]
	s_waitcnt vmcnt(31)
	ds_write_b32 v12, v60
	s_waitcnt vmcnt(30)
	ds_write_b32 v14, v61
	s_waitcnt vmcnt(29)
	ds_write_b32 v16, v62
	s_waitcnt vmcnt(28)
	ds_write_b32 v18, v63
	s_waitcnt vmcnt(27)
	ds_write_b32 v20, v64
	s_waitcnt vmcnt(26)
	ds_write_b32 v22, v65
	s_waitcnt vmcnt(25)
	ds_write_b32 v24, v66
	s_waitcnt vmcnt(24)
	ds_write_b32 v26, v67
	s_waitcnt vmcnt(23)
	ds_write_b32 v28, v68
	s_waitcnt vmcnt(22)
	ds_write_b32 v30, v69
	s_waitcnt vmcnt(21)
	ds_write_b32 v32, v70
	s_waitcnt vmcnt(20)
	ds_write_b32 v34, v71
	s_waitcnt vmcnt(19)
	ds_write_b32 v36, v72
	s_waitcnt vmcnt(18)
	ds_write_b32 v38, v73
	s_waitcnt vmcnt(17)
	ds_write_b32 v40, v74
	s_waitcnt vmcnt(16)
	ds_write_b32 v42, v75
	s_waitcnt vmcnt(15)
	ds_write_b32 v84, v132
	s_waitcnt vmcnt(14)
	ds_write_b32 v86, v133
	s_waitcnt vmcnt(13)
	ds_write_b32 v88, v134
	s_waitcnt vmcnt(12)
	ds_write_b32 v90, v135
	s_waitcnt vmcnt(11)
	ds_write_b32 v92, v136
	s_waitcnt vmcnt(10)
	ds_write_b32 v94, v137
	s_waitcnt vmcnt(9)
	ds_write_b32 v96, v138
	s_waitcnt vmcnt(8)
	ds_write_b32 v98, v139
	s_waitcnt vmcnt(7)
	ds_write_b32 v100, v140
	s_waitcnt vmcnt(6)
	ds_write_b32 v102, v141
	s_waitcnt vmcnt(5)
	ds_write_b32 v104, v142
	s_waitcnt vmcnt(4)
	ds_write_b32 v106, v143
	s_waitcnt vmcnt(3)
	ds_write_b32 v108, v144
	s_waitcnt vmcnt(2)
	ds_write_b32 v110, v145
	s_waitcnt vmcnt(1)
	ds_write_b32 v112, v146
	s_waitcnt vmcnt(0)
	ds_write_b32 v114, v147
	s_waitcnt lgkmcnt(0)
	ds_read2_b32 v[8:9], v3 offset1:16
	ds_read2_b32 v[18:19], v3 offset0:33 offset1:49
	ds_read2_b32 v[20:21], v3 offset0:66 offset1:82
	ds_read2_b32 v[22:23], v3 offset0:99 offset1:115
	ds_read2_b32 v[26:27], v3 offset0:132 offset1:148
	ds_read2_b32 v[30:31], v3 offset0:165 offset1:181
	ds_read2_b32 v[32:33], v3 offset0:198 offset1:214
	ds_read2_b32 v[34:35], v3 offset0:231 offset1:247
	s_ashr_i32 s7, s6, 31
	s_waitcnt lgkmcnt(7)
; #define LAS __attribute__((address_space(3)))
; __device__ __forceinline__ unsigned pk4_f8(float a, float b, float c, float d) { int w = __builtin_amdgcn_cvt_pk_fp8_f32(a, b, 0, false); w = __builtin_amdgcn_cvt_pk_fp8_f32(c, d, w, true); return (unsigned)w; }
; #define LDS_WAIT() asm volatile("s_waitcnt lgkmcnt(0)" ::: "memory")
;     ...
;         for (int j = 0; j < 2; ++j) { const int n = (lane >> 2) + 16 * j; const LAS float* sp = scr + (16 * c) * 33 + n;
;             u32x4 o;
;             if (QI8) { o.x = pk4_i8(sp[0 * 33], sp[1 * 33], sp[2 * 33], sp[3 * 33], scl); o.y = pk4_i8(sp[4 * 33], sp[5 * 33], sp[6 * 33], sp[7 * 33], scl);
;                 o.z = pk4_i8(sp[8 * 33], sp[9 * 33], sp[10 * 33], sp[11 * 33], scl); o.w = pk4_i8(sp[12 * 33], sp[13 * 33], sp[14 * 33], sp[15 * 33], scl); }
;             else {
;             o.x = pk4_f8(sp[0 * 33] * scl, sp[1 * 33] * scl, sp[2 * 33] * scl, sp[3 * 33] * scl); o.y = pk4_f8(sp[4 * 33] * scl, sp[5 * 33] * scl, sp[6 * 33] * scl, sp[7 * 33] * scl);
;             o.z = pk4_f8(sp[8 * 33] * scl, sp[9 * 33] * scl, sp[10 * 33] * scl, sp[11 * 33] * scl); o.w = pk4_f8(sp[12 * 33] * scl, sp[13 * 33] * scl, sp[14 * 33] * scl, sp[15 * 33] * scl); }
;             *(u32x4*)(WT + (size_t)(dr0 + n) * K + k0 + 16 * c) = o; }
;         LDS_WAIT(); asm volatile("" ::: "memory"); }
	v_mul_f32_e32 v8, 0x45559673, v8
	v_med3_f32 v12, v8, s3, v11
	s_waitcnt lgkmcnt(6)
	v_mul_f32_e32 v8, 0x45559673, v18
	v_med3_f32 v14, v8, s3, v11
	s_waitcnt lgkmcnt(5)
	v_mul_f32_e32 v8, 0x45559673, v20
	v_med3_f32 v24, v8, s3, v11
	s_waitcnt lgkmcnt(4)
	v_mul_f32_e32 v8, 0x45559673, v22
	v_med3_f32 v28, v8, s3, v11
	s_waitcnt lgkmcnt(3)
	v_mul_f32_e32 v8, 0x45559673, v26
	v_med3_f32 v13, v8, s3, v11
	s_waitcnt lgkmcnt(2)
	v_mul_f32_e32 v8, 0x45559673, v30
	v_med3_f32 v15, v8, s3, v11
	s_waitcnt lgkmcnt(1)
	v_mul_f32_e32 v8, 0x45559673, v32
	v_med3_f32 v25, v8, s3, v11
	s_waitcnt lgkmcnt(0)
	v_mul_f32_e32 v8, 0x45559673, v34
	v_med3_f32 v29, v8, s3, v11
	v_pk_add_f32 v[14:15], v[14:15], s[0:1] op_sel_hi:[1,0]
	v_pk_add_f32 v[28:29], v[28:29], s[0:1] op_sel_hi:[1,0]
	v_pk_add_f32 v[12:13], v[12:13], s[0:1] op_sel_hi:[1,0]
	v_pk_add_f32 v[24:25], v[24:25], s[0:1] op_sel_hi:[1,0]
	v_lshlrev_b32_e32 v8, 8, v15
	v_lshlrev_b32_e32 v20, 24, v29
	v_and_b32_e32 v8, 0xff00, v8
	v_lshlrev_b32_e32 v15, 16, v25
	v_or_b32_sdwa v13, v20, v13 dst_sel:DWORD dst_unused:UNUSED_PAD src0_sel:DWORD src1_sel:BYTE_0
	v_and_b32_e32 v15, 0xff0000, v15
	v_or_b32_e32 v8, v13, v8
	v_or_b32_e32 v13, v8, v15
	v_add_u32_e32 v8, 0x400, v3
	v_lshlrev_b32_e32 v18, 16, v24
	v_lshlrev_b32_e32 v22, 24, v28
	ds_read2_b32 v[24:25], v8 offset0:8 offset1:24
	ds_read2_b32 v[28:29], v8 offset0:41 offset1:57
	ds_read2_b32 v[36:37], v8 offset0:74 offset1:90
	ds_read2_b32 v[38:39], v8 offset0:107 offset1:123
	ds_read2_b32 v[44:45], v8 offset0:140 offset1:156
	ds_read2_b32 v[48:49], v8 offset0:173 offset1:189
	ds_read2_b32 v[50:51], v8 offset0:206 offset1:222
	ds_read2_b32 v[52:53], v8 offset0:239 offset1:255
	s_waitcnt lgkmcnt(6)
	v_mul_f32_e32 v15, 0x45559673, v28
	v_med3_f32 v40, v15, s3, v11
	s_waitcnt lgkmcnt(5)
	v_mul_f32_e32 v15, 0x45559673, v36
	v_med3_f32 v42, v15, s3, v11
	s_waitcnt lgkmcnt(4)
	v_mul_f32_e32 v15, 0x45559673, v38
	s_waitcnt lgkmcnt(3)
	v_mul_f32_e32 v8, 0x45559673, v44
	v_med3_f32 v46, v15, s3, v11
	v_med3_f32 v15, v8, s3, v11
	s_waitcnt lgkmcnt(2)
	v_mul_f32_e32 v8, 0x45559673, v48
	v_lshlrev_b32_e32 v14, 8, v14
	v_med3_f32 v41, v8, s3, v11
	s_waitcnt lgkmcnt(1)
	v_mul_f32_e32 v8, 0x45559673, v50
	v_and_b32_e32 v14, 0xff00, v14
	v_or_b32_sdwa v12, v22, v12 dst_sel:DWORD dst_unused:UNUSED_PAD src0_sel:DWORD src1_sel:BYTE_0
	v_med3_f32 v43, v8, s3, v11
	s_waitcnt lgkmcnt(0)
	v_mul_f32_e32 v8, 0x45559673, v52
	v_or_b32_e32 v12, v12, v14
	v_mul_f32_e32 v14, 0x45559673, v24
	v_med3_f32 v47, v8, s3, v11
	v_and_b32_e32 v18, 0xff0000, v18
	v_med3_f32 v14, v14, s3, v11
	v_pk_add_f32 v[40:41], v[40:41], s[0:1] op_sel_hi:[1,0]
	v_pk_add_f32 v[46:47], v[46:47], s[0:1] op_sel_hi:[1,0]
	v_or_b32_e32 v12, v12, v18
	v_pk_add_f32 v[14:15], v[14:15], s[0:1] op_sel_hi:[1,0]
	v_pk_add_f32 v[42:43], v[42:43], s[0:1] op_sel_hi:[1,0]
	v_lshlrev_b32_e32 v8, 8, v41
	v_lshlrev_b32_e32 v18, 8, v40
	v_lshlrev_b32_e32 v24, 24, v47
	v_lshlrev_b32_e32 v26, 24, v46
	v_or_b32_e32 v40, s4, v163
	v_and_b32_e32 v8, 0xff00, v8
	v_and_b32_e32 v18, 0xff00, v18
	v_lshlrev_b32_e32 v20, 16, v43
	v_lshlrev_b32_e32 v22, 16, v42
	v_or_b32_sdwa v15, v24, v15 dst_sel:DWORD dst_unused:UNUSED_PAD src0_sel:DWORD src1_sel:BYTE_0
	v_or_b32_sdwa v14, v26, v14 dst_sel:DWORD dst_unused:UNUSED_PAD src0_sel:DWORD src1_sel:BYTE_0
	v_ashrrev_i32_e32 v41, 31, v40
	v_lshl_add_u64 v[16:17], v[6:7], 0, s[6:7]
	v_and_b32_e32 v20, 0xff0000, v20
	v_and_b32_e32 v22, 0xff0000, v22
	v_or_b32_e32 v8, v15, v8
	v_or_b32_e32 v14, v14, v18
	v_lshlrev_b64 v[40:41], 12, v[40:41]
	v_or_b32_e32 v15, v8, v20
	v_or_b32_e32 v14, v14, v22
	v_lshl_add_u64 v[40:41], v[16:17], 0, v[40:41]
	v_mul_f32_e32 v8, 0x45559673, v9
	v_mul_f32_e32 v9, 0x45559673, v19
	global_store_dwordx4 v[40:41], v[12:15], off
	v_mul_f32_e32 v19, 0x45559673, v35
	v_med3_f32 v19, v19, s3, v11
	v_med3_f32 v12, v9, s3, v11
	v_mul_f32_e32 v9, 0x45559673, v21
	v_med3_f32 v14, v9, s3, v11
	v_mul_f32_e32 v9, 0x45559673, v23
	v_mul_f32_e32 v13, 0x45559673, v31
	v_med3_f32 v18, v9, s3, v11
	v_mul_f32_e32 v9, 0x45559673, v27
	v_med3_f32 v13, v13, s3, v11
	v_mul_f32_e32 v15, 0x45559673, v33
	v_med3_f32 v8, v8, s3, v11
	v_med3_f32 v9, v9, s3, v11
	v_med3_f32 v15, v15, s3, v11
	v_pk_add_f32 v[12:13], v[12:13], s[0:1] op_sel_hi:[1,0]
	v_pk_add_f32 v[18:19], v[18:19], s[0:1] op_sel_hi:[1,0]
	v_pk_add_f32 v[8:9], v[8:9], s[0:1] op_sel_hi:[1,0]
	v_pk_add_f32 v[14:15], v[14:15], s[0:1] op_sel_hi:[1,0]
	v_lshlrev_b32_e32 v13, 8, v13
	v_lshlrev_b32_e32 v19, 24, v19
	v_lshlrev_b32_e32 v12, 8, v12
	v_and_b32_e32 v13, 0xff00, v13
	v_lshlrev_b32_e32 v15, 16, v15
	v_lshlrev_b32_e32 v18, 24, v18
	v_or_b32_sdwa v9, v19, v9 dst_sel:DWORD dst_unused:UNUSED_PAD src0_sel:DWORD src1_sel:BYTE_0
	v_and_b32_e32 v12, 0xff00, v12
	v_lshlrev_b32_e32 v14, 16, v14
	v_and_b32_e32 v15, 0xff0000, v15
	v_or_b32_sdwa v8, v18, v8 dst_sel:DWORD dst_unused:UNUSED_PAD src0_sel:DWORD src1_sel:BYTE_0
	v_or_b32_e32 v9, v9, v13
	v_and_b32_e32 v14, 0xff0000, v14
	v_or_b32_e32 v8, v8, v12
	v_or_b32_e32 v13, v9, v15
	v_mul_f32_e32 v9, 0x45559673, v29
	v_or_b32_e32 v12, v8, v14
	v_med3_f32 v14, v9, s3, v11
	v_mul_f32_e32 v9, 0x45559673, v37
	v_med3_f32 v18, v9, s3, v11
	v_mul_f32_e32 v9, 0x45559673, v39
	v_mul_f32_e32 v15, 0x45559673, v49
	v_mul_f32_e32 v21, 0x45559673, v53
	v_mul_f32_e32 v8, 0x45559673, v25
	v_med3_f32 v20, v9, s3, v11
	v_mul_f32_e32 v9, 0x45559673, v45
	v_med3_f32 v15, v15, s3, v11
	v_mul_f32_e32 v19, 0x45559673, v51
	v_med3_f32 v21, v21, s3, v11
	v_med3_f32 v8, v8, s3, v11
	v_med3_f32 v9, v9, s3, v11
	v_med3_f32 v19, v19, s3, v11
	v_pk_add_f32 v[14:15], v[14:15], s[0:1] op_sel_hi:[1,0]
	v_pk_add_f32 v[20:21], v[20:21], s[0:1] op_sel_hi:[1,0]
	v_pk_add_f32 v[8:9], v[8:9], s[0:1] op_sel_hi:[1,0]
	v_pk_add_f32 v[18:19], v[18:19], s[0:1] op_sel_hi:[1,0]
	v_lshlrev_b32_e32 v14, 8, v14
	v_lshlrev_b32_e32 v20, 24, v20
	v_lshlrev_b32_e32 v15, 8, v15
	v_and_b32_e32 v14, 0xff00, v14
	v_lshlrev_b32_e32 v18, 16, v18
	v_lshlrev_b32_e32 v21, 24, v21
	v_or_b32_sdwa v8, v20, v8 dst_sel:DWORD dst_unused:UNUSED_PAD src0_sel:DWORD src1_sel:BYTE_0
	v_and_b32_e32 v15, 0xff00, v15
	v_lshlrev_b32_e32 v19, 16, v19
	v_and_b32_e32 v18, 0xff0000, v18
	v_or_b32_sdwa v9, v21, v9 dst_sel:DWORD dst_unused:UNUSED_PAD src0_sel:DWORD src1_sel:BYTE_0
	v_or_b32_e32 v8, v8, v14
	v_and_b32_e32 v19, 0xff0000, v19
	v_or_b32_e32 v9, v9, v15
	v_or_b32_e32 v14, v8, v18
	v_or_b32_e32 v8, s4, v10
	v_or_b32_e32 v15, v9, v19
	v_ashrrev_i32_e32 v9, 31, v8
	v_lshlrev_b64 v[8:9], 12, v[8:9]
	v_lshl_add_u64 v[8:9], v[16:17], 0, v[8:9]
	global_store_dwordx4 v[8:9], v[12:15], off
	s_waitcnt lgkmcnt(0)
	s_add_i32 s8, s8, s92
	s_cmpk_lt_i32 s8, 0x2000
	s_cbranch_scc1 .LBB0_69
; __device__ __forceinline__ unsigned f2bf(float f) { return cvt_pk_bf16(f, 0.f) & 0xffffu; }
; __device__ __forceinline__ void lora_weight(Frame& F, const float* W, int KR, int KP, bf16* dst) {
;     const int total = 2048 * KP; const int gt = blockIdx.x * 512 + F.tid, NT = F.G * 512;
;     for (int e = gt; e < total; e += NT) { const int n = e / KP, k = e % KP; dst[e] = (bf16)(k < KR ? f2bf(W[(size_t)k * 2048 + n]) : 0u); }
; }
; __device__ __forceinline__ void p0_prologue(Frame& F) {
;     ...
;     lora_weight(F, F.in[I_W2], 128, 256, (bf16*)(F.ws + WS_LW2));
;     lora_weight(F, F.in[I_A2], 128, 256, (bf16*)(F.ws + WS_LA2));
;     lora_weight(F, F.in[I_G2], 480, 512, (bf16*)(F.ws + WS_LG2));
.LBB0_72:
	s_lshl_b32 s49, s96, 9
	s_mov_b32 s0, 0x100000
	v_cmp_gt_i32_e64 s[4:5], s0, v168
	s_mov_b64 s[0:1], exec
	s_nop 0
	v_writelane_b32 v240, s4, 7
	s_nop 1
	v_writelane_b32 v240, s5, 8
	s_load_dwordx2 s[6:7], s[74:75], 0x88
	s_load_dwordx2 s[8:9], s[74:75], 0x98
	s_load_dwordx2 s[10:11], s[74:75], 0xa0
	v_mbcnt_lo_u32_b32 v128, -1, 0
	v_mbcnt_hi_u32_b32 v128, -1, v128
	v_lshlrev_b32_e32 v129, 9, v128
	v_lshlrev_b32_e32 v130, 10, v128
	v_lshlrev_b32_e32 v128, 2, v128
	s_mov_b32 s38, s94
	s_waitcnt lgkmcnt(0)
	s_cmpk_lt_i32 s38, 0x400
	s_cbranch_scc0 .Llw_done
.Llw_task:
	s_cmpk_lt_i32 s38, 0x200
	s_cbranch_scc0 .Llw_g2
	s_mov_b32 s39, 0x6be00000
	s_cmpk_lt_i32 s38, 0x100
	s_cselect_b32 s34, s6, s8
	s_cselect_b32 s35, s7, s9
	s_cselect_b32 s39, 0x6bd00000, s39
	s_and_b32 s40, s38, 0xff
	s_mov_b32 s41, 4
	s_mov_b32 s42, 15
	v_mov_b32_e32 v131, v129
	s_branch .Llw_dec
.Llw_g2:
	s_mov_b64 s[34:35], s[10:11]
	s_mov_b32 s39, 0x6bf00000
	s_sub_i32 s40, s38, 0x200
	s_mov_b32 s41, 15
	s_mov_b32 s42, 16
	v_mov_b32_e32 v131, v130
.Llw_dec:
	s_lshr_b32 s43, s40, 5
	s_and_b32 s44, s40, 31
	s_lshl_b32 s45, s44, s42
	s_lshl_b32 s46, s43, 6
	s_add_u32 s45, s45, s46
	s_add_u32 s36, s90, s39
	s_addc_u32 s37, s91, 0
	s_add_u32 s36, s36, s45
	s_addc_u32 s37, s37, 0
	s_cmp_lt_u32 s43, s41
	s_cbranch_scc0 .Llw_zero
	s_lshl_b32 s45, s43, 18
	s_lshl_b32 s46, s44, 8
	s_add_u32 s45, s45, s46
	s_add_u32 s34, s34, s45
	s_addc_u32 s35, s35, 0
	global_load_dword v80, v128, s[34:35]
	s_add_u32 s34, s34, 0x2000
	s_addc_u32 s35, s35, 0
	global_load_dword v81, v128, s[34:35]
	s_add_u32 s34, s34, 0x2000
	s_addc_u32 s35, s35, 0
	global_load_dword v82, v128, s[34:35]
	s_add_u32 s34, s34, 0x2000
	s_addc_u32 s35, s35, 0
	global_load_dword v83, v128, s[34:35]
	s_add_u32 s34, s34, 0x2000
	s_addc_u32 s35, s35, 0
	global_load_dword v84, v128, s[34:35]
	s_add_u32 s34, s34, 0x2000
	s_addc_u32 s35, s35, 0
	global_load_dword v85, v128, s[34:35]
	s_add_u32 s34, s34, 0x2000
	s_addc_u32 s35, s35, 0
	global_load_dword v86, v128, s[34:35]
	s_add_u32 s34, s34, 0x2000
	s_addc_u32 s35, s35, 0
	global_load_dword v87, v128, s[34:35]
	s_add_u32 s34, s34, 0x2000
	s_addc_u32 s35, s35, 0
	global_load_dword v88, v128, s[34:35]
	s_add_u32 s34, s34, 0x2000
	s_addc_u32 s35, s35, 0
	global_load_dword v89, v128, s[34:35]
	s_add_u32 s34, s34, 0x2000
	s_addc_u32 s35, s35, 0
	global_load_dword v90, v128, s[34:35]
	s_add_u32 s34, s34, 0x2000
	s_addc_u32 s35, s35, 0
	global_load_dword v91, v128, s[34:35]
	s_add_u32 s34, s34, 0x2000
	s_addc_u32 s35, s35, 0
	global_load_dword v92, v128, s[34:35]
	s_add_u32 s34, s34, 0x2000
	s_addc_u32 s35, s35, 0
	global_load_dword v93, v128, s[34:35]
	s_add_u32 s34, s34, 0x2000
	s_addc_u32 s35, s35, 0
	global_load_dword v94, v128, s[34:35]
	s_add_u32 s34, s34, 0x2000
	s_addc_u32 s35, s35, 0
	global_load_dword v95, v128, s[34:35]
	s_add_u32 s34, s34, 0x2000
	s_addc_u32 s35, s35, 0
	global_load_dword v96, v128, s[34:35]
	s_add_u32 s34, s34, 0x2000
	s_addc_u32 s35, s35, 0
	global_load_dword v97, v128, s[34:35]
	s_add_u32 s34, s34, 0x2000
	s_addc_u32 s35, s35, 0
	global_load_dword v98, v128, s[34:35]
	s_add_u32 s34, s34, 0x2000
	s_addc_u32 s35, s35, 0
	global_load_dword v99, v128, s[34:35]
	s_add_u32 s34, s34, 0x2000
	s_addc_u32 s35, s35, 0
	global_load_dword v100, v128, s[34:35]
	s_add_u32 s34, s34, 0x2000
	s_addc_u32 s35, s35, 0
	global_load_dword v101, v128, s[34:35]
	s_add_u32 s34, s34, 0x2000
	s_addc_u32 s35, s35, 0
	global_load_dword v102, v128, s[34:35]
	s_add_u32 s34, s34, 0x2000
	s_addc_u32 s35, s35, 0
	global_load_dword v103, v128, s[34:35]
	s_add_u32 s34, s34, 0x2000
	s_addc_u32 s35, s35, 0
	global_load_dword v104, v128, s[34:35]
	s_add_u32 s34, s34, 0x2000
	s_addc_u32 s35, s35, 0
	global_load_dword v105, v128, s[34:35]
	s_add_u32 s34, s34, 0x2000
	s_addc_u32 s35, s35, 0
	global_load_dword v106, v128, s[34:35]
	s_add_u32 s34, s34, 0x2000
	s_addc_u32 s35, s35, 0
	global_load_dword v107, v128, s[34:35]
	s_add_u32 s34, s34, 0x2000
	s_addc_u32 s35, s35, 0
	global_load_dword v108, v128, s[34:35]
	s_add_u32 s34, s34, 0x2000
	s_addc_u32 s35, s35, 0
	global_load_dword v109, v128, s[34:35]
	s_add_u32 s34, s34, 0x2000
	s_addc_u32 s35, s35, 0
	global_load_dword v110, v128, s[34:35]
	s_add_u32 s34, s34, 0x2000
	s_addc_u32 s35, s35, 0
	global_load_dword v111, v128, s[34:35]
	s_waitcnt vmcnt(0)
	v_cvt_pk_bf16_f32 v112, v80, v81
	v_cvt_pk_bf16_f32 v113, v82, v83
	v_cvt_pk_bf16_f32 v114, v84, v85
	v_cvt_pk_bf16_f32 v115, v86, v87
	v_cvt_pk_bf16_f32 v116, v88, v89
	v_cvt_pk_bf16_f32 v117, v90, v91
	v_cvt_pk_bf16_f32 v118, v92, v93
	v_cvt_pk_bf16_f32 v119, v94, v95
	v_cvt_pk_bf16_f32 v120, v96, v97
	v_cvt_pk_bf16_f32 v121, v98, v99
	v_cvt_pk_bf16_f32 v122, v100, v101
	v_cvt_pk_bf16_f32 v123, v102, v103
	v_cvt_pk_bf16_f32 v124, v104, v105
	v_cvt_pk_bf16_f32 v125, v106, v107
	v_cvt_pk_bf16_f32 v126, v108, v109
	v_cvt_pk_bf16_f32 v127, v110, v111
	s_branch .Llw_store
; __device__ __forceinline__ unsigned f2bf(float f) { return cvt_pk_bf16(f, 0.f) & 0xffffu; }
; __device__ __forceinline__ unsigned xb_ld(unsigned* p)              { return __hip_atomic_load(p, __ATOMIC_RELAXED, __HIP_MEMORY_SCOPE_AGENT); }
; __device__ __forceinline__ void xcd_barrier_complete(unsigned* bar, unsigned x, unsigned& nloc, unsigned& nx) {
;     const unsigned G = gridDim.x * gridDim.y * gridDim.z;
;     unsigned sum, cnt, mine, sp = 0u;
;     for (;;) {
;         sum = 0u; cnt = 0u; mine = 0u;
; #pragma unroll
;         for (unsigned j = 0; j < 16; ++j) { const unsigned c = xb_ld(&bar[XB_XCNT(j)]); sum += c; cnt += (c > 0u) ? 1u : 0u; mine = (j == x) ? c : mine; }
;         if (sum == G) break;
;         __builtin_amdgcn_s_sleep(1);
;         if ((++sp & 255u) == 0u) { if (xb_ld(&bar[XB_TMO])) break; if (sp > XB_SPIN_CAP) { atomicAdd(&bar[XB_TMO], 1u); break; } }
;     }
;     nloc = mine > 0u ? mine : 1u; nx = cnt > 0u ? cnt : 1u;
; }
; __device__ __forceinline__ void xcd_barrier(const XcdBarrier& b) {
;     asm volatile("s_waitcnt vmcnt(0)" ::: "memory");
;     __syncthreads();
;     if (threadIdx.x == 0) {
;         unsigned* bar = b.bar;
;         __builtin_amdgcn_s_waitcnt(0);
;         unsigned nloc = b.st[0], nx = b.st[1];
;         if (nloc == 0u) { xcd_barrier_complete(bar, b.x, nloc, nx); b.st[0] = nloc; b.st[1] = nx; }
; __device__ __forceinline__ void lora_weight(Frame& F, const float* W, int KR, int KP, bf16* dst) {
;     const int total = 2048 * KP; const int gt = blockIdx.x * 512 + F.tid, NT = F.G * 512;
;     for (int e = gt; e < total; e += NT) { const int n = e / KP, k = e % KP; dst[e] = (bf16)(k < KR ? f2bf(W[(size_t)k * 2048 + n]) : 0u); }
; }
.Llw_zero:
	v_mov_b32_e32 v112, 0
	v_mov_b32_e32 v113, 0
	v_mov_b32_e32 v114, 0
	v_mov_b32_e32 v115, 0
	v_mov_b32_e32 v116, 0
	v_mov_b32_e32 v117, 0
	v_mov_b32_e32 v118, 0
	v_mov_b32_e32 v119, 0
	v_mov_b32_e32 v120, 0
	v_mov_b32_e32 v121, 0
	v_mov_b32_e32 v122, 0
	v_mov_b32_e32 v123, 0
	v_mov_b32_e32 v124, 0
	v_mov_b32_e32 v125, 0
	v_mov_b32_e32 v126, 0
	v_mov_b32_e32 v127, 0
.Llw_store:
	global_store_dwordx4 v131, v[112:115], s[36:37]
	global_store_dwordx4 v131, v[116:119], s[36:37] offset:16
	global_store_dwordx4 v131, v[120:123], s[36:37] offset:32
	global_store_dwordx4 v131, v[124:127], s[36:37] offset:48
	s_add_i32 s38, s38, s92
	s_cmpk_lt_i32 s38, 0x400
	s_cbranch_scc1 .Llw_task
.Llw_done:
.LBB0_86:
	s_or_b64 exec, exec, s[0:1]
	s_waitcnt vmcnt(0)
	s_waitcnt lgkmcnt(0)
	s_barrier
	s_and_saveexec_b64 s[0:1], s[80:81]
	s_cbranch_execz .LBB0_138
	s_add_i32 s3, 0, 0x23f20
	v_mov_b32_e32 v1, s3
	s_waitcnt vmcnt(0) expcnt(0) lgkmcnt(0)
	ds_read_b32 v3, v1
	s_add_i32 s3, 0, 0x23f24
	v_mov_b32_e32 v1, s3
	ds_read_b32 v1, v1
	s_waitcnt lgkmcnt(1)
	v_cmp_ne_u32_e32 vcc, 0, v3
	s_cbranch_vccnz .LBB0_102
	s_load_dwordx2 s[8:9], s[82:83], 0x4
	s_add_u32 s4, s90, 0x1200
	s_addc_u32 s5, s91, 0
	s_add_u32 s6, s90, 0x1400
	s_addc_u32 s7, s91, 0
	s_waitcnt lgkmcnt(0)
	s_mul_i32 s3, s8, s96
	s_add_u32 s8, s90, 0x1500
	s_mul_i32 s3, s3, s9
	s_addc_u32 s9, s91, 0
	s_add_u32 s10, s90, 0x1600
	s_addc_u32 s11, s91, 0
	s_add_u32 s12, s90, 0x1700
	s_addc_u32 s13, s91, 0
	s_add_u32 s14, s90, 0x1800
	s_addc_u32 s15, s91, 0
	s_add_u32 s16, s90, 0x1900
	s_addc_u32 s17, s91, 0
	s_add_u32 s18, s90, 0x1a00
	s_addc_u32 s19, s91, 0
	s_add_u32 s20, s90, 0x1b00
	s_addc_u32 s21, s91, 0
	s_add_u32 s22, s90, 0x1c00
	s_addc_u32 s23, s91, 0
	s_add_u32 s24, s90, 0x1d00
	s_addc_u32 s25, s91, 0
	s_add_u32 s26, s90, 0x1e00
	s_addc_u32 s27, s91, 0
	s_add_u32 s28, s90, 0x1f00
	s_addc_u32 s29, s91, 0
	s_add_u32 s30, s90, 0x2000
	s_addc_u32 s31, s91, 0
	s_add_u32 s34, s90, 0x2100
	s_addc_u32 s35, s91, 0
	s_add_u32 s36, s90, 0x2200
	s_addc_u32 s37, s91, 0
	s_add_u32 s38, s90, 0x2300
	s_addc_u32 s39, s91, 0
	s_mov_b32 s46, 1
	v_mov_b32_e32 v17, 0
	s_branch .LBB0_90

; __device__ __forceinline__ float bf2f(bf16 x) { return __uint_as_float(((unsigned)x) << 16); }
; #define PREP_LD(R_, K_, V_, L_, A_, t) do { _Pragma("unroll") for (int q = 0; q < 8; ++q) { const size_t o_ = (size_t)((t) + q); R_[q] = zp[o_ * LDZR]; K_[q] = zp[o_ * LDZR + 2048]; V_[q] = zp[o_ * LDZR + 4096]; L_[q] = lp[o_ * DH]; A_[q] = ap[o_ * DH]; } } while (0)
; __device__ __forceinline__ float zr_prev(const bf16* ZR, const float* sh0, int row, int col) {
;     if (row < MPR) return row == 0 ? 0.f : bf2f(ZR[(size_t)(row - 1) * LDZR + col]);
;     const int q = row - MPR, s = q >> 4, t = q & 15;
;     return t == 0 ? sh0[(size_t)s * DRIN + col] : bf2f(ZR[(size_t)(row - 1) * LDZR + col]);
; }
; __device__ __forceinline__ void rw_prep(Frame& F) {
;     const bf16* ZR = (const bf16*)(F.ws + WS_ZR); const bf16* LOGW = (const bf16*)F.out; const bf16* ASIG = (const bf16*)F.out + (size_t)MP * DH;
;     float* REC = (float*)(F.ws + WS_REC); float* RK = (float*)(F.ws + WS_RK); float* WC = (float*)(F.ws + WS_WC); float* VS = (float*)(F.ws + WS_VS);
;     const float* mu = F.in[I_MU]; const float* sh0 = F.in[I_SSH];
;     const int lane = F.lane;
;     for (int u = F.gw; u < RWU; u += F.NGW) {
;         int h, row0, n, rec0; rw_unit_decode(u, h, row0, n, rec0);
;         const int col = h * 64 + lane;
;         const float mur = mu[col], muk = mu[2048 + col], muv = mu[4096 + col], kkw = F.in[I_KK][col], kaw = F.in[I_KA][col], rkw = F.in[I_RK][col];
;         float pr = zr_prev(ZR, sh0, row0, col), pk = zr_prev(ZR, sh0, row0, 2048 + col), pv = zr_prev(ZR, sh0, row0, 4096 + col);
;         float Lw = 0.f;
;         bf16 cr[8], ck[8], cv[8], lw[8], as[8], nr[8], nk[8], nv[8], nl[8], na[8];
;         const bf16* zp = ZR + (size_t)row0 * LDZR + col; const bf16* lp = LOGW + (size_t)row0 * DH + col; const bf16* ap = ASIG + (size_t)row0 * DH + col;
;     ...
;         PREP_LD(cr, ck, cv, lw, as, 0);
;         for (int t0 = 0; t0 < n; t0 += 8) {
;             { const int tn = t0 + 8 < n ? t0 + 8 : t0; PREP_LD(nr, nk, nv, nl, na, tn); }
.LBB0_910:
	s_or_b64 exec, exec, s[0:1]
	s_add_u32 s3, s90, 0x6e200000
	s_addc_u32 s80, s91, 0
	s_add_u32 s4, s90, 0x28700000
	s_addc_u32 s5, s91, 0
	s_cmpk_gt_i32 s94, 0x20ff
	v_lshlrev_b32_e32 v58, 2, v178
	s_waitcnt lgkmcnt(0)
	s_barrier
	s_cbranch_scc1 .LBB0_966
	s_load_dwordx2 s[0:1], s[74:75], 0x20
	s_load_dwordx2 s[8:9], s[74:75], 0x78
	s_load_dwordx4 s[12:15], s[74:75], 0xa8
	s_load_dwordx2 s[10:11], s[74:75], 0xb8
	v_lshlrev_b32_e32 v11, 1, v178
	v_add_u32_e32 v12, 0x1000, v11
	v_add_u32_e32 v13, 0x2000, v11
	v_lshlrev_b32_e32 v14, 2, v178
	v_mov_b32_e32 v15, 0x260
	s_mov_b32 s56, 0xbfb8aa3b
	s_mov_b32 s58, 0x3f317217
	s_mov_b32 s59, 0xf800000
	s_mov_b32 s16, s94
	s_waitcnt lgkmcnt(0)
.Lpp_unit:
	s_cmpk_lt_i32 s16, 0x2000
	s_cbranch_scc0 .Lpp_samp
	s_lshr_b32 s17, s16, 8
	s_and_b32 s20, s16, 0xff
	s_lshl_b32 s20, s20, 6
	s_mov_b32 s21, 4
	s_lshl_b32 s22, s17, 14
	s_add_i32 s22, s22, s20
	s_branch .Lpp_dec
.Lpp_samp:
	s_sub_i32 s23, s16, 0x2000
	s_and_b32 s17, s23, 31
	s_lshr_b32 s20, s23, 5
	s_lshl_b32 s20, s20, 4
	s_add_i32 s20, s20, 0x4000
	s_mov_b32 s21, 1
	s_lshl_b32 s22, s23, 4
	s_add_i32 s22, s22, 0x80000
.Lpp_dec:
	s_lshl_b32 s23, s17, 8
	s_add_u32 s46, s8, s23
	s_addc_u32 s47, s9, 0
	global_load_dword v1, v14, s[46:47]
	s_add_u32 s48, s46, 0x2000
	s_addc_u32 s49, s47, 0
	global_load_dword v2, v14, s[48:49]
	s_add_u32 s48, s46, 0x4000
	s_addc_u32 s49, s47, 0
	global_load_dword v3, v14, s[48:49]
	s_add_u32 s48, s12, s23
	s_addc_u32 s49, s13, 0
	global_load_dword v4, v14, s[48:49]
	s_add_u32 s48, s14, s23
	s_addc_u32 s49, s15, 0
	global_load_dword v5, v14, s[48:49]
	s_add_u32 s48, s10, s23
	s_addc_u32 s49, s11, 0
	global_load_dword v6, v14, s[48:49]
	s_mul_i32 s23, s20, 13824
	s_lshl_b32 s46, s17, 7
	s_add_u32 s23, s23, s46
	s_add_u32 s50, s90, s23
	s_addc_u32 s51, s91, 0
	s_add_u32 s50, s50, 0x49d00000
	s_addc_u32 s51, s51, 0
	s_lshl_b32 s23, s20, 12
	s_add_u32 s23, s23, s46
	s_add_u32 s52, s88, s23
	s_addc_u32 s53, s89, 0
	s_add_u32 s54, s52, 0x4100000
	s_addc_u32 s55, s53, 0
	s_cmp_eq_u32 s20, 0
	s_cbranch_scc1 .Lpp_prev0
	s_cmpk_lt_i32 s20, 0x4000
	s_cbranch_scc0 .Lpp_prevs
	s_sub_u32 s46, s50, 13824
	s_subb_u32 s47, s51, 0
	global_load_ushort v7, v11, s[46:47]
	global_load_ushort v8, v12, s[46:47]
	global_load_ushort v9, v13, s[46:47]
	s_waitcnt vmcnt(0)
	v_lshlrev_b32_e32 v7, 16, v7
	v_lshlrev_b32_e32 v8, 16, v8
	v_lshlrev_b32_e32 v9, 16, v9
	s_branch .Lpp_prevok
.Lpp_prevs:
	s_sub_i32 s46, s20, 0x4000
	s_lshr_b32 s46, s46, 4
	s_mul_i32 s46, s46, 27520
	s_lshl_b32 s47, s17, 8
	s_add_u32 s46, s46, s47
	s_add_u32 s46, s0, s46
	s_addc_u32 s47, s1, 0
	global_load_dword v7, v14, s[46:47]
	s_add_u32 s48, s46, 0x2000
	s_addc_u32 s49, s47, 0
	global_load_dword v8, v14, s[48:49]
	s_add_u32 s48, s46, 0x4000
	s_addc_u32 s49, s47, 0
	global_load_dword v9, v14, s[48:49]
	s_branch .Lpp_prevok
.Lpp_prev0:
	v_mov_b32_e32 v7, 0
	v_mov_b32_e32 v8, 0
	v_mov_b32_e32 v9, 0
.Lpp_prevok:
	s_lshr_b32 s47, s22, 22
	s_lshl_b32 s46, s22, 10
	s_add_u32 s40, s90, s46
	s_addc_u32 s41, s91, s47
	s_add_u32 s40, s40, 0x8300000
	s_addc_u32 s41, s41, 0
	s_lshl_b32 s46, s20, 13
	s_lshl_b32 s47, s17, 8
	s_add_u32 s46, s46, s47
	s_add_u32 s42, s90, s46
	s_addc_u32 s43, s91, 0
	s_add_u32 s42, s42, 0x28700000
	s_addc_u32 s43, s43, 0
	s_lshl_b32 s46, s20, 7
	s_lshl_b32 s47, s17, 2
	s_add_u32 s46, s46, s47
	s_add_u32 s44, s90, s46
	s_addc_u32 s45, s91, 0
	s_add_u32 s44, s44, 0x6e200000
	s_addc_u32 s45, s45, 0
	v_mov_b32_e32 v10, 0
	global_load_ushort v64, v11, s[50:51]
	global_load_ushort v65, v12, s[50:51]
	global_load_ushort v66, v13, s[50:51]
	global_load_ushort v67, v11, s[52:53]
	global_load_ushort v68, v11, s[54:55]
	s_add_u32 s50, s50, 13824
	s_addc_u32 s51, s51, 0
	s_add_u32 s52, s52, 0x1000
	s_addc_u32 s53, s53, 0
	s_add_u32 s54, s54, 0x1000
	s_addc_u32 s55, s55, 0
	global_load_ushort v69, v11, s[50:51]
	global_load_ushort v70, v12, s[50:51]
	global_load_ushort v71, v13, s[50:51]
	global_load_ushort v72, v11, s[52:53]
	global_load_ushort v73, v11, s[54:55]
	s_add_u32 s50, s50, 13824
	s_addc_u32 s51, s51, 0
	s_add_u32 s52, s52, 0x1000
	s_addc_u32 s53, s53, 0
	s_add_u32 s54, s54, 0x1000
	s_addc_u32 s55, s55, 0
	global_load_ushort v74, v11, s[50:51]
	global_load_ushort v75, v12, s[50:51]
	global_load_ushort v76, v13, s[50:51]
	global_load_ushort v77, v11, s[52:53]
	global_load_ushort v78, v11, s[54:55]
	s_add_u32 s50, s50, 13824
	s_addc_u32 s51, s51, 0
	s_add_u32 s52, s52, 0x1000
	s_addc_u32 s53, s53, 0
	s_add_u32 s54, s54, 0x1000
	s_addc_u32 s55, s55, 0
	global_load_ushort v79, v11, s[50:51]
	global_load_ushort v80, v12, s[50:51]
	global_load_ushort v81, v13, s[50:51]
	global_load_ushort v82, v11, s[52:53]
	global_load_ushort v83, v11, s[54:55]
	s_add_u32 s50, s50, 13824
	s_addc_u32 s51, s51, 0
	s_add_u32 s52, s52, 0x1000
	s_addc_u32 s53, s53, 0
	s_add_u32 s54, s54, 0x1000
	s_addc_u32 s55, s55, 0
	global_load_ushort v84, v11, s[50:51]
	global_load_ushort v85, v12, s[50:51]
	global_load_ushort v86, v13, s[50:51]
	global_load_ushort v87, v11, s[52:53]
	global_load_ushort v88, v11, s[54:55]
	s_add_u32 s50, s50, 13824
	s_addc_u32 s51, s51, 0
	s_add_u32 s52, s52, 0x1000
	s_addc_u32 s53, s53, 0
	s_add_u32 s54, s54, 0x1000
	s_addc_u32 s55, s55, 0
	global_load_ushort v89, v11, s[50:51]
	global_load_ushort v90, v12, s[50:51]
	global_load_ushort v91, v13, s[50:51]
	global_load_ushort v92, v11, s[52:53]
	global_load_ushort v93, v11, s[54:55]
	s_add_u32 s50, s50, 13824
	s_addc_u32 s51, s51, 0
	s_add_u32 s52, s52, 0x1000
	s_addc_u32 s53, s53, 0
	s_add_u32 s54, s54, 0x1000
	s_addc_u32 s55, s55, 0
	global_load_ushort v94, v11, s[50:51]
	global_load_ushort v95, v12, s[50:51]
	global_load_ushort v96, v13, s[50:51]
	global_load_ushort v97, v11, s[52:53]
	global_load_ushort v98, v11, s[54:55]
	s_add_u32 s50, s50, 13824
	s_addc_u32 s51, s51, 0
	s_add_u32 s52, s52, 0x1000
	s_addc_u32 s53, s53, 0
	s_add_u32 s54, s54, 0x1000
	s_addc_u32 s55, s55, 0
	global_load_ushort v99, v11, s[50:51]
	global_load_ushort v100, v12, s[50:51]
	global_load_ushort v101, v13, s[50:51]
	global_load_ushort v102, v11, s[52:53]
	global_load_ushort v103, v11, s[54:55]
	s_add_u32 s50, s50, 13824
	s_addc_u32 s51, s51, 0
	s_add_u32 s52, s52, 0x1000
	s_addc_u32 s53, s53, 0
	s_add_u32 s54, s54, 0x1000
	s_addc_u32 s55, s55, 0
	s_waitcnt vmcnt(0)
; __device__ __forceinline__ float bf2f(bf16 x) { return __uint_as_float(((unsigned)x) << 16); }
; __device__ __forceinline__ float sigmoidf_(float x) { return __builtin_amdgcn_rcpf(1.0f + __expf(-x)); }
; __device__ __forceinline__ float dpp_xor1(float x) { return __builtin_bit_cast(float, __builtin_amdgcn_update_dpp(0, __builtin_bit_cast(int, x), 0xB1, 0xF, 0xF, true)); }
; __device__ __forceinline__ float dpp_xor2(float x) { return __builtin_bit_cast(float, __builtin_amdgcn_update_dpp(0, __builtin_bit_cast(int, x), 0x4E, 0xF, 0xF, true)); }
; __device__ __forceinline__ float red16(float x) { x += dpp_xor1(x); x += dpp_xor2(x); x += dpp_hmir(x); x += dpp_mir(x); return x; }
; __device__ __forceinline__ float wsum(float x) {
;     x = red16(x); const int xi = __builtin_bit_cast(int, x);
;     const float r0 = __builtin_bit_cast(float, __builtin_amdgcn_readlane(xi, 0)), r1 = __builtin_bit_cast(float, __builtin_amdgcn_readlane(xi, 16));
;     const float r2 = __builtin_bit_cast(float, __builtin_amdgcn_readlane(xi, 32)), r3 = __builtin_bit_cast(float, __builtin_amdgcn_readlane(xi, 48));
;     return (r0 + r1) + (r2 + r3);
; __device__ __forceinline__ void rw_prep(Frame& F) {
;     ...
;             for (int q = 0; q < 8; ++q) { const int row = row0 + t0 + q;
;                 const float crq = bf2f(cr[q]), ckq = bf2f(ck[q]), cvq = bf2f(cv[q]);
;                 const float rr = crq + (pr - crq) * mur, kv = ckq + (pk - ckq) * muk;
;                 const float nx = -bf2f(lw[q]); const float sp = fmaxf(nx, 0.f) + __logf(1.0f + __expf(-fabsf(nx))); const float lgw = -__expf(-sp - 0.5f); const float asg = sigmoidf_(bf2f(as[q]));
;                 float kk = kv * kkw; const float nrm = sqrtf(wsum(kk * kk)); kk = kk / fmaxf(nrm, 1e-12f);
;                 const float k_ = kv * (1.f + (asg - 1.f) * kaw);
;                 const float rk = wsum(rr * k_ * rkw);
;                 const float eex = __expf(Lw); Lw += lgw; const float ein = __expf(Lw), einv = __expf(-Lw);
;                 float* rec = REC + (size_t)(rec0 + t0 + q) * 256;
;                 rec[lane] = -kk * eex; rec[64 + lane] = kk * asg * einv; rec[128 + lane] = k_ * einv; rec[192 + lane] = rr * ein;
;                 if (lane == 0) RK[(size_t)row * 32 + h] = rk;
;                 VS[(size_t)row * DH + col] = cvq + (pv - cvq) * muv;
;                 pr = crq; pk = ckq; pv = cvq; }
.Lpp_pair:
	v_lshlrev_b32_e32 v20, 16, v64
	v_lshlrev_b32_e32 v21, 16, v65
	v_lshlrev_b32_e32 v23, 16, v67
	v_lshlrev_b32_e32 v24, 16, v68
	v_lshlrev_b32_e32 v22, 16, v66
	v_sub_f32_e32 v26, v8, v21
	v_sub_f32_e32 v25, v7, v20
	v_fma_f32 v26, v2, v26, v21
	v_fma_f32 v25, v1, v25, v20
	v_mul_f32_e32 v32, v4, v26
	v_mul_f32_e32 v33, v32, v32
	v_max_f32_e64 v27, -v23, -v23
	v_mul_f32_e64 v28, |v23|, s56
	v_mov_b32_dpp v33, v33 quad_perm:[1,0,3,2] row_mask:0xf bank_mask:0xf bound_ctrl:1
	v_fmac_f32_e32 v33, v32, v32
	v_exp_f32_e32 v28, v28
	v_max_f32_e32 v27, 0, v27
	v_add_f32_dpp v33, v33, v33 quad_perm:[2,3,0,1] row_mask:0xf bank_mask:0xf bound_ctrl:1
	v_add_f32_e32 v28, 1.0, v28
	v_mul_f32_e32 v31, 0xbfb8aa3b, v24
	v_add_f32_dpp v33, v33, v33 row_half_mirror row_mask:0xf bank_mask:0xf bound_ctrl:1
	v_log_f32_e32 v28, v28
	v_exp_f32_e32 v31, v31
	v_add_f32_dpp v33, v33, v33 row_mirror row_mask:0xf bank_mask:0xf bound_ctrl:1
	v_mul_f32_e32 v29, 0x3f317217, v28
	v_readlane_b32 s24, v33, 16
	v_readlane_b32 s25, v33, 48
	v_readlane_b32 s26, v33, 0
	v_readlane_b32 s27, v33, 32
	v_fma_f32 v29, v28, s58, -v29
	v_fmac_f32_e32 v29, 0x3377d1cf, v28
	v_mov_b32_e32 v33, s24
	v_mov_b32_e32 v40, s25
	v_add_f32_e32 v33, s26, v33
	v_add_f32_e32 v40, s27, v40
	v_fmac_f32_e32 v29, 0x3f317217, v28
	v_add_f32_e32 v33, v33, v40
	v_add_f32_e32 v31, 1.0, v31
	v_rcp_f32_e32 v31, v31
	v_add_f32_e32 v27, v27, v29
	v_sub_f32_e32 v27, -0.5, v27
	v_mul_f32_e32 v27, 0x3fb8aa3b, v27
	v_exp_f32_e32 v27, v27
	v_cmp_gt_f32_e32 vcc, s59, v33
	v_mul_f32_e32 v40, 0x4f800000, v33
	v_sub_f32_e32 v30, v10, v27
	v_cndmask_b32_e32 v33, v33, v40, vcc
	v_sqrt_f32_e32 v34, v33
	v_add_f32_e32 v36, -1.0, v31
	v_add_u32_e32 v41, -1, v34
	v_fma_f32 v42, -v41, v34, v33
	v_cmp_ge_f32_e64 s[28:29], 0, v42
	v_add_u32_e32 v42, 1, v34
	v_fma_f32 v36, v5, v36, 1.0
	v_cndmask_b32_e64 v41, v34, v41, s[28:29]
	v_fma_f32 v34, -v42, v34, v33
	v_cmp_lt_f32_e64 s[28:29], 0, v34
	v_mul_f32_e32 v37, v26, v36
	v_mul_f32_e32 v38, v25, v37
	v_cndmask_b32_e64 v34, v41, v42, s[28:29]
	v_mul_f32_e32 v41, 0x37800000, v34
	v_mul_f32_e32 v39, v6, v38
	v_cndmask_b32_e32 v34, v34, v41, vcc
	v_cmp_class_f32_e32 vcc, v33, v15
	v_mov_b32_dpp v39, v39 quad_perm:[1,0,3,2] row_mask:0xf bank_mask:0xf bound_ctrl:1
	v_fmac_f32_e32 v39, v6, v38
	v_cndmask_b32_e32 v34, v34, v33, vcc
	v_max_f32_e32 v34, 0x2b8cbccc, v34
	v_add_f32_dpp v39, v39, v39 quad_perm:[2,3,0,1] row_mask:0xf bank_mask:0xf bound_ctrl:1
	v_div_scale_f32 v40, s[28:29], v34, v34, v32
	v_rcp_f32_e32 v41, v40
	v_add_f32_dpp v39, v39, v39 row_half_mirror row_mask:0xf bank_mask:0xf bound_ctrl:1
	v_fma_f32 v42, -v40, v41, 1.0
	v_fmac_f32_e32 v41, v42, v41
	v_add_f32_dpp v39, v39, v39 row_mirror row_mask:0xf bank_mask:0xf bound_ctrl:1
	v_div_scale_f32 v42, vcc, v32, v34, v32
	v_mul_f32_e32 v43, v42, v41
	v_fma_f32 v44, -v40, v43, v42
	v_fmac_f32_e32 v43, v44, v41
	v_fma_f32 v40, -v40, v43, v42
	v_readlane_b32 s24, v39, 0
	v_readlane_b32 s25, v39, 16
	v_readlane_b32 s26, v39, 32
	v_readlane_b32 s27, v39, 48
	v_div_fmas_f32 v40, v40, v41, v43
	v_div_fixup_f32 v35, v40, v34, v32
	v_mul_f32_e32 v46, 0x3fb8aa3b, v10
	v_mul_f32_e32 v47, 0x3fb8aa3b, v30
	v_mul_f32_e32 v48, 0xbfb8aa3b, v30
	v_exp_f32_e32 v46, v46
	v_exp_f32_e32 v47, v47
	v_exp_f32_e32 v48, v48
	v_mul_f32_e32 v45, v31, v35
	v_mov_b32_e32 v41, s25
	v_mov_b32_e32 v42, s27
	v_add_f32_e32 v41, s24, v41
	v_add_f32_e32 v42, s26, v42
	v_mul_f32_e64 v49, v46, -v35
	v_mul_f32_e32 v50, v48, v45
	v_mul_f32_e32 v51, v37, v48
	v_mul_f32_e32 v52, v25, v47
	v_add_f32_e32 v41, v41, v42
	global_store_dword v14, v49, s[40:41]
	global_store_dword v14, v50, s[40:41] offset:256
	global_store_dword v14, v51, s[40:41] offset:512
	global_store_dword v14, v52, s[40:41] offset:768
	v_sub_f32_e32 v53, v9, v22
	v_fma_f32 v53, v3, v53, v22
	global_store_dword v14, v53, s[42:43]
	s_mov_b64 s[60:61], exec
	s_mov_b64 exec, 1
	v_mov_b32_e32 v42, 0
	global_store_dword v42, v41, s[44:45]
	s_mov_b64 exec, s[60:61]
	v_mov_b32_e32 v7, v20
	v_mov_b32_e32 v8, v21
	v_mov_b32_e32 v9, v22
	v_mov_b32_e32 v10, v30
	s_add_u32 s40, s40, 0x400
	s_addc_u32 s41, s41, 0
	s_add_u32 s42, s42, 0x2000
	s_addc_u32 s43, s43, 0
	s_add_u32 s44, s44, 0x80
	s_addc_u32 s45, s45, 0
	v_lshlrev_b32_e32 v20, 16, v69
	v_lshlrev_b32_e32 v21, 16, v70
	v_lshlrev_b32_e32 v23, 16, v72
	v_lshlrev_b32_e32 v24, 16, v73
	v_lshlrev_b32_e32 v22, 16, v71
	v_sub_f32_e32 v26, v8, v21
	v_sub_f32_e32 v25, v7, v20
	v_fma_f32 v26, v2, v26, v21
	v_fma_f32 v25, v1, v25, v20
	v_mul_f32_e32 v32, v4, v26
	v_mul_f32_e32 v33, v32, v32
	v_max_f32_e64 v27, -v23, -v23
	v_mul_f32_e64 v28, |v23|, s56
	v_mov_b32_dpp v33, v33 quad_perm:[1,0,3,2] row_mask:0xf bank_mask:0xf bound_ctrl:1
	v_fmac_f32_e32 v33, v32, v32
	v_exp_f32_e32 v28, v28
	v_max_f32_e32 v27, 0, v27
	v_add_f32_dpp v33, v33, v33 quad_perm:[2,3,0,1] row_mask:0xf bank_mask:0xf bound_ctrl:1
	v_add_f32_e32 v28, 1.0, v28
	v_mul_f32_e32 v31, 0xbfb8aa3b, v24
	v_add_f32_dpp v33, v33, v33 row_half_mirror row_mask:0xf bank_mask:0xf bound_ctrl:1
	v_log_f32_e32 v28, v28
	v_exp_f32_e32 v31, v31
	v_add_f32_dpp v33, v33, v33 row_mirror row_mask:0xf bank_mask:0xf bound_ctrl:1
	v_mul_f32_e32 v29, 0x3f317217, v28
	v_readlane_b32 s24, v33, 16
	v_readlane_b32 s25, v33, 48
	v_readlane_b32 s26, v33, 0
	v_readlane_b32 s27, v33, 32
	v_fma_f32 v29, v28, s58, -v29
	v_fmac_f32_e32 v29, 0x3377d1cf, v28
	v_mov_b32_e32 v33, s24
	v_mov_b32_e32 v40, s25
	v_add_f32_e32 v33, s26, v33
	v_add_f32_e32 v40, s27, v40
	v_fmac_f32_e32 v29, 0x3f317217, v28
	v_add_f32_e32 v33, v33, v40
	v_add_f32_e32 v31, 1.0, v31
	v_rcp_f32_e32 v31, v31
	v_add_f32_e32 v27, v27, v29
; __device__ __forceinline__ float bf2f(bf16 x) { return __uint_as_float(((unsigned)x) << 16); }
; __device__ __forceinline__ float sigmoidf_(float x) { return __builtin_amdgcn_rcpf(1.0f + __expf(-x)); }
; __device__ __forceinline__ float dpp_xor1(float x) { return __builtin_bit_cast(float, __builtin_amdgcn_update_dpp(0, __builtin_bit_cast(int, x), 0xB1, 0xF, 0xF, true)); }
; __device__ __forceinline__ float dpp_xor2(float x) { return __builtin_bit_cast(float, __builtin_amdgcn_update_dpp(0, __builtin_bit_cast(int, x), 0x4E, 0xF, 0xF, true)); }
; __device__ __forceinline__ float red16(float x) { x += dpp_xor1(x); x += dpp_xor2(x); x += dpp_hmir(x); x += dpp_mir(x); return x; }
; __device__ __forceinline__ float wsum(float x) {
;     x = red16(x); const int xi = __builtin_bit_cast(int, x);
;     const float r0 = __builtin_bit_cast(float, __builtin_amdgcn_readlane(xi, 0)), r1 = __builtin_bit_cast(float, __builtin_amdgcn_readlane(xi, 16));
;     const float r2 = __builtin_bit_cast(float, __builtin_amdgcn_readlane(xi, 32)), r3 = __builtin_bit_cast(float, __builtin_amdgcn_readlane(xi, 48));
;     return (r0 + r1) + (r2 + r3);
; __device__ __forceinline__ void rw_prep(Frame& F) {
;     ...
;             for (int q = 0; q < 8; ++q) { const int row = row0 + t0 + q;
;                 const float crq = bf2f(cr[q]), ckq = bf2f(ck[q]), cvq = bf2f(cv[q]);
;                 const float rr = crq + (pr - crq) * mur, kv = ckq + (pk - ckq) * muk;
;                 const float nx = -bf2f(lw[q]); const float sp = fmaxf(nx, 0.f) + __logf(1.0f + __expf(-fabsf(nx))); const float lgw = -__expf(-sp - 0.5f); const float asg = sigmoidf_(bf2f(as[q]));
;                 float kk = kv * kkw; const float nrm = sqrtf(wsum(kk * kk)); kk = kk / fmaxf(nrm, 1e-12f);
;                 const float k_ = kv * (1.f + (asg - 1.f) * kaw);
;                 const float rk = wsum(rr * k_ * rkw);
;                 const float eex = __expf(Lw); Lw += lgw; const float ein = __expf(Lw), einv = __expf(-Lw);
;                 float* rec = REC + (size_t)(rec0 + t0 + q) * 256;
;                 rec[lane] = -kk * eex; rec[64 + lane] = kk * asg * einv; rec[128 + lane] = k_ * einv; rec[192 + lane] = rr * ein;
;                 if (lane == 0) RK[(size_t)row * 32 + h] = rk;
;                 VS[(size_t)row * DH + col] = cvq + (pv - cvq) * muv;
;                 pr = crq; pk = ckq; pv = cvq; }
	v_sub_f32_e32 v27, -0.5, v27
	v_mul_f32_e32 v27, 0x3fb8aa3b, v27
	v_exp_f32_e32 v27, v27
	v_cmp_gt_f32_e32 vcc, s59, v33
	v_mul_f32_e32 v40, 0x4f800000, v33
	v_sub_f32_e32 v30, v10, v27
	v_cndmask_b32_e32 v33, v33, v40, vcc
	v_sqrt_f32_e32 v34, v33
	v_add_f32_e32 v36, -1.0, v31
	v_add_u32_e32 v41, -1, v34
	v_fma_f32 v42, -v41, v34, v33
	v_cmp_ge_f32_e64 s[28:29], 0, v42
	v_add_u32_e32 v42, 1, v34
	v_fma_f32 v36, v5, v36, 1.0
	v_cndmask_b32_e64 v41, v34, v41, s[28:29]
	v_fma_f32 v34, -v42, v34, v33
	v_cmp_lt_f32_e64 s[28:29], 0, v34
	v_mul_f32_e32 v37, v26, v36
	v_mul_f32_e32 v38, v25, v37
	v_cndmask_b32_e64 v34, v41, v42, s[28:29]
	v_mul_f32_e32 v41, 0x37800000, v34
	v_mul_f32_e32 v39, v6, v38
	v_cndmask_b32_e32 v34, v34, v41, vcc
	v_cmp_class_f32_e32 vcc, v33, v15
	v_mov_b32_dpp v39, v39 quad_perm:[1,0,3,2] row_mask:0xf bank_mask:0xf bound_ctrl:1
	v_fmac_f32_e32 v39, v6, v38
	v_cndmask_b32_e32 v34, v34, v33, vcc
	v_max_f32_e32 v34, 0x2b8cbccc, v34
	v_add_f32_dpp v39, v39, v39 quad_perm:[2,3,0,1] row_mask:0xf bank_mask:0xf bound_ctrl:1
	v_div_scale_f32 v40, s[28:29], v34, v34, v32
	v_rcp_f32_e32 v41, v40
	v_add_f32_dpp v39, v39, v39 row_half_mirror row_mask:0xf bank_mask:0xf bound_ctrl:1
	v_fma_f32 v42, -v40, v41, 1.0
	v_fmac_f32_e32 v41, v42, v41
	v_add_f32_dpp v39, v39, v39 row_mirror row_mask:0xf bank_mask:0xf bound_ctrl:1
	v_div_scale_f32 v42, vcc, v32, v34, v32
	v_mul_f32_e32 v43, v42, v41
	v_fma_f32 v44, -v40, v43, v42
	v_fmac_f32_e32 v43, v44, v41
	v_fma_f32 v40, -v40, v43, v42
	v_readlane_b32 s24, v39, 0
	v_readlane_b32 s25, v39, 16
	v_readlane_b32 s26, v39, 32
	v_readlane_b32 s27, v39, 48
	v_div_fmas_f32 v40, v40, v41, v43
	v_div_fixup_f32 v35, v40, v34, v32
	v_mul_f32_e32 v46, 0x3fb8aa3b, v10
	v_mul_f32_e32 v47, 0x3fb8aa3b, v30
	v_mul_f32_e32 v48, 0xbfb8aa3b, v30
	v_exp_f32_e32 v46, v46
	v_exp_f32_e32 v47, v47
	v_exp_f32_e32 v48, v48
	v_mul_f32_e32 v45, v31, v35
	v_mov_b32_e32 v41, s25
	v_mov_b32_e32 v42, s27
	v_add_f32_e32 v41, s24, v41
	v_add_f32_e32 v42, s26, v42
	v_mul_f32_e64 v49, v46, -v35
	v_mul_f32_e32 v50, v48, v45
	v_mul_f32_e32 v51, v37, v48
	v_mul_f32_e32 v52, v25, v47
	v_add_f32_e32 v41, v41, v42
	global_store_dword v14, v49, s[40:41]
	global_store_dword v14, v50, s[40:41] offset:256
	global_store_dword v14, v51, s[40:41] offset:512
	global_store_dword v14, v52, s[40:41] offset:768
	v_sub_f32_e32 v53, v9, v22
	v_fma_f32 v53, v3, v53, v22
	global_store_dword v14, v53, s[42:43]
	s_mov_b64 s[60:61], exec
	s_mov_b64 exec, 1
	v_mov_b32_e32 v42, 0
	global_store_dword v42, v41, s[44:45]
	s_mov_b64 exec, s[60:61]
	v_mov_b32_e32 v7, v20
	v_mov_b32_e32 v8, v21
	v_mov_b32_e32 v9, v22
	v_mov_b32_e32 v10, v30
	s_add_u32 s40, s40, 0x400
	s_addc_u32 s41, s41, 0
	s_add_u32 s42, s42, 0x2000
	s_addc_u32 s43, s43, 0
	s_add_u32 s44, s44, 0x80
	s_addc_u32 s45, s45, 0
	v_lshlrev_b32_e32 v20, 16, v74
	v_lshlrev_b32_e32 v21, 16, v75
	v_lshlrev_b32_e32 v23, 16, v77
	v_lshlrev_b32_e32 v24, 16, v78
	v_lshlrev_b32_e32 v22, 16, v76
	v_sub_f32_e32 v26, v8, v21
	v_sub_f32_e32 v25, v7, v20
	v_fma_f32 v26, v2, v26, v21
	v_fma_f32 v25, v1, v25, v20
	v_mul_f32_e32 v32, v4, v26
	v_mul_f32_e32 v33, v32, v32
	v_max_f32_e64 v27, -v23, -v23
	v_mul_f32_e64 v28, |v23|, s56
	v_mov_b32_dpp v33, v33 quad_perm:[1,0,3,2] row_mask:0xf bank_mask:0xf bound_ctrl:1
	v_fmac_f32_e32 v33, v32, v32
	v_exp_f32_e32 v28, v28
	v_max_f32_e32 v27, 0, v27
	v_add_f32_dpp v33, v33, v33 quad_perm:[2,3,0,1] row_mask:0xf bank_mask:0xf bound_ctrl:1
	v_add_f32_e32 v28, 1.0, v28
	v_mul_f32_e32 v31, 0xbfb8aa3b, v24
	v_add_f32_dpp v33, v33, v33 row_half_mirror row_mask:0xf bank_mask:0xf bound_ctrl:1
	v_log_f32_e32 v28, v28
	v_exp_f32_e32 v31, v31
	v_add_f32_dpp v33, v33, v33 row_mirror row_mask:0xf bank_mask:0xf bound_ctrl:1
	v_mul_f32_e32 v29, 0x3f317217, v28
	v_readlane_b32 s24, v33, 16
	v_readlane_b32 s25, v33, 48
	v_readlane_b32 s26, v33, 0
	v_readlane_b32 s27, v33, 32
	v_fma_f32 v29, v28, s58, -v29
	v_fmac_f32_e32 v29, 0x3377d1cf, v28
	v_mov_b32_e32 v33, s24
	v_mov_b32_e32 v40, s25
	v_add_f32_e32 v33, s26, v33
	v_add_f32_e32 v40, s27, v40
	v_fmac_f32_e32 v29, 0x3f317217, v28
	v_add_f32_e32 v33, v33, v40
	v_add_f32_e32 v31, 1.0, v31
	v_rcp_f32_e32 v31, v31
	v_add_f32_e32 v27, v27, v29
	v_sub_f32_e32 v27, -0.5, v27
	v_mul_f32_e32 v27, 0x3fb8aa3b, v27
	v_exp_f32_e32 v27, v27
	v_cmp_gt_f32_e32 vcc, s59, v33
	v_mul_f32_e32 v40, 0x4f800000, v33
	v_sub_f32_e32 v30, v10, v27
	v_cndmask_b32_e32 v33, v33, v40, vcc
	v_sqrt_f32_e32 v34, v33
	v_add_f32_e32 v36, -1.0, v31
	v_add_u32_e32 v41, -1, v34
	v_fma_f32 v42, -v41, v34, v33
	v_cmp_ge_f32_e64 s[28:29], 0, v42
	v_add_u32_e32 v42, 1, v34
	v_fma_f32 v36, v5, v36, 1.0
	v_cndmask_b32_e64 v41, v34, v41, s[28:29]
	v_fma_f32 v34, -v42, v34, v33
	v_cmp_lt_f32_e64 s[28:29], 0, v34
	v_mul_f32_e32 v37, v26, v36
	v_mul_f32_e32 v38, v25, v37
	v_cndmask_b32_e64 v34, v41, v42, s[28:29]
	v_mul_f32_e32 v41, 0x37800000, v34
	v_mul_f32_e32 v39, v6, v38
	v_cndmask_b32_e32 v34, v34, v41, vcc
	v_cmp_class_f32_e32 vcc, v33, v15
	v_mov_b32_dpp v39, v39 quad_perm:[1,0,3,2] row_mask:0xf bank_mask:0xf bound_ctrl:1
	v_fmac_f32_e32 v39, v6, v38
	v_cndmask_b32_e32 v34, v34, v33, vcc
	v_max_f32_e32 v34, 0x2b8cbccc, v34
	v_add_f32_dpp v39, v39, v39 quad_perm:[2,3,0,1] row_mask:0xf bank_mask:0xf bound_ctrl:1
	v_div_scale_f32 v40, s[28:29], v34, v34, v32
	v_rcp_f32_e32 v41, v40
	v_add_f32_dpp v39, v39, v39 row_half_mirror row_mask:0xf bank_mask:0xf bound_ctrl:1
	v_fma_f32 v42, -v40, v41, 1.0
	v_fmac_f32_e32 v41, v42, v41
	v_add_f32_dpp v39, v39, v39 row_mirror row_mask:0xf bank_mask:0xf bound_ctrl:1
	v_div_scale_f32 v42, vcc, v32, v34, v32
	v_mul_f32_e32 v43, v42, v41
; __device__ __forceinline__ float bf2f(bf16 x) { return __uint_as_float(((unsigned)x) << 16); }
; __device__ __forceinline__ float sigmoidf_(float x) { return __builtin_amdgcn_rcpf(1.0f + __expf(-x)); }
; __device__ __forceinline__ float dpp_xor1(float x) { return __builtin_bit_cast(float, __builtin_amdgcn_update_dpp(0, __builtin_bit_cast(int, x), 0xB1, 0xF, 0xF, true)); }
; __device__ __forceinline__ float dpp_xor2(float x) { return __builtin_bit_cast(float, __builtin_amdgcn_update_dpp(0, __builtin_bit_cast(int, x), 0x4E, 0xF, 0xF, true)); }
; __device__ __forceinline__ float red16(float x) { x += dpp_xor1(x); x += dpp_xor2(x); x += dpp_hmir(x); x += dpp_mir(x); return x; }
; __device__ __forceinline__ float wsum(float x) {
;     x = red16(x); const int xi = __builtin_bit_cast(int, x);
;     const float r0 = __builtin_bit_cast(float, __builtin_amdgcn_readlane(xi, 0)), r1 = __builtin_bit_cast(float, __builtin_amdgcn_readlane(xi, 16));
;     const float r2 = __builtin_bit_cast(float, __builtin_amdgcn_readlane(xi, 32)), r3 = __builtin_bit_cast(float, __builtin_amdgcn_readlane(xi, 48));
;     return (r0 + r1) + (r2 + r3);
; __device__ __forceinline__ void rw_prep(Frame& F) {
;     ...
;             for (int q = 0; q < 8; ++q) { const int row = row0 + t0 + q;
;                 const float crq = bf2f(cr[q]), ckq = bf2f(ck[q]), cvq = bf2f(cv[q]);
;                 const float rr = crq + (pr - crq) * mur, kv = ckq + (pk - ckq) * muk;
;                 const float nx = -bf2f(lw[q]); const float sp = fmaxf(nx, 0.f) + __logf(1.0f + __expf(-fabsf(nx))); const float lgw = -__expf(-sp - 0.5f); const float asg = sigmoidf_(bf2f(as[q]));
;                 float kk = kv * kkw; const float nrm = sqrtf(wsum(kk * kk)); kk = kk / fmaxf(nrm, 1e-12f);
;                 const float k_ = kv * (1.f + (asg - 1.f) * kaw);
;                 const float rk = wsum(rr * k_ * rkw);
;                 const float eex = __expf(Lw); Lw += lgw; const float ein = __expf(Lw), einv = __expf(-Lw);
;                 float* rec = REC + (size_t)(rec0 + t0 + q) * 256;
;                 rec[lane] = -kk * eex; rec[64 + lane] = kk * asg * einv; rec[128 + lane] = k_ * einv; rec[192 + lane] = rr * ein;
;                 if (lane == 0) RK[(size_t)row * 32 + h] = rk;
;                 VS[(size_t)row * DH + col] = cvq + (pv - cvq) * muv;
;                 pr = crq; pk = ckq; pv = cvq; }
	v_fma_f32 v44, -v40, v43, v42
	v_fmac_f32_e32 v43, v44, v41
	v_fma_f32 v40, -v40, v43, v42
	v_readlane_b32 s24, v39, 0
	v_readlane_b32 s25, v39, 16
	v_readlane_b32 s26, v39, 32
	v_readlane_b32 s27, v39, 48
	v_div_fmas_f32 v40, v40, v41, v43
	v_div_fixup_f32 v35, v40, v34, v32
	v_mul_f32_e32 v46, 0x3fb8aa3b, v10
	v_mul_f32_e32 v47, 0x3fb8aa3b, v30
	v_mul_f32_e32 v48, 0xbfb8aa3b, v30
	v_exp_f32_e32 v46, v46
	v_exp_f32_e32 v47, v47
	v_exp_f32_e32 v48, v48
	v_mul_f32_e32 v45, v31, v35
	v_mov_b32_e32 v41, s25
	v_mov_b32_e32 v42, s27
	v_add_f32_e32 v41, s24, v41
	v_add_f32_e32 v42, s26, v42
	v_mul_f32_e64 v49, v46, -v35
	v_mul_f32_e32 v50, v48, v45
	v_mul_f32_e32 v51, v37, v48
	v_mul_f32_e32 v52, v25, v47
	v_add_f32_e32 v41, v41, v42
	global_store_dword v14, v49, s[40:41]
	global_store_dword v14, v50, s[40:41] offset:256
	global_store_dword v14, v51, s[40:41] offset:512
	global_store_dword v14, v52, s[40:41] offset:768
	v_sub_f32_e32 v53, v9, v22
	v_fma_f32 v53, v3, v53, v22
	global_store_dword v14, v53, s[42:43]
	s_mov_b64 s[60:61], exec
	s_mov_b64 exec, 1
	v_mov_b32_e32 v42, 0
	global_store_dword v42, v41, s[44:45]
	s_mov_b64 exec, s[60:61]
	v_mov_b32_e32 v7, v20
	v_mov_b32_e32 v8, v21
	v_mov_b32_e32 v9, v22
	v_mov_b32_e32 v10, v30
	s_add_u32 s40, s40, 0x400
	s_addc_u32 s41, s41, 0
	s_add_u32 s42, s42, 0x2000
	s_addc_u32 s43, s43, 0
	s_add_u32 s44, s44, 0x80
	s_addc_u32 s45, s45, 0
	v_lshlrev_b32_e32 v20, 16, v79
	v_lshlrev_b32_e32 v21, 16, v80
	v_lshlrev_b32_e32 v23, 16, v82
	v_lshlrev_b32_e32 v24, 16, v83
	v_lshlrev_b32_e32 v22, 16, v81
	v_sub_f32_e32 v26, v8, v21
	v_sub_f32_e32 v25, v7, v20
	v_fma_f32 v26, v2, v26, v21
	v_fma_f32 v25, v1, v25, v20
	v_mul_f32_e32 v32, v4, v26
	v_mul_f32_e32 v33, v32, v32
	v_max_f32_e64 v27, -v23, -v23
	v_mul_f32_e64 v28, |v23|, s56
	v_mov_b32_dpp v33, v33 quad_perm:[1,0,3,2] row_mask:0xf bank_mask:0xf bound_ctrl:1
	v_fmac_f32_e32 v33, v32, v32
	v_exp_f32_e32 v28, v28
	v_max_f32_e32 v27, 0, v27
	v_add_f32_dpp v33, v33, v33 quad_perm:[2,3,0,1] row_mask:0xf bank_mask:0xf bound_ctrl:1
	v_add_f32_e32 v28, 1.0, v28
	v_mul_f32_e32 v31, 0xbfb8aa3b, v24
	v_add_f32_dpp v33, v33, v33 row_half_mirror row_mask:0xf bank_mask:0xf bound_ctrl:1
	v_log_f32_e32 v28, v28
	v_exp_f32_e32 v31, v31
	v_add_f32_dpp v33, v33, v33 row_mirror row_mask:0xf bank_mask:0xf bound_ctrl:1
	v_mul_f32_e32 v29, 0x3f317217, v28
	v_readlane_b32 s24, v33, 16
	v_readlane_b32 s25, v33, 48
	v_readlane_b32 s26, v33, 0
	v_readlane_b32 s27, v33, 32
	v_fma_f32 v29, v28, s58, -v29
	v_fmac_f32_e32 v29, 0x3377d1cf, v28
	v_mov_b32_e32 v33, s24
	v_mov_b32_e32 v40, s25
	v_add_f32_e32 v33, s26, v33
	v_add_f32_e32 v40, s27, v40
	v_fmac_f32_e32 v29, 0x3f317217, v28
	v_add_f32_e32 v33, v33, v40
	v_add_f32_e32 v31, 1.0, v31
	v_rcp_f32_e32 v31, v31
	v_add_f32_e32 v27, v27, v29
	v_sub_f32_e32 v27, -0.5, v27
	v_mul_f32_e32 v27, 0x3fb8aa3b, v27
	v_exp_f32_e32 v27, v27
	v_cmp_gt_f32_e32 vcc, s59, v33
	v_mul_f32_e32 v40, 0x4f800000, v33
	v_sub_f32_e32 v30, v10, v27
	v_cndmask_b32_e32 v33, v33, v40, vcc
	v_sqrt_f32_e32 v34, v33
	v_add_f32_e32 v36, -1.0, v31
	v_add_u32_e32 v41, -1, v34
	v_fma_f32 v42, -v41, v34, v33
	v_cmp_ge_f32_e64 s[28:29], 0, v42
	v_add_u32_e32 v42, 1, v34
	v_fma_f32 v36, v5, v36, 1.0
	v_cndmask_b32_e64 v41, v34, v41, s[28:29]
	v_fma_f32 v34, -v42, v34, v33
	v_cmp_lt_f32_e64 s[28:29], 0, v34
	v_mul_f32_e32 v37, v26, v36
	v_mul_f32_e32 v38, v25, v37
	v_cndmask_b32_e64 v34, v41, v42, s[28:29]
	v_mul_f32_e32 v41, 0x37800000, v34
	v_mul_f32_e32 v39, v6, v38
	v_cndmask_b32_e32 v34, v34, v41, vcc
	v_cmp_class_f32_e32 vcc, v33, v15
	v_mov_b32_dpp v39, v39 quad_perm:[1,0,3,2] row_mask:0xf bank_mask:0xf bound_ctrl:1
	v_fmac_f32_e32 v39, v6, v38
	v_cndmask_b32_e32 v34, v34, v33, vcc
	v_max_f32_e32 v34, 0x2b8cbccc, v34
	v_add_f32_dpp v39, v39, v39 quad_perm:[2,3,0,1] row_mask:0xf bank_mask:0xf bound_ctrl:1
	v_div_scale_f32 v40, s[28:29], v34, v34, v32
	v_rcp_f32_e32 v41, v40
	v_add_f32_dpp v39, v39, v39 row_half_mirror row_mask:0xf bank_mask:0xf bound_ctrl:1
	v_fma_f32 v42, -v40, v41, 1.0
	v_fmac_f32_e32 v41, v42, v41
	v_add_f32_dpp v39, v39, v39 row_mirror row_mask:0xf bank_mask:0xf bound_ctrl:1
	v_div_scale_f32 v42, vcc, v32, v34, v32
	v_mul_f32_e32 v43, v42, v41
	v_fma_f32 v44, -v40, v43, v42
	v_fmac_f32_e32 v43, v44, v41
	v_fma_f32 v40, -v40, v43, v42
	v_readlane_b32 s24, v39, 0
	v_readlane_b32 s25, v39, 16
	v_readlane_b32 s26, v39, 32
	v_readlane_b32 s27, v39, 48
	v_div_fmas_f32 v40, v40, v41, v43
	v_div_fixup_f32 v35, v40, v34, v32
	v_mul_f32_e32 v46, 0x3fb8aa3b, v10
	v_mul_f32_e32 v47, 0x3fb8aa3b, v30
	v_mul_f32_e32 v48, 0xbfb8aa3b, v30
	v_exp_f32_e32 v46, v46
	v_exp_f32_e32 v47, v47
	v_exp_f32_e32 v48, v48
	v_mul_f32_e32 v45, v31, v35
	v_mov_b32_e32 v41, s25
	v_mov_b32_e32 v42, s27
	v_add_f32_e32 v41, s24, v41
	v_add_f32_e32 v42, s26, v42
	v_mul_f32_e64 v49, v46, -v35
	v_mul_f32_e32 v50, v48, v45
	v_mul_f32_e32 v51, v37, v48
	v_mul_f32_e32 v52, v25, v47
	v_add_f32_e32 v41, v41, v42
	global_store_dword v14, v49, s[40:41]
	global_store_dword v14, v50, s[40:41] offset:256
	global_store_dword v14, v51, s[40:41] offset:512
	global_store_dword v14, v52, s[40:41] offset:768
	v_sub_f32_e32 v53, v9, v22
	v_fma_f32 v53, v3, v53, v22
	global_store_dword v14, v53, s[42:43]
	s_mov_b64 s[60:61], exec
	s_mov_b64 exec, 1
	v_mov_b32_e32 v42, 0
	global_store_dword v42, v41, s[44:45]
	s_mov_b64 exec, s[60:61]
	v_mov_b32_e32 v7, v20
	v_mov_b32_e32 v8, v21
	v_mov_b32_e32 v9, v22
	v_mov_b32_e32 v10, v30
	s_add_u32 s40, s40, 0x400
	s_addc_u32 s41, s41, 0
	s_add_u32 s42, s42, 0x2000
	s_addc_u32 s43, s43, 0
	s_add_u32 s44, s44, 0x80
	s_addc_u32 s45, s45, 0
; __device__ __forceinline__ float bf2f(bf16 x) { return __uint_as_float(((unsigned)x) << 16); }
; __device__ __forceinline__ float sigmoidf_(float x) { return __builtin_amdgcn_rcpf(1.0f + __expf(-x)); }
; #define PREP_LD(R_, K_, V_, L_, A_, t) do { _Pragma("unroll") for (int q = 0; q < 8; ++q) { const size_t o_ = (size_t)((t) + q); R_[q] = zp[o_ * LDZR]; K_[q] = zp[o_ * LDZR + 2048]; V_[q] = zp[o_ * LDZR + 4096]; L_[q] = lp[o_ * DH]; A_[q] = ap[o_ * DH]; } } while (0)
; __device__ __forceinline__ void rw_prep(Frame& F) {
;     ...
;         PREP_LD(cr, ck, cv, lw, as, 0);
;         for (int t0 = 0; t0 < n; t0 += 8) {
;             { const int tn = t0 + 8 < n ? t0 + 8 : t0; PREP_LD(nr, nk, nv, nl, na, tn); }
; #pragma unroll
;             for (int q = 0; q < 8; ++q) { const int row = row0 + t0 + q;
;                 const float crq = bf2f(cr[q]), ckq = bf2f(ck[q]), cvq = bf2f(cv[q]);
;                 const float rr = crq + (pr - crq) * mur, kv = ckq + (pk - ckq) * muk;
;                 const float nx = -bf2f(lw[q]); const float sp = fmaxf(nx, 0.f) + __logf(1.0f + __expf(-fabsf(nx))); const float lgw = -__expf(-sp - 0.5f); const float asg = sigmoidf_(bf2f(as[q]));
;                 float kk = kv * kkw; const float nrm = sqrtf(wsum(kk * kk)); kk = kk / fmaxf(nrm, 1e-12f);
;                 const float k_ = kv * (1.f + (asg - 1.f) * kaw);
;                 const float rk = wsum(rr * k_ * rkw);
;                 const float eex = __expf(Lw); Lw += lgw; const float ein = __expf(Lw), einv = __expf(-Lw);
;                 float* rec = REC + (size_t)(rec0 + t0 + q) * 256;
;                 rec[lane] = -kk * eex; rec[64 + lane] = kk * asg * einv; rec[128 + lane] = k_ * einv; rec[192 + lane] = rr * ein;
;                 if (lane == 0) RK[(size_t)row * 32 + h] = rk;
;                 VS[(size_t)row * DH + col] = cvq + (pv - cvq) * muv;
;                 pr = crq; pk = ckq; pv = cvq; }
	global_load_ushort v104, v11, s[50:51]
	global_load_ushort v105, v12, s[50:51]
	global_load_ushort v106, v13, s[50:51]
	global_load_ushort v107, v11, s[52:53]
	global_load_ushort v108, v11, s[54:55]
	s_add_u32 s50, s50, 13824
	s_addc_u32 s51, s51, 0
	s_add_u32 s52, s52, 0x1000
	s_addc_u32 s53, s53, 0
	s_add_u32 s54, s54, 0x1000
	s_addc_u32 s55, s55, 0
	global_load_ushort v109, v11, s[50:51]
	global_load_ushort v110, v12, s[50:51]
	global_load_ushort v111, v13, s[50:51]
	global_load_ushort v112, v11, s[52:53]
	global_load_ushort v113, v11, s[54:55]
	s_add_u32 s50, s50, 13824
	s_addc_u32 s51, s51, 0
	s_add_u32 s52, s52, 0x1000
	s_addc_u32 s53, s53, 0
	s_add_u32 s54, s54, 0x1000
	s_addc_u32 s55, s55, 0
	global_load_ushort v114, v11, s[50:51]
	global_load_ushort v115, v12, s[50:51]
	global_load_ushort v116, v13, s[50:51]
	global_load_ushort v117, v11, s[52:53]
	global_load_ushort v118, v11, s[54:55]
	s_add_u32 s50, s50, 13824
	s_addc_u32 s51, s51, 0
	s_add_u32 s52, s52, 0x1000
	s_addc_u32 s53, s53, 0
	s_add_u32 s54, s54, 0x1000
	s_addc_u32 s55, s55, 0
	global_load_ushort v119, v11, s[50:51]
	global_load_ushort v120, v12, s[50:51]
	global_load_ushort v121, v13, s[50:51]
	global_load_ushort v122, v11, s[52:53]
	global_load_ushort v123, v11, s[54:55]
	s_add_u32 s50, s50, 13824
	s_addc_u32 s51, s51, 0
	s_add_u32 s52, s52, 0x1000
	s_addc_u32 s53, s53, 0
	s_add_u32 s54, s54, 0x1000
	s_addc_u32 s55, s55, 0
	global_load_ushort v124, v11, s[50:51]
	global_load_ushort v125, v12, s[50:51]
	global_load_ushort v126, v13, s[50:51]
	global_load_ushort v127, v11, s[52:53]
	global_load_ushort v128, v11, s[54:55]
	s_add_u32 s50, s50, 13824
	s_addc_u32 s51, s51, 0
	s_add_u32 s52, s52, 0x1000
	s_addc_u32 s53, s53, 0
	s_add_u32 s54, s54, 0x1000
	s_addc_u32 s55, s55, 0
	global_load_ushort v129, v11, s[50:51]
	global_load_ushort v130, v12, s[50:51]
	global_load_ushort v131, v13, s[50:51]
	global_load_ushort v132, v11, s[52:53]
	global_load_ushort v133, v11, s[54:55]
	s_add_u32 s50, s50, 13824
	s_addc_u32 s51, s51, 0
	s_add_u32 s52, s52, 0x1000
	s_addc_u32 s53, s53, 0
	s_add_u32 s54, s54, 0x1000
	s_addc_u32 s55, s55, 0
	global_load_ushort v134, v11, s[50:51]
	global_load_ushort v135, v12, s[50:51]
	global_load_ushort v136, v13, s[50:51]
	global_load_ushort v137, v11, s[52:53]
	global_load_ushort v138, v11, s[54:55]
	s_add_u32 s50, s50, 13824
	s_addc_u32 s51, s51, 0
	s_add_u32 s52, s52, 0x1000
	s_addc_u32 s53, s53, 0
	s_add_u32 s54, s54, 0x1000
	s_addc_u32 s55, s55, 0
	global_load_ushort v139, v11, s[50:51]
	global_load_ushort v140, v12, s[50:51]
	global_load_ushort v141, v13, s[50:51]
	global_load_ushort v142, v11, s[52:53]
	global_load_ushort v143, v11, s[54:55]
	s_add_u32 s50, s50, 13824
	s_addc_u32 s51, s51, 0
	s_add_u32 s52, s52, 0x1000
	s_addc_u32 s53, s53, 0
	s_add_u32 s54, s54, 0x1000
	s_addc_u32 s55, s55, 0
	v_lshlrev_b32_e32 v20, 16, v84
	v_lshlrev_b32_e32 v21, 16, v85
	v_lshlrev_b32_e32 v23, 16, v87
	v_lshlrev_b32_e32 v24, 16, v88
	v_lshlrev_b32_e32 v22, 16, v86
	v_sub_f32_e32 v26, v8, v21
	v_sub_f32_e32 v25, v7, v20
	v_fma_f32 v26, v2, v26, v21
	v_fma_f32 v25, v1, v25, v20
	v_mul_f32_e32 v32, v4, v26
	v_mul_f32_e32 v33, v32, v32
	v_max_f32_e64 v27, -v23, -v23
	v_mul_f32_e64 v28, |v23|, s56
	v_mov_b32_dpp v33, v33 quad_perm:[1,0,3,2] row_mask:0xf bank_mask:0xf bound_ctrl:1
	v_fmac_f32_e32 v33, v32, v32
	v_exp_f32_e32 v28, v28
	v_max_f32_e32 v27, 0, v27
	v_add_f32_dpp v33, v33, v33 quad_perm:[2,3,0,1] row_mask:0xf bank_mask:0xf bound_ctrl:1
	v_add_f32_e32 v28, 1.0, v28
	v_mul_f32_e32 v31, 0xbfb8aa3b, v24
	v_add_f32_dpp v33, v33, v33 row_half_mirror row_mask:0xf bank_mask:0xf bound_ctrl:1
	v_log_f32_e32 v28, v28
	v_exp_f32_e32 v31, v31
	v_add_f32_dpp v33, v33, v33 row_mirror row_mask:0xf bank_mask:0xf bound_ctrl:1
	v_mul_f32_e32 v29, 0x3f317217, v28
	v_readlane_b32 s24, v33, 16
	v_readlane_b32 s25, v33, 48
	v_readlane_b32 s26, v33, 0
	v_readlane_b32 s27, v33, 32
	v_fma_f32 v29, v28, s58, -v29
	v_fmac_f32_e32 v29, 0x3377d1cf, v28
	v_mov_b32_e32 v33, s24
	v_mov_b32_e32 v40, s25
	v_add_f32_e32 v33, s26, v33
	v_add_f32_e32 v40, s27, v40
	v_fmac_f32_e32 v29, 0x3f317217, v28
	v_add_f32_e32 v33, v33, v40
	v_add_f32_e32 v31, 1.0, v31
	v_rcp_f32_e32 v31, v31
	v_add_f32_e32 v27, v27, v29
	v_sub_f32_e32 v27, -0.5, v27
	v_mul_f32_e32 v27, 0x3fb8aa3b, v27
	v_exp_f32_e32 v27, v27
	v_cmp_gt_f32_e32 vcc, s59, v33
	v_mul_f32_e32 v40, 0x4f800000, v33
	v_sub_f32_e32 v30, v10, v27
	v_cndmask_b32_e32 v33, v33, v40, vcc
	v_sqrt_f32_e32 v34, v33
	v_add_f32_e32 v36, -1.0, v31
	v_add_u32_e32 v41, -1, v34
	v_fma_f32 v42, -v41, v34, v33
	v_cmp_ge_f32_e64 s[28:29], 0, v42
	v_add_u32_e32 v42, 1, v34
	v_fma_f32 v36, v5, v36, 1.0
	v_cndmask_b32_e64 v41, v34, v41, s[28:29]
	v_fma_f32 v34, -v42, v34, v33
	v_cmp_lt_f32_e64 s[28:29], 0, v34
	v_mul_f32_e32 v37, v26, v36
	v_mul_f32_e32 v38, v25, v37
	v_cndmask_b32_e64 v34, v41, v42, s[28:29]
	v_mul_f32_e32 v41, 0x37800000, v34
	v_mul_f32_e32 v39, v6, v38
	v_cndmask_b32_e32 v34, v34, v41, vcc
	v_cmp_class_f32_e32 vcc, v33, v15
	v_mov_b32_dpp v39, v39 quad_perm:[1,0,3,2] row_mask:0xf bank_mask:0xf bound_ctrl:1
	v_fmac_f32_e32 v39, v6, v38
	v_cndmask_b32_e32 v34, v34, v33, vcc
	v_max_f32_e32 v34, 0x2b8cbccc, v34
	v_add_f32_dpp v39, v39, v39 quad_perm:[2,3,0,1] row_mask:0xf bank_mask:0xf bound_ctrl:1
	v_div_scale_f32 v40, s[28:29], v34, v34, v32
	v_rcp_f32_e32 v41, v40
	v_add_f32_dpp v39, v39, v39 row_half_mirror row_mask:0xf bank_mask:0xf bound_ctrl:1
	v_fma_f32 v42, -v40, v41, 1.0
	v_fmac_f32_e32 v41, v42, v41
	v_add_f32_dpp v39, v39, v39 row_mirror row_mask:0xf bank_mask:0xf bound_ctrl:1
	v_div_scale_f32 v42, vcc, v32, v34, v32
; __device__ __forceinline__ float bf2f(bf16 x) { return __uint_as_float(((unsigned)x) << 16); }
; __device__ __forceinline__ float sigmoidf_(float x) { return __builtin_amdgcn_rcpf(1.0f + __expf(-x)); }
; __device__ __forceinline__ float dpp_xor1(float x) { return __builtin_bit_cast(float, __builtin_amdgcn_update_dpp(0, __builtin_bit_cast(int, x), 0xB1, 0xF, 0xF, true)); }
; __device__ __forceinline__ float dpp_xor2(float x) { return __builtin_bit_cast(float, __builtin_amdgcn_update_dpp(0, __builtin_bit_cast(int, x), 0x4E, 0xF, 0xF, true)); }
; __device__ __forceinline__ float red16(float x) { x += dpp_xor1(x); x += dpp_xor2(x); x += dpp_hmir(x); x += dpp_mir(x); return x; }
; __device__ __forceinline__ float wsum(float x) {
;     x = red16(x); const int xi = __builtin_bit_cast(int, x);
;     const float r0 = __builtin_bit_cast(float, __builtin_amdgcn_readlane(xi, 0)), r1 = __builtin_bit_cast(float, __builtin_amdgcn_readlane(xi, 16));
;     const float r2 = __builtin_bit_cast(float, __builtin_amdgcn_readlane(xi, 32)), r3 = __builtin_bit_cast(float, __builtin_amdgcn_readlane(xi, 48));
;     return (r0 + r1) + (r2 + r3);
; __device__ __forceinline__ void rw_prep(Frame& F) {
;     ...
;             for (int q = 0; q < 8; ++q) { const int row = row0 + t0 + q;
;                 const float crq = bf2f(cr[q]), ckq = bf2f(ck[q]), cvq = bf2f(cv[q]);
;                 const float rr = crq + (pr - crq) * mur, kv = ckq + (pk - ckq) * muk;
;                 const float nx = -bf2f(lw[q]); const float sp = fmaxf(nx, 0.f) + __logf(1.0f + __expf(-fabsf(nx))); const float lgw = -__expf(-sp - 0.5f); const float asg = sigmoidf_(bf2f(as[q]));
;                 float kk = kv * kkw; const float nrm = sqrtf(wsum(kk * kk)); kk = kk / fmaxf(nrm, 1e-12f);
;                 const float k_ = kv * (1.f + (asg - 1.f) * kaw);
;                 const float rk = wsum(rr * k_ * rkw);
;                 const float eex = __expf(Lw); Lw += lgw; const float ein = __expf(Lw), einv = __expf(-Lw);
;                 float* rec = REC + (size_t)(rec0 + t0 + q) * 256;
;                 rec[lane] = -kk * eex; rec[64 + lane] = kk * asg * einv; rec[128 + lane] = k_ * einv; rec[192 + lane] = rr * ein;
;                 if (lane == 0) RK[(size_t)row * 32 + h] = rk;
;                 VS[(size_t)row * DH + col] = cvq + (pv - cvq) * muv;
;                 pr = crq; pk = ckq; pv = cvq; }
	v_mul_f32_e32 v43, v42, v41
	v_fma_f32 v44, -v40, v43, v42
	v_fmac_f32_e32 v43, v44, v41
	v_fma_f32 v40, -v40, v43, v42
	v_readlane_b32 s24, v39, 0
	v_readlane_b32 s25, v39, 16
	v_readlane_b32 s26, v39, 32
	v_readlane_b32 s27, v39, 48
	v_div_fmas_f32 v40, v40, v41, v43
	v_div_fixup_f32 v35, v40, v34, v32
	v_mul_f32_e32 v46, 0x3fb8aa3b, v10
	v_mul_f32_e32 v47, 0x3fb8aa3b, v30
	v_mul_f32_e32 v48, 0xbfb8aa3b, v30
	v_exp_f32_e32 v46, v46
	v_exp_f32_e32 v47, v47
	v_exp_f32_e32 v48, v48
	v_mul_f32_e32 v45, v31, v35
	v_mov_b32_e32 v41, s25
	v_mov_b32_e32 v42, s27
	v_add_f32_e32 v41, s24, v41
	v_add_f32_e32 v42, s26, v42
	v_mul_f32_e64 v49, v46, -v35
	v_mul_f32_e32 v50, v48, v45
	v_mul_f32_e32 v51, v37, v48
	v_mul_f32_e32 v52, v25, v47
	v_add_f32_e32 v41, v41, v42
	global_store_dword v14, v49, s[40:41]
	global_store_dword v14, v50, s[40:41] offset:256
	global_store_dword v14, v51, s[40:41] offset:512
	global_store_dword v14, v52, s[40:41] offset:768
	v_sub_f32_e32 v53, v9, v22
	v_fma_f32 v53, v3, v53, v22
	global_store_dword v14, v53, s[42:43]
	s_mov_b64 s[60:61], exec
	s_mov_b64 exec, 1
	v_mov_b32_e32 v42, 0
	global_store_dword v42, v41, s[44:45]
	s_mov_b64 exec, s[60:61]
	v_mov_b32_e32 v7, v20
	v_mov_b32_e32 v8, v21
	v_mov_b32_e32 v9, v22
	v_mov_b32_e32 v10, v30
	s_add_u32 s40, s40, 0x400
	s_addc_u32 s41, s41, 0
	s_add_u32 s42, s42, 0x2000
	s_addc_u32 s43, s43, 0
	s_add_u32 s44, s44, 0x80
	s_addc_u32 s45, s45, 0
	v_lshlrev_b32_e32 v20, 16, v89
	v_lshlrev_b32_e32 v21, 16, v90
	v_lshlrev_b32_e32 v23, 16, v92
	v_lshlrev_b32_e32 v24, 16, v93
	v_lshlrev_b32_e32 v22, 16, v91
	v_sub_f32_e32 v26, v8, v21
	v_sub_f32_e32 v25, v7, v20
	v_fma_f32 v26, v2, v26, v21
	v_fma_f32 v25, v1, v25, v20
	v_mul_f32_e32 v32, v4, v26
	v_mul_f32_e32 v33, v32, v32
	v_max_f32_e64 v27, -v23, -v23
	v_mul_f32_e64 v28, |v23|, s56
	v_mov_b32_dpp v33, v33 quad_perm:[1,0,3,2] row_mask:0xf bank_mask:0xf bound_ctrl:1
	v_fmac_f32_e32 v33, v32, v32
	v_exp_f32_e32 v28, v28
	v_max_f32_e32 v27, 0, v27
	v_add_f32_dpp v33, v33, v33 quad_perm:[2,3,0,1] row_mask:0xf bank_mask:0xf bound_ctrl:1
	v_add_f32_e32 v28, 1.0, v28
	v_mul_f32_e32 v31, 0xbfb8aa3b, v24
	v_add_f32_dpp v33, v33, v33 row_half_mirror row_mask:0xf bank_mask:0xf bound_ctrl:1
	v_log_f32_e32 v28, v28
	v_exp_f32_e32 v31, v31
	v_add_f32_dpp v33, v33, v33 row_mirror row_mask:0xf bank_mask:0xf bound_ctrl:1
	v_mul_f32_e32 v29, 0x3f317217, v28
	v_readlane_b32 s24, v33, 16
	v_readlane_b32 s25, v33, 48
	v_readlane_b32 s26, v33, 0
	v_readlane_b32 s27, v33, 32
	v_fma_f32 v29, v28, s58, -v29
	v_fmac_f32_e32 v29, 0x3377d1cf, v28
	v_mov_b32_e32 v33, s24
	v_mov_b32_e32 v40, s25
	v_add_f32_e32 v33, s26, v33
	v_add_f32_e32 v40, s27, v40
	v_fmac_f32_e32 v29, 0x3f317217, v28
	v_add_f32_e32 v33, v33, v40
	v_add_f32_e32 v31, 1.0, v31
	v_rcp_f32_e32 v31, v31
	v_add_f32_e32 v27, v27, v29
	v_sub_f32_e32 v27, -0.5, v27
	v_mul_f32_e32 v27, 0x3fb8aa3b, v27
	v_exp_f32_e32 v27, v27
	v_cmp_gt_f32_e32 vcc, s59, v33
	v_mul_f32_e32 v40, 0x4f800000, v33
	v_sub_f32_e32 v30, v10, v27
	v_cndmask_b32_e32 v33, v33, v40, vcc
	v_sqrt_f32_e32 v34, v33
	v_add_f32_e32 v36, -1.0, v31
	v_add_u32_e32 v41, -1, v34
	v_fma_f32 v42, -v41, v34, v33
	v_cmp_ge_f32_e64 s[28:29], 0, v42
	v_add_u32_e32 v42, 1, v34
	v_fma_f32 v36, v5, v36, 1.0
	v_cndmask_b32_e64 v41, v34, v41, s[28:29]
	v_fma_f32 v34, -v42, v34, v33
	v_cmp_lt_f32_e64 s[28:29], 0, v34
	v_mul_f32_e32 v37, v26, v36
	v_mul_f32_e32 v38, v25, v37
	v_cndmask_b32_e64 v34, v41, v42, s[28:29]
	v_mul_f32_e32 v41, 0x37800000, v34
	v_mul_f32_e32 v39, v6, v38
	v_cndmask_b32_e32 v34, v34, v41, vcc
	v_cmp_class_f32_e32 vcc, v33, v15
	v_mov_b32_dpp v39, v39 quad_perm:[1,0,3,2] row_mask:0xf bank_mask:0xf bound_ctrl:1
	v_fmac_f32_e32 v39, v6, v38
	v_cndmask_b32_e32 v34, v34, v33, vcc
	v_max_f32_e32 v34, 0x2b8cbccc, v34
	v_add_f32_dpp v39, v39, v39 quad_perm:[2,3,0,1] row_mask:0xf bank_mask:0xf bound_ctrl:1
	v_div_scale_f32 v40, s[28:29], v34, v34, v32
	v_rcp_f32_e32 v41, v40
	v_add_f32_dpp v39, v39, v39 row_half_mirror row_mask:0xf bank_mask:0xf bound_ctrl:1
	v_fma_f32 v42, -v40, v41, 1.0
	v_fmac_f32_e32 v41, v42, v41
	v_add_f32_dpp v39, v39, v39 row_mirror row_mask:0xf bank_mask:0xf bound_ctrl:1
	v_div_scale_f32 v42, vcc, v32, v34, v32
	v_mul_f32_e32 v43, v42, v41
	v_fma_f32 v44, -v40, v43, v42
	v_fmac_f32_e32 v43, v44, v41
	v_fma_f32 v40, -v40, v43, v42
	v_readlane_b32 s24, v39, 0
	v_readlane_b32 s25, v39, 16
	v_readlane_b32 s26, v39, 32
	v_readlane_b32 s27, v39, 48
	v_div_fmas_f32 v40, v40, v41, v43
	v_div_fixup_f32 v35, v40, v34, v32
	v_mul_f32_e32 v46, 0x3fb8aa3b, v10
	v_mul_f32_e32 v47, 0x3fb8aa3b, v30
	v_mul_f32_e32 v48, 0xbfb8aa3b, v30
	v_exp_f32_e32 v46, v46
	v_exp_f32_e32 v47, v47
	v_exp_f32_e32 v48, v48
	v_mul_f32_e32 v45, v31, v35
	v_mov_b32_e32 v41, s25
	v_mov_b32_e32 v42, s27
	v_add_f32_e32 v41, s24, v41
	v_add_f32_e32 v42, s26, v42
	v_mul_f32_e64 v49, v46, -v35
	v_mul_f32_e32 v50, v48, v45
	v_mul_f32_e32 v51, v37, v48
	v_mul_f32_e32 v52, v25, v47
	v_add_f32_e32 v41, v41, v42
	global_store_dword v14, v49, s[40:41]
	global_store_dword v14, v50, s[40:41] offset:256
	global_store_dword v14, v51, s[40:41] offset:512
	global_store_dword v14, v52, s[40:41] offset:768
	v_sub_f32_e32 v53, v9, v22
	v_fma_f32 v53, v3, v53, v22
	global_store_dword v14, v53, s[42:43]
	s_mov_b64 s[60:61], exec
	s_mov_b64 exec, 1
	v_mov_b32_e32 v42, 0
	global_store_dword v42, v41, s[44:45]
	s_mov_b64 exec, s[60:61]
	v_mov_b32_e32 v7, v20
	v_mov_b32_e32 v8, v21
	v_mov_b32_e32 v9, v22
	v_mov_b32_e32 v10, v30
	s_add_u32 s40, s40, 0x400
	s_addc_u32 s41, s41, 0
	s_add_u32 s42, s42, 0x2000
	s_addc_u32 s43, s43, 0
	s_add_u32 s44, s44, 0x80
	s_addc_u32 s45, s45, 0
; __device__ __forceinline__ float bf2f(bf16 x) { return __uint_as_float(((unsigned)x) << 16); }
; __device__ __forceinline__ float sigmoidf_(float x) { return __builtin_amdgcn_rcpf(1.0f + __expf(-x)); }
; __device__ __forceinline__ float dpp_xor1(float x) { return __builtin_bit_cast(float, __builtin_amdgcn_update_dpp(0, __builtin_bit_cast(int, x), 0xB1, 0xF, 0xF, true)); }
; __device__ __forceinline__ float dpp_xor2(float x) { return __builtin_bit_cast(float, __builtin_amdgcn_update_dpp(0, __builtin_bit_cast(int, x), 0x4E, 0xF, 0xF, true)); }
; __device__ __forceinline__ float red16(float x) { x += dpp_xor1(x); x += dpp_xor2(x); x += dpp_hmir(x); x += dpp_mir(x); return x; }
; __device__ __forceinline__ float wsum(float x) {
;     x = red16(x); const int xi = __builtin_bit_cast(int, x);
;     const float r0 = __builtin_bit_cast(float, __builtin_amdgcn_readlane(xi, 0)), r1 = __builtin_bit_cast(float, __builtin_amdgcn_readlane(xi, 16));
;     const float r2 = __builtin_bit_cast(float, __builtin_amdgcn_readlane(xi, 32)), r3 = __builtin_bit_cast(float, __builtin_amdgcn_readlane(xi, 48));
;     return (r0 + r1) + (r2 + r3);
; __device__ __forceinline__ void rw_prep(Frame& F) {
;     ...
;             for (int q = 0; q < 8; ++q) { const int row = row0 + t0 + q;
;                 const float crq = bf2f(cr[q]), ckq = bf2f(ck[q]), cvq = bf2f(cv[q]);
;                 const float rr = crq + (pr - crq) * mur, kv = ckq + (pk - ckq) * muk;
;                 const float nx = -bf2f(lw[q]); const float sp = fmaxf(nx, 0.f) + __logf(1.0f + __expf(-fabsf(nx))); const float lgw = -__expf(-sp - 0.5f); const float asg = sigmoidf_(bf2f(as[q]));
;                 float kk = kv * kkw; const float nrm = sqrtf(wsum(kk * kk)); kk = kk / fmaxf(nrm, 1e-12f);
;                 const float k_ = kv * (1.f + (asg - 1.f) * kaw);
;                 const float rk = wsum(rr * k_ * rkw);
;                 const float eex = __expf(Lw); Lw += lgw; const float ein = __expf(Lw), einv = __expf(-Lw);
;                 float* rec = REC + (size_t)(rec0 + t0 + q) * 256;
;                 rec[lane] = -kk * eex; rec[64 + lane] = kk * asg * einv; rec[128 + lane] = k_ * einv; rec[192 + lane] = rr * ein;
;                 if (lane == 0) RK[(size_t)row * 32 + h] = rk;
;                 VS[(size_t)row * DH + col] = cvq + (pv - cvq) * muv;
;                 pr = crq; pk = ckq; pv = cvq; }
	v_lshlrev_b32_e32 v20, 16, v94
	v_lshlrev_b32_e32 v21, 16, v95
	v_lshlrev_b32_e32 v23, 16, v97
	v_lshlrev_b32_e32 v24, 16, v98
	v_lshlrev_b32_e32 v22, 16, v96
	v_sub_f32_e32 v26, v8, v21
	v_sub_f32_e32 v25, v7, v20
	v_fma_f32 v26, v2, v26, v21
	v_fma_f32 v25, v1, v25, v20
	v_mul_f32_e32 v32, v4, v26
	v_mul_f32_e32 v33, v32, v32
	v_max_f32_e64 v27, -v23, -v23
	v_mul_f32_e64 v28, |v23|, s56
	v_mov_b32_dpp v33, v33 quad_perm:[1,0,3,2] row_mask:0xf bank_mask:0xf bound_ctrl:1
	v_fmac_f32_e32 v33, v32, v32
	v_exp_f32_e32 v28, v28
	v_max_f32_e32 v27, 0, v27
	v_add_f32_dpp v33, v33, v33 quad_perm:[2,3,0,1] row_mask:0xf bank_mask:0xf bound_ctrl:1
	v_add_f32_e32 v28, 1.0, v28
	v_mul_f32_e32 v31, 0xbfb8aa3b, v24
	v_add_f32_dpp v33, v33, v33 row_half_mirror row_mask:0xf bank_mask:0xf bound_ctrl:1
	v_log_f32_e32 v28, v28
	v_exp_f32_e32 v31, v31
	v_add_f32_dpp v33, v33, v33 row_mirror row_mask:0xf bank_mask:0xf bound_ctrl:1
	v_mul_f32_e32 v29, 0x3f317217, v28
	v_readlane_b32 s24, v33, 16
	v_readlane_b32 s25, v33, 48
	v_readlane_b32 s26, v33, 0
	v_readlane_b32 s27, v33, 32
	v_fma_f32 v29, v28, s58, -v29
	v_fmac_f32_e32 v29, 0x3377d1cf, v28
	v_mov_b32_e32 v33, s24
	v_mov_b32_e32 v40, s25
	v_add_f32_e32 v33, s26, v33
	v_add_f32_e32 v40, s27, v40
	v_fmac_f32_e32 v29, 0x3f317217, v28
	v_add_f32_e32 v33, v33, v40
	v_add_f32_e32 v31, 1.0, v31
	v_rcp_f32_e32 v31, v31
	v_add_f32_e32 v27, v27, v29
	v_sub_f32_e32 v27, -0.5, v27
	v_mul_f32_e32 v27, 0x3fb8aa3b, v27
	v_exp_f32_e32 v27, v27
	v_cmp_gt_f32_e32 vcc, s59, v33
	v_mul_f32_e32 v40, 0x4f800000, v33
	v_sub_f32_e32 v30, v10, v27
	v_cndmask_b32_e32 v33, v33, v40, vcc
	v_sqrt_f32_e32 v34, v33
	v_add_f32_e32 v36, -1.0, v31
	v_add_u32_e32 v41, -1, v34
	v_fma_f32 v42, -v41, v34, v33
	v_cmp_ge_f32_e64 s[28:29], 0, v42
	v_add_u32_e32 v42, 1, v34
	v_fma_f32 v36, v5, v36, 1.0
	v_cndmask_b32_e64 v41, v34, v41, s[28:29]
	v_fma_f32 v34, -v42, v34, v33
	v_cmp_lt_f32_e64 s[28:29], 0, v34
	v_mul_f32_e32 v37, v26, v36
	v_mul_f32_e32 v38, v25, v37
	v_cndmask_b32_e64 v34, v41, v42, s[28:29]
	v_mul_f32_e32 v41, 0x37800000, v34
	v_mul_f32_e32 v39, v6, v38
	v_cndmask_b32_e32 v34, v34, v41, vcc
	v_cmp_class_f32_e32 vcc, v33, v15
	v_mov_b32_dpp v39, v39 quad_perm:[1,0,3,2] row_mask:0xf bank_mask:0xf bound_ctrl:1
	v_fmac_f32_e32 v39, v6, v38
	v_cndmask_b32_e32 v34, v34, v33, vcc
	v_max_f32_e32 v34, 0x2b8cbccc, v34
	v_add_f32_dpp v39, v39, v39 quad_perm:[2,3,0,1] row_mask:0xf bank_mask:0xf bound_ctrl:1
	v_div_scale_f32 v40, s[28:29], v34, v34, v32
	v_rcp_f32_e32 v41, v40
	v_add_f32_dpp v39, v39, v39 row_half_mirror row_mask:0xf bank_mask:0xf bound_ctrl:1
	v_fma_f32 v42, -v40, v41, 1.0
	v_fmac_f32_e32 v41, v42, v41
	v_add_f32_dpp v39, v39, v39 row_mirror row_mask:0xf bank_mask:0xf bound_ctrl:1
	v_div_scale_f32 v42, vcc, v32, v34, v32
	v_mul_f32_e32 v43, v42, v41
	v_fma_f32 v44, -v40, v43, v42
	v_fmac_f32_e32 v43, v44, v41
	v_fma_f32 v40, -v40, v43, v42
	v_readlane_b32 s24, v39, 0
	v_readlane_b32 s25, v39, 16
	v_readlane_b32 s26, v39, 32
	v_readlane_b32 s27, v39, 48
	v_div_fmas_f32 v40, v40, v41, v43
	v_div_fixup_f32 v35, v40, v34, v32
	v_mul_f32_e32 v46, 0x3fb8aa3b, v10
	v_mul_f32_e32 v47, 0x3fb8aa3b, v30
	v_mul_f32_e32 v48, 0xbfb8aa3b, v30
	v_exp_f32_e32 v46, v46
	v_exp_f32_e32 v47, v47
	v_exp_f32_e32 v48, v48
	v_mul_f32_e32 v45, v31, v35
	v_mov_b32_e32 v41, s25
	v_mov_b32_e32 v42, s27
	v_add_f32_e32 v41, s24, v41
	v_add_f32_e32 v42, s26, v42
	v_mul_f32_e64 v49, v46, -v35
	v_mul_f32_e32 v50, v48, v45
	v_mul_f32_e32 v51, v37, v48
	v_mul_f32_e32 v52, v25, v47
	v_add_f32_e32 v41, v41, v42
	global_store_dword v14, v49, s[40:41]
	global_store_dword v14, v50, s[40:41] offset:256
	global_store_dword v14, v51, s[40:41] offset:512
	global_store_dword v14, v52, s[40:41] offset:768
	v_sub_f32_e32 v53, v9, v22
	v_fma_f32 v53, v3, v53, v22
	global_store_dword v14, v53, s[42:43]
	s_mov_b64 s[60:61], exec
	s_mov_b64 exec, 1
	v_mov_b32_e32 v42, 0
	global_store_dword v42, v41, s[44:45]
	s_mov_b64 exec, s[60:61]
	v_mov_b32_e32 v7, v20
	v_mov_b32_e32 v8, v21
	v_mov_b32_e32 v9, v22
	v_mov_b32_e32 v10, v30
	s_add_u32 s40, s40, 0x400
	s_addc_u32 s41, s41, 0
	s_add_u32 s42, s42, 0x2000
	s_addc_u32 s43, s43, 0
	s_add_u32 s44, s44, 0x80
	s_addc_u32 s45, s45, 0
	v_lshlrev_b32_e32 v20, 16, v99
	v_lshlrev_b32_e32 v21, 16, v100
	v_lshlrev_b32_e32 v23, 16, v102
	v_lshlrev_b32_e32 v24, 16, v103
	v_lshlrev_b32_e32 v22, 16, v101
	v_sub_f32_e32 v26, v8, v21
	v_sub_f32_e32 v25, v7, v20
	v_fma_f32 v26, v2, v26, v21
	v_fma_f32 v25, v1, v25, v20
	v_mul_f32_e32 v32, v4, v26
	v_mul_f32_e32 v33, v32, v32
	v_max_f32_e64 v27, -v23, -v23
	v_mul_f32_e64 v28, |v23|, s56
	v_mov_b32_dpp v33, v33 quad_perm:[1,0,3,2] row_mask:0xf bank_mask:0xf bound_ctrl:1
	v_fmac_f32_e32 v33, v32, v32
	v_exp_f32_e32 v28, v28
	v_max_f32_e32 v27, 0, v27
	v_add_f32_dpp v33, v33, v33 quad_perm:[2,3,0,1] row_mask:0xf bank_mask:0xf bound_ctrl:1
	v_add_f32_e32 v28, 1.0, v28
	v_mul_f32_e32 v31, 0xbfb8aa3b, v24
	v_add_f32_dpp v33, v33, v33 row_half_mirror row_mask:0xf bank_mask:0xf bound_ctrl:1
	v_log_f32_e32 v28, v28
	v_exp_f32_e32 v31, v31
	v_add_f32_dpp v33, v33, v33 row_mirror row_mask:0xf bank_mask:0xf bound_ctrl:1
	v_mul_f32_e32 v29, 0x3f317217, v28
	v_readlane_b32 s24, v33, 16
	v_readlane_b32 s25, v33, 48
	v_readlane_b32 s26, v33, 0
	v_readlane_b32 s27, v33, 32
	v_fma_f32 v29, v28, s58, -v29
	v_fmac_f32_e32 v29, 0x3377d1cf, v28
	v_mov_b32_e32 v33, s24
	v_mov_b32_e32 v40, s25
	v_add_f32_e32 v33, s26, v33
	v_add_f32_e32 v40, s27, v40
	v_fmac_f32_e32 v29, 0x3f317217, v28
	v_add_f32_e32 v33, v33, v40
	v_add_f32_e32 v31, 1.0, v31
	v_rcp_f32_e32 v31, v31
	v_add_f32_e32 v27, v27, v29
	v_sub_f32_e32 v27, -0.5, v27
; __device__ __forceinline__ float bf2f(bf16 x) { return __uint_as_float(((unsigned)x) << 16); }
; __device__ __forceinline__ float sigmoidf_(float x) { return __builtin_amdgcn_rcpf(1.0f + __expf(-x)); }
; __device__ __forceinline__ float dpp_xor1(float x) { return __builtin_bit_cast(float, __builtin_amdgcn_update_dpp(0, __builtin_bit_cast(int, x), 0xB1, 0xF, 0xF, true)); }
; __device__ __forceinline__ float dpp_xor2(float x) { return __builtin_bit_cast(float, __builtin_amdgcn_update_dpp(0, __builtin_bit_cast(int, x), 0x4E, 0xF, 0xF, true)); }
; __device__ __forceinline__ float red16(float x) { x += dpp_xor1(x); x += dpp_xor2(x); x += dpp_hmir(x); x += dpp_mir(x); return x; }
; __device__ __forceinline__ float wsum(float x) {
;     x = red16(x); const int xi = __builtin_bit_cast(int, x);
;     const float r0 = __builtin_bit_cast(float, __builtin_amdgcn_readlane(xi, 0)), r1 = __builtin_bit_cast(float, __builtin_amdgcn_readlane(xi, 16));
;     const float r2 = __builtin_bit_cast(float, __builtin_amdgcn_readlane(xi, 32)), r3 = __builtin_bit_cast(float, __builtin_amdgcn_readlane(xi, 48));
;     return (r0 + r1) + (r2 + r3);
; __device__ __forceinline__ void rw_prep(Frame& F) {
;     ...
;             for (int q = 0; q < 8; ++q) { const int row = row0 + t0 + q;
;                 const float crq = bf2f(cr[q]), ckq = bf2f(ck[q]), cvq = bf2f(cv[q]);
;                 const float rr = crq + (pr - crq) * mur, kv = ckq + (pk - ckq) * muk;
;                 const float nx = -bf2f(lw[q]); const float sp = fmaxf(nx, 0.f) + __logf(1.0f + __expf(-fabsf(nx))); const float lgw = -__expf(-sp - 0.5f); const float asg = sigmoidf_(bf2f(as[q]));
;                 float kk = kv * kkw; const float nrm = sqrtf(wsum(kk * kk)); kk = kk / fmaxf(nrm, 1e-12f);
;                 const float k_ = kv * (1.f + (asg - 1.f) * kaw);
;                 const float rk = wsum(rr * k_ * rkw);
;                 const float eex = __expf(Lw); Lw += lgw; const float ein = __expf(Lw), einv = __expf(-Lw);
;                 float* rec = REC + (size_t)(rec0 + t0 + q) * 256;
;                 rec[lane] = -kk * eex; rec[64 + lane] = kk * asg * einv; rec[128 + lane] = k_ * einv; rec[192 + lane] = rr * ein;
;                 if (lane == 0) RK[(size_t)row * 32 + h] = rk;
;                 VS[(size_t)row * DH + col] = cvq + (pv - cvq) * muv;
;                 pr = crq; pk = ckq; pv = cvq; }
	v_mul_f32_e32 v27, 0x3fb8aa3b, v27
	v_exp_f32_e32 v27, v27
	v_cmp_gt_f32_e32 vcc, s59, v33
	v_mul_f32_e32 v40, 0x4f800000, v33
	v_sub_f32_e32 v30, v10, v27
	v_cndmask_b32_e32 v33, v33, v40, vcc
	v_sqrt_f32_e32 v34, v33
	v_add_f32_e32 v36, -1.0, v31
	v_add_u32_e32 v41, -1, v34
	v_fma_f32 v42, -v41, v34, v33
	v_cmp_ge_f32_e64 s[28:29], 0, v42
	v_add_u32_e32 v42, 1, v34
	v_fma_f32 v36, v5, v36, 1.0
	v_cndmask_b32_e64 v41, v34, v41, s[28:29]
	v_fma_f32 v34, -v42, v34, v33
	v_cmp_lt_f32_e64 s[28:29], 0, v34
	v_mul_f32_e32 v37, v26, v36
	v_mul_f32_e32 v38, v25, v37
	v_cndmask_b32_e64 v34, v41, v42, s[28:29]
	v_mul_f32_e32 v41, 0x37800000, v34
	v_mul_f32_e32 v39, v6, v38
	v_cndmask_b32_e32 v34, v34, v41, vcc
	v_cmp_class_f32_e32 vcc, v33, v15
	v_mov_b32_dpp v39, v39 quad_perm:[1,0,3,2] row_mask:0xf bank_mask:0xf bound_ctrl:1
	v_fmac_f32_e32 v39, v6, v38
	v_cndmask_b32_e32 v34, v34, v33, vcc
	v_max_f32_e32 v34, 0x2b8cbccc, v34
	v_add_f32_dpp v39, v39, v39 quad_perm:[2,3,0,1] row_mask:0xf bank_mask:0xf bound_ctrl:1
	v_div_scale_f32 v40, s[28:29], v34, v34, v32
	v_rcp_f32_e32 v41, v40
	v_add_f32_dpp v39, v39, v39 row_half_mirror row_mask:0xf bank_mask:0xf bound_ctrl:1
	v_fma_f32 v42, -v40, v41, 1.0
	v_fmac_f32_e32 v41, v42, v41
	v_add_f32_dpp v39, v39, v39 row_mirror row_mask:0xf bank_mask:0xf bound_ctrl:1
	v_div_scale_f32 v42, vcc, v32, v34, v32
	v_mul_f32_e32 v43, v42, v41
	v_fma_f32 v44, -v40, v43, v42
	v_fmac_f32_e32 v43, v44, v41
	v_fma_f32 v40, -v40, v43, v42
	v_readlane_b32 s24, v39, 0
	v_readlane_b32 s25, v39, 16
	v_readlane_b32 s26, v39, 32
	v_readlane_b32 s27, v39, 48
	v_div_fmas_f32 v40, v40, v41, v43
	v_div_fixup_f32 v35, v40, v34, v32
	v_mul_f32_e32 v46, 0x3fb8aa3b, v10
	v_mul_f32_e32 v47, 0x3fb8aa3b, v30
	v_mul_f32_e32 v48, 0xbfb8aa3b, v30
	v_exp_f32_e32 v46, v46
	v_exp_f32_e32 v47, v47
	v_exp_f32_e32 v48, v48
	v_mul_f32_e32 v45, v31, v35
	v_mov_b32_e32 v41, s25
	v_mov_b32_e32 v42, s27
	v_add_f32_e32 v41, s24, v41
	v_add_f32_e32 v42, s26, v42
	v_mul_f32_e64 v49, v46, -v35
	v_mul_f32_e32 v50, v48, v45
	v_mul_f32_e32 v51, v37, v48
	v_mul_f32_e32 v52, v25, v47
	v_add_f32_e32 v41, v41, v42
	global_store_dword v14, v49, s[40:41]
	global_store_dword v14, v50, s[40:41] offset:256
	global_store_dword v14, v51, s[40:41] offset:512
	global_store_dword v14, v52, s[40:41] offset:768
	v_sub_f32_e32 v53, v9, v22
	v_fma_f32 v53, v3, v53, v22
	global_store_dword v14, v53, s[42:43]
	s_mov_b64 s[60:61], exec
	s_mov_b64 exec, 1
	v_mov_b32_e32 v42, 0
	global_store_dword v42, v41, s[44:45]
	s_mov_b64 exec, s[60:61]
	v_mov_b32_e32 v7, v20
	v_mov_b32_e32 v8, v21
	v_mov_b32_e32 v9, v22
	v_mov_b32_e32 v10, v30
	s_add_u32 s40, s40, 0x400
	s_addc_u32 s41, s41, 0
	s_add_u32 s42, s42, 0x2000
	s_addc_u32 s43, s43, 0
	s_add_u32 s44, s44, 0x80
	s_addc_u32 s45, s45, 0
	s_waitcnt vmcnt(24)
	v_lshlrev_b32_e32 v20, 16, v104
	v_lshlrev_b32_e32 v21, 16, v105
	v_lshlrev_b32_e32 v23, 16, v107
	v_lshlrev_b32_e32 v24, 16, v108
	v_lshlrev_b32_e32 v22, 16, v106
	v_sub_f32_e32 v26, v8, v21
	v_sub_f32_e32 v25, v7, v20
	v_fma_f32 v26, v2, v26, v21
	v_fma_f32 v25, v1, v25, v20
	v_mul_f32_e32 v32, v4, v26
	v_mul_f32_e32 v33, v32, v32
	v_max_f32_e64 v27, -v23, -v23
	v_mul_f32_e64 v28, |v23|, s56
	v_mov_b32_dpp v33, v33 quad_perm:[1,0,3,2] row_mask:0xf bank_mask:0xf bound_ctrl:1
	v_fmac_f32_e32 v33, v32, v32
	v_exp_f32_e32 v28, v28
	v_max_f32_e32 v27, 0, v27
	v_add_f32_dpp v33, v33, v33 quad_perm:[2,3,0,1] row_mask:0xf bank_mask:0xf bound_ctrl:1
	v_add_f32_e32 v28, 1.0, v28
	v_mul_f32_e32 v31, 0xbfb8aa3b, v24
	v_add_f32_dpp v33, v33, v33 row_half_mirror row_mask:0xf bank_mask:0xf bound_ctrl:1
	v_log_f32_e32 v28, v28
	v_exp_f32_e32 v31, v31
	v_add_f32_dpp v33, v33, v33 row_mirror row_mask:0xf bank_mask:0xf bound_ctrl:1
	v_mul_f32_e32 v29, 0x3f317217, v28
	v_readlane_b32 s24, v33, 16
	v_readlane_b32 s25, v33, 48
	v_readlane_b32 s26, v33, 0
	v_readlane_b32 s27, v33, 32
	v_fma_f32 v29, v28, s58, -v29
	v_fmac_f32_e32 v29, 0x3377d1cf, v28
	v_mov_b32_e32 v33, s24
	v_mov_b32_e32 v40, s25
	v_add_f32_e32 v33, s26, v33
	v_add_f32_e32 v40, s27, v40
	v_fmac_f32_e32 v29, 0x3f317217, v28
	v_add_f32_e32 v33, v33, v40
	v_add_f32_e32 v31, 1.0, v31
	v_rcp_f32_e32 v31, v31
	v_add_f32_e32 v27, v27, v29
	v_sub_f32_e32 v27, -0.5, v27
	v_mul_f32_e32 v27, 0x3fb8aa3b, v27
	v_exp_f32_e32 v27, v27
	v_cmp_gt_f32_e32 vcc, s59, v33
	v_mul_f32_e32 v40, 0x4f800000, v33
	v_sub_f32_e32 v30, v10, v27
	v_cndmask_b32_e32 v33, v33, v40, vcc
	v_sqrt_f32_e32 v34, v33
	v_add_f32_e32 v36, -1.0, v31
	v_add_u32_e32 v41, -1, v34
	v_fma_f32 v42, -v41, v34, v33
	v_cmp_ge_f32_e64 s[28:29], 0, v42
	v_add_u32_e32 v42, 1, v34
	v_fma_f32 v36, v5, v36, 1.0
	v_cndmask_b32_e64 v41, v34, v41, s[28:29]
	v_fma_f32 v34, -v42, v34, v33
	v_cmp_lt_f32_e64 s[28:29], 0, v34
	v_mul_f32_e32 v37, v26, v36
	v_mul_f32_e32 v38, v25, v37
	v_cndmask_b32_e64 v34, v41, v42, s[28:29]
	v_mul_f32_e32 v41, 0x37800000, v34
	v_mul_f32_e32 v39, v6, v38
	v_cndmask_b32_e32 v34, v34, v41, vcc
	v_cmp_class_f32_e32 vcc, v33, v15
	v_mov_b32_dpp v39, v39 quad_perm:[1,0,3,2] row_mask:0xf bank_mask:0xf bound_ctrl:1
	v_fmac_f32_e32 v39, v6, v38
	v_cndmask_b32_e32 v34, v34, v33, vcc
	v_max_f32_e32 v34, 0x2b8cbccc, v34
	v_add_f32_dpp v39, v39, v39 quad_perm:[2,3,0,1] row_mask:0xf bank_mask:0xf bound_ctrl:1
	v_div_scale_f32 v40, s[28:29], v34, v34, v32
	v_rcp_f32_e32 v41, v40
	v_add_f32_dpp v39, v39, v39 row_half_mirror row_mask:0xf bank_mask:0xf bound_ctrl:1
	v_fma_f32 v42, -v40, v41, 1.0
	v_fmac_f32_e32 v41, v42, v41
	v_add_f32_dpp v39, v39, v39 row_mirror row_mask:0xf bank_mask:0xf bound_ctrl:1
	v_div_scale_f32 v42, vcc, v32, v34, v32
	v_mul_f32_e32 v43, v42, v41
; __device__ __forceinline__ float bf2f(bf16 x) { return __uint_as_float(((unsigned)x) << 16); }
; __device__ __forceinline__ float sigmoidf_(float x) { return __builtin_amdgcn_rcpf(1.0f + __expf(-x)); }
; __device__ __forceinline__ void rw_prep(Frame& F) {
;     ...
;             for (int q = 0; q < 8; ++q) { const int row = row0 + t0 + q;
;                 const float crq = bf2f(cr[q]), ckq = bf2f(ck[q]), cvq = bf2f(cv[q]);
;                 const float rr = crq + (pr - crq) * mur, kv = ckq + (pk - ckq) * muk;
;                 const float nx = -bf2f(lw[q]); const float sp = fmaxf(nx, 0.f) + __logf(1.0f + __expf(-fabsf(nx))); const float lgw = -__expf(-sp - 0.5f); const float asg = sigmoidf_(bf2f(as[q]));
;                 float kk = kv * kkw; const float nrm = sqrtf(wsum(kk * kk)); kk = kk / fmaxf(nrm, 1e-12f);
;                 const float k_ = kv * (1.f + (asg - 1.f) * kaw);
;                 const float rk = wsum(rr * k_ * rkw);
;                 const float eex = __expf(Lw); Lw += lgw; const float ein = __expf(Lw), einv = __expf(-Lw);
;                 float* rec = REC + (size_t)(rec0 + t0 + q) * 256;
;                 rec[lane] = -kk * eex; rec[64 + lane] = kk * asg * einv; rec[128 + lane] = k_ * einv; rec[192 + lane] = rr * ein;
;                 if (lane == 0) RK[(size_t)row * 32 + h] = rk;
;                 VS[(size_t)row * DH + col] = cvq + (pv - cvq) * muv;
;                 pr = crq; pk = ckq; pv = cvq; }
	v_fma_f32 v44, -v40, v43, v42
	v_fmac_f32_e32 v43, v44, v41
	v_fma_f32 v40, -v40, v43, v42
	v_readlane_b32 s24, v39, 0
	v_readlane_b32 s25, v39, 16
	v_readlane_b32 s26, v39, 32
	v_readlane_b32 s27, v39, 48
	v_div_fmas_f32 v40, v40, v41, v43
	v_div_fixup_f32 v35, v40, v34, v32
	v_mul_f32_e32 v46, 0x3fb8aa3b, v10
	v_mul_f32_e32 v47, 0x3fb8aa3b, v30
	v_mul_f32_e32 v48, 0xbfb8aa3b, v30
	v_exp_f32_e32 v46, v46
	v_exp_f32_e32 v47, v47
	v_exp_f32_e32 v48, v48
	v_mul_f32_e32 v45, v31, v35
	v_mov_b32_e32 v41, s25
	v_mov_b32_e32 v42, s27
	v_add_f32_e32 v41, s24, v41
	v_add_f32_e32 v42, s26, v42
	v_mul_f32_e64 v49, v46, -v35
	v_mul_f32_e32 v50, v48, v45
	v_mul_f32_e32 v51, v37, v48
	v_mul_f32_e32 v52, v25, v47
	v_add_f32_e32 v41, v41, v42
	global_store_dword v14, v49, s[40:41]
	global_store_dword v14, v50, s[40:41] offset:256
	global_store_dword v14, v51, s[40:41] offset:512
	global_store_dword v14, v52, s[40:41] offset:768
	v_sub_f32_e32 v53, v9, v22
	v_fma_f32 v53, v3, v53, v22
	global_store_dword v14, v53, s[42:43]
	s_mov_b64 s[60:61], exec
	s_mov_b64 exec, 1
	v_mov_b32_e32 v42, 0
	global_store_dword v42, v41, s[44:45]
	s_mov_b64 exec, s[60:61]
	v_mov_b32_e32 v7, v20
	v_mov_b32_e32 v8, v21
	v_mov_b32_e32 v9, v22
	v_mov_b32_e32 v10, v30
	s_add_u32 s40, s40, 0x400
	s_addc_u32 s41, s41, 0
	s_add_u32 s42, s42, 0x2000
	s_addc_u32 s43, s43, 0
	s_add_u32 s44, s44, 0x80
	s_addc_u32 s45, s45, 0
	v_lshlrev_b32_e32 v20, 16, v109
	v_lshlrev_b32_e32 v21, 16, v110
	v_lshlrev_b32_e32 v23, 16, v112
	v_lshlrev_b32_e32 v24, 16, v113
	v_lshlrev_b32_e32 v22, 16, v111
	v_sub_f32_e32 v26, v8, v21
	v_sub_f32_e32 v25, v7, v20
	v_fma_f32 v26, v2, v26, v21
	v_fma_f32 v25, v1, v25, v20
	v_mul_f32_e32 v32, v4, v26
	v_mul_f32_e32 v33, v32, v32
	v_max_f32_e64 v27, -v23, -v23
	v_mul_f32_e64 v28, |v23|, s56
	v_mov_b32_dpp v33, v33 quad_perm:[1,0,3,2] row_mask:0xf bank_mask:0xf bound_ctrl:1
	v_fmac_f32_e32 v33, v32, v32
	v_exp_f32_e32 v28, v28
	v_max_f32_e32 v27, 0, v27
	v_add_f32_dpp v33, v33, v33 quad_perm:[2,3,0,1] row_mask:0xf bank_mask:0xf bound_ctrl:1
	v_add_f32_e32 v28, 1.0, v28
	v_mul_f32_e32 v31, 0xbfb8aa3b, v24
	v_add_f32_dpp v33, v33, v33 row_half_mirror row_mask:0xf bank_mask:0xf bound_ctrl:1
	v_log_f32_e32 v28, v28
	v_exp_f32_e32 v31, v31
	v_add_f32_dpp v33, v33, v33 row_mirror row_mask:0xf bank_mask:0xf bound_ctrl:1
	v_mul_f32_e32 v29, 0x3f317217, v28
	v_readlane_b32 s24, v33, 16
	v_readlane_b32 s25, v33, 48
	v_readlane_b32 s26, v33, 0
	v_readlane_b32 s27, v33, 32
	v_fma_f32 v29, v28, s58, -v29
	v_fmac_f32_e32 v29, 0x3377d1cf, v28
	v_mov_b32_e32 v33, s24
	v_mov_b32_e32 v40, s25
	v_add_f32_e32 v33, s26, v33
	v_add_f32_e32 v40, s27, v40
	v_fmac_f32_e32 v29, 0x3f317217, v28
	v_add_f32_e32 v33, v33, v40
	v_add_f32_e32 v31, 1.0, v31
	v_rcp_f32_e32 v31, v31
	v_add_f32_e32 v27, v27, v29
	v_sub_f32_e32 v27, -0.5, v27
	v_mul_f32_e32 v27, 0x3fb8aa3b, v27
	v_exp_f32_e32 v27, v27
	v_cmp_gt_f32_e32 vcc, s59, v33
	v_mul_f32_e32 v40, 0x4f800000, v33
	v_sub_f32_e32 v30, v10, v27
	v_cndmask_b32_e32 v33, v33, v40, vcc
	v_sqrt_f32_e32 v34, v33
	v_add_f32_e32 v36, -1.0, v31
	v_add_u32_e32 v41, -1, v34
	v_fma_f32 v42, -v41, v34, v33
	v_cmp_ge_f32_e64 s[28:29], 0, v42
	v_add_u32_e32 v42, 1, v34
	v_fma_f32 v36, v5, v36, 1.0
	v_cndmask_b32_e64 v41, v34, v41, s[28:29]
	v_fma_f32 v34, -v42, v34, v33
	v_cmp_lt_f32_e64 s[28:29], 0, v34
	v_mul_f32_e32 v37, v26, v36
	v_mul_f32_e32 v38, v25, v37
	v_cndmask_b32_e64 v34, v41, v42, s[28:29]
	v_mul_f32_e32 v41, 0x37800000, v34
	v_mul_f32_e32 v39, v6, v38
	v_cndmask_b32_e32 v34, v34, v41, vcc
	v_cmp_class_f32_e32 vcc, v33, v15
	v_mov_b32_dpp v39, v39 quad_perm:[1,0,3,2] row_mask:0xf bank_mask:0xf bound_ctrl:1
	v_fmac_f32_e32 v39, v6, v38
	v_cndmask_b32_e32 v34, v34, v33, vcc
	v_max_f32_e32 v34, 0x2b8cbccc, v34
	v_add_f32_dpp v39, v39, v39 quad_perm:[2,3,0,1] row_mask:0xf bank_mask:0xf bound_ctrl:1
	v_div_scale_f32 v40, s[28:29], v34, v34, v32
	v_rcp_f32_e32 v41, v40
	v_add_f32_dpp v39, v39, v39 row_half_mirror row_mask:0xf bank_mask:0xf bound_ctrl:1
	v_fma_f32 v42, -v40, v41, 1.0
	v_fmac_f32_e32 v41, v42, v41
	v_add_f32_dpp v39, v39, v39 row_mirror row_mask:0xf bank_mask:0xf bound_ctrl:1
	v_div_scale_f32 v42, vcc, v32, v34, v32
	v_mul_f32_e32 v43, v42, v41
	v_fma_f32 v44, -v40, v43, v42
	v_fmac_f32_e32 v43, v44, v41
	v_fma_f32 v40, -v40, v43, v42
	v_readlane_b32 s24, v39, 0
	v_readlane_b32 s25, v39, 16
	v_readlane_b32 s26, v39, 32
	v_readlane_b32 s27, v39, 48
	v_div_fmas_f32 v40, v40, v41, v43
	v_div_fixup_f32 v35, v40, v34, v32
	v_mul_f32_e32 v46, 0x3fb8aa3b, v10
	v_mul_f32_e32 v47, 0x3fb8aa3b, v30
	v_mul_f32_e32 v48, 0xbfb8aa3b, v30
	v_exp_f32_e32 v46, v46
	v_exp_f32_e32 v47, v47
	v_exp_f32_e32 v48, v48
	v_mul_f32_e32 v45, v31, v35
	v_mov_b32_e32 v41, s25
	v_mov_b32_e32 v42, s27
	v_add_f32_e32 v41, s24, v41
	v_add_f32_e32 v42, s26, v42
	v_mul_f32_e64 v49, v46, -v35
	v_mul_f32_e32 v50, v48, v45
	v_mul_f32_e32 v51, v37, v48
	v_mul_f32_e32 v52, v25, v47
	v_add_f32_e32 v41, v41, v42
	global_store_dword v14, v49, s[40:41]
	global_store_dword v14, v50, s[40:41] offset:256
	global_store_dword v14, v51, s[40:41] offset:512
	global_store_dword v14, v52, s[40:41] offset:768
	v_sub_f32_e32 v53, v9, v22
	v_fma_f32 v53, v3, v53, v22
	global_store_dword v14, v53, s[42:43]
	s_mov_b64 s[60:61], exec
	s_mov_b64 exec, 1
	v_mov_b32_e32 v42, 0
	global_store_dword v42, v41, s[44:45]
	s_mov_b64 exec, s[60:61]
	v_mov_b32_e32 v7, v20
	v_mov_b32_e32 v8, v21
	v_mov_b32_e32 v9, v22
	v_mov_b32_e32 v10, v30
	s_add_u32 s40, s40, 0x400
	s_addc_u32 s41, s41, 0
	s_add_u32 s42, s42, 0x2000
	s_addc_u32 s43, s43, 0
	s_add_u32 s44, s44, 0x80
	s_addc_u32 s45, s45, 0
; __device__ __forceinline__ float bf2f(bf16 x) { return __uint_as_float(((unsigned)x) << 16); }
; __device__ __forceinline__ float sigmoidf_(float x) { return __builtin_amdgcn_rcpf(1.0f + __expf(-x)); }
; __device__ __forceinline__ void rw_prep(Frame& F) {
;     ...
;             for (int q = 0; q < 8; ++q) { const int row = row0 + t0 + q;
;                 const float crq = bf2f(cr[q]), ckq = bf2f(ck[q]), cvq = bf2f(cv[q]);
;                 const float rr = crq + (pr - crq) * mur, kv = ckq + (pk - ckq) * muk;
;                 const float nx = -bf2f(lw[q]); const float sp = fmaxf(nx, 0.f) + __logf(1.0f + __expf(-fabsf(nx))); const float lgw = -__expf(-sp - 0.5f); const float asg = sigmoidf_(bf2f(as[q]));
;                 float kk = kv * kkw; const float nrm = sqrtf(wsum(kk * kk)); kk = kk / fmaxf(nrm, 1e-12f);
;                 const float k_ = kv * (1.f + (asg - 1.f) * kaw);
;                 const float rk = wsum(rr * k_ * rkw);
;                 const float eex = __expf(Lw); Lw += lgw; const float ein = __expf(Lw), einv = __expf(-Lw);
;                 float* rec = REC + (size_t)(rec0 + t0 + q) * 256;
;                 rec[lane] = -kk * eex; rec[64 + lane] = kk * asg * einv; rec[128 + lane] = k_ * einv; rec[192 + lane] = rr * ein;
;                 if (lane == 0) RK[(size_t)row * 32 + h] = rk;
;                 VS[(size_t)row * DH + col] = cvq + (pv - cvq) * muv;
;                 pr = crq; pk = ckq; pv = cvq; }
	v_lshlrev_b32_e32 v20, 16, v114
	v_lshlrev_b32_e32 v21, 16, v115
	v_lshlrev_b32_e32 v23, 16, v117
	v_lshlrev_b32_e32 v24, 16, v118
	v_lshlrev_b32_e32 v22, 16, v116
	v_sub_f32_e32 v26, v8, v21
	v_sub_f32_e32 v25, v7, v20
	v_fma_f32 v26, v2, v26, v21
	v_fma_f32 v25, v1, v25, v20
	v_mul_f32_e32 v32, v4, v26
	v_mul_f32_e32 v33, v32, v32
	v_max_f32_e64 v27, -v23, -v23
	v_mul_f32_e64 v28, |v23|, s56
	v_mov_b32_dpp v33, v33 quad_perm:[1,0,3,2] row_mask:0xf bank_mask:0xf bound_ctrl:1
	v_fmac_f32_e32 v33, v32, v32
	v_exp_f32_e32 v28, v28
	v_max_f32_e32 v27, 0, v27
	v_add_f32_dpp v33, v33, v33 quad_perm:[2,3,0,1] row_mask:0xf bank_mask:0xf bound_ctrl:1
	v_add_f32_e32 v28, 1.0, v28
	v_mul_f32_e32 v31, 0xbfb8aa3b, v24
	v_add_f32_dpp v33, v33, v33 row_half_mirror row_mask:0xf bank_mask:0xf bound_ctrl:1
	v_log_f32_e32 v28, v28
	v_exp_f32_e32 v31, v31
	v_add_f32_dpp v33, v33, v33 row_mirror row_mask:0xf bank_mask:0xf bound_ctrl:1
	v_mul_f32_e32 v29, 0x3f317217, v28
	v_readlane_b32 s24, v33, 16
	v_readlane_b32 s25, v33, 48
	v_readlane_b32 s26, v33, 0
	v_readlane_b32 s27, v33, 32
	v_fma_f32 v29, v28, s58, -v29
	v_fmac_f32_e32 v29, 0x3377d1cf, v28
	v_mov_b32_e32 v33, s24
	v_mov_b32_e32 v40, s25
	v_add_f32_e32 v33, s26, v33
	v_add_f32_e32 v40, s27, v40
	v_fmac_f32_e32 v29, 0x3f317217, v28
	v_add_f32_e32 v33, v33, v40
	v_add_f32_e32 v31, 1.0, v31
	v_rcp_f32_e32 v31, v31
	v_add_f32_e32 v27, v27, v29
	v_sub_f32_e32 v27, -0.5, v27
	v_mul_f32_e32 v27, 0x3fb8aa3b, v27
	v_exp_f32_e32 v27, v27
	v_cmp_gt_f32_e32 vcc, s59, v33
	v_mul_f32_e32 v40, 0x4f800000, v33
	v_sub_f32_e32 v30, v10, v27
	v_cndmask_b32_e32 v33, v33, v40, vcc
	v_sqrt_f32_e32 v34, v33
	v_add_f32_e32 v36, -1.0, v31
	v_add_u32_e32 v41, -1, v34
	v_fma_f32 v42, -v41, v34, v33
	v_cmp_ge_f32_e64 s[28:29], 0, v42
	v_add_u32_e32 v42, 1, v34
	v_fma_f32 v36, v5, v36, 1.0
	v_cndmask_b32_e64 v41, v34, v41, s[28:29]
	v_fma_f32 v34, -v42, v34, v33
	v_cmp_lt_f32_e64 s[28:29], 0, v34
	v_mul_f32_e32 v37, v26, v36
	v_mul_f32_e32 v38, v25, v37
	v_cndmask_b32_e64 v34, v41, v42, s[28:29]
	v_mul_f32_e32 v41, 0x37800000, v34
	v_mul_f32_e32 v39, v6, v38
	v_cndmask_b32_e32 v34, v34, v41, vcc
	v_cmp_class_f32_e32 vcc, v33, v15
	v_mov_b32_dpp v39, v39 quad_perm:[1,0,3,2] row_mask:0xf bank_mask:0xf bound_ctrl:1
	v_fmac_f32_e32 v39, v6, v38
	v_cndmask_b32_e32 v34, v34, v33, vcc
	v_max_f32_e32 v34, 0x2b8cbccc, v34
	v_add_f32_dpp v39, v39, v39 quad_perm:[2,3,0,1] row_mask:0xf bank_mask:0xf bound_ctrl:1
	v_div_scale_f32 v40, s[28:29], v34, v34, v32
	v_rcp_f32_e32 v41, v40
	v_add_f32_dpp v39, v39, v39 row_half_mirror row_mask:0xf bank_mask:0xf bound_ctrl:1
	v_fma_f32 v42, -v40, v41, 1.0
	v_fmac_f32_e32 v41, v42, v41
	v_add_f32_dpp v39, v39, v39 row_mirror row_mask:0xf bank_mask:0xf bound_ctrl:1
	v_div_scale_f32 v42, vcc, v32, v34, v32
	v_mul_f32_e32 v43, v42, v41
	v_fma_f32 v44, -v40, v43, v42
	v_fmac_f32_e32 v43, v44, v41
	v_fma_f32 v40, -v40, v43, v42
	v_readlane_b32 s24, v39, 0
	v_readlane_b32 s25, v39, 16
	v_readlane_b32 s26, v39, 32
	v_readlane_b32 s27, v39, 48
	v_div_fmas_f32 v40, v40, v41, v43
	v_div_fixup_f32 v35, v40, v34, v32
	v_mul_f32_e32 v46, 0x3fb8aa3b, v10
	v_mul_f32_e32 v47, 0x3fb8aa3b, v30
	v_mul_f32_e32 v48, 0xbfb8aa3b, v30
	v_exp_f32_e32 v46, v46
	v_exp_f32_e32 v47, v47
	v_exp_f32_e32 v48, v48
	v_mul_f32_e32 v45, v31, v35
	v_mov_b32_e32 v41, s25
	v_mov_b32_e32 v42, s27
	v_add_f32_e32 v41, s24, v41
	v_add_f32_e32 v42, s26, v42
	v_mul_f32_e64 v49, v46, -v35
	v_mul_f32_e32 v50, v48, v45
	v_mul_f32_e32 v51, v37, v48
	v_mul_f32_e32 v52, v25, v47
	v_add_f32_e32 v41, v41, v42
	global_store_dword v14, v49, s[40:41]
	global_store_dword v14, v50, s[40:41] offset:256
	global_store_dword v14, v51, s[40:41] offset:512
	global_store_dword v14, v52, s[40:41] offset:768
	v_sub_f32_e32 v53, v9, v22
	v_fma_f32 v53, v3, v53, v22
	global_store_dword v14, v53, s[42:43]
	s_mov_b64 s[60:61], exec
	s_mov_b64 exec, 1
	v_mov_b32_e32 v42, 0
	global_store_dword v42, v41, s[44:45]
	s_mov_b64 exec, s[60:61]
	v_mov_b32_e32 v7, v20
	v_mov_b32_e32 v8, v21
	v_mov_b32_e32 v9, v22
	v_mov_b32_e32 v10, v30
	s_add_u32 s40, s40, 0x400
	s_addc_u32 s41, s41, 0
	s_add_u32 s42, s42, 0x2000
	s_addc_u32 s43, s43, 0
	s_add_u32 s44, s44, 0x80
	s_addc_u32 s45, s45, 0
	v_lshlrev_b32_e32 v20, 16, v119
	v_lshlrev_b32_e32 v21, 16, v120
	v_lshlrev_b32_e32 v23, 16, v122
	v_lshlrev_b32_e32 v24, 16, v123
	v_lshlrev_b32_e32 v22, 16, v121
	v_sub_f32_e32 v26, v8, v21
	v_sub_f32_e32 v25, v7, v20
	v_fma_f32 v26, v2, v26, v21
	v_fma_f32 v25, v1, v25, v20
	v_mul_f32_e32 v32, v4, v26
	v_mul_f32_e32 v33, v32, v32
	v_max_f32_e64 v27, -v23, -v23
	v_mul_f32_e64 v28, |v23|, s56
	v_mov_b32_dpp v33, v33 quad_perm:[1,0,3,2] row_mask:0xf bank_mask:0xf bound_ctrl:1
	v_fmac_f32_e32 v33, v32, v32
	v_exp_f32_e32 v28, v28
	v_max_f32_e32 v27, 0, v27
	v_add_f32_dpp v33, v33, v33 quad_perm:[2,3,0,1] row_mask:0xf bank_mask:0xf bound_ctrl:1
	v_add_f32_e32 v28, 1.0, v28
	v_mul_f32_e32 v31, 0xbfb8aa3b, v24
	v_add_f32_dpp v33, v33, v33 row_half_mirror row_mask:0xf bank_mask:0xf bound_ctrl:1
	v_log_f32_e32 v28, v28
	v_exp_f32_e32 v31, v31
	v_add_f32_dpp v33, v33, v33 row_mirror row_mask:0xf bank_mask:0xf bound_ctrl:1
	v_mul_f32_e32 v29, 0x3f317217, v28
	v_readlane_b32 s24, v33, 16
	v_readlane_b32 s25, v33, 48
	v_readlane_b32 s26, v33, 0
	v_readlane_b32 s27, v33, 32
	v_fma_f32 v29, v28, s58, -v29
	v_fmac_f32_e32 v29, 0x3377d1cf, v28
	v_mov_b32_e32 v33, s24
	v_mov_b32_e32 v40, s25
	v_add_f32_e32 v33, s26, v33
	v_add_f32_e32 v40, s27, v40
	v_fmac_f32_e32 v29, 0x3f317217, v28
	v_add_f32_e32 v33, v33, v40
	v_add_f32_e32 v31, 1.0, v31
	v_rcp_f32_e32 v31, v31
	v_add_f32_e32 v27, v27, v29
; __device__ __forceinline__ float bf2f(bf16 x) { return __uint_as_float(((unsigned)x) << 16); }
; __device__ __forceinline__ float sigmoidf_(float x) { return __builtin_amdgcn_rcpf(1.0f + __expf(-x)); }
; #define PREP_LD(R_, K_, V_, L_, A_, t) do { _Pragma("unroll") for (int q = 0; q < 8; ++q) { const size_t o_ = (size_t)((t) + q); R_[q] = zp[o_ * LDZR]; K_[q] = zp[o_ * LDZR + 2048]; V_[q] = zp[o_ * LDZR + 4096]; L_[q] = lp[o_ * DH]; A_[q] = ap[o_ * DH]; } } while (0)
; __device__ __forceinline__ void rw_prep(Frame& F) {
;     ...
;         PREP_LD(cr, ck, cv, lw, as, 0);
;         for (int t0 = 0; t0 < n; t0 += 8) {
;             { const int tn = t0 + 8 < n ? t0 + 8 : t0; PREP_LD(nr, nk, nv, nl, na, tn); }
;     ...
;             for (int q = 0; q < 8; ++q) { const int row = row0 + t0 + q;
;                 const float crq = bf2f(cr[q]), ckq = bf2f(ck[q]), cvq = bf2f(cv[q]);
;                 const float rr = crq + (pr - crq) * mur, kv = ckq + (pk - ckq) * muk;
;                 const float nx = -bf2f(lw[q]); const float sp = fmaxf(nx, 0.f) + __logf(1.0f + __expf(-fabsf(nx))); const float lgw = -__expf(-sp - 0.5f); const float asg = sigmoidf_(bf2f(as[q]));
;                 float kk = kv * kkw; const float nrm = sqrtf(wsum(kk * kk)); kk = kk / fmaxf(nrm, 1e-12f);
;                 const float k_ = kv * (1.f + (asg - 1.f) * kaw);
;                 const float rk = wsum(rr * k_ * rkw);
;                 const float eex = __expf(Lw); Lw += lgw; const float ein = __expf(Lw), einv = __expf(-Lw);
;                 float* rec = REC + (size_t)(rec0 + t0 + q) * 256;
;                 rec[lane] = -kk * eex; rec[64 + lane] = kk * asg * einv; rec[128 + lane] = k_ * einv; rec[192 + lane] = rr * ein;
;                 if (lane == 0) RK[(size_t)row * 32 + h] = rk;
;                 VS[(size_t)row * DH + col] = cvq + (pv - cvq) * muv;
;                 pr = crq; pk = ckq; pv = cvq; }
	v_sub_f32_e32 v27, -0.5, v27
	v_mul_f32_e32 v27, 0x3fb8aa3b, v27
	v_exp_f32_e32 v27, v27
	v_cmp_gt_f32_e32 vcc, s59, v33
	v_mul_f32_e32 v40, 0x4f800000, v33
	v_sub_f32_e32 v30, v10, v27
	v_cndmask_b32_e32 v33, v33, v40, vcc
	v_sqrt_f32_e32 v34, v33
	v_add_f32_e32 v36, -1.0, v31
	v_add_u32_e32 v41, -1, v34
	v_fma_f32 v42, -v41, v34, v33
	v_cmp_ge_f32_e64 s[28:29], 0, v42
	v_add_u32_e32 v42, 1, v34
	v_fma_f32 v36, v5, v36, 1.0
	v_cndmask_b32_e64 v41, v34, v41, s[28:29]
	v_fma_f32 v34, -v42, v34, v33
	v_cmp_lt_f32_e64 s[28:29], 0, v34
	v_mul_f32_e32 v37, v26, v36
	v_mul_f32_e32 v38, v25, v37
	v_cndmask_b32_e64 v34, v41, v42, s[28:29]
	v_mul_f32_e32 v41, 0x37800000, v34
	v_mul_f32_e32 v39, v6, v38
	v_cndmask_b32_e32 v34, v34, v41, vcc
	v_cmp_class_f32_e32 vcc, v33, v15
	v_mov_b32_dpp v39, v39 quad_perm:[1,0,3,2] row_mask:0xf bank_mask:0xf bound_ctrl:1
	v_fmac_f32_e32 v39, v6, v38
	v_cndmask_b32_e32 v34, v34, v33, vcc
	v_max_f32_e32 v34, 0x2b8cbccc, v34
	v_add_f32_dpp v39, v39, v39 quad_perm:[2,3,0,1] row_mask:0xf bank_mask:0xf bound_ctrl:1
	v_div_scale_f32 v40, s[28:29], v34, v34, v32
	v_rcp_f32_e32 v41, v40
	v_add_f32_dpp v39, v39, v39 row_half_mirror row_mask:0xf bank_mask:0xf bound_ctrl:1
	v_fma_f32 v42, -v40, v41, 1.0
	v_fmac_f32_e32 v41, v42, v41
	v_add_f32_dpp v39, v39, v39 row_mirror row_mask:0xf bank_mask:0xf bound_ctrl:1
	v_div_scale_f32 v42, vcc, v32, v34, v32
	v_mul_f32_e32 v43, v42, v41
	v_fma_f32 v44, -v40, v43, v42
	v_fmac_f32_e32 v43, v44, v41
	v_fma_f32 v40, -v40, v43, v42
	v_readlane_b32 s24, v39, 0
	v_readlane_b32 s25, v39, 16
	v_readlane_b32 s26, v39, 32
	v_readlane_b32 s27, v39, 48
	v_div_fmas_f32 v40, v40, v41, v43
	v_div_fixup_f32 v35, v40, v34, v32
	v_mul_f32_e32 v46, 0x3fb8aa3b, v10
	v_mul_f32_e32 v47, 0x3fb8aa3b, v30
	v_mul_f32_e32 v48, 0xbfb8aa3b, v30
	v_exp_f32_e32 v46, v46
	v_exp_f32_e32 v47, v47
	v_exp_f32_e32 v48, v48
	v_mul_f32_e32 v45, v31, v35
	v_mov_b32_e32 v41, s25
	v_mov_b32_e32 v42, s27
	v_add_f32_e32 v41, s24, v41
	v_add_f32_e32 v42, s26, v42
	v_mul_f32_e64 v49, v46, -v35
	v_mul_f32_e32 v50, v48, v45
	v_mul_f32_e32 v51, v37, v48
	v_mul_f32_e32 v52, v25, v47
	v_add_f32_e32 v41, v41, v42
	global_store_dword v14, v49, s[40:41]
	global_store_dword v14, v50, s[40:41] offset:256
	global_store_dword v14, v51, s[40:41] offset:512
	global_store_dword v14, v52, s[40:41] offset:768
	v_sub_f32_e32 v53, v9, v22
	v_fma_f32 v53, v3, v53, v22
	global_store_dword v14, v53, s[42:43]
	s_mov_b64 s[60:61], exec
	s_mov_b64 exec, 1
	v_mov_b32_e32 v42, 0
	global_store_dword v42, v41, s[44:45]
	s_mov_b64 exec, s[60:61]
	v_mov_b32_e32 v7, v20
	v_mov_b32_e32 v8, v21
	v_mov_b32_e32 v9, v22
	v_mov_b32_e32 v10, v30
	s_add_u32 s40, s40, 0x400
	s_addc_u32 s41, s41, 0
	s_add_u32 s42, s42, 0x2000
	s_addc_u32 s43, s43, 0
	s_add_u32 s44, s44, 0x80
	s_addc_u32 s45, s45, 0
	s_cmp_eq_u32 s21, 1
	s_cbranch_scc1 .Lpp_nopf
	global_load_ushort v64, v11, s[50:51]
	global_load_ushort v65, v12, s[50:51]
	global_load_ushort v66, v13, s[50:51]
	global_load_ushort v67, v11, s[52:53]
	global_load_ushort v68, v11, s[54:55]
	s_add_u32 s50, s50, 13824
	s_addc_u32 s51, s51, 0
	s_add_u32 s52, s52, 0x1000
	s_addc_u32 s53, s53, 0
	s_add_u32 s54, s54, 0x1000
	s_addc_u32 s55, s55, 0
	global_load_ushort v69, v11, s[50:51]
	global_load_ushort v70, v12, s[50:51]
	global_load_ushort v71, v13, s[50:51]
	global_load_ushort v72, v11, s[52:53]
	global_load_ushort v73, v11, s[54:55]
	s_add_u32 s50, s50, 13824
	s_addc_u32 s51, s51, 0
	s_add_u32 s52, s52, 0x1000
	s_addc_u32 s53, s53, 0
	s_add_u32 s54, s54, 0x1000
	s_addc_u32 s55, s55, 0
	global_load_ushort v74, v11, s[50:51]
	global_load_ushort v75, v12, s[50:51]
	global_load_ushort v76, v13, s[50:51]
	global_load_ushort v77, v11, s[52:53]
	global_load_ushort v78, v11, s[54:55]
	s_add_u32 s50, s50, 13824
	s_addc_u32 s51, s51, 0
	s_add_u32 s52, s52, 0x1000
	s_addc_u32 s53, s53, 0
	s_add_u32 s54, s54, 0x1000
	s_addc_u32 s55, s55, 0
	global_load_ushort v79, v11, s[50:51]
	global_load_ushort v80, v12, s[50:51]
	global_load_ushort v81, v13, s[50:51]
	global_load_ushort v82, v11, s[52:53]
	global_load_ushort v83, v11, s[54:55]
	s_add_u32 s50, s50, 13824
	s_addc_u32 s51, s51, 0
	s_add_u32 s52, s52, 0x1000
	s_addc_u32 s53, s53, 0
	s_add_u32 s54, s54, 0x1000
	s_addc_u32 s55, s55, 0
	global_load_ushort v84, v11, s[50:51]
	global_load_ushort v85, v12, s[50:51]
	global_load_ushort v86, v13, s[50:51]
	global_load_ushort v87, v11, s[52:53]
	global_load_ushort v88, v11, s[54:55]
	s_add_u32 s50, s50, 13824
	s_addc_u32 s51, s51, 0
	s_add_u32 s52, s52, 0x1000
	s_addc_u32 s53, s53, 0
	s_add_u32 s54, s54, 0x1000
	s_addc_u32 s55, s55, 0
	global_load_ushort v89, v11, s[50:51]
	global_load_ushort v90, v12, s[50:51]
	global_load_ushort v91, v13, s[50:51]
	global_load_ushort v92, v11, s[52:53]
	global_load_ushort v93, v11, s[54:55]
	s_add_u32 s50, s50, 13824
	s_addc_u32 s51, s51, 0
	s_add_u32 s52, s52, 0x1000
	s_addc_u32 s53, s53, 0
	s_add_u32 s54, s54, 0x1000
	s_addc_u32 s55, s55, 0
	global_load_ushort v94, v11, s[50:51]
	global_load_ushort v95, v12, s[50:51]
	global_load_ushort v96, v13, s[50:51]
	global_load_ushort v97, v11, s[52:53]
	global_load_ushort v98, v11, s[54:55]
	s_add_u32 s50, s50, 13824
	s_addc_u32 s51, s51, 0
	s_add_u32 s52, s52, 0x1000
	s_addc_u32 s53, s53, 0
	s_add_u32 s54, s54, 0x1000
	s_addc_u32 s55, s55, 0
	global_load_ushort v99, v11, s[50:51]
	global_load_ushort v100, v12, s[50:51]
	global_load_ushort v101, v13, s[50:51]
	global_load_ushort v102, v11, s[52:53]
	global_load_ushort v103, v11, s[54:55]
	s_add_u32 s50, s50, 13824
	s_addc_u32 s51, s51, 0
	s_add_u32 s52, s52, 0x1000
	s_addc_u32 s53, s53, 0
	s_add_u32 s54, s54, 0x1000
	s_addc_u32 s55, s55, 0
; __device__ __forceinline__ float bf2f(bf16 x) { return __uint_as_float(((unsigned)x) << 16); }
; __device__ __forceinline__ float sigmoidf_(float x) { return __builtin_amdgcn_rcpf(1.0f + __expf(-x)); }
; __device__ __forceinline__ void rw_prep(Frame& F) {
;     ...
;             for (int q = 0; q < 8; ++q) { const int row = row0 + t0 + q;
;                 const float crq = bf2f(cr[q]), ckq = bf2f(ck[q]), cvq = bf2f(cv[q]);
;                 const float rr = crq + (pr - crq) * mur, kv = ckq + (pk - ckq) * muk;
;                 const float nx = -bf2f(lw[q]); const float sp = fmaxf(nx, 0.f) + __logf(1.0f + __expf(-fabsf(nx))); const float lgw = -__expf(-sp - 0.5f); const float asg = sigmoidf_(bf2f(as[q]));
;                 float kk = kv * kkw; const float nrm = sqrtf(wsum(kk * kk)); kk = kk / fmaxf(nrm, 1e-12f);
;                 const float k_ = kv * (1.f + (asg - 1.f) * kaw);
;                 const float rk = wsum(rr * k_ * rkw);
;                 const float eex = __expf(Lw); Lw += lgw; const float ein = __expf(Lw), einv = __expf(-Lw);
;                 float* rec = REC + (size_t)(rec0 + t0 + q) * 256;
;                 rec[lane] = -kk * eex; rec[64 + lane] = kk * asg * einv; rec[128 + lane] = k_ * einv; rec[192 + lane] = rr * ein;
;                 if (lane == 0) RK[(size_t)row * 32 + h] = rk;
;                 VS[(size_t)row * DH + col] = cvq + (pv - cvq) * muv;
;                 pr = crq; pk = ckq; pv = cvq; }
.Lpp_nopf:
	v_lshlrev_b32_e32 v20, 16, v124
	v_lshlrev_b32_e32 v21, 16, v125
	v_lshlrev_b32_e32 v23, 16, v127
	v_lshlrev_b32_e32 v24, 16, v128
	v_lshlrev_b32_e32 v22, 16, v126
	v_sub_f32_e32 v26, v8, v21
	v_sub_f32_e32 v25, v7, v20
	v_fma_f32 v26, v2, v26, v21
	v_fma_f32 v25, v1, v25, v20
	v_mul_f32_e32 v32, v4, v26
	v_mul_f32_e32 v33, v32, v32
	v_max_f32_e64 v27, -v23, -v23
	v_mul_f32_e64 v28, |v23|, s56
	v_mov_b32_dpp v33, v33 quad_perm:[1,0,3,2] row_mask:0xf bank_mask:0xf bound_ctrl:1
	v_fmac_f32_e32 v33, v32, v32
	v_exp_f32_e32 v28, v28
	v_max_f32_e32 v27, 0, v27
	v_add_f32_dpp v33, v33, v33 quad_perm:[2,3,0,1] row_mask:0xf bank_mask:0xf bound_ctrl:1
	v_add_f32_e32 v28, 1.0, v28
	v_mul_f32_e32 v31, 0xbfb8aa3b, v24
	v_add_f32_dpp v33, v33, v33 row_half_mirror row_mask:0xf bank_mask:0xf bound_ctrl:1
	v_log_f32_e32 v28, v28
	v_exp_f32_e32 v31, v31
	v_add_f32_dpp v33, v33, v33 row_mirror row_mask:0xf bank_mask:0xf bound_ctrl:1
	v_mul_f32_e32 v29, 0x3f317217, v28
	v_readlane_b32 s24, v33, 16
	v_readlane_b32 s25, v33, 48
	v_readlane_b32 s26, v33, 0
	v_readlane_b32 s27, v33, 32
	v_fma_f32 v29, v28, s58, -v29
	v_fmac_f32_e32 v29, 0x3377d1cf, v28
	v_mov_b32_e32 v33, s24
	v_mov_b32_e32 v40, s25
	v_add_f32_e32 v33, s26, v33
	v_add_f32_e32 v40, s27, v40
	v_fmac_f32_e32 v29, 0x3f317217, v28
	v_add_f32_e32 v33, v33, v40
	v_add_f32_e32 v31, 1.0, v31
	v_rcp_f32_e32 v31, v31
	v_add_f32_e32 v27, v27, v29
	v_sub_f32_e32 v27, -0.5, v27
	v_mul_f32_e32 v27, 0x3fb8aa3b, v27
	v_exp_f32_e32 v27, v27
	v_cmp_gt_f32_e32 vcc, s59, v33
	v_mul_f32_e32 v40, 0x4f800000, v33
	v_sub_f32_e32 v30, v10, v27
	v_cndmask_b32_e32 v33, v33, v40, vcc
	v_sqrt_f32_e32 v34, v33
	v_add_f32_e32 v36, -1.0, v31
	v_add_u32_e32 v41, -1, v34
	v_fma_f32 v42, -v41, v34, v33
	v_cmp_ge_f32_e64 s[28:29], 0, v42
	v_add_u32_e32 v42, 1, v34
	v_fma_f32 v36, v5, v36, 1.0
	v_cndmask_b32_e64 v41, v34, v41, s[28:29]
	v_fma_f32 v34, -v42, v34, v33
	v_cmp_lt_f32_e64 s[28:29], 0, v34
	v_mul_f32_e32 v37, v26, v36
	v_mul_f32_e32 v38, v25, v37
	v_cndmask_b32_e64 v34, v41, v42, s[28:29]
	v_mul_f32_e32 v41, 0x37800000, v34
	v_mul_f32_e32 v39, v6, v38
	v_cndmask_b32_e32 v34, v34, v41, vcc
	v_cmp_class_f32_e32 vcc, v33, v15
	v_mov_b32_dpp v39, v39 quad_perm:[1,0,3,2] row_mask:0xf bank_mask:0xf bound_ctrl:1
	v_fmac_f32_e32 v39, v6, v38
	v_cndmask_b32_e32 v34, v34, v33, vcc
	v_max_f32_e32 v34, 0x2b8cbccc, v34
	v_add_f32_dpp v39, v39, v39 quad_perm:[2,3,0,1] row_mask:0xf bank_mask:0xf bound_ctrl:1
	v_div_scale_f32 v40, s[28:29], v34, v34, v32
	v_rcp_f32_e32 v41, v40
	v_add_f32_dpp v39, v39, v39 row_half_mirror row_mask:0xf bank_mask:0xf bound_ctrl:1
	v_fma_f32 v42, -v40, v41, 1.0
	v_fmac_f32_e32 v41, v42, v41
	v_add_f32_dpp v39, v39, v39 row_mirror row_mask:0xf bank_mask:0xf bound_ctrl:1
	v_div_scale_f32 v42, vcc, v32, v34, v32
	v_mul_f32_e32 v43, v42, v41
	v_fma_f32 v44, -v40, v43, v42
	v_fmac_f32_e32 v43, v44, v41
	v_fma_f32 v40, -v40, v43, v42
	v_readlane_b32 s24, v39, 0
	v_readlane_b32 s25, v39, 16
	v_readlane_b32 s26, v39, 32
	v_readlane_b32 s27, v39, 48
	v_div_fmas_f32 v40, v40, v41, v43
	v_div_fixup_f32 v35, v40, v34, v32
	v_mul_f32_e32 v46, 0x3fb8aa3b, v10
	v_mul_f32_e32 v47, 0x3fb8aa3b, v30
	v_mul_f32_e32 v48, 0xbfb8aa3b, v30
	v_exp_f32_e32 v46, v46
	v_exp_f32_e32 v47, v47
	v_exp_f32_e32 v48, v48
	v_mul_f32_e32 v45, v31, v35
	v_mov_b32_e32 v41, s25
	v_mov_b32_e32 v42, s27
	v_add_f32_e32 v41, s24, v41
	v_add_f32_e32 v42, s26, v42
	v_mul_f32_e64 v49, v46, -v35
	v_mul_f32_e32 v50, v48, v45
	v_mul_f32_e32 v51, v37, v48
	v_mul_f32_e32 v52, v25, v47
	v_add_f32_e32 v41, v41, v42
	global_store_dword v14, v49, s[40:41]
	global_store_dword v14, v50, s[40:41] offset:256
	global_store_dword v14, v51, s[40:41] offset:512
	global_store_dword v14, v52, s[40:41] offset:768
	v_sub_f32_e32 v53, v9, v22
	v_fma_f32 v53, v3, v53, v22
	global_store_dword v14, v53, s[42:43]
	s_mov_b64 s[60:61], exec
	s_mov_b64 exec, 1
	v_mov_b32_e32 v42, 0
	global_store_dword v42, v41, s[44:45]
	s_mov_b64 exec, s[60:61]
	v_mov_b32_e32 v7, v20
	v_mov_b32_e32 v8, v21
	v_mov_b32_e32 v9, v22
	v_mov_b32_e32 v10, v30
	s_add_u32 s40, s40, 0x400
	s_addc_u32 s41, s41, 0
	s_add_u32 s42, s42, 0x2000
	s_addc_u32 s43, s43, 0
	s_add_u32 s44, s44, 0x80
	s_addc_u32 s45, s45, 0
	v_lshlrev_b32_e32 v20, 16, v129
	v_lshlrev_b32_e32 v21, 16, v130
	v_lshlrev_b32_e32 v23, 16, v132
	v_lshlrev_b32_e32 v24, 16, v133
	v_lshlrev_b32_e32 v22, 16, v131
	v_sub_f32_e32 v26, v8, v21
	v_sub_f32_e32 v25, v7, v20
	v_fma_f32 v26, v2, v26, v21
	v_fma_f32 v25, v1, v25, v20
	v_mul_f32_e32 v32, v4, v26
	v_mul_f32_e32 v33, v32, v32
	v_max_f32_e64 v27, -v23, -v23
	v_mul_f32_e64 v28, |v23|, s56
	v_mov_b32_dpp v33, v33 quad_perm:[1,0,3,2] row_mask:0xf bank_mask:0xf bound_ctrl:1
	v_fmac_f32_e32 v33, v32, v32
	v_exp_f32_e32 v28, v28
	v_max_f32_e32 v27, 0, v27
	v_add_f32_dpp v33, v33, v33 quad_perm:[2,3,0,1] row_mask:0xf bank_mask:0xf bound_ctrl:1
	v_add_f32_e32 v28, 1.0, v28
	v_mul_f32_e32 v31, 0xbfb8aa3b, v24
	v_add_f32_dpp v33, v33, v33 row_half_mirror row_mask:0xf bank_mask:0xf bound_ctrl:1
	v_log_f32_e32 v28, v28
	v_exp_f32_e32 v31, v31
	v_add_f32_dpp v33, v33, v33 row_mirror row_mask:0xf bank_mask:0xf bound_ctrl:1
	v_mul_f32_e32 v29, 0x3f317217, v28
	v_readlane_b32 s24, v33, 16
	v_readlane_b32 s25, v33, 48
	v_readlane_b32 s26, v33, 0
	v_readlane_b32 s27, v33, 32
	v_fma_f32 v29, v28, s58, -v29
	v_fmac_f32_e32 v29, 0x3377d1cf, v28
	v_mov_b32_e32 v33, s24
	v_mov_b32_e32 v40, s25
	v_add_f32_e32 v33, s26, v33
	v_add_f32_e32 v40, s27, v40
	v_fmac_f32_e32 v29, 0x3f317217, v28
	v_add_f32_e32 v33, v33, v40
	v_add_f32_e32 v31, 1.0, v31
	v_rcp_f32_e32 v31, v31
	v_add_f32_e32 v27, v27, v29
; __device__ __forceinline__ float bf2f(bf16 x) { return __uint_as_float(((unsigned)x) << 16); }
; __device__ __forceinline__ float sigmoidf_(float x) { return __builtin_amdgcn_rcpf(1.0f + __expf(-x)); }
; __device__ __forceinline__ void rw_prep(Frame& F) {
;     ...
;             for (int q = 0; q < 8; ++q) { const int row = row0 + t0 + q;
;                 const float crq = bf2f(cr[q]), ckq = bf2f(ck[q]), cvq = bf2f(cv[q]);
;                 const float rr = crq + (pr - crq) * mur, kv = ckq + (pk - ckq) * muk;
;                 const float nx = -bf2f(lw[q]); const float sp = fmaxf(nx, 0.f) + __logf(1.0f + __expf(-fabsf(nx))); const float lgw = -__expf(-sp - 0.5f); const float asg = sigmoidf_(bf2f(as[q]));
;                 float kk = kv * kkw; const float nrm = sqrtf(wsum(kk * kk)); kk = kk / fmaxf(nrm, 1e-12f);
;                 const float k_ = kv * (1.f + (asg - 1.f) * kaw);
;                 const float rk = wsum(rr * k_ * rkw);
;                 const float eex = __expf(Lw); Lw += lgw; const float ein = __expf(Lw), einv = __expf(-Lw);
;                 float* rec = REC + (size_t)(rec0 + t0 + q) * 256;
;                 rec[lane] = -kk * eex; rec[64 + lane] = kk * asg * einv; rec[128 + lane] = k_ * einv; rec[192 + lane] = rr * ein;
;                 if (lane == 0) RK[(size_t)row * 32 + h] = rk;
;                 VS[(size_t)row * DH + col] = cvq + (pv - cvq) * muv;
;                 pr = crq; pk = ckq; pv = cvq; }
	v_sub_f32_e32 v27, -0.5, v27
	v_mul_f32_e32 v27, 0x3fb8aa3b, v27
	v_exp_f32_e32 v27, v27
	v_cmp_gt_f32_e32 vcc, s59, v33
	v_mul_f32_e32 v40, 0x4f800000, v33
	v_sub_f32_e32 v30, v10, v27
	v_cndmask_b32_e32 v33, v33, v40, vcc
	v_sqrt_f32_e32 v34, v33
	v_add_f32_e32 v36, -1.0, v31
	v_add_u32_e32 v41, -1, v34
	v_fma_f32 v42, -v41, v34, v33
	v_cmp_ge_f32_e64 s[28:29], 0, v42
	v_add_u32_e32 v42, 1, v34
	v_fma_f32 v36, v5, v36, 1.0
	v_cndmask_b32_e64 v41, v34, v41, s[28:29]
	v_fma_f32 v34, -v42, v34, v33
	v_cmp_lt_f32_e64 s[28:29], 0, v34
	v_mul_f32_e32 v37, v26, v36
	v_mul_f32_e32 v38, v25, v37
	v_cndmask_b32_e64 v34, v41, v42, s[28:29]
	v_mul_f32_e32 v41, 0x37800000, v34
	v_mul_f32_e32 v39, v6, v38
	v_cndmask_b32_e32 v34, v34, v41, vcc
	v_cmp_class_f32_e32 vcc, v33, v15
	v_mov_b32_dpp v39, v39 quad_perm:[1,0,3,2] row_mask:0xf bank_mask:0xf bound_ctrl:1
	v_fmac_f32_e32 v39, v6, v38
	v_cndmask_b32_e32 v34, v34, v33, vcc
	v_max_f32_e32 v34, 0x2b8cbccc, v34
	v_add_f32_dpp v39, v39, v39 quad_perm:[2,3,0,1] row_mask:0xf bank_mask:0xf bound_ctrl:1
	v_div_scale_f32 v40, s[28:29], v34, v34, v32
	v_rcp_f32_e32 v41, v40
	v_add_f32_dpp v39, v39, v39 row_half_mirror row_mask:0xf bank_mask:0xf bound_ctrl:1
	v_fma_f32 v42, -v40, v41, 1.0
	v_fmac_f32_e32 v41, v42, v41
	v_add_f32_dpp v39, v39, v39 row_mirror row_mask:0xf bank_mask:0xf bound_ctrl:1
	v_div_scale_f32 v42, vcc, v32, v34, v32
	v_mul_f32_e32 v43, v42, v41
	v_fma_f32 v44, -v40, v43, v42
	v_fmac_f32_e32 v43, v44, v41
	v_fma_f32 v40, -v40, v43, v42
	v_readlane_b32 s24, v39, 0
	v_readlane_b32 s25, v39, 16
	v_readlane_b32 s26, v39, 32
	v_readlane_b32 s27, v39, 48
	v_div_fmas_f32 v40, v40, v41, v43
	v_div_fixup_f32 v35, v40, v34, v32
	v_mul_f32_e32 v46, 0x3fb8aa3b, v10
	v_mul_f32_e32 v47, 0x3fb8aa3b, v30
	v_mul_f32_e32 v48, 0xbfb8aa3b, v30
	v_exp_f32_e32 v46, v46
	v_exp_f32_e32 v47, v47
	v_exp_f32_e32 v48, v48
	v_mul_f32_e32 v45, v31, v35
	v_mov_b32_e32 v41, s25
	v_mov_b32_e32 v42, s27
	v_add_f32_e32 v41, s24, v41
	v_add_f32_e32 v42, s26, v42
	v_mul_f32_e64 v49, v46, -v35
	v_mul_f32_e32 v50, v48, v45
	v_mul_f32_e32 v51, v37, v48
	v_mul_f32_e32 v52, v25, v47
	v_add_f32_e32 v41, v41, v42
	global_store_dword v14, v49, s[40:41]
	global_store_dword v14, v50, s[40:41] offset:256
	global_store_dword v14, v51, s[40:41] offset:512
	global_store_dword v14, v52, s[40:41] offset:768
	v_sub_f32_e32 v53, v9, v22
	v_fma_f32 v53, v3, v53, v22
	global_store_dword v14, v53, s[42:43]
	s_mov_b64 s[60:61], exec
	s_mov_b64 exec, 1
	v_mov_b32_e32 v42, 0
	global_store_dword v42, v41, s[44:45]
	s_mov_b64 exec, s[60:61]
	v_mov_b32_e32 v7, v20
	v_mov_b32_e32 v8, v21
	v_mov_b32_e32 v9, v22
	v_mov_b32_e32 v10, v30
	s_add_u32 s40, s40, 0x400
	s_addc_u32 s41, s41, 0
	s_add_u32 s42, s42, 0x2000
	s_addc_u32 s43, s43, 0
	s_add_u32 s44, s44, 0x80
	s_addc_u32 s45, s45, 0
	v_lshlrev_b32_e32 v20, 16, v134
	v_lshlrev_b32_e32 v21, 16, v135
	v_lshlrev_b32_e32 v23, 16, v137
	v_lshlrev_b32_e32 v24, 16, v138
	v_lshlrev_b32_e32 v22, 16, v136
	v_sub_f32_e32 v26, v8, v21
	v_sub_f32_e32 v25, v7, v20
	v_fma_f32 v26, v2, v26, v21
	v_fma_f32 v25, v1, v25, v20
	v_mul_f32_e32 v32, v4, v26
	v_mul_f32_e32 v33, v32, v32
	v_max_f32_e64 v27, -v23, -v23
	v_mul_f32_e64 v28, |v23|, s56
	v_mov_b32_dpp v33, v33 quad_perm:[1,0,3,2] row_mask:0xf bank_mask:0xf bound_ctrl:1
	v_fmac_f32_e32 v33, v32, v32
	v_exp_f32_e32 v28, v28
	v_max_f32_e32 v27, 0, v27
	v_add_f32_dpp v33, v33, v33 quad_perm:[2,3,0,1] row_mask:0xf bank_mask:0xf bound_ctrl:1
	v_add_f32_e32 v28, 1.0, v28
	v_mul_f32_e32 v31, 0xbfb8aa3b, v24
	v_add_f32_dpp v33, v33, v33 row_half_mirror row_mask:0xf bank_mask:0xf bound_ctrl:1
	v_log_f32_e32 v28, v28
	v_exp_f32_e32 v31, v31
	v_add_f32_dpp v33, v33, v33 row_mirror row_mask:0xf bank_mask:0xf bound_ctrl:1
	v_mul_f32_e32 v29, 0x3f317217, v28
	v_readlane_b32 s24, v33, 16
	v_readlane_b32 s25, v33, 48
	v_readlane_b32 s26, v33, 0
	v_readlane_b32 s27, v33, 32
	v_fma_f32 v29, v28, s58, -v29
	v_fmac_f32_e32 v29, 0x3377d1cf, v28
	v_mov_b32_e32 v33, s24
	v_mov_b32_e32 v40, s25
	v_add_f32_e32 v33, s26, v33
	v_add_f32_e32 v40, s27, v40
	v_fmac_f32_e32 v29, 0x3f317217, v28
	v_add_f32_e32 v33, v33, v40
	v_add_f32_e32 v31, 1.0, v31
	v_rcp_f32_e32 v31, v31
	v_add_f32_e32 v27, v27, v29
	v_sub_f32_e32 v27, -0.5, v27
	v_mul_f32_e32 v27, 0x3fb8aa3b, v27
	v_exp_f32_e32 v27, v27
	v_cmp_gt_f32_e32 vcc, s59, v33
	v_mul_f32_e32 v40, 0x4f800000, v33
	v_sub_f32_e32 v30, v10, v27
	v_cndmask_b32_e32 v33, v33, v40, vcc
	v_sqrt_f32_e32 v34, v33
	v_add_f32_e32 v36, -1.0, v31
	v_add_u32_e32 v41, -1, v34
	v_fma_f32 v42, -v41, v34, v33
	v_cmp_ge_f32_e64 s[28:29], 0, v42
	v_add_u32_e32 v42, 1, v34
	v_fma_f32 v36, v5, v36, 1.0
	v_cndmask_b32_e64 v41, v34, v41, s[28:29]
	v_fma_f32 v34, -v42, v34, v33
	v_cmp_lt_f32_e64 s[28:29], 0, v34
	v_mul_f32_e32 v37, v26, v36
	v_mul_f32_e32 v38, v25, v37
	v_cndmask_b32_e64 v34, v41, v42, s[28:29]
	v_mul_f32_e32 v41, 0x37800000, v34
	v_mul_f32_e32 v39, v6, v38
	v_cndmask_b32_e32 v34, v34, v41, vcc
	v_cmp_class_f32_e32 vcc, v33, v15
	v_mov_b32_dpp v39, v39 quad_perm:[1,0,3,2] row_mask:0xf bank_mask:0xf bound_ctrl:1
	v_fmac_f32_e32 v39, v6, v38
	v_cndmask_b32_e32 v34, v34, v33, vcc
	v_max_f32_e32 v34, 0x2b8cbccc, v34
	v_add_f32_dpp v39, v39, v39 quad_perm:[2,3,0,1] row_mask:0xf bank_mask:0xf bound_ctrl:1
	v_div_scale_f32 v40, s[28:29], v34, v34, v32
	v_rcp_f32_e32 v41, v40
	v_add_f32_dpp v39, v39, v39 row_half_mirror row_mask:0xf bank_mask:0xf bound_ctrl:1
	v_fma_f32 v42, -v40, v41, 1.0
	v_fmac_f32_e32 v41, v42, v41
	v_add_f32_dpp v39, v39, v39 row_mirror row_mask:0xf bank_mask:0xf bound_ctrl:1
	v_div_scale_f32 v42, vcc, v32, v34, v32
	v_mul_f32_e32 v43, v42, v41
; __device__ __forceinline__ float bf2f(bf16 x) { return __uint_as_float(((unsigned)x) << 16); }
; __device__ __forceinline__ float sigmoidf_(float x) { return __builtin_amdgcn_rcpf(1.0f + __expf(-x)); }
; __device__ __forceinline__ void rw_prep(Frame& F) {
;     ...
;             for (int q = 0; q < 8; ++q) { const int row = row0 + t0 + q;
;                 const float crq = bf2f(cr[q]), ckq = bf2f(ck[q]), cvq = bf2f(cv[q]);
;                 const float rr = crq + (pr - crq) * mur, kv = ckq + (pk - ckq) * muk;
;                 const float nx = -bf2f(lw[q]); const float sp = fmaxf(nx, 0.f) + __logf(1.0f + __expf(-fabsf(nx))); const float lgw = -__expf(-sp - 0.5f); const float asg = sigmoidf_(bf2f(as[q]));
;                 float kk = kv * kkw; const float nrm = sqrtf(wsum(kk * kk)); kk = kk / fmaxf(nrm, 1e-12f);
;                 const float k_ = kv * (1.f + (asg - 1.f) * kaw);
;                 const float rk = wsum(rr * k_ * rkw);
;                 const float eex = __expf(Lw); Lw += lgw; const float ein = __expf(Lw), einv = __expf(-Lw);
;                 float* rec = REC + (size_t)(rec0 + t0 + q) * 256;
;                 rec[lane] = -kk * eex; rec[64 + lane] = kk * asg * einv; rec[128 + lane] = k_ * einv; rec[192 + lane] = rr * ein;
;                 if (lane == 0) RK[(size_t)row * 32 + h] = rk;
;                 VS[(size_t)row * DH + col] = cvq + (pv - cvq) * muv;
;                 pr = crq; pk = ckq; pv = cvq; }
; #pragma unroll
;             for (int q = 0; q < 8; ++q) { cr[q] = nr[q]; ck[q] = nk[q]; cv[q] = nv[q]; lw[q] = nl[q]; as[q] = na[q]; }
;         }
;     ...
;         WC[(size_t)u * 64 + lane] = __expf(Lw);
	v_fma_f32 v44, -v40, v43, v42
	v_fmac_f32_e32 v43, v44, v41
	v_fma_f32 v40, -v40, v43, v42
	v_readlane_b32 s24, v39, 0
	v_readlane_b32 s25, v39, 16
	v_readlane_b32 s26, v39, 32
	v_readlane_b32 s27, v39, 48
	v_div_fmas_f32 v40, v40, v41, v43
	v_div_fixup_f32 v35, v40, v34, v32
	v_mul_f32_e32 v46, 0x3fb8aa3b, v10
	v_mul_f32_e32 v47, 0x3fb8aa3b, v30
	v_mul_f32_e32 v48, 0xbfb8aa3b, v30
	v_exp_f32_e32 v46, v46
	v_exp_f32_e32 v47, v47
	v_exp_f32_e32 v48, v48
	v_mul_f32_e32 v45, v31, v35
	v_mov_b32_e32 v41, s25
	v_mov_b32_e32 v42, s27
	v_add_f32_e32 v41, s24, v41
	v_add_f32_e32 v42, s26, v42
	v_mul_f32_e64 v49, v46, -v35
	v_mul_f32_e32 v50, v48, v45
	v_mul_f32_e32 v51, v37, v48
	v_mul_f32_e32 v52, v25, v47
	v_add_f32_e32 v41, v41, v42
	global_store_dword v14, v49, s[40:41]
	global_store_dword v14, v50, s[40:41] offset:256
	global_store_dword v14, v51, s[40:41] offset:512
	global_store_dword v14, v52, s[40:41] offset:768
	v_sub_f32_e32 v53, v9, v22
	v_fma_f32 v53, v3, v53, v22
	global_store_dword v14, v53, s[42:43]
	s_mov_b64 s[60:61], exec
	s_mov_b64 exec, 1
	v_mov_b32_e32 v42, 0
	global_store_dword v42, v41, s[44:45]
	s_mov_b64 exec, s[60:61]
	v_mov_b32_e32 v7, v20
	v_mov_b32_e32 v8, v21
	v_mov_b32_e32 v9, v22
	v_mov_b32_e32 v10, v30
	s_add_u32 s40, s40, 0x400
	s_addc_u32 s41, s41, 0
	s_add_u32 s42, s42, 0x2000
	s_addc_u32 s43, s43, 0
	s_add_u32 s44, s44, 0x80
	s_addc_u32 s45, s45, 0
	v_lshlrev_b32_e32 v20, 16, v139
	v_lshlrev_b32_e32 v21, 16, v140
	v_lshlrev_b32_e32 v23, 16, v142
	v_lshlrev_b32_e32 v24, 16, v143
	v_lshlrev_b32_e32 v22, 16, v141
	v_sub_f32_e32 v26, v8, v21
	v_sub_f32_e32 v25, v7, v20
	v_fma_f32 v26, v2, v26, v21
	v_fma_f32 v25, v1, v25, v20
	v_mul_f32_e32 v32, v4, v26
	v_mul_f32_e32 v33, v32, v32
	v_max_f32_e64 v27, -v23, -v23
	v_mul_f32_e64 v28, |v23|, s56
	v_mov_b32_dpp v33, v33 quad_perm:[1,0,3,2] row_mask:0xf bank_mask:0xf bound_ctrl:1
	v_fmac_f32_e32 v33, v32, v32
	v_exp_f32_e32 v28, v28
	v_max_f32_e32 v27, 0, v27
	v_add_f32_dpp v33, v33, v33 quad_perm:[2,3,0,1] row_mask:0xf bank_mask:0xf bound_ctrl:1
	v_add_f32_e32 v28, 1.0, v28
	v_mul_f32_e32 v31, 0xbfb8aa3b, v24
	v_add_f32_dpp v33, v33, v33 row_half_mirror row_mask:0xf bank_mask:0xf bound_ctrl:1
	v_log_f32_e32 v28, v28
	v_exp_f32_e32 v31, v31
	v_add_f32_dpp v33, v33, v33 row_mirror row_mask:0xf bank_mask:0xf bound_ctrl:1
	v_mul_f32_e32 v29, 0x3f317217, v28
	v_readlane_b32 s24, v33, 16
	v_readlane_b32 s25, v33, 48
	v_readlane_b32 s26, v33, 0
	v_readlane_b32 s27, v33, 32
	v_fma_f32 v29, v28, s58, -v29
	v_fmac_f32_e32 v29, 0x3377d1cf, v28
	v_mov_b32_e32 v33, s24
	v_mov_b32_e32 v40, s25
	v_add_f32_e32 v33, s26, v33
	v_add_f32_e32 v40, s27, v40
	v_fmac_f32_e32 v29, 0x3f317217, v28
	v_add_f32_e32 v33, v33, v40
	v_add_f32_e32 v31, 1.0, v31
	v_rcp_f32_e32 v31, v31
	v_add_f32_e32 v27, v27, v29
	v_sub_f32_e32 v27, -0.5, v27
	v_mul_f32_e32 v27, 0x3fb8aa3b, v27
	v_exp_f32_e32 v27, v27
	v_cmp_gt_f32_e32 vcc, s59, v33
	v_mul_f32_e32 v40, 0x4f800000, v33
	v_sub_f32_e32 v30, v10, v27
	v_cndmask_b32_e32 v33, v33, v40, vcc
	v_sqrt_f32_e32 v34, v33
	v_add_f32_e32 v36, -1.0, v31
	v_add_u32_e32 v41, -1, v34
	v_fma_f32 v42, -v41, v34, v33
	v_cmp_ge_f32_e64 s[28:29], 0, v42
	v_add_u32_e32 v42, 1, v34
	v_fma_f32 v36, v5, v36, 1.0
	v_cndmask_b32_e64 v41, v34, v41, s[28:29]
	v_fma_f32 v34, -v42, v34, v33
	v_cmp_lt_f32_e64 s[28:29], 0, v34
	v_mul_f32_e32 v37, v26, v36
	v_mul_f32_e32 v38, v25, v37
	v_cndmask_b32_e64 v34, v41, v42, s[28:29]
	v_mul_f32_e32 v41, 0x37800000, v34
	v_mul_f32_e32 v39, v6, v38
	v_cndmask_b32_e32 v34, v34, v41, vcc
	v_cmp_class_f32_e32 vcc, v33, v15
	v_mov_b32_dpp v39, v39 quad_perm:[1,0,3,2] row_mask:0xf bank_mask:0xf bound_ctrl:1
	v_fmac_f32_e32 v39, v6, v38
	v_cndmask_b32_e32 v34, v34, v33, vcc
	v_max_f32_e32 v34, 0x2b8cbccc, v34
	v_add_f32_dpp v39, v39, v39 quad_perm:[2,3,0,1] row_mask:0xf bank_mask:0xf bound_ctrl:1
	v_div_scale_f32 v40, s[28:29], v34, v34, v32
	v_rcp_f32_e32 v41, v40
	v_add_f32_dpp v39, v39, v39 row_half_mirror row_mask:0xf bank_mask:0xf bound_ctrl:1
	v_fma_f32 v42, -v40, v41, 1.0
	v_fmac_f32_e32 v41, v42, v41
	v_add_f32_dpp v39, v39, v39 row_mirror row_mask:0xf bank_mask:0xf bound_ctrl:1
	v_div_scale_f32 v42, vcc, v32, v34, v32
	v_mul_f32_e32 v43, v42, v41
	v_fma_f32 v44, -v40, v43, v42
	v_fmac_f32_e32 v43, v44, v41
	v_fma_f32 v40, -v40, v43, v42
	v_readlane_b32 s24, v39, 0
	v_readlane_b32 s25, v39, 16
	v_readlane_b32 s26, v39, 32
	v_readlane_b32 s27, v39, 48
	v_div_fmas_f32 v40, v40, v41, v43
	v_div_fixup_f32 v35, v40, v34, v32
	v_mul_f32_e32 v46, 0x3fb8aa3b, v10
	v_mul_f32_e32 v47, 0x3fb8aa3b, v30
	v_mul_f32_e32 v48, 0xbfb8aa3b, v30
	v_exp_f32_e32 v46, v46
	v_exp_f32_e32 v47, v47
	v_exp_f32_e32 v48, v48
	v_mul_f32_e32 v45, v31, v35
	v_mov_b32_e32 v41, s25
	v_mov_b32_e32 v42, s27
	v_add_f32_e32 v41, s24, v41
	v_add_f32_e32 v42, s26, v42
	v_mul_f32_e64 v49, v46, -v35
	v_mul_f32_e32 v50, v48, v45
	v_mul_f32_e32 v51, v37, v48
	v_mul_f32_e32 v52, v25, v47
	v_add_f32_e32 v41, v41, v42
	global_store_dword v14, v49, s[40:41]
	global_store_dword v14, v50, s[40:41] offset:256
	global_store_dword v14, v51, s[40:41] offset:512
	global_store_dword v14, v52, s[40:41] offset:768
	v_sub_f32_e32 v53, v9, v22
	v_fma_f32 v53, v3, v53, v22
	global_store_dword v14, v53, s[42:43]
	s_mov_b64 s[60:61], exec
	s_mov_b64 exec, 1
	v_mov_b32_e32 v42, 0
	global_store_dword v42, v41, s[44:45]
	s_mov_b64 exec, s[60:61]
	v_mov_b32_e32 v7, v20
	v_mov_b32_e32 v8, v21
	v_mov_b32_e32 v9, v22
	v_mov_b32_e32 v10, v30
	s_add_u32 s40, s40, 0x400
	s_addc_u32 s41, s41, 0
	s_add_u32 s42, s42, 0x2000
	s_addc_u32 s43, s43, 0
	s_add_u32 s44, s44, 0x80
	s_addc_u32 s45, s45, 0
	s_waitcnt vmcnt(24)
	s_sub_u32 s21, s21, 1
	s_cmp_lg_u32 s21, 0
	s_cbranch_scc1 .Lpp_pair
	v_mul_f32_e32 v20, 0x3fb8aa3b, v10
	v_exp_f32_e32 v20, v20
	s_lshl_b32 s46, s16, 8
	s_add_u32 s46, s90, s46
	s_addc_u32 s47, s91, 0
	s_add_u32 s46, s46, 0x6e500000
	s_addc_u32 s47, s47, 0
	global_store_dword v14, v20, s[46:47]
	s_add_i32 s16, s16, s92
	s_cmpk_lt_i32 s16, 0x2100
	s_cbranch_scc1 .Lpp_unit

;     ...
;     for (int item = F.gw; item < nitems; item += F.NGW) { const int kb = item / nblk, nb = item % nblk, k0 = 64 * kb, n0 = 32 * nb;
;         int dr0 = n0; if (MAP == 1) { if (n0 < DFF) dr0 = (n0 >> 7) * 256 + (n0 & 127); else { const int uo = n0 - DFF; dr0 = (uo >> 7) * 256 + 128 + (uo & 127); } }
; #pragma unroll 8
;         for (int i = 0; i < 32; ++i) { const int kk = 2 * i + (lane >> 5); scr[kk * 33 + (lane & 31)] = W[(size_t)(k0 + kk) * ldw + n0 + (lane & 31)]; }
.LBB0_1177:
	s_lshl_b32 s14, s6, 1
	s_lshl_b32 s15, s7, 1
	v_or_b32_e32 v46, s14, v1
	v_or_b32_e32 v47, s15, v162
	s_add_i32 s16, s14, 4
	s_add_i32 s17, s15, 4
	s_add_i32 s18, s14, 8
	s_add_i32 s19, s15, 8
	s_add_i32 s20, s14, 12
	s_add_i32 s21, s15, 12
	s_add_i32 s22, s14, 16
	s_add_i32 s23, s15, 16
	s_add_i32 s24, s14, 20
	s_add_i32 s25, s15, 20
	s_add_i32 s26, s14, 24
	s_add_i32 s27, s15, 24
	s_add_i32 s14, s14, 28
	s_add_i32 s15, s15, 28
	v_add_u32_e32 v14, s4, v47
	v_or_b32_e32 v48, s16, v1
	v_or_b32_e32 v49, s17, v162
	v_or_b32_e32 v50, s18, v1
	v_or_b32_e32 v51, s19, v162
	v_or_b32_e32 v52, s20, v1
	v_or_b32_e32 v53, s21, v162
	v_or_b32_e32 v54, s22, v1
	v_or_b32_e32 v55, s23, v162
	v_or_b32_e32 v56, s24, v1
	v_or_b32_e32 v57, s25, v162
	v_or_b32_e32 v58, s26, v1
	v_or_b32_e32 v59, s27, v162
	v_or_b32_e32 v60, s14, v1
	v_or_b32_e32 v61, s15, v162
	v_add_u32_e32 v16, s5, v46
	v_mad_i64_i32 v[14:15], s[14:15], v14, s3, v[10:11]
	v_add_u32_e32 v20, s5, v48
	v_add_u32_e32 v18, s4, v49
	v_add_u32_e32 v24, s5, v50
	v_add_u32_e32 v22, s4, v51
	v_add_u32_e32 v28, s5, v52
	v_add_u32_e32 v26, s4, v53
	v_add_u32_e32 v32, s5, v54
	v_add_u32_e32 v30, s4, v55
	v_add_u32_e32 v36, s5, v56
	v_add_u32_e32 v34, s4, v57
	v_add_u32_e32 v40, s5, v58
	v_add_u32_e32 v38, s4, v59
	v_add_u32_e32 v44, s5, v60
	v_add_u32_e32 v42, s4, v61
	v_mad_i64_i32 v[16:17], s[14:15], v16, s3, v[10:11]
	v_mad_i64_i32 v[18:19], s[14:15], v18, s3, v[10:11]
	v_mad_i64_i32 v[20:21], s[14:15], v20, s3, v[10:11]
	v_mad_i64_i32 v[22:23], s[14:15], v22, s3, v[10:11]
	v_mad_i64_i32 v[24:25], s[14:15], v24, s3, v[10:11]
	v_mad_i64_i32 v[26:27], s[14:15], v26, s3, v[10:11]
	v_mad_i64_i32 v[28:29], s[14:15], v28, s3, v[10:11]
	v_mad_i64_i32 v[30:31], s[14:15], v30, s3, v[10:11]
	v_mad_i64_i32 v[32:33], s[14:15], v32, s3, v[10:11]
	v_mad_i64_i32 v[34:35], s[14:15], v34, s3, v[10:11]
	v_mad_i64_i32 v[36:37], s[14:15], v36, s3, v[10:11]
	v_mad_i64_i32 v[38:39], s[14:15], v38, s3, v[10:11]
	v_mad_i64_i32 v[40:41], s[14:15], v40, s3, v[10:11]
	v_mad_i64_i32 v[42:43], s[14:15], v42, s3, v[10:11]
	v_mad_i64_i32 v[44:45], s[14:15], v44, s3, v[10:11]
	global_load_dword v62, v[14:15], off
	global_load_dword v63, v[16:17], off
	global_load_dword v64, v[18:19], off
	global_load_dword v65, v[20:21], off
	global_load_dword v66, v[22:23], off
	global_load_dword v67, v[24:25], off
	global_load_dword v68, v[26:27], off
	global_load_dword v69, v[28:29], off
	global_load_dword v70, v[30:31], off
	global_load_dword v71, v[32:33], off
	global_load_dword v72, v[34:35], off
	global_load_dword v73, v[36:37], off
	global_load_dword v74, v[38:39], off
	global_load_dword v75, v[40:41], off
	global_load_dword v76, v[42:43], off
	global_load_dword v77, v[44:45], off
	s_add_i32 s7, s7, 16
	s_add_i32 s6, s6, 16
	s_add_i32 s13, s13, -16
	v_mad_u64_u32 v[14:15], s[14:15], v47, s1, v[4:5]
	s_cmp_lg_u32 s13, 0
	v_mad_u64_u32 v[16:17], s[14:15], v46, s1, v[4:5]
	v_mad_u64_u32 v[18:19], s[14:15], v49, s1, v[4:5]
	v_mad_u64_u32 v[20:21], s[14:15], v48, s1, v[4:5]
	v_mad_u64_u32 v[22:23], s[14:15], v51, s1, v[4:5]
	v_mad_u64_u32 v[24:25], s[14:15], v50, s1, v[4:5]
	v_mad_u64_u32 v[26:27], s[14:15], v53, s1, v[4:5]
	v_mad_u64_u32 v[28:29], s[14:15], v52, s1, v[4:5]
	v_mad_u64_u32 v[30:31], s[14:15], v55, s1, v[4:5]
	v_mad_u64_u32 v[32:33], s[14:15], v54, s1, v[4:5]
	v_mad_u64_u32 v[34:35], s[14:15], v57, s1, v[4:5]
	v_mad_u64_u32 v[36:37], s[14:15], v56, s1, v[4:5]
	v_mad_u64_u32 v[38:39], s[14:15], v59, s1, v[4:5]
	v_mad_u64_u32 v[40:41], s[14:15], v58, s1, v[4:5]
	v_mad_u64_u32 v[42:43], s[14:15], v61, s1, v[4:5]
	v_mad_u64_u32 v[44:45], s[14:15], v60, s1, v[4:5]
	s_lshl_b32 s14, s6, 1
	s_lshl_b32 s15, s7, 1
	v_or_b32_e32 v116, s14, v1
	v_or_b32_e32 v117, s15, v162
	s_add_i32 s16, s14, 4
	s_add_i32 s17, s15, 4
	s_add_i32 s18, s14, 8
	s_add_i32 s19, s15, 8
	s_add_i32 s20, s14, 12
	s_add_i32 s21, s15, 12
	s_add_i32 s22, s14, 16
	s_add_i32 s23, s15, 16
	s_add_i32 s24, s14, 20
	s_add_i32 s25, s15, 20
	s_add_i32 s26, s14, 24
	s_add_i32 s27, s15, 24
	s_add_i32 s14, s14, 28
	s_add_i32 s15, s15, 28
	v_add_u32_e32 v84, s4, v117
	v_or_b32_e32 v118, s16, v1
	v_or_b32_e32 v119, s17, v162
	v_or_b32_e32 v120, s18, v1
	v_or_b32_e32 v121, s19, v162
	v_or_b32_e32 v122, s20, v1
	v_or_b32_e32 v123, s21, v162
	v_or_b32_e32 v124, s22, v1
	v_or_b32_e32 v125, s23, v162
	v_or_b32_e32 v126, s24, v1
	v_or_b32_e32 v127, s25, v162
	v_or_b32_e32 v128, s26, v1
	v_or_b32_e32 v129, s27, v162
	v_or_b32_e32 v130, s14, v1
	v_or_b32_e32 v131, s15, v162
	v_add_u32_e32 v86, s5, v116
	v_mad_i64_i32 v[84:85], s[14:15], v84, s3, v[10:11]
	v_add_u32_e32 v90, s5, v118
	v_add_u32_e32 v88, s4, v119
	v_add_u32_e32 v94, s5, v120
	v_add_u32_e32 v92, s4, v121
	v_add_u32_e32 v98, s5, v122
	v_add_u32_e32 v96, s4, v123
	v_add_u32_e32 v102, s5, v124
	v_add_u32_e32 v100, s4, v125
	v_add_u32_e32 v106, s5, v126
	v_add_u32_e32 v104, s4, v127
	v_add_u32_e32 v110, s5, v128
	v_add_u32_e32 v108, s4, v129
	v_add_u32_e32 v114, s5, v130
	v_add_u32_e32 v112, s4, v131
	v_mad_i64_i32 v[86:87], s[14:15], v86, s3, v[10:11]
	v_mad_i64_i32 v[88:89], s[14:15], v88, s3, v[10:11]
	v_mad_i64_i32 v[90:91], s[14:15], v90, s3, v[10:11]
	v_mad_i64_i32 v[92:93], s[14:15], v92, s3, v[10:11]
	v_mad_i64_i32 v[94:95], s[14:15], v94, s3, v[10:11]
	v_mad_i64_i32 v[96:97], s[14:15], v96, s3, v[10:11]
	v_mad_i64_i32 v[98:99], s[14:15], v98, s3, v[10:11]
	v_mad_i64_i32 v[100:101], s[14:15], v100, s3, v[10:11]
	v_mad_i64_i32 v[102:103], s[14:15], v102, s3, v[10:11]
	v_mad_i64_i32 v[104:105], s[14:15], v104, s3, v[10:11]
	v_mad_i64_i32 v[106:107], s[14:15], v106, s3, v[10:11]
	v_mad_i64_i32 v[108:109], s[14:15], v108, s3, v[10:11]
; #define LAS __attribute__((address_space(3)))
; #define LDS_WAIT() asm volatile("s_waitcnt lgkmcnt(0)" ::: "memory")
;     ...
;     for (int item = F.gw; item < nitems; item += F.NGW) { const int kb = item / nblk, nb = item % nblk, k0 = 64 * kb, n0 = 32 * nb;
;         int dr0 = n0; if (MAP == 1) { if (n0 < DFF) dr0 = (n0 >> 7) * 256 + (n0 & 127); else { const int uo = n0 - DFF; dr0 = (uo >> 7) * 256 + 128 + (uo & 127); } }
; #pragma unroll 8
;         for (int i = 0; i < 32; ++i) { const int kk = 2 * i + (lane >> 5); scr[kk * 33 + (lane & 31)] = W[(size_t)(k0 + kk) * ldw + n0 + (lane & 31)]; }
;         LDS_WAIT(); asm volatile("" ::: "memory");
;         const int c = lane & 3;
; #pragma unroll
;         for (int j = 0; j < 2; ++j) { const int n = (lane >> 2) + 16 * j; const LAS float* sp = scr + (16 * c) * 33 + n;
;             u32x4 o;
;             if (QI8) { o.x = pk4_i8(sp[0 * 33], sp[1 * 33], sp[2 * 33], sp[3 * 33], scl); o.y = pk4_i8(sp[4 * 33], sp[5 * 33], sp[6 * 33], sp[7 * 33], scl);
;                 o.z = pk4_i8(sp[8 * 33], sp[9 * 33], sp[10 * 33], sp[11 * 33], scl); o.w = pk4_i8(sp[12 * 33], sp[13 * 33], sp[14 * 33], sp[15 * 33], scl); }
	v_mad_i64_i32 v[110:111], s[14:15], v110, s3, v[10:11]
	v_mad_i64_i32 v[112:113], s[14:15], v112, s3, v[10:11]
	v_mad_i64_i32 v[114:115], s[14:15], v114, s3, v[10:11]
	global_load_dword v132, v[84:85], off
	global_load_dword v133, v[86:87], off
	global_load_dword v134, v[88:89], off
	global_load_dword v135, v[90:91], off
	global_load_dword v136, v[92:93], off
	global_load_dword v137, v[94:95], off
	global_load_dword v138, v[96:97], off
	global_load_dword v139, v[98:99], off
	global_load_dword v140, v[100:101], off
	global_load_dword v141, v[102:103], off
	global_load_dword v142, v[104:105], off
	global_load_dword v143, v[106:107], off
	global_load_dword v144, v[108:109], off
	global_load_dword v145, v[110:111], off
	global_load_dword v146, v[112:113], off
	global_load_dword v147, v[114:115], off
	s_add_i32 s7, s7, 16
	s_add_i32 s6, s6, 16
	s_add_i32 s13, s13, -16
	v_mad_u64_u32 v[84:85], s[14:15], v117, s1, v[4:5]
	s_cmp_lg_u32 s13, 0
	v_mad_u64_u32 v[86:87], s[14:15], v116, s1, v[4:5]
	v_mad_u64_u32 v[88:89], s[14:15], v119, s1, v[4:5]
	v_mad_u64_u32 v[90:91], s[14:15], v118, s1, v[4:5]
	v_mad_u64_u32 v[92:93], s[14:15], v121, s1, v[4:5]
	v_mad_u64_u32 v[94:95], s[14:15], v120, s1, v[4:5]
	v_mad_u64_u32 v[96:97], s[14:15], v123, s1, v[4:5]
	v_mad_u64_u32 v[98:99], s[14:15], v122, s1, v[4:5]
	v_mad_u64_u32 v[100:101], s[14:15], v125, s1, v[4:5]
	v_mad_u64_u32 v[102:103], s[14:15], v124, s1, v[4:5]
	v_mad_u64_u32 v[104:105], s[14:15], v127, s1, v[4:5]
	v_mad_u64_u32 v[106:107], s[14:15], v126, s1, v[4:5]
	v_mad_u64_u32 v[108:109], s[14:15], v129, s1, v[4:5]
	v_mad_u64_u32 v[110:111], s[14:15], v128, s1, v[4:5]
	v_mad_u64_u32 v[112:113], s[14:15], v131, s1, v[4:5]
	v_mad_u64_u32 v[114:115], s[14:15], v130, s1, v[4:5]
	s_waitcnt vmcnt(31)
	ds_write_b32 v14, v62
	s_waitcnt vmcnt(30)
	ds_write_b32 v16, v63
	s_waitcnt vmcnt(29)
	ds_write_b32 v18, v64
	s_waitcnt vmcnt(28)
	ds_write_b32 v20, v65
	s_waitcnt vmcnt(27)
	ds_write_b32 v22, v66
	s_waitcnt vmcnt(26)
	ds_write_b32 v24, v67
	s_waitcnt vmcnt(25)
	ds_write_b32 v26, v68
	s_waitcnt vmcnt(24)
	ds_write_b32 v28, v69
	s_waitcnt vmcnt(23)
	ds_write_b32 v30, v70
	s_waitcnt vmcnt(22)
	ds_write_b32 v32, v71
	s_waitcnt vmcnt(21)
	ds_write_b32 v34, v72
	s_waitcnt vmcnt(20)
	ds_write_b32 v36, v73
	s_waitcnt vmcnt(19)
	ds_write_b32 v38, v74
	s_waitcnt vmcnt(18)
	ds_write_b32 v40, v75
	s_waitcnt vmcnt(17)
	ds_write_b32 v42, v76
	s_waitcnt vmcnt(16)
	ds_write_b32 v44, v77
	s_waitcnt vmcnt(15)
	ds_write_b32 v84, v132
	s_waitcnt vmcnt(14)
	ds_write_b32 v86, v133
	s_waitcnt vmcnt(13)
	ds_write_b32 v88, v134
	s_waitcnt vmcnt(12)
	ds_write_b32 v90, v135
	s_waitcnt vmcnt(11)
	ds_write_b32 v92, v136
	s_waitcnt vmcnt(10)
	ds_write_b32 v94, v137
	s_waitcnt vmcnt(9)
	ds_write_b32 v96, v138
	s_waitcnt vmcnt(8)
	ds_write_b32 v98, v139
	s_waitcnt vmcnt(7)
	ds_write_b32 v100, v140
	s_waitcnt vmcnt(6)
	ds_write_b32 v102, v141
	s_waitcnt vmcnt(5)
	ds_write_b32 v104, v142
	s_waitcnt vmcnt(4)
	ds_write_b32 v106, v143
	s_waitcnt vmcnt(3)
	ds_write_b32 v108, v144
	s_waitcnt vmcnt(2)
	ds_write_b32 v110, v145
	s_waitcnt vmcnt(1)
	ds_write_b32 v112, v146
	s_waitcnt vmcnt(0)
	ds_write_b32 v114, v147
	s_waitcnt lgkmcnt(0)
	ds_read2_b32 v[10:11], v3 offset1:16
	ds_read2_b32 v[20:21], v3 offset0:33 offset1:49
	ds_read2_b32 v[22:23], v3 offset0:66 offset1:82
	ds_read2_b32 v[24:25], v3 offset0:99 offset1:115
	ds_read2_b32 v[28:29], v3 offset0:132 offset1:148
	ds_read2_b32 v[32:33], v3 offset0:165 offset1:181
	ds_read2_b32 v[34:35], v3 offset0:198 offset1:214
	ds_read2_b32 v[36:37], v3 offset0:231 offset1:247
	s_ashr_i32 s5, s4, 31
	s_waitcnt lgkmcnt(7)
	v_mul_f32_e32 v10, 0x44fe0000, v10
	v_med3_f32 v14, v10, s10, v12
	s_waitcnt lgkmcnt(6)
	v_mul_f32_e32 v10, 0x44fe0000, v20
	v_med3_f32 v16, v10, s10, v12
	s_waitcnt lgkmcnt(5)
	v_mul_f32_e32 v10, 0x44fe0000, v22
	v_med3_f32 v26, v10, s10, v12
	s_waitcnt lgkmcnt(4)
	v_mul_f32_e32 v10, 0x44fe0000, v24
	v_med3_f32 v30, v10, s10, v12
	s_waitcnt lgkmcnt(3)
	v_mul_f32_e32 v10, 0x44fe0000, v28
	v_med3_f32 v15, v10, s10, v12
	s_waitcnt lgkmcnt(2)
	v_mul_f32_e32 v10, 0x44fe0000, v32
	v_med3_f32 v17, v10, s10, v12
	s_waitcnt lgkmcnt(1)
	v_mul_f32_e32 v10, 0x44fe0000, v34
	v_med3_f32 v27, v10, s10, v12
	s_waitcnt lgkmcnt(0)
	v_mul_f32_e32 v10, 0x44fe0000, v36
	v_pk_add_f32 v[16:17], v[16:17], s[0:1] op_sel_hi:[1,0]
	v_pk_add_f32 v[26:27], v[26:27], s[0:1] op_sel_hi:[1,0]
	v_med3_f32 v31, v10, s10, v12
	v_lshlrev_b32_e32 v10, 8, v17
	v_lshlrev_b32_e32 v17, 16, v27
	v_lshlrev_b32_e32 v20, 16, v26
	ds_read2_b32 v[26:27], v13 offset0:8 offset1:24
	v_pk_add_f32 v[30:31], v[30:31], s[0:1] op_sel_hi:[1,0]
	v_pk_add_f32 v[14:15], v[14:15], s[0:1] op_sel_hi:[1,0]
	v_lshlrev_b32_e32 v22, 24, v31
	v_and_b32_e32 v10, 0xff00, v10
	v_lshlrev_b32_e32 v24, 24, v30
	v_or_b32_sdwa v15, v22, v15 dst_sel:DWORD dst_unused:UNUSED_PAD src0_sel:DWORD src1_sel:BYTE_0
	ds_read2_b32 v[30:31], v13 offset0:41 offset1:57
	ds_read2_b32 v[38:39], v13 offset0:74 offset1:90
	ds_read2_b32 v[40:41], v13 offset0:107 offset1:123
	v_lshlrev_b32_e32 v16, 8, v16
	v_and_b32_e32 v17, 0xff0000, v17
	v_or_b32_e32 v10, v15, v10
	ds_read2_b32 v[46:47], v13 offset0:140 offset1:156
	v_and_b32_e32 v16, 0xff00, v16
	v_or_b32_sdwa v14, v24, v14 dst_sel:DWORD dst_unused:UNUSED_PAD src0_sel:DWORD src1_sel:BYTE_0
	v_or_b32_e32 v15, v10, v17
	s_waitcnt lgkmcnt(4)
; __device__ __forceinline__ unsigned pk4_f8(float a, float b, float c, float d) { int w = __builtin_amdgcn_cvt_pk_fp8_f32(a, b, 0, false); w = __builtin_amdgcn_cvt_pk_fp8_f32(c, d, w, true); return (unsigned)w; }
; #define LDS_WAIT() asm volatile("s_waitcnt lgkmcnt(0)" ::: "memory")
;     ...
;             if (QI8) { o.x = pk4_i8(sp[0 * 33], sp[1 * 33], sp[2 * 33], sp[3 * 33], scl); o.y = pk4_i8(sp[4 * 33], sp[5 * 33], sp[6 * 33], sp[7 * 33], scl);
;                 o.z = pk4_i8(sp[8 * 33], sp[9 * 33], sp[10 * 33], sp[11 * 33], scl); o.w = pk4_i8(sp[12 * 33], sp[13 * 33], sp[14 * 33], sp[15 * 33], scl); }
;             else {
;             o.x = pk4_f8(sp[0 * 33] * scl, sp[1 * 33] * scl, sp[2 * 33] * scl, sp[3 * 33] * scl); o.y = pk4_f8(sp[4 * 33] * scl, sp[5 * 33] * scl, sp[6 * 33] * scl, sp[7 * 33] * scl);
;             o.z = pk4_f8(sp[8 * 33] * scl, sp[9 * 33] * scl, sp[10 * 33] * scl, sp[11 * 33] * scl); o.w = pk4_f8(sp[12 * 33] * scl, sp[13 * 33] * scl, sp[14 * 33] * scl, sp[15 * 33] * scl); }
;             *(u32x4*)(WT + (size_t)(dr0 + n) * K + k0 + 16 * c) = o; }
;         LDS_WAIT(); asm volatile("" ::: "memory"); }
	v_mul_f32_e32 v10, 0x44fe0000, v26
	v_or_b32_e32 v14, v14, v16
	v_med3_f32 v16, v10, s10, v12
	s_waitcnt lgkmcnt(3)
	v_mul_f32_e32 v10, 0x44fe0000, v30
	v_med3_f32 v42, v10, s10, v12
	s_waitcnt lgkmcnt(2)
	v_mul_f32_e32 v10, 0x44fe0000, v38
	ds_read2_b32 v[50:51], v13 offset0:173 offset1:189
	ds_read2_b32 v[52:53], v13 offset0:206 offset1:222
	ds_read2_b32 v[54:55], v13 offset0:239 offset1:255
	v_med3_f32 v44, v10, s10, v12
	s_waitcnt lgkmcnt(4)
	v_mul_f32_e32 v10, 0x44fe0000, v40
	v_med3_f32 v48, v10, s10, v12
	s_waitcnt lgkmcnt(3)
	v_mul_f32_e32 v10, 0x44fe0000, v46
	v_med3_f32 v17, v10, s10, v12
	s_waitcnt lgkmcnt(2)
	v_mul_f32_e32 v10, 0x44fe0000, v50
	v_med3_f32 v43, v10, s10, v12
	s_waitcnt lgkmcnt(1)
	v_mul_f32_e32 v10, 0x44fe0000, v52
	v_med3_f32 v45, v10, s10, v12
	s_waitcnt lgkmcnt(0)
	v_mul_f32_e32 v10, 0x44fe0000, v54
	v_med3_f32 v49, v10, s10, v12
	v_and_b32_e32 v20, 0xff0000, v20
	v_pk_add_f32 v[42:43], v[42:43], s[0:1] op_sel_hi:[1,0]
	v_pk_add_f32 v[48:49], v[48:49], s[0:1] op_sel_hi:[1,0]
	v_or_b32_e32 v14, v14, v20
	v_pk_add_f32 v[16:17], v[16:17], s[0:1] op_sel_hi:[1,0]
	v_pk_add_f32 v[44:45], v[44:45], s[0:1] op_sel_hi:[1,0]
	v_lshlrev_b32_e32 v10, 8, v43
	v_lshlrev_b32_e32 v20, 8, v42
	v_lshlrev_b32_e32 v26, 24, v49
	v_lshlrev_b32_e32 v28, 24, v48
	v_add_u32_e32 v42, s12, v163
	v_and_b32_e32 v10, 0xff00, v10
	v_and_b32_e32 v20, 0xff00, v20
	v_lshlrev_b32_e32 v22, 16, v45
	v_lshlrev_b32_e32 v24, 16, v44
	v_or_b32_sdwa v17, v26, v17 dst_sel:DWORD dst_unused:UNUSED_PAD src0_sel:DWORD src1_sel:BYTE_0
	v_or_b32_sdwa v16, v28, v16 dst_sel:DWORD dst_unused:UNUSED_PAD src0_sel:DWORD src1_sel:BYTE_0
	v_ashrrev_i32_e32 v43, 31, v42
	v_lshl_add_u64 v[18:19], v[8:9], 0, s[4:5]
	v_and_b32_e32 v22, 0xff0000, v22
	v_and_b32_e32 v24, 0xff0000, v24
	v_or_b32_e32 v10, v17, v10
	v_or_b32_e32 v16, v16, v20
	v_lshlrev_b64 v[42:43], 12, v[42:43]
	v_or_b32_e32 v17, v10, v22
	v_or_b32_e32 v16, v16, v24
	v_lshl_add_u64 v[42:43], v[18:19], 0, v[42:43]
	v_mul_f32_e32 v10, 0x44fe0000, v11
	v_mul_f32_e32 v11, 0x44fe0000, v21
	global_store_dwordx4 v[42:43], v[14:17], off
	v_mul_f32_e32 v21, 0x44fe0000, v37
	v_med3_f32 v21, v21, s10, v12
	v_med3_f32 v14, v11, s10, v12
	v_mul_f32_e32 v11, 0x44fe0000, v23
	v_med3_f32 v16, v11, s10, v12
	v_mul_f32_e32 v11, 0x44fe0000, v25
	v_mul_f32_e32 v15, 0x44fe0000, v33
	v_med3_f32 v20, v11, s10, v12
	v_mul_f32_e32 v11, 0x44fe0000, v29
	v_med3_f32 v15, v15, s10, v12
	v_mul_f32_e32 v17, 0x44fe0000, v35
	v_med3_f32 v10, v10, s10, v12
	v_med3_f32 v11, v11, s10, v12
	v_med3_f32 v17, v17, s10, v12
	v_pk_add_f32 v[14:15], v[14:15], s[0:1] op_sel_hi:[1,0]
	v_pk_add_f32 v[20:21], v[20:21], s[0:1] op_sel_hi:[1,0]
	v_pk_add_f32 v[10:11], v[10:11], s[0:1] op_sel_hi:[1,0]
	v_pk_add_f32 v[16:17], v[16:17], s[0:1] op_sel_hi:[1,0]
	v_lshlrev_b32_e32 v15, 8, v15
	v_lshlrev_b32_e32 v21, 24, v21
	v_lshlrev_b32_e32 v14, 8, v14
	v_and_b32_e32 v15, 0xff00, v15
	v_lshlrev_b32_e32 v17, 16, v17
	v_lshlrev_b32_e32 v20, 24, v20
	v_or_b32_sdwa v11, v21, v11 dst_sel:DWORD dst_unused:UNUSED_PAD src0_sel:DWORD src1_sel:BYTE_0
	v_and_b32_e32 v14, 0xff00, v14
	v_lshlrev_b32_e32 v16, 16, v16
	v_and_b32_e32 v17, 0xff0000, v17
	v_or_b32_sdwa v10, v20, v10 dst_sel:DWORD dst_unused:UNUSED_PAD src0_sel:DWORD src1_sel:BYTE_0
	v_or_b32_e32 v11, v11, v15
	v_and_b32_e32 v16, 0xff0000, v16
	v_or_b32_e32 v10, v10, v14
	v_or_b32_e32 v15, v11, v17
	v_mul_f32_e32 v11, 0x44fe0000, v31
	v_or_b32_e32 v14, v10, v16
	v_med3_f32 v16, v11, s10, v12
	v_mul_f32_e32 v11, 0x44fe0000, v39
	v_med3_f32 v20, v11, s10, v12
	v_mul_f32_e32 v11, 0x44fe0000, v41
	v_mul_f32_e32 v17, 0x44fe0000, v51
	v_mul_f32_e32 v23, 0x44fe0000, v55
	v_mul_f32_e32 v10, 0x44fe0000, v27
	v_med3_f32 v22, v11, s10, v12
	v_mul_f32_e32 v11, 0x44fe0000, v47
	v_med3_f32 v17, v17, s10, v12
	v_mul_f32_e32 v21, 0x44fe0000, v53
	v_med3_f32 v23, v23, s10, v12
	v_med3_f32 v10, v10, s10, v12
	v_med3_f32 v11, v11, s10, v12
	v_med3_f32 v21, v21, s10, v12
	v_pk_add_f32 v[16:17], v[16:17], s[0:1] op_sel_hi:[1,0]
	v_pk_add_f32 v[22:23], v[22:23], s[0:1] op_sel_hi:[1,0]
	v_pk_add_f32 v[10:11], v[10:11], s[0:1] op_sel_hi:[1,0]
	v_pk_add_f32 v[20:21], v[20:21], s[0:1] op_sel_hi:[1,0]
	v_lshlrev_b32_e32 v16, 8, v16
	v_lshlrev_b32_e32 v22, 24, v22
	v_lshlrev_b32_e32 v17, 8, v17
	v_and_b32_e32 v16, 0xff00, v16
	v_lshlrev_b32_e32 v20, 16, v20
	v_lshlrev_b32_e32 v23, 24, v23
	v_or_b32_sdwa v10, v22, v10 dst_sel:DWORD dst_unused:UNUSED_PAD src0_sel:DWORD src1_sel:BYTE_0
	v_and_b32_e32 v17, 0xff00, v17
	v_lshlrev_b32_e32 v21, 16, v21
	v_and_b32_e32 v20, 0xff0000, v20
	v_or_b32_sdwa v11, v23, v11 dst_sel:DWORD dst_unused:UNUSED_PAD src0_sel:DWORD src1_sel:BYTE_0
	v_or_b32_e32 v10, v10, v16
	v_and_b32_e32 v21, 0xff0000, v21
	v_or_b32_e32 v11, v11, v17
	v_or_b32_e32 v16, v10, v20
	v_add_u32_e32 v10, s12, v5
	v_or_b32_e32 v17, v11, v21
	v_ashrrev_i32_e32 v11, 31, v10
	v_lshlrev_b64 v[10:11], 12, v[10:11]
	v_lshl_add_u64 v[10:11], v[18:19], 0, v[10:11]
	global_store_dwordx4 v[10:11], v[14:17], off
	s_waitcnt lgkmcnt(0)
	s_add_i32 s11, s11, s92
	s_cmp_lt_i32 s11, 0xac00
	s_cbranch_scc1 .LBB0_1172

;     ...
;     for (int item = F.gw; item < nitems; item += F.NGW) { const int kb = item / nblk, nb = item % nblk, k0 = 64 * kb, n0 = 32 * nb;
;         int dr0 = n0; if (MAP == 1) { if (n0 < DFF) dr0 = (n0 >> 7) * 256 + (n0 & 127); else { const int uo = n0 - DFF; dr0 = (uo >> 7) * 256 + 128 + (uo & 127); } }
; #pragma unroll 8
;         for (int i = 0; i < 32; ++i) { const int kk = 2 * i + (lane >> 5); scr[kk * 33 + (lane & 31)] = W[(size_t)(k0 + kk) * ldw + n0 + (lane & 31)]; }
.LBB0_1182:
	s_lshl_b32 s12, s11, 1
	s_lshl_b32 s13, s10, 1
	v_or_b32_e32 v11, s12, v1
	v_or_b32_e32 v44, s13, v162
	s_add_i32 s14, s12, 4
	s_add_i32 s15, s13, 4
	s_add_i32 s16, s12, 8
	s_add_i32 s17, s13, 8
	s_add_i32 s18, s12, 12
	s_add_i32 s19, s13, 12
	s_add_i32 s20, s12, 16
	s_add_i32 s21, s13, 16
	s_add_i32 s22, s12, 20
	s_add_i32 s23, s13, 20
	s_add_i32 s24, s12, 24
	s_add_i32 s25, s13, 24
	s_add_i32 s12, s12, 28
	s_add_i32 s13, s13, 28
	v_add_u32_e32 v14, s4, v44
	v_or_b32_e32 v45, s14, v1
	v_or_b32_e32 v46, s15, v162
	v_or_b32_e32 v47, s16, v1
	v_or_b32_e32 v48, s17, v162
	v_or_b32_e32 v49, s18, v1
	v_or_b32_e32 v50, s19, v162
	v_or_b32_e32 v51, s20, v1
	v_or_b32_e32 v52, s21, v162
	v_or_b32_e32 v53, s22, v1
	v_or_b32_e32 v54, s23, v162
	v_or_b32_e32 v55, s24, v1
	v_or_b32_e32 v56, s25, v162
	v_or_b32_e32 v57, s12, v1
	v_or_b32_e32 v58, s13, v162
	v_add_u32_e32 v12, s1, v11
	v_ashrrev_i32_e32 v15, 31, v14
	v_add_u32_e32 v16, s1, v45
	v_add_u32_e32 v18, s4, v46
	v_add_u32_e32 v20, s1, v47
	v_add_u32_e32 v22, s4, v48
	v_add_u32_e32 v24, s1, v49
	v_add_u32_e32 v26, s4, v50
	v_add_u32_e32 v28, s1, v51
	v_add_u32_e32 v30, s4, v52
	v_add_u32_e32 v32, s1, v53
	v_add_u32_e32 v34, s4, v54
	v_add_u32_e32 v36, s1, v55
	v_add_u32_e32 v38, s4, v56
	v_add_u32_e32 v40, s1, v57
	v_add_u32_e32 v42, s4, v58
	v_ashrrev_i32_e32 v13, 31, v12
	v_lshlrev_b64 v[14:15], 14, v[14:15]
	v_ashrrev_i32_e32 v19, 31, v18
	v_ashrrev_i32_e32 v17, 31, v16
	v_ashrrev_i32_e32 v23, 31, v22
	v_ashrrev_i32_e32 v21, 31, v20
	v_ashrrev_i32_e32 v27, 31, v26
	v_ashrrev_i32_e32 v25, 31, v24
	v_ashrrev_i32_e32 v31, 31, v30
	v_ashrrev_i32_e32 v29, 31, v28
	v_ashrrev_i32_e32 v35, 31, v34
	v_ashrrev_i32_e32 v33, 31, v32
	v_ashrrev_i32_e32 v39, 31, v38
	v_ashrrev_i32_e32 v37, 31, v36
	v_ashrrev_i32_e32 v43, 31, v42
	v_ashrrev_i32_e32 v41, 31, v40
	v_lshlrev_b64 v[12:13], 14, v[12:13]
	v_lshl_add_u64 v[14:15], v[8:9], 0, v[14:15]
	v_lshlrev_b64 v[16:17], 14, v[16:17]
	v_lshlrev_b64 v[18:19], 14, v[18:19]
	v_lshlrev_b64 v[20:21], 14, v[20:21]
	v_lshlrev_b64 v[22:23], 14, v[22:23]
	v_lshlrev_b64 v[24:25], 14, v[24:25]
	v_lshlrev_b64 v[26:27], 14, v[26:27]
	v_lshlrev_b64 v[28:29], 14, v[28:29]
	v_lshlrev_b64 v[30:31], 14, v[30:31]
	v_lshlrev_b64 v[32:33], 14, v[32:33]
	v_lshlrev_b64 v[34:35], 14, v[34:35]
	v_lshlrev_b64 v[36:37], 14, v[36:37]
	v_lshlrev_b64 v[38:39], 14, v[38:39]
	v_lshlrev_b64 v[40:41], 14, v[40:41]
	v_lshlrev_b64 v[42:43], 14, v[42:43]
	v_lshl_add_u64 v[12:13], v[8:9], 0, v[12:13]
	v_lshl_add_u64 v[18:19], v[8:9], 0, v[18:19]
	v_lshl_add_u64 v[16:17], v[8:9], 0, v[16:17]
	v_lshl_add_u64 v[22:23], v[8:9], 0, v[22:23]
	v_lshl_add_u64 v[20:21], v[8:9], 0, v[20:21]
	v_lshl_add_u64 v[26:27], v[8:9], 0, v[26:27]
	v_lshl_add_u64 v[24:25], v[8:9], 0, v[24:25]
	v_lshl_add_u64 v[30:31], v[8:9], 0, v[30:31]
	v_lshl_add_u64 v[28:29], v[8:9], 0, v[28:29]
	v_lshl_add_u64 v[34:35], v[8:9], 0, v[34:35]
	v_lshl_add_u64 v[32:33], v[8:9], 0, v[32:33]
	v_lshl_add_u64 v[38:39], v[8:9], 0, v[38:39]
	v_lshl_add_u64 v[36:37], v[8:9], 0, v[36:37]
	v_lshl_add_u64 v[42:43], v[8:9], 0, v[42:43]
	v_lshl_add_u64 v[40:41], v[8:9], 0, v[40:41]
	global_load_dword v59, v[14:15], off
	global_load_dword v60, v[12:13], off
	global_load_dword v61, v[18:19], off
	global_load_dword v62, v[16:17], off
	global_load_dword v63, v[22:23], off
	global_load_dword v64, v[20:21], off
	global_load_dword v65, v[26:27], off
	global_load_dword v66, v[24:25], off
	global_load_dword v67, v[30:31], off
	global_load_dword v68, v[28:29], off
	global_load_dword v69, v[34:35], off
	global_load_dword v70, v[32:33], off
	global_load_dword v71, v[38:39], off
	global_load_dword v72, v[36:37], off
	global_load_dword v73, v[42:43], off
	global_load_dword v74, v[40:41], off
	s_add_i32 s10, s10, 16
	s_add_i32 s11, s11, 16
	s_add_i32 s5, s5, -16
	v_mad_u64_u32 v[12:13], s[12:13], v44, s3, v[4:5]
	s_cmp_lg_u32 s5, 0
	v_mad_u64_u32 v[14:15], s[12:13], v11, s3, v[4:5]
	v_mad_u64_u32 v[16:17], s[12:13], v46, s3, v[4:5]
	v_mad_u64_u32 v[18:19], s[12:13], v45, s3, v[4:5]
	v_mad_u64_u32 v[20:21], s[12:13], v48, s3, v[4:5]
	v_mad_u64_u32 v[22:23], s[12:13], v47, s3, v[4:5]
	v_mad_u64_u32 v[24:25], s[12:13], v50, s3, v[4:5]
	v_mad_u64_u32 v[26:27], s[12:13], v49, s3, v[4:5]
	v_mad_u64_u32 v[28:29], s[12:13], v52, s3, v[4:5]
	v_mad_u64_u32 v[30:31], s[12:13], v51, s3, v[4:5]
	v_mad_u64_u32 v[32:33], s[12:13], v54, s3, v[4:5]
	v_mad_u64_u32 v[34:35], s[12:13], v53, s3, v[4:5]
	v_mad_u64_u32 v[36:37], s[12:13], v56, s3, v[4:5]
	v_mad_u64_u32 v[38:39], s[12:13], v55, s3, v[4:5]
	v_mad_u64_u32 v[40:41], s[12:13], v58, s3, v[4:5]
	v_mad_u64_u32 v[42:43], s[12:13], v57, s3, v[4:5]
	s_lshl_b32 s12, s11, 1
	s_lshl_b32 s13, s10, 1
	v_or_b32_e32 v85, s12, v1
	v_or_b32_e32 v118, s13, v162
	s_add_i32 s14, s12, 4
	s_add_i32 s15, s13, 4
	s_add_i32 s16, s12, 8
	s_add_i32 s17, s13, 8
	s_add_i32 s18, s12, 12
	s_add_i32 s19, s13, 12
	s_add_i32 s20, s12, 16
	s_add_i32 s21, s13, 16
	s_add_i32 s22, s12, 20
	s_add_i32 s23, s13, 20
	s_add_i32 s24, s12, 24
	s_add_i32 s25, s13, 24
	s_add_i32 s12, s12, 28
	s_add_i32 s13, s13, 28
	v_add_u32_e32 v88, s4, v118
	v_or_b32_e32 v119, s14, v1
	v_or_b32_e32 v120, s15, v162
	v_or_b32_e32 v121, s16, v1
	v_or_b32_e32 v122, s17, v162
	v_or_b32_e32 v123, s18, v1
	v_or_b32_e32 v124, s19, v162
	v_or_b32_e32 v125, s20, v1
	v_or_b32_e32 v126, s21, v162
	v_or_b32_e32 v127, s22, v1
	v_or_b32_e32 v128, s23, v162
	v_or_b32_e32 v129, s24, v1
	v_or_b32_e32 v130, s25, v162
	v_or_b32_e32 v131, s12, v1
	v_or_b32_e32 v132, s13, v162
	v_add_u32_e32 v86, s1, v85
	v_ashrrev_i32_e32 v89, 31, v88
	v_add_u32_e32 v90, s1, v119
	v_add_u32_e32 v92, s4, v120
; #define LDS_WAIT() asm volatile("s_waitcnt lgkmcnt(0)" ::: "memory")
;     ...
;     for (int item = F.gw; item < nitems; item += F.NGW) { const int kb = item / nblk, nb = item % nblk, k0 = 64 * kb, n0 = 32 * nb;
;         int dr0 = n0; if (MAP == 1) { if (n0 < DFF) dr0 = (n0 >> 7) * 256 + (n0 & 127); else { const int uo = n0 - DFF; dr0 = (uo >> 7) * 256 + 128 + (uo & 127); } }
; #pragma unroll 8
;         for (int i = 0; i < 32; ++i) { const int kk = 2 * i + (lane >> 5); scr[kk * 33 + (lane & 31)] = W[(size_t)(k0 + kk) * ldw + n0 + (lane & 31)]; }
;         LDS_WAIT(); asm volatile("" ::: "memory");
	v_add_u32_e32 v94, s1, v121
	v_add_u32_e32 v96, s4, v122
	v_add_u32_e32 v98, s1, v123
	v_add_u32_e32 v100, s4, v124
	v_add_u32_e32 v102, s1, v125
	v_add_u32_e32 v104, s4, v126
	v_add_u32_e32 v106, s1, v127
	v_add_u32_e32 v108, s4, v128
	v_add_u32_e32 v110, s1, v129
	v_add_u32_e32 v112, s4, v130
	v_add_u32_e32 v114, s1, v131
	v_add_u32_e32 v116, s4, v132
	v_ashrrev_i32_e32 v87, 31, v86
	v_lshlrev_b64 v[88:89], 14, v[88:89]
	v_ashrrev_i32_e32 v93, 31, v92
	v_ashrrev_i32_e32 v91, 31, v90
	v_ashrrev_i32_e32 v97, 31, v96
	v_ashrrev_i32_e32 v95, 31, v94
	v_ashrrev_i32_e32 v101, 31, v100
	v_ashrrev_i32_e32 v99, 31, v98
	v_ashrrev_i32_e32 v105, 31, v104
	v_ashrrev_i32_e32 v103, 31, v102
	v_ashrrev_i32_e32 v109, 31, v108
	v_ashrrev_i32_e32 v107, 31, v106
	v_ashrrev_i32_e32 v113, 31, v112
	v_ashrrev_i32_e32 v111, 31, v110
	v_ashrrev_i32_e32 v117, 31, v116
	v_ashrrev_i32_e32 v115, 31, v114
	v_lshlrev_b64 v[86:87], 14, v[86:87]
	v_lshl_add_u64 v[88:89], v[8:9], 0, v[88:89]
	v_lshlrev_b64 v[90:91], 14, v[90:91]
	v_lshlrev_b64 v[92:93], 14, v[92:93]
	v_lshlrev_b64 v[94:95], 14, v[94:95]
	v_lshlrev_b64 v[96:97], 14, v[96:97]
	v_lshlrev_b64 v[98:99], 14, v[98:99]
	v_lshlrev_b64 v[100:101], 14, v[100:101]
	v_lshlrev_b64 v[102:103], 14, v[102:103]
	v_lshlrev_b64 v[104:105], 14, v[104:105]
	v_lshlrev_b64 v[106:107], 14, v[106:107]
	v_lshlrev_b64 v[108:109], 14, v[108:109]
	v_lshlrev_b64 v[110:111], 14, v[110:111]
	v_lshlrev_b64 v[112:113], 14, v[112:113]
	v_lshlrev_b64 v[114:115], 14, v[114:115]
	v_lshlrev_b64 v[116:117], 14, v[116:117]
	v_lshl_add_u64 v[86:87], v[8:9], 0, v[86:87]
	v_lshl_add_u64 v[92:93], v[8:9], 0, v[92:93]
	v_lshl_add_u64 v[90:91], v[8:9], 0, v[90:91]
	v_lshl_add_u64 v[96:97], v[8:9], 0, v[96:97]
	v_lshl_add_u64 v[94:95], v[8:9], 0, v[94:95]
	v_lshl_add_u64 v[100:101], v[8:9], 0, v[100:101]
	v_lshl_add_u64 v[98:99], v[8:9], 0, v[98:99]
	v_lshl_add_u64 v[104:105], v[8:9], 0, v[104:105]
	v_lshl_add_u64 v[102:103], v[8:9], 0, v[102:103]
	v_lshl_add_u64 v[108:109], v[8:9], 0, v[108:109]
	v_lshl_add_u64 v[106:107], v[8:9], 0, v[106:107]
	v_lshl_add_u64 v[112:113], v[8:9], 0, v[112:113]
	v_lshl_add_u64 v[110:111], v[8:9], 0, v[110:111]
	v_lshl_add_u64 v[116:117], v[8:9], 0, v[116:117]
	v_lshl_add_u64 v[114:115], v[8:9], 0, v[114:115]
	global_load_dword v133, v[88:89], off
	global_load_dword v134, v[86:87], off
	global_load_dword v135, v[92:93], off
	global_load_dword v136, v[90:91], off
	global_load_dword v137, v[96:97], off
	global_load_dword v138, v[94:95], off
	global_load_dword v139, v[100:101], off
	global_load_dword v140, v[98:99], off
	global_load_dword v141, v[104:105], off
	global_load_dword v142, v[102:103], off
	global_load_dword v143, v[108:109], off
	global_load_dword v144, v[106:107], off
	global_load_dword v145, v[112:113], off
	global_load_dword v146, v[110:111], off
	global_load_dword v147, v[116:117], off
	global_load_dword v148, v[114:115], off
	s_add_i32 s10, s10, 16
	s_add_i32 s11, s11, 16
	s_add_i32 s5, s5, -16
	v_mad_u64_u32 v[86:87], s[12:13], v118, s3, v[4:5]
	s_cmp_lg_u32 s5, 0
	v_mad_u64_u32 v[88:89], s[12:13], v85, s3, v[4:5]
	v_mad_u64_u32 v[90:91], s[12:13], v120, s3, v[4:5]
	v_mad_u64_u32 v[92:93], s[12:13], v119, s3, v[4:5]
	v_mad_u64_u32 v[94:95], s[12:13], v122, s3, v[4:5]
	v_mad_u64_u32 v[96:97], s[12:13], v121, s3, v[4:5]
	v_mad_u64_u32 v[98:99], s[12:13], v124, s3, v[4:5]
	v_mad_u64_u32 v[100:101], s[12:13], v123, s3, v[4:5]
	v_mad_u64_u32 v[102:103], s[12:13], v126, s3, v[4:5]
	v_mad_u64_u32 v[104:105], s[12:13], v125, s3, v[4:5]
	v_mad_u64_u32 v[106:107], s[12:13], v128, s3, v[4:5]
	v_mad_u64_u32 v[108:109], s[12:13], v127, s3, v[4:5]
	v_mad_u64_u32 v[110:111], s[12:13], v130, s3, v[4:5]
	v_mad_u64_u32 v[112:113], s[12:13], v129, s3, v[4:5]
	v_mad_u64_u32 v[114:115], s[12:13], v132, s3, v[4:5]
	v_mad_u64_u32 v[116:117], s[12:13], v131, s3, v[4:5]
	s_waitcnt vmcnt(31)
	ds_write_b32 v12, v59
	s_waitcnt vmcnt(30)
	ds_write_b32 v14, v60
	s_waitcnt vmcnt(29)
	ds_write_b32 v16, v61
	s_waitcnt vmcnt(28)
	ds_write_b32 v18, v62
	s_waitcnt vmcnt(27)
	ds_write_b32 v20, v63
	s_waitcnt vmcnt(26)
	ds_write_b32 v22, v64
	s_waitcnt vmcnt(25)
	ds_write_b32 v24, v65
	s_waitcnt vmcnt(24)
	ds_write_b32 v26, v66
	s_waitcnt vmcnt(23)
	ds_write_b32 v28, v67
	s_waitcnt vmcnt(22)
	ds_write_b32 v30, v68
	s_waitcnt vmcnt(21)
	ds_write_b32 v32, v69
	s_waitcnt vmcnt(20)
	ds_write_b32 v34, v70
	s_waitcnt vmcnt(19)
	ds_write_b32 v36, v71
	s_waitcnt vmcnt(18)
; #define LAS __attribute__((address_space(3)))
; __device__ __forceinline__ unsigned pk4_f8(float a, float b, float c, float d) { int w = __builtin_amdgcn_cvt_pk_fp8_f32(a, b, 0, false); w = __builtin_amdgcn_cvt_pk_fp8_f32(c, d, w, true); return (unsigned)w; }
; #define LDS_WAIT() asm volatile("s_waitcnt lgkmcnt(0)" ::: "memory")
;     ...
;         for (int i = 0; i < 32; ++i) { const int kk = 2 * i + (lane >> 5); scr[kk * 33 + (lane & 31)] = W[(size_t)(k0 + kk) * ldw + n0 + (lane & 31)]; }
;         LDS_WAIT(); asm volatile("" ::: "memory");
;         const int c = lane & 3;
; #pragma unroll
;         for (int j = 0; j < 2; ++j) { const int n = (lane >> 2) + 16 * j; const LAS float* sp = scr + (16 * c) * 33 + n;
;             u32x4 o;
;             if (QI8) { o.x = pk4_i8(sp[0 * 33], sp[1 * 33], sp[2 * 33], sp[3 * 33], scl); o.y = pk4_i8(sp[4 * 33], sp[5 * 33], sp[6 * 33], sp[7 * 33], scl);
;                 o.z = pk4_i8(sp[8 * 33], sp[9 * 33], sp[10 * 33], sp[11 * 33], scl); o.w = pk4_i8(sp[12 * 33], sp[13 * 33], sp[14 * 33], sp[15 * 33], scl); }
;             else {
;             o.x = pk4_f8(sp[0 * 33] * scl, sp[1 * 33] * scl, sp[2 * 33] * scl, sp[3 * 33] * scl); o.y = pk4_f8(sp[4 * 33] * scl, sp[5 * 33] * scl, sp[6 * 33] * scl, sp[7 * 33] * scl);
;             o.z = pk4_f8(sp[8 * 33] * scl, sp[9 * 33] * scl, sp[10 * 33] * scl, sp[11 * 33] * scl); o.w = pk4_f8(sp[12 * 33] * scl, sp[13 * 33] * scl, sp[14 * 33] * scl, sp[15 * 33] * scl); }
;             *(u32x4*)(WT + (size_t)(dr0 + n) * K + k0 + 16 * c) = o; }
;         LDS_WAIT(); asm volatile("" ::: "memory"); }
	ds_write_b32 v38, v72
	s_waitcnt vmcnt(17)
	ds_write_b32 v40, v73
	s_waitcnt vmcnt(16)
	ds_write_b32 v42, v74
	s_waitcnt vmcnt(15)
	ds_write_b32 v86, v133
	s_waitcnt vmcnt(14)
	ds_write_b32 v88, v134
	s_waitcnt vmcnt(13)
	ds_write_b32 v90, v135
	s_waitcnt vmcnt(12)
	ds_write_b32 v92, v136
	s_waitcnt vmcnt(11)
	ds_write_b32 v94, v137
	s_waitcnt vmcnt(10)
	ds_write_b32 v96, v138
	s_waitcnt vmcnt(9)
	ds_write_b32 v98, v139
	s_waitcnt vmcnt(8)
	ds_write_b32 v100, v140
	s_waitcnt vmcnt(7)
	ds_write_b32 v102, v141
	s_waitcnt vmcnt(6)
	ds_write_b32 v104, v142
	s_waitcnt vmcnt(5)
	ds_write_b32 v106, v143
	s_waitcnt vmcnt(4)
	ds_write_b32 v108, v144
	s_waitcnt vmcnt(3)
	ds_write_b32 v110, v145
	s_waitcnt vmcnt(2)
	ds_write_b32 v112, v146
	s_waitcnt vmcnt(1)
	ds_write_b32 v114, v147
	s_waitcnt vmcnt(0)
	ds_write_b32 v116, v148
	s_waitcnt lgkmcnt(0)
	ds_read2_b32 v[8:9], v5 offset1:16
	ds_read2_b32 v[16:17], v5 offset0:33 offset1:49
	ds_read2_b32 v[18:19], v5 offset0:66 offset1:82
	ds_read2_b32 v[22:23], v5 offset0:99 offset1:115
	v_mov_b32_e32 v12, 0
	s_waitcnt lgkmcnt(3)
	v_mul_f32_e32 v8, 0x43000000, v8
	s_waitcnt lgkmcnt(2)
	v_mul_f32_e32 v11, 0x43000000, v16
	v_cvt_pk_fp8_f32 v12, v8, v11
	ds_read2_b32 v[24:25], v5 offset0:132 offset1:148
	ds_read2_b32 v[26:27], v5 offset0:165 offset1:181
	ds_read2_b32 v[28:29], v5 offset0:198 offset1:214
	s_waitcnt lgkmcnt(4)
	v_mul_f32_e32 v13, 0x43000000, v18
	s_waitcnt lgkmcnt(3)
	v_mul_f32_e32 v8, 0x43000000, v22
	v_cvt_pk_fp8_f32 v12, v13, v8 op_sel:[0,0,1]
	s_waitcnt lgkmcnt(2)
	v_mul_f32_e32 v8, 0x43000000, v24
	s_waitcnt lgkmcnt(1)
	v_mul_f32_e32 v11, 0x43000000, v26
	v_mov_b32_e32 v13, 0
	ds_read2_b32 v[30:31], v5 offset0:231 offset1:247
	v_cvt_pk_fp8_f32 v13, v8, v11
	v_add_u32_e32 v8, 0x400, v5
	ds_read2_b32 v[32:33], v8 offset0:8 offset1:24
	ds_read2_b32 v[34:35], v8 offset0:41 offset1:57
	ds_read2_b32 v[36:37], v8 offset0:74 offset1:90
	ds_read2_b32 v[38:39], v8 offset0:107 offset1:123
	ds_read2_b32 v[40:41], v8 offset0:140 offset1:156
	ds_read2_b32 v[42:43], v8 offset0:173 offset1:189
	s_waitcnt lgkmcnt(7)
	v_mul_f32_e32 v14, 0x43000000, v28
	s_waitcnt lgkmcnt(6)
	v_mul_f32_e32 v11, 0x43000000, v30
	v_cvt_pk_fp8_f32 v13, v14, v11 op_sel:[0,0,1]
	s_waitcnt lgkmcnt(5)
	v_mul_f32_e32 v11, 0x43000000, v32
	s_waitcnt lgkmcnt(4)
	v_mul_f32_e32 v15, 0x43000000, v34
	v_mov_b32_e32 v14, 0
	ds_read2_b32 v[44:45], v8 offset0:206 offset1:222
	ds_read2_b32 v[46:47], v8 offset0:239 offset1:255
	v_cvt_pk_fp8_f32 v14, v11, v15
	s_waitcnt lgkmcnt(3)
	v_mul_f32_e32 v11, 0x43000000, v40
	s_waitcnt lgkmcnt(2)
	v_mul_f32_e32 v22, 0x43000000, v42
	v_mov_b32_e32 v15, 0
	v_cvt_pk_fp8_f32 v15, v11, v22
	v_mul_f32_e32 v16, 0x43000000, v36
	v_mul_f32_e32 v18, 0x43000000, v38
	s_waitcnt lgkmcnt(1)
	v_mul_f32_e32 v8, 0x43000000, v44
	s_waitcnt lgkmcnt(0)
	v_mul_f32_e32 v11, 0x43000000, v46
	v_cvt_pk_fp8_f32 v14, v16, v18 op_sel:[0,0,1]
	v_cvt_pk_fp8_f32 v15, v8, v11 op_sel:[0,0,1]
	v_or_b32_e32 v8, s0, v163
	s_ashr_i32 s5, s4, 31
	v_mul_lo_u32 v48, v8, s6
	v_lshl_add_u64 v[20:21], v[2:3], 0, s[4:5]
	v_ashrrev_i32_e32 v49, 31, v48
	v_lshl_add_u64 v[48:49], v[20:21], 0, v[48:49]
	global_store_dwordx4 v[48:49], v[12:15], off
	v_mul_f32_e32 v8, 0x43000000, v9
	v_mul_f32_e32 v9, 0x43000000, v17
	v_mov_b32_e32 v12, 0
	v_cvt_pk_fp8_f32 v12, v8, v9
	v_mul_f32_e32 v8, 0x43000000, v25
	v_mul_f32_e32 v9, 0x43000000, v27
	v_mov_b32_e32 v13, 0
	v_cvt_pk_fp8_f32 v13, v8, v9
	v_mul_f32_e32 v11, 0x43000000, v19
	v_mul_f32_e32 v14, 0x43000000, v23
	v_mul_f32_e32 v8, 0x43000000, v29
	v_mul_f32_e32 v9, 0x43000000, v31
	v_cvt_pk_fp8_f32 v12, v11, v14 op_sel:[0,0,1]
	v_cvt_pk_fp8_f32 v13, v8, v9 op_sel:[0,0,1]
	v_mul_f32_e32 v8, 0x43000000, v33
	v_mul_f32_e32 v9, 0x43000000, v35
	v_mov_b32_e32 v14, 0
	v_cvt_pk_fp8_f32 v14, v8, v9
	v_mul_f32_e32 v8, 0x43000000, v41
	v_mul_f32_e32 v9, 0x43000000, v43
	v_mov_b32_e32 v15, 0
	v_cvt_pk_fp8_f32 v15, v8, v9
	v_mul_f32_e32 v11, 0x43000000, v37
	v_mul_f32_e32 v16, 0x43000000, v39
	v_mul_f32_e32 v8, 0x43000000, v45
	v_mul_f32_e32 v9, 0x43000000, v47
	v_cvt_pk_fp8_f32 v14, v11, v16 op_sel:[0,0,1]
	v_cvt_pk_fp8_f32 v15, v8, v9 op_sel:[0,0,1]
	v_or_b32_e32 v8, s0, v10
	v_mul_lo_u32 v8, v8, s6
	v_ashrrev_i32_e32 v9, 31, v8
	v_lshl_add_u64 v[8:9], v[20:21], 0, v[8:9]
	global_store_dwordx4 v[8:9], v[12:15], off
	s_waitcnt lgkmcnt(0)
	s_add_i32 s7, s7, s92
	s_cmpk_lt_i32 s7, 0x5600
	s_cbranch_scc1 .LBB0_1181
